# first K-tile of every K-loop peeled with SrcC=0 so the 128-register accumulator zero-init is gone; loop-tail bumps now sit after the full 32-MFMA block; EpiSV rescale packed
# speedup vs baseline: 1.0126x; 1.0114x over previous
; #define PG8_STAGE(bufoff, gbase, voff, p64) do { _Pragma("unroll") for (int _i = 0; _i < 2; ++_i) { \
;         const char* _gb = (const char*)(gbase) + (size_t)_i * (p64); const unsigned _la = ldsbase + (unsigned)(bufoff) + (unsigned)_i * 8192u; \
;         asm volatile("s_mov_b32 m0, %0\n\ts_nop 0\n\tglobal_load_lds_dwordx4 %1, %2" :: "s"(_la), "v"(voff), "s"(_gb) : "memory"); } } while (0)
; #define PG8_LDA(dst, b, h) do { _Pragma("unroll") for (int m = 0; m < 4; ++m) _Pragma("unroll") for (int k = 0; k < 2; ++k) dst[m][k] = *(const LAS bf16x8*)(lds + PG8_SA(b, h) + aoff + m * 2048 + k * 1024); } while (0)
; #define PG8_LDB(dst, b, h) do { _Pragma("unroll") for (int n = 0; n < 2; ++n) _Pragma("unroll") for (int k = 0; k < 2; ++k) dst[n][k] = *(const LAS bf16x8*)(lds + PG8_SB(b, h) + boff + n * 2048 + k * 1024); } while (0)
; #define PG8_MMA(ai, bj, At, Bt) do { __builtin_amdgcn_s_setprio(1); _Pragma("unroll") for (int m = 0; m < 4; ++m) _Pragma("unroll") for (int n = 0; n < 2; ++n) _Pragma("unroll") for (int k = 0; k < 2; ++k) \
;         acc[ai][bj][m][n] = __builtin_amdgcn_mfma_f32_16x16x32_bf16(Bt[n][k], At[m][k], acc[ai][bj][m][n], 0, 0, 0); __builtin_amdgcn_s_setprio(0); } while (0)
; #define PG8_WAIT_V(n) asm volatile("s_waitcnt vmcnt(" #n ")" ::: "memory")
; #define PG8_WAIT_L(n) asm volatile("s_waitcnt lgkmcnt(" #n ")" ::: "memory")
; #define PG8_BAR __builtin_amdgcn_s_barrier()
; template <class Epi, class Sched>
; __device__ __forceinline__ void gemm_phase(LAS unsigned char* lds, const Sched& S, const Epi& E) {
;     ...
; #pragma unroll
;     for (int a = 0; a < 2; ++a)
; #pragma unroll
;         for (int b = 0; b < 2; ++b)
; #pragma unroll
;             for (int m = 0; m < 4; ++m)
; #pragma unroll
;                 for (int n = 0; n < 2; ++n) acc[a][b][m][n] = (f32x4){0.f, 0.f, 0.f, 0.f};
;     ...
;             PG8_LDB(B0, 0, 0); PG8_LDB(B1, 0, 1); PG8_SCHED; PG8_LDA(At, 0, 0); PG8_STAGE(PG8_SA(1, 1), a1 + hA, voffA, hA / 2);
;             PG8_WAIT_V(8); PG8_WAIT_L(0); PG8_BAR; PG8_MMA(0, 0, At, B0); PG8_MMA(0, 1, At, B1); PG8_BAR; PG8_SCHED;
;             PG8_LDA(At, 0, 1); PG8_STAGE(PG8_SB(0, 0), b2, vB2, hB2 / 2); PG8_STAGE(PG8_SB(0, 1), b2 + hB2, vB2, hB2 / 2); PG8_STAGE(PG8_SA(0, 0), a2, vA2, hA2 / 2);
;             PG8_WAIT_V(8); PG8_WAIT_L(0); PG8_BAR; PG8_MMA(1, 0, At, B0); PG8_MMA(1, 1, At, B1); PG8_BAR; PG8_SCHED;
.LBB0_303:
	s_add_u32 s38, s38, 0x40080
	s_addc_u32 s39, s39, 0
	s_add_u32 s62, s40, 0x100
	s_addc_u32 s63, s41, 0
	s_mov_b32 s64, -2
	ds_read_b128 v[144:147], v138
	ds_read_b128 v[148:151], v138 offset:1024
	ds_read_b128 v[152:155], v138 offset:2048
	ds_read_b128 v[156:159], v138 offset:3072
	ds_read_b128 v[160:163], v139
	ds_read_b128 v[164:167], v139 offset:1024
	ds_read_b128 v[168:171], v139 offset:2048
	ds_read_b128 v[172:175], v139 offset:3072
	s_add_u32 s30, s38, 0xfffc0080
	s_addc_u32 s31, s39, -1
	s_cmp_eq_u32 s64, 12
	s_cselect_b32 s40, s24, s30
	s_cselect_b32 s41, s25, s31
	s_cselect_b32 s44, s26, s62
	s_cselect_b32 s45, s27, s63
	s_add_u32 s42, s40, 0x80
	s_addc_u32 s43, s41, 0
	ds_read_b128 v[178:181], v140
	ds_read_b128 v[182:185], v140 offset:1024
	ds_read_b128 v[186:189], v140 offset:2048
	ds_read_b128 v[190:193], v140 offset:3072
	ds_read_b128 v[194:197], v140 offset:4096
	ds_read_b128 v[198:201], v140 offset:5120
	ds_read_b128 v[202:205], v140 offset:6144
	ds_read_b128 v[206:209], v140 offset:7168
	s_mov_b32 m0, s55
	s_nop 0
	global_load_lds_dwordx4 v134, s[38:39]
	s_add_u32 s66, s38, 0x20000
	s_mov_b32 m0, s56
	s_addc_u32 s67, s39, 0
	global_load_lds_dwordx4 v134, s[66:67]
	s_waitcnt vmcnt(8) lgkmcnt(0)
	s_barrier
	s_setprio 1
	v_mfma_f32_16x16x32_bf16 v[124:127], v[144:147], v[178:181], 0
	v_mfma_f32_16x16x32_bf16 v[120:123], v[152:155], v[178:181], 0
	v_mfma_f32_16x16x32_bf16 v[108:111], v[144:147], v[186:189], 0
	v_mfma_f32_16x16x32_bf16 v[104:107], v[152:155], v[186:189], 0
	v_mfma_f32_16x16x32_bf16 v[92:95], v[144:147], v[194:197], 0
	v_mfma_f32_16x16x32_bf16 v[88:91], v[152:155], v[194:197], 0
	v_mfma_f32_16x16x32_bf16 v[76:79], v[144:147], v[202:205], 0
	v_mfma_f32_16x16x32_bf16 v[72:75], v[152:155], v[202:205], 0
	v_mfma_f32_16x16x32_bf16 v[124:127], v[148:151], v[182:185], v[124:127]
	v_mfma_f32_16x16x32_bf16 v[120:123], v[156:159], v[182:185], v[120:123]
	v_mfma_f32_16x16x32_bf16 v[108:111], v[148:151], v[190:193], v[108:111]
	v_mfma_f32_16x16x32_bf16 v[104:107], v[156:159], v[190:193], v[104:107]
	v_mfma_f32_16x16x32_bf16 v[92:95], v[148:151], v[198:201], v[92:95]
	v_mfma_f32_16x16x32_bf16 v[88:91], v[156:159], v[198:201], v[88:91]
	v_mfma_f32_16x16x32_bf16 v[76:79], v[148:151], v[206:209], v[76:79]
	v_mfma_f32_16x16x32_bf16 v[72:75], v[156:159], v[206:209], v[72:75]
	v_mfma_f32_16x16x32_bf16 v[116:119], v[160:163], v[178:181], 0
	v_mfma_f32_16x16x32_bf16 v[112:115], v[168:171], v[178:181], 0
	v_mfma_f32_16x16x32_bf16 v[100:103], v[160:163], v[186:189], 0
	v_mfma_f32_16x16x32_bf16 v[96:99], v[168:171], v[186:189], 0
	v_mfma_f32_16x16x32_bf16 v[84:87], v[160:163], v[194:197], 0
	v_mfma_f32_16x16x32_bf16 v[80:83], v[168:171], v[194:197], 0
	v_mfma_f32_16x16x32_bf16 v[68:71], v[160:163], v[202:205], 0
	v_mfma_f32_16x16x32_bf16 v[64:67], v[168:171], v[202:205], 0
	v_mfma_f32_16x16x32_bf16 v[116:119], v[164:167], v[182:185], v[116:119]
	v_mfma_f32_16x16x32_bf16 v[112:115], v[172:175], v[182:185], v[112:115]
	v_mfma_f32_16x16x32_bf16 v[100:103], v[164:167], v[190:193], v[100:103]
	v_mfma_f32_16x16x32_bf16 v[96:99], v[172:175], v[190:193], v[96:99]
	v_mfma_f32_16x16x32_bf16 v[84:87], v[164:167], v[198:201], v[84:87]
	v_mfma_f32_16x16x32_bf16 v[80:83], v[172:175], v[198:201], v[80:83]
	v_mfma_f32_16x16x32_bf16 v[68:71], v[164:167], v[206:209], v[68:71]
	v_mfma_f32_16x16x32_bf16 v[64:67], v[172:175], v[206:209], v[64:67]
	s_add_i32 s64, s64, 2
	s_add_u32 s38, s38, 0x100
	s_addc_u32 s39, s39, 0
	s_add_u32 s62, s62, 0x100
	s_addc_u32 s63, s63, 0
	s_setprio 0
	s_barrier
	s_add_u32 s66, s44, 0x20000
	ds_read_b128 v[178:181], v140 offset:16384
	ds_read_b128 v[182:185], v140 offset:17408
	ds_read_b128 v[186:189], v140 offset:18432
	ds_read_b128 v[190:193], v140 offset:19456
	ds_read_b128 v[194:197], v140 offset:20480
	ds_read_b128 v[198:201], v140 offset:21504
	ds_read_b128 v[202:205], v140 offset:22528
	ds_read_b128 v[206:209], v140 offset:23552
	s_mov_b32 m0, s33
	s_nop 0
	global_load_lds_dwordx4 v135, s[44:45]
	s_mov_b32 m0, s34
	s_addc_u32 s67, s45, 0
	global_load_lds_dwordx4 v135, s[66:67]
	s_add_u32 s66, s44, 0x40000
	s_mov_b32 m0, s35
	s_addc_u32 s67, s45, 0
	global_load_lds_dwordx4 v135, s[66:67]
	s_add_u32 s66, s44, 0x60000
	s_mov_b32 m0, s36
	s_addc_u32 s67, s45, 0
	global_load_lds_dwordx4 v135, s[66:67]
	s_mov_b32 m0, s12
	s_nop 0
	global_load_lds_dwordx4 v134, s[40:41]
	s_add_u32 s66, s40, 0x20000
	s_mov_b32 m0, s37
	s_addc_u32 s67, s41, 0
	global_load_lds_dwordx4 v134, s[66:67]
	s_waitcnt vmcnt(8) lgkmcnt(0)
	s_barrier
	s_setprio 1
	v_mfma_f32_16x16x32_bf16 v[60:63], v[144:147], v[178:181], 0
	v_mfma_f32_16x16x32_bf16 v[56:59], v[152:155], v[178:181], 0
	v_mfma_f32_16x16x32_bf16 v[44:47], v[144:147], v[186:189], 0
	v_mfma_f32_16x16x32_bf16 v[40:43], v[152:155], v[186:189], 0
	v_mfma_f32_16x16x32_bf16 v[28:31], v[144:147], v[194:197], 0
	v_mfma_f32_16x16x32_bf16 v[24:27], v[152:155], v[194:197], 0
	v_mfma_f32_16x16x32_bf16 v[12:15], v[144:147], v[202:205], 0
	v_mfma_f32_16x16x32_bf16 v[8:11], v[152:155], v[202:205], 0
	v_mfma_f32_16x16x32_bf16 v[60:63], v[148:151], v[182:185], v[60:63]
	v_mfma_f32_16x16x32_bf16 v[56:59], v[156:159], v[182:185], v[56:59]
	v_mfma_f32_16x16x32_bf16 v[44:47], v[148:151], v[190:193], v[44:47]
	v_mfma_f32_16x16x32_bf16 v[40:43], v[156:159], v[190:193], v[40:43]
	v_mfma_f32_16x16x32_bf16 v[28:31], v[148:151], v[198:201], v[28:31]
	v_mfma_f32_16x16x32_bf16 v[24:27], v[156:159], v[198:201], v[24:27]
	v_mfma_f32_16x16x32_bf16 v[12:15], v[148:151], v[206:209], v[12:15]
	v_mfma_f32_16x16x32_bf16 v[8:11], v[156:159], v[206:209], v[8:11]
	v_mfma_f32_16x16x32_bf16 v[52:55], v[160:163], v[178:181], 0
	v_mfma_f32_16x16x32_bf16 v[48:51], v[168:171], v[178:181], 0
	v_mfma_f32_16x16x32_bf16 v[36:39], v[160:163], v[186:189], 0
	v_mfma_f32_16x16x32_bf16 v[32:35], v[168:171], v[186:189], 0
	v_mfma_f32_16x16x32_bf16 v[20:23], v[160:163], v[194:197], 0
	v_mfma_f32_16x16x32_bf16 v[16:19], v[168:171], v[194:197], 0
	v_mfma_f32_16x16x32_bf16 v[4:7], v[160:163], v[202:205], 0
	v_mfma_f32_16x16x32_bf16 v[0:3], v[168:171], v[202:205], 0
	v_mfma_f32_16x16x32_bf16 v[52:55], v[164:167], v[182:185], v[52:55]
	v_mfma_f32_16x16x32_bf16 v[48:51], v[172:175], v[182:185], v[48:51]
	v_mfma_f32_16x16x32_bf16 v[36:39], v[164:167], v[190:193], v[36:39]
	v_mfma_f32_16x16x32_bf16 v[32:35], v[172:175], v[190:193], v[32:35]
	v_mfma_f32_16x16x32_bf16 v[20:23], v[164:167], v[198:201], v[20:23]
	v_mfma_f32_16x16x32_bf16 v[16:19], v[172:175], v[198:201], v[16:19]
	v_mfma_f32_16x16x32_bf16 v[4:7], v[164:167], v[206:209], v[4:7]
	v_mfma_f32_16x16x32_bf16 v[0:3], v[172:175], v[206:209], v[0:3]
	s_setprio 0
	s_barrier
	s_branch .Lpeel_mid_5680
; #define PG8_STAGE(bufoff, gbase, voff, p64) do { _Pragma("unroll") for (int _i = 0; _i < 2; ++_i) { \
;         const char* _gb = (const char*)(gbase) + (size_t)_i * (p64); const unsigned _la = ldsbase + (unsigned)(bufoff) + (unsigned)_i * 8192u; \
;         asm volatile("s_mov_b32 m0, %0\n\ts_nop 0\n\tglobal_load_lds_dwordx4 %1, %2" :: "s"(_la), "v"(voff), "s"(_gb) : "memory"); } } while (0)
; #define PG8_LDA(dst, b, h) do { _Pragma("unroll") for (int m = 0; m < 4; ++m) _Pragma("unroll") for (int k = 0; k < 2; ++k) dst[m][k] = *(const LAS bf16x8*)(lds + PG8_SA(b, h) + aoff + m * 2048 + k * 1024); } while (0)
; #define PG8_LDB(dst, b, h) do { _Pragma("unroll") for (int n = 0; n < 2; ++n) _Pragma("unroll") for (int k = 0; k < 2; ++k) dst[n][k] = *(const LAS bf16x8*)(lds + PG8_SB(b, h) + boff + n * 2048 + k * 1024); } while (0)
; #define PG8_MMA(ai, bj, At, Bt) do { __builtin_amdgcn_s_setprio(1); _Pragma("unroll") for (int m = 0; m < 4; ++m) _Pragma("unroll") for (int n = 0; n < 2; ++n) _Pragma("unroll") for (int k = 0; k < 2; ++k) \
;         acc[ai][bj][m][n] = __builtin_amdgcn_mfma_f32_16x16x32_bf16(Bt[n][k], At[m][k], acc[ai][bj][m][n], 0, 0, 0); __builtin_amdgcn_s_setprio(0); } while (0)
; #define PG8_WAIT_V(n) asm volatile("s_waitcnt vmcnt(" #n ")" ::: "memory")
; #define PG8_WAIT_L(n) asm volatile("s_waitcnt lgkmcnt(" #n ")" ::: "memory")
; #define PG8_BAR __builtin_amdgcn_s_barrier()
; #define PG8_SCHED __builtin_amdgcn_sched_barrier(0)
; template <class Epi, class Sched>
; __device__ __forceinline__ void gemm_phase(LAS unsigned char* lds, const Sched& S, const Epi& E) {
;     ...
;             PG8_LDB(B0, 0, 0); PG8_LDB(B1, 0, 1); PG8_SCHED; PG8_LDA(At, 0, 0); PG8_STAGE(PG8_SA(1, 1), a1 + hA, voffA, hA / 2);
;             PG8_WAIT_V(8); PG8_WAIT_L(0); PG8_BAR; PG8_MMA(0, 0, At, B0); PG8_MMA(0, 1, At, B1); PG8_BAR; PG8_SCHED;
;             PG8_LDA(At, 0, 1); PG8_STAGE(PG8_SB(0, 0), b2, vB2, hB2 / 2); PG8_STAGE(PG8_SB(0, 1), b2 + hB2, vB2, hB2 / 2); PG8_STAGE(PG8_SA(0, 0), a2, vA2, hA2 / 2);
;             PG8_WAIT_V(8); PG8_WAIT_L(0); PG8_BAR; PG8_MMA(1, 0, At, B0); PG8_MMA(1, 1, At, B1); PG8_BAR; PG8_SCHED;
.LBB0_304:
	ds_read_b128 v[144:147], v138
	ds_read_b128 v[148:151], v138 offset:1024
	ds_read_b128 v[152:155], v138 offset:2048
	ds_read_b128 v[156:159], v138 offset:3072
	ds_read_b128 v[160:163], v139
	ds_read_b128 v[164:167], v139 offset:1024
	ds_read_b128 v[168:171], v139 offset:2048
	ds_read_b128 v[172:175], v139 offset:3072
	s_add_u32 s30, s38, 0xfffc0080
	s_addc_u32 s31, s39, -1
	s_cmp_eq_u32 s64, 12
	s_cselect_b32 s40, s24, s30
	s_cselect_b32 s41, s25, s31
	s_cselect_b32 s44, s26, s62
	s_cselect_b32 s45, s27, s63
	s_add_u32 s42, s40, 0x80
	s_addc_u32 s43, s41, 0
	ds_read_b128 v[178:181], v140
	ds_read_b128 v[182:185], v140 offset:1024
	ds_read_b128 v[186:189], v140 offset:2048
	ds_read_b128 v[190:193], v140 offset:3072
	ds_read_b128 v[194:197], v140 offset:4096
	ds_read_b128 v[198:201], v140 offset:5120
	ds_read_b128 v[202:205], v140 offset:6144
	ds_read_b128 v[206:209], v140 offset:7168
	s_mov_b32 m0, s55
	s_nop 0
	global_load_lds_dwordx4 v134, s[38:39]
	s_add_u32 s66, s38, 0x20000
	s_mov_b32 m0, s56
	s_addc_u32 s67, s39, 0
	global_load_lds_dwordx4 v134, s[66:67]
	s_waitcnt vmcnt(8) lgkmcnt(0)
	s_barrier
	s_setprio 1
	v_mfma_f32_16x16x32_bf16 v[124:127], v[144:147], v[178:181], v[124:127]
	v_mfma_f32_16x16x32_bf16 v[120:123], v[152:155], v[178:181], v[120:123]
	v_mfma_f32_16x16x32_bf16 v[108:111], v[144:147], v[186:189], v[108:111]
	v_mfma_f32_16x16x32_bf16 v[104:107], v[152:155], v[186:189], v[104:107]
	v_mfma_f32_16x16x32_bf16 v[92:95], v[144:147], v[194:197], v[92:95]
	v_mfma_f32_16x16x32_bf16 v[88:91], v[152:155], v[194:197], v[88:91]
	v_mfma_f32_16x16x32_bf16 v[76:79], v[144:147], v[202:205], v[76:79]
	v_mfma_f32_16x16x32_bf16 v[72:75], v[152:155], v[202:205], v[72:75]
	v_mfma_f32_16x16x32_bf16 v[124:127], v[148:151], v[182:185], v[124:127]
	v_mfma_f32_16x16x32_bf16 v[120:123], v[156:159], v[182:185], v[120:123]
	v_mfma_f32_16x16x32_bf16 v[108:111], v[148:151], v[190:193], v[108:111]
	v_mfma_f32_16x16x32_bf16 v[104:107], v[156:159], v[190:193], v[104:107]
	v_mfma_f32_16x16x32_bf16 v[92:95], v[148:151], v[198:201], v[92:95]
	v_mfma_f32_16x16x32_bf16 v[88:91], v[156:159], v[198:201], v[88:91]
	v_mfma_f32_16x16x32_bf16 v[76:79], v[148:151], v[206:209], v[76:79]
	v_mfma_f32_16x16x32_bf16 v[72:75], v[156:159], v[206:209], v[72:75]
	v_mfma_f32_16x16x32_bf16 v[116:119], v[160:163], v[178:181], v[116:119]
	v_mfma_f32_16x16x32_bf16 v[112:115], v[168:171], v[178:181], v[112:115]
	v_mfma_f32_16x16x32_bf16 v[100:103], v[160:163], v[186:189], v[100:103]
	v_mfma_f32_16x16x32_bf16 v[96:99], v[168:171], v[186:189], v[96:99]
	v_mfma_f32_16x16x32_bf16 v[84:87], v[160:163], v[194:197], v[84:87]
	v_mfma_f32_16x16x32_bf16 v[80:83], v[168:171], v[194:197], v[80:83]
	v_mfma_f32_16x16x32_bf16 v[68:71], v[160:163], v[202:205], v[68:71]
	v_mfma_f32_16x16x32_bf16 v[64:67], v[168:171], v[202:205], v[64:67]
	v_mfma_f32_16x16x32_bf16 v[116:119], v[164:167], v[182:185], v[116:119]
	v_mfma_f32_16x16x32_bf16 v[112:115], v[172:175], v[182:185], v[112:115]
	v_mfma_f32_16x16x32_bf16 v[100:103], v[164:167], v[190:193], v[100:103]
	v_mfma_f32_16x16x32_bf16 v[96:99], v[172:175], v[190:193], v[96:99]
	v_mfma_f32_16x16x32_bf16 v[84:87], v[164:167], v[198:201], v[84:87]
	v_mfma_f32_16x16x32_bf16 v[80:83], v[172:175], v[198:201], v[80:83]
	v_mfma_f32_16x16x32_bf16 v[68:71], v[164:167], v[206:209], v[68:71]
	v_mfma_f32_16x16x32_bf16 v[64:67], v[172:175], v[206:209], v[64:67]
	s_add_i32 s64, s64, 2
	s_add_u32 s38, s38, 0x100
	s_addc_u32 s39, s39, 0
	s_add_u32 s62, s62, 0x100
	s_addc_u32 s63, s63, 0
	s_setprio 0
	s_barrier
	s_add_u32 s66, s44, 0x20000
	ds_read_b128 v[178:181], v140 offset:16384
	ds_read_b128 v[182:185], v140 offset:17408
	ds_read_b128 v[186:189], v140 offset:18432
	ds_read_b128 v[190:193], v140 offset:19456
	ds_read_b128 v[194:197], v140 offset:20480
	ds_read_b128 v[198:201], v140 offset:21504
	ds_read_b128 v[202:205], v140 offset:22528
	ds_read_b128 v[206:209], v140 offset:23552
	s_mov_b32 m0, s33
	s_nop 0
	global_load_lds_dwordx4 v135, s[44:45]
	s_mov_b32 m0, s34
	s_addc_u32 s67, s45, 0
	global_load_lds_dwordx4 v135, s[66:67]
	s_add_u32 s66, s44, 0x40000
	s_mov_b32 m0, s35
	s_addc_u32 s67, s45, 0
	global_load_lds_dwordx4 v135, s[66:67]
	s_add_u32 s66, s44, 0x60000
	s_mov_b32 m0, s36
	s_addc_u32 s67, s45, 0
	global_load_lds_dwordx4 v135, s[66:67]
	s_mov_b32 m0, s12
	s_nop 0
	global_load_lds_dwordx4 v134, s[40:41]
	s_add_u32 s66, s40, 0x20000
	s_mov_b32 m0, s37
	s_addc_u32 s67, s41, 0
	global_load_lds_dwordx4 v134, s[66:67]
	s_waitcnt vmcnt(8) lgkmcnt(0)
	s_barrier
	s_setprio 1
	v_mfma_f32_16x16x32_bf16 v[60:63], v[144:147], v[178:181], v[60:63]
	v_mfma_f32_16x16x32_bf16 v[56:59], v[152:155], v[178:181], v[56:59]
	v_mfma_f32_16x16x32_bf16 v[44:47], v[144:147], v[186:189], v[44:47]
	v_mfma_f32_16x16x32_bf16 v[40:43], v[152:155], v[186:189], v[40:43]
	v_mfma_f32_16x16x32_bf16 v[28:31], v[144:147], v[194:197], v[28:31]
	v_mfma_f32_16x16x32_bf16 v[24:27], v[152:155], v[194:197], v[24:27]
	v_mfma_f32_16x16x32_bf16 v[12:15], v[144:147], v[202:205], v[12:15]
	v_mfma_f32_16x16x32_bf16 v[8:11], v[152:155], v[202:205], v[8:11]
	v_mfma_f32_16x16x32_bf16 v[60:63], v[148:151], v[182:185], v[60:63]
	v_mfma_f32_16x16x32_bf16 v[56:59], v[156:159], v[182:185], v[56:59]
	v_mfma_f32_16x16x32_bf16 v[44:47], v[148:151], v[190:193], v[44:47]
	v_mfma_f32_16x16x32_bf16 v[40:43], v[156:159], v[190:193], v[40:43]
	v_mfma_f32_16x16x32_bf16 v[28:31], v[148:151], v[198:201], v[28:31]
	v_mfma_f32_16x16x32_bf16 v[24:27], v[156:159], v[198:201], v[24:27]
	v_mfma_f32_16x16x32_bf16 v[12:15], v[148:151], v[206:209], v[12:15]
	v_mfma_f32_16x16x32_bf16 v[8:11], v[156:159], v[206:209], v[8:11]
	v_mfma_f32_16x16x32_bf16 v[52:55], v[160:163], v[178:181], v[52:55]
	v_mfma_f32_16x16x32_bf16 v[48:51], v[168:171], v[178:181], v[48:51]
	v_mfma_f32_16x16x32_bf16 v[36:39], v[160:163], v[186:189], v[36:39]
	v_mfma_f32_16x16x32_bf16 v[32:35], v[168:171], v[186:189], v[32:35]
	v_mfma_f32_16x16x32_bf16 v[20:23], v[160:163], v[194:197], v[20:23]
	v_mfma_f32_16x16x32_bf16 v[16:19], v[168:171], v[194:197], v[16:19]
	v_mfma_f32_16x16x32_bf16 v[4:7], v[160:163], v[202:205], v[4:7]
	v_mfma_f32_16x16x32_bf16 v[0:3], v[168:171], v[202:205], v[0:3]
	v_mfma_f32_16x16x32_bf16 v[52:55], v[164:167], v[182:185], v[52:55]
	v_mfma_f32_16x16x32_bf16 v[48:51], v[172:175], v[182:185], v[48:51]
	v_mfma_f32_16x16x32_bf16 v[36:39], v[164:167], v[190:193], v[36:39]
	v_mfma_f32_16x16x32_bf16 v[32:35], v[172:175], v[190:193], v[32:35]
	v_mfma_f32_16x16x32_bf16 v[20:23], v[164:167], v[198:201], v[20:23]
	v_mfma_f32_16x16x32_bf16 v[16:19], v[172:175], v[198:201], v[16:19]
	v_mfma_f32_16x16x32_bf16 v[4:7], v[164:167], v[206:209], v[4:7]
	v_mfma_f32_16x16x32_bf16 v[0:3], v[172:175], v[206:209], v[0:3]
	s_setprio 0
	s_barrier
; #define PG8_STAGE(bufoff, gbase, voff, p64) do { _Pragma("unroll") for (int _i = 0; _i < 2; ++_i) { \
;         const char* _gb = (const char*)(gbase) + (size_t)_i * (p64); const unsigned _la = ldsbase + (unsigned)(bufoff) + (unsigned)_i * 8192u; \
;         asm volatile("s_mov_b32 m0, %0\n\ts_nop 0\n\tglobal_load_lds_dwordx4 %1, %2" :: "s"(_la), "v"(voff), "s"(_gb) : "memory"); } } while (0)
; #define PG8_LDA(dst, b, h) do { _Pragma("unroll") for (int m = 0; m < 4; ++m) _Pragma("unroll") for (int k = 0; k < 2; ++k) dst[m][k] = *(const LAS bf16x8*)(lds + PG8_SA(b, h) + aoff + m * 2048 + k * 1024); } while (0)
; #define PG8_LDB(dst, b, h) do { _Pragma("unroll") for (int n = 0; n < 2; ++n) _Pragma("unroll") for (int k = 0; k < 2; ++k) dst[n][k] = *(const LAS bf16x8*)(lds + PG8_SB(b, h) + boff + n * 2048 + k * 1024); } while (0)
; #define PG8_MMA(ai, bj, At, Bt) do { __builtin_amdgcn_s_setprio(1); _Pragma("unroll") for (int m = 0; m < 4; ++m) _Pragma("unroll") for (int n = 0; n < 2; ++n) _Pragma("unroll") for (int k = 0; k < 2; ++k) \
;         acc[ai][bj][m][n] = __builtin_amdgcn_mfma_f32_16x16x32_bf16(Bt[n][k], At[m][k], acc[ai][bj][m][n], 0, 0, 0); __builtin_amdgcn_s_setprio(0); } while (0)
; #define PG8_WAIT_V(n) asm volatile("s_waitcnt vmcnt(" #n ")" ::: "memory")
; #define PG8_WAIT_L(n) asm volatile("s_waitcnt lgkmcnt(" #n ")" ::: "memory")
; #define PG8_BAR __builtin_amdgcn_s_barrier()
; #define PG8_SCHED __builtin_amdgcn_sched_barrier(0)
; template <class Epi, class Sched>
; __device__ __forceinline__ void gemm_phase(LAS unsigned char* lds, const Sched& S, const Epi& E) {
;     ...
;             PG8_LDB(B0, 1, 0); PG8_LDB(B1, 1, 1); PG8_SCHED; PG8_LDA(At, 1, 0); PG8_STAGE(PG8_SA(0, 1), a2 + hA2, vA2, hA2 / 2);
;             PG8_WAIT_V(8); PG8_WAIT_L(0); PG8_BAR; PG8_MMA(0, 0, At, B0); PG8_MMA(0, 1, At, B1); PG8_BAR; PG8_SCHED;
;             PG8_LDA(At, 1, 1); PG8_STAGE(PG8_SB(1, 0), b3, vB2, hB2 / 2); PG8_STAGE(PG8_SB(1, 1), b3 + hB2, vB2, hB2 / 2); PG8_STAGE(PG8_SA(1, 0), a3, vA2, hA2 / 2);
;             PG8_WAIT_V(8); PG8_WAIT_L(0); PG8_BAR; PG8_MMA(1, 0, At, B0); PG8_MMA(1, 1, At, B1); PG8_BAR; PG8_SCHED;
;         }
;         if (wr == 0) PG8_BAR;
.Lpeel_mid_5680:
	ds_read_b128 v[144:147], v141
	ds_read_b128 v[148:151], v141 offset:1024
	ds_read_b128 v[152:155], v141 offset:2048
	ds_read_b128 v[156:159], v141 offset:3072
	ds_read_b128 v[160:163], v142
	ds_read_b128 v[164:167], v142 offset:1024
	ds_read_b128 v[168:171], v142 offset:2048
	ds_read_b128 v[172:175], v142 offset:3072
	ds_read_b128 v[178:181], v140 offset:32768
	ds_read_b128 v[182:185], v140 offset:33792
	ds_read_b128 v[186:189], v140 offset:34816
	ds_read_b128 v[190:193], v140 offset:35840
	ds_read_b128 v[194:197], v140 offset:36864
	ds_read_b128 v[198:201], v140 offset:37888
	ds_read_b128 v[202:205], v140 offset:38912
	ds_read_b128 v[206:209], v140 offset:39936
	s_add_u32 s66, s40, 0x40000
	s_mov_b32 m0, s46
	s_addc_u32 s67, s41, 0
	global_load_lds_dwordx4 v134, s[66:67]
	s_add_u32 s66, s40, 0x60000
	s_mov_b32 m0, s47
	s_addc_u32 s67, s41, 0
	global_load_lds_dwordx4 v134, s[66:67]
	s_waitcnt vmcnt(8) lgkmcnt(0)
	s_barrier
	s_setprio 1
	v_mfma_f32_16x16x32_bf16 v[124:127], v[144:147], v[178:181], v[124:127]
	v_mfma_f32_16x16x32_bf16 v[120:123], v[152:155], v[178:181], v[120:123]
	v_mfma_f32_16x16x32_bf16 v[108:111], v[144:147], v[186:189], v[108:111]
	v_mfma_f32_16x16x32_bf16 v[104:107], v[152:155], v[186:189], v[104:107]
	v_mfma_f32_16x16x32_bf16 v[92:95], v[144:147], v[194:197], v[92:95]
	v_mfma_f32_16x16x32_bf16 v[88:91], v[152:155], v[194:197], v[88:91]
	v_mfma_f32_16x16x32_bf16 v[76:79], v[144:147], v[202:205], v[76:79]
	v_mfma_f32_16x16x32_bf16 v[72:75], v[152:155], v[202:205], v[72:75]
	v_mfma_f32_16x16x32_bf16 v[124:127], v[148:151], v[182:185], v[124:127]
	v_mfma_f32_16x16x32_bf16 v[120:123], v[156:159], v[182:185], v[120:123]
	v_mfma_f32_16x16x32_bf16 v[108:111], v[148:151], v[190:193], v[108:111]
	v_mfma_f32_16x16x32_bf16 v[104:107], v[156:159], v[190:193], v[104:107]
	v_mfma_f32_16x16x32_bf16 v[92:95], v[148:151], v[198:201], v[92:95]
	v_mfma_f32_16x16x32_bf16 v[88:91], v[156:159], v[198:201], v[88:91]
	v_mfma_f32_16x16x32_bf16 v[76:79], v[148:151], v[206:209], v[76:79]
	v_mfma_f32_16x16x32_bf16 v[72:75], v[156:159], v[206:209], v[72:75]
	v_mfma_f32_16x16x32_bf16 v[116:119], v[160:163], v[178:181], v[116:119]
	v_mfma_f32_16x16x32_bf16 v[112:115], v[168:171], v[178:181], v[112:115]
	v_mfma_f32_16x16x32_bf16 v[100:103], v[160:163], v[186:189], v[100:103]
	v_mfma_f32_16x16x32_bf16 v[96:99], v[168:171], v[186:189], v[96:99]
	v_mfma_f32_16x16x32_bf16 v[84:87], v[160:163], v[194:197], v[84:87]
	v_mfma_f32_16x16x32_bf16 v[80:83], v[168:171], v[194:197], v[80:83]
	v_mfma_f32_16x16x32_bf16 v[68:71], v[160:163], v[202:205], v[68:71]
	v_mfma_f32_16x16x32_bf16 v[64:67], v[168:171], v[202:205], v[64:67]
	v_mfma_f32_16x16x32_bf16 v[116:119], v[164:167], v[182:185], v[116:119]
	v_mfma_f32_16x16x32_bf16 v[112:115], v[172:175], v[182:185], v[112:115]
	v_mfma_f32_16x16x32_bf16 v[100:103], v[164:167], v[190:193], v[100:103]
	v_mfma_f32_16x16x32_bf16 v[96:99], v[172:175], v[190:193], v[96:99]
	v_mfma_f32_16x16x32_bf16 v[84:87], v[164:167], v[198:201], v[84:87]
	v_mfma_f32_16x16x32_bf16 v[80:83], v[172:175], v[198:201], v[80:83]
	v_mfma_f32_16x16x32_bf16 v[68:71], v[164:167], v[206:209], v[68:71]
	v_mfma_f32_16x16x32_bf16 v[64:67], v[172:175], v[206:209], v[64:67]
	s_setprio 0
	s_barrier
	s_add_u32 s66, s44, 0x80
	s_addc_u32 s67, s45, 0
	ds_read_b128 v[178:181], v140 offset:49152
	ds_read_b128 v[182:185], v140 offset:50176
	ds_read_b128 v[186:189], v140 offset:51200
	ds_read_b128 v[190:193], v140 offset:52224
	ds_read_b128 v[194:197], v140 offset:53248
	ds_read_b128 v[198:201], v140 offset:54272
	ds_read_b128 v[202:205], v140 offset:55296
	ds_read_b128 v[206:209], v140 offset:56320
	s_mov_b32 m0, s49
	s_nop 0
	global_load_lds_dwordx4 v135, s[66:67]
	s_add_u32 s66, s44, 0x20080
	s_mov_b32 m0, s50
	s_addc_u32 s67, s45, 0
	global_load_lds_dwordx4 v135, s[66:67]
	s_add_u32 s66, s44, 0x40080
	s_mov_b32 m0, s53
	s_addc_u32 s67, s45, 0
	global_load_lds_dwordx4 v135, s[66:67]
	s_add_u32 s44, s44, 0x60080
	s_mov_b32 m0, s54
	s_addc_u32 s45, s45, 0
	global_load_lds_dwordx4 v135, s[44:45]
	s_mov_b32 m0, s51
	s_nop 0
	global_load_lds_dwordx4 v134, s[42:43]
	s_add_u32 s40, s40, 0x20080
	s_mov_b32 m0, s52
	s_addc_u32 s41, s41, 0
	global_load_lds_dwordx4 v134, s[40:41]
	s_waitcnt vmcnt(8) lgkmcnt(0)
	s_barrier
	s_setprio 1
	v_mfma_f32_16x16x32_bf16 v[60:63], v[144:147], v[178:181], v[60:63]
	v_mfma_f32_16x16x32_bf16 v[56:59], v[152:155], v[178:181], v[56:59]
	v_mfma_f32_16x16x32_bf16 v[44:47], v[144:147], v[186:189], v[44:47]
	v_mfma_f32_16x16x32_bf16 v[40:43], v[152:155], v[186:189], v[40:43]
	v_mfma_f32_16x16x32_bf16 v[28:31], v[144:147], v[194:197], v[28:31]
	v_mfma_f32_16x16x32_bf16 v[24:27], v[152:155], v[194:197], v[24:27]
	v_mfma_f32_16x16x32_bf16 v[12:15], v[144:147], v[202:205], v[12:15]
	v_mfma_f32_16x16x32_bf16 v[8:11], v[152:155], v[202:205], v[8:11]
	v_mfma_f32_16x16x32_bf16 v[60:63], v[148:151], v[182:185], v[60:63]
	v_mfma_f32_16x16x32_bf16 v[56:59], v[156:159], v[182:185], v[56:59]
	v_mfma_f32_16x16x32_bf16 v[44:47], v[148:151], v[190:193], v[44:47]
	v_mfma_f32_16x16x32_bf16 v[40:43], v[156:159], v[190:193], v[40:43]
	v_mfma_f32_16x16x32_bf16 v[28:31], v[148:151], v[198:201], v[28:31]
	v_mfma_f32_16x16x32_bf16 v[24:27], v[156:159], v[198:201], v[24:27]
	v_mfma_f32_16x16x32_bf16 v[12:15], v[148:151], v[206:209], v[12:15]
	v_mfma_f32_16x16x32_bf16 v[8:11], v[156:159], v[206:209], v[8:11]
	v_mfma_f32_16x16x32_bf16 v[52:55], v[160:163], v[178:181], v[52:55]
	v_mfma_f32_16x16x32_bf16 v[48:51], v[168:171], v[178:181], v[48:51]
	v_mfma_f32_16x16x32_bf16 v[36:39], v[160:163], v[186:189], v[36:39]
	v_mfma_f32_16x16x32_bf16 v[32:35], v[168:171], v[186:189], v[32:35]
	v_mfma_f32_16x16x32_bf16 v[20:23], v[160:163], v[194:197], v[20:23]
	v_mfma_f32_16x16x32_bf16 v[16:19], v[168:171], v[194:197], v[16:19]
	v_mfma_f32_16x16x32_bf16 v[4:7], v[160:163], v[202:205], v[4:7]
	v_mfma_f32_16x16x32_bf16 v[0:3], v[168:171], v[202:205], v[0:3]
	v_mfma_f32_16x16x32_bf16 v[52:55], v[164:167], v[182:185], v[52:55]
	v_mfma_f32_16x16x32_bf16 v[48:51], v[172:175], v[182:185], v[48:51]
	v_mfma_f32_16x16x32_bf16 v[36:39], v[164:167], v[190:193], v[36:39]
	v_mfma_f32_16x16x32_bf16 v[32:35], v[172:175], v[190:193], v[32:35]
	v_mfma_f32_16x16x32_bf16 v[20:23], v[164:167], v[198:201], v[20:23]
	v_mfma_f32_16x16x32_bf16 v[16:19], v[172:175], v[198:201], v[16:19]
	v_mfma_f32_16x16x32_bf16 v[4:7], v[164:167], v[206:209], v[4:7]
	v_mfma_f32_16x16x32_bf16 v[0:3], v[172:175], v[206:209], v[0:3]
	s_setprio 0
	s_barrier
	s_cmp_gt_u32 s64, 13
	s_cbranch_scc0 .LBB0_304
	s_and_b64 vcc, exec, s[18:19]
	s_cbranch_vccz .LBB0_307
	s_barrier

; #define PG8_STAGE(bufoff, gbase, voff, p64) do { _Pragma("unroll") for (int _i = 0; _i < 2; ++_i) { \
;         const char* _gb = (const char*)(gbase) + (size_t)_i * (p64); const unsigned _la = ldsbase + (unsigned)(bufoff) + (unsigned)_i * 8192u; \
;         asm volatile("s_mov_b32 m0, %0\n\ts_nop 0\n\tglobal_load_lds_dwordx4 %1, %2" :: "s"(_la), "v"(voff), "s"(_gb) : "memory"); } } while (0)
; #define PG8_LDA(dst, b, h) do { _Pragma("unroll") for (int m = 0; m < 4; ++m) _Pragma("unroll") for (int k = 0; k < 2; ++k) dst[m][k] = *(const LAS bf16x8*)(lds + PG8_SA(b, h) + aoff + m * 2048 + k * 1024); } while (0)
; #define PG8_LDB(dst, b, h) do { _Pragma("unroll") for (int n = 0; n < 2; ++n) _Pragma("unroll") for (int k = 0; k < 2; ++k) dst[n][k] = *(const LAS bf16x8*)(lds + PG8_SB(b, h) + boff + n * 2048 + k * 1024); } while (0)
; #define PG8_MMA(ai, bj, At, Bt) do { __builtin_amdgcn_s_setprio(1); _Pragma("unroll") for (int m = 0; m < 4; ++m) _Pragma("unroll") for (int n = 0; n < 2; ++n) _Pragma("unroll") for (int k = 0; k < 2; ++k) \
;         acc[ai][bj][m][n] = __builtin_amdgcn_mfma_f32_16x16x32_bf16(Bt[n][k], At[m][k], acc[ai][bj][m][n], 0, 0, 0); __builtin_amdgcn_s_setprio(0); } while (0)
; #define PG8_WAIT_V(n) asm volatile("s_waitcnt vmcnt(" #n ")" ::: "memory")
; #define PG8_WAIT_L(n) asm volatile("s_waitcnt lgkmcnt(" #n ")" ::: "memory")
; #define PG8_BAR __builtin_amdgcn_s_barrier()
; template <class Epi, class Sched>
; __device__ __forceinline__ void gemm_phase(LAS unsigned char* lds, const Sched& S, const Epi& E) {
;     ...
; #pragma unroll
;     for (int a = 0; a < 2; ++a)
; #pragma unroll
;         for (int b = 0; b < 2; ++b)
; #pragma unroll
;             for (int m = 0; m < 4; ++m)
; #pragma unroll
;                 for (int n = 0; n < 2; ++n) acc[a][b][m][n] = (f32x4){0.f, 0.f, 0.f, 0.f};
;     ...
;             PG8_LDB(B0, 0, 0); PG8_LDB(B1, 0, 1); PG8_SCHED; PG8_LDA(At, 0, 0); PG8_STAGE(PG8_SA(1, 1), a1 + hA, voffA, hA / 2);
;             PG8_WAIT_V(8); PG8_WAIT_L(0); PG8_BAR; PG8_MMA(0, 0, At, B0); PG8_MMA(0, 1, At, B1); PG8_BAR; PG8_SCHED;
;             PG8_LDA(At, 0, 1); PG8_STAGE(PG8_SB(0, 0), b2, vB2, hB2 / 2); PG8_STAGE(PG8_SB(0, 1), b2 + hB2, vB2, hB2 / 2); PG8_STAGE(PG8_SA(0, 0), a2, vA2, hA2 / 2);
;             PG8_WAIT_V(8); PG8_WAIT_L(0); PG8_BAR; PG8_MMA(1, 0, At, B0); PG8_MMA(1, 1, At, B1); PG8_BAR; PG8_SCHED;
.LBB0_397:
	s_and_b64 s[42:43], s[26:27], exec
	s_cselect_b32 s44, s25, s41
	s_cselect_b32 s45, s24, s40
	s_cselect_b32 s66, s23, s39
	s_cselect_b32 s67, s22, s38
	s_add_i32 s68, s21, -2
	s_add_u32 s69, s38, 0x100
	s_addc_u32 s70, s39, 0
	s_add_u32 s71, s40, 0x100
	s_addc_u32 s72, s41, 0
	s_mov_b32 s38, 0
	ds_read_b128 v[130:133], v164
	ds_read_b128 v[134:137], v164 offset:1024
	ds_read_b128 v[138:141], v164 offset:2048
	ds_read_b128 v[142:145], v164 offset:3072
	ds_read_b128 v[146:149], v165
	ds_read_b128 v[150:153], v165 offset:1024
	ds_read_b128 v[154:157], v165 offset:2048
	ds_read_b128 v[158:161], v165 offset:3072
	s_add_i32 s73, s38, 2
	s_cmp_eq_u32 s68, s38
	s_cselect_b32 s38, s67, s69
	s_cselect_b32 s39, s66, s70
	s_cselect_b32 s42, s45, s71
	s_cselect_b32 s43, s44, s72
	s_add_u32 s40, s38, 0x80
	s_addc_u32 s41, s39, 0
	ds_read_b128 v[170:173], v166
	ds_read_b128 v[178:181], v166 offset:1024
	ds_read_b128 v[182:185], v166 offset:2048
	ds_read_b128 v[186:189], v166 offset:3072
	ds_read_b128 v[190:193], v166 offset:4096
	ds_read_b128 v[194:197], v166 offset:5120
	ds_read_b128 v[198:201], v166 offset:6144
	ds_read_b128 v[202:205], v166 offset:7168
	s_add_u32 s74, s69, 0xaff80
	s_mov_b32 m0, s59
	s_addc_u32 s75, s70, 0
	global_load_lds_dwordx4 v128, s[74:75]
	s_add_u32 s74, s69, 0x107f80
	s_mov_b32 m0, s60
	s_addc_u32 s75, s70, 0
	global_load_lds_dwordx4 v128, s[74:75]
	s_waitcnt vmcnt(8) lgkmcnt(0)
	s_barrier
	s_setprio 1
	v_mfma_f32_16x16x32_bf16 v[124:127], v[130:133], v[170:173], 0
	v_mfma_f32_16x16x32_bf16 v[120:123], v[138:141], v[170:173], 0
	v_mfma_f32_16x16x32_bf16 v[116:119], v[130:133], v[182:185], 0
	v_mfma_f32_16x16x32_bf16 v[112:115], v[138:141], v[182:185], 0
	v_mfma_f32_16x16x32_bf16 v[108:111], v[130:133], v[190:193], 0
	v_mfma_f32_16x16x32_bf16 v[104:107], v[138:141], v[190:193], 0
	v_mfma_f32_16x16x32_bf16 v[100:103], v[130:133], v[198:201], 0
	v_mfma_f32_16x16x32_bf16 v[96:99], v[138:141], v[198:201], 0
	v_mfma_f32_16x16x32_bf16 v[124:127], v[134:137], v[178:181], v[124:127]
	v_mfma_f32_16x16x32_bf16 v[120:123], v[142:145], v[178:181], v[120:123]
	v_mfma_f32_16x16x32_bf16 v[116:119], v[134:137], v[186:189], v[116:119]
	v_mfma_f32_16x16x32_bf16 v[112:115], v[142:145], v[186:189], v[112:115]
	v_mfma_f32_16x16x32_bf16 v[108:111], v[134:137], v[194:197], v[108:111]
	v_mfma_f32_16x16x32_bf16 v[104:107], v[142:145], v[194:197], v[104:107]
	v_mfma_f32_16x16x32_bf16 v[100:103], v[134:137], v[202:205], v[100:103]
	v_mfma_f32_16x16x32_bf16 v[96:99], v[142:145], v[202:205], v[96:99]
	v_mfma_f32_16x16x32_bf16 v[60:63], v[146:149], v[170:173], 0
	v_mfma_f32_16x16x32_bf16 v[56:59], v[154:157], v[170:173], 0
	v_mfma_f32_16x16x32_bf16 v[52:55], v[146:149], v[182:185], 0
	v_mfma_f32_16x16x32_bf16 v[48:51], v[154:157], v[182:185], 0
	v_mfma_f32_16x16x32_bf16 v[44:47], v[146:149], v[190:193], 0
	v_mfma_f32_16x16x32_bf16 v[40:43], v[154:157], v[190:193], 0
	v_mfma_f32_16x16x32_bf16 v[36:39], v[146:149], v[198:201], 0
	v_mfma_f32_16x16x32_bf16 v[32:35], v[154:157], v[198:201], 0
	v_mfma_f32_16x16x32_bf16 v[60:63], v[150:153], v[178:181], v[60:63]
	v_mfma_f32_16x16x32_bf16 v[56:59], v[158:161], v[178:181], v[56:59]
	v_mfma_f32_16x16x32_bf16 v[52:55], v[150:153], v[186:189], v[52:55]
	v_mfma_f32_16x16x32_bf16 v[48:51], v[158:161], v[186:189], v[48:51]
	v_mfma_f32_16x16x32_bf16 v[44:47], v[150:153], v[194:197], v[44:47]
	v_mfma_f32_16x16x32_bf16 v[40:43], v[158:161], v[194:197], v[40:43]
	v_mfma_f32_16x16x32_bf16 v[36:39], v[150:153], v[202:205], v[36:39]
	v_mfma_f32_16x16x32_bf16 v[32:35], v[158:161], v[202:205], v[32:35]
	s_add_u32 s69, s69, 0x100
	s_addc_u32 s70, s70, 0
	s_add_u32 s71, s71, 0x100
	s_addc_u32 s72, s72, 0
	s_setprio 0
	s_barrier
	s_add_u32 s74, s42, 0x58000
	ds_read_b128 v[170:173], v166 offset:16384
	ds_read_b128 v[178:181], v166 offset:17408
	ds_read_b128 v[182:185], v166 offset:18432
	ds_read_b128 v[186:189], v166 offset:19456
	ds_read_b128 v[190:193], v166 offset:20480
	ds_read_b128 v[194:197], v166 offset:21504
	ds_read_b128 v[198:201], v166 offset:22528
	ds_read_b128 v[202:205], v166 offset:23552
	s_mov_b32 m0, s15
	s_nop 0
	global_load_lds_dwordx4 v129, s[42:43]
	s_mov_b32 m0, s33
	s_addc_u32 s75, s43, 0
	global_load_lds_dwordx4 v129, s[74:75]
	s_add_u32 s74, s42, 0xb0000
	s_mov_b32 m0, s34
	s_addc_u32 s75, s43, 0
	global_load_lds_dwordx4 v129, s[74:75]
	s_add_u32 s74, s42, 0x108000
	s_mov_b32 m0, s35
	s_addc_u32 s75, s43, 0
	global_load_lds_dwordx4 v129, s[74:75]
	s_mov_b32 m0, s14
	s_nop 0
	global_load_lds_dwordx4 v128, s[38:39]
	s_add_u32 s74, s38, 0x58000
	s_mov_b32 m0, s36
	s_addc_u32 s75, s39, 0
	global_load_lds_dwordx4 v128, s[74:75]
	s_waitcnt vmcnt(8) lgkmcnt(0)
	s_barrier
	s_setprio 1
	v_mfma_f32_16x16x32_bf16 v[92:95], v[130:133], v[170:173], 0
	v_mfma_f32_16x16x32_bf16 v[88:91], v[138:141], v[170:173], 0
	v_mfma_f32_16x16x32_bf16 v[84:87], v[130:133], v[182:185], 0
	v_mfma_f32_16x16x32_bf16 v[80:83], v[138:141], v[182:185], 0
	v_mfma_f32_16x16x32_bf16 v[76:79], v[130:133], v[190:193], 0
	v_mfma_f32_16x16x32_bf16 v[72:75], v[138:141], v[190:193], 0
	v_mfma_f32_16x16x32_bf16 v[68:71], v[130:133], v[198:201], 0
	v_mfma_f32_16x16x32_bf16 v[64:67], v[138:141], v[198:201], 0
	v_mfma_f32_16x16x32_bf16 v[92:95], v[134:137], v[178:181], v[92:95]
	v_mfma_f32_16x16x32_bf16 v[88:91], v[142:145], v[178:181], v[88:91]
	v_mfma_f32_16x16x32_bf16 v[84:87], v[134:137], v[186:189], v[84:87]
	v_mfma_f32_16x16x32_bf16 v[80:83], v[142:145], v[186:189], v[80:83]
	v_mfma_f32_16x16x32_bf16 v[76:79], v[134:137], v[194:197], v[76:79]
	v_mfma_f32_16x16x32_bf16 v[72:75], v[142:145], v[194:197], v[72:75]
	v_mfma_f32_16x16x32_bf16 v[68:71], v[134:137], v[202:205], v[68:71]
	v_mfma_f32_16x16x32_bf16 v[64:67], v[142:145], v[202:205], v[64:67]
	v_mfma_f32_16x16x32_bf16 v[28:31], v[146:149], v[170:173], 0
	v_mfma_f32_16x16x32_bf16 v[24:27], v[154:157], v[170:173], 0
	v_mfma_f32_16x16x32_bf16 v[20:23], v[146:149], v[182:185], 0
	v_mfma_f32_16x16x32_bf16 v[16:19], v[154:157], v[182:185], 0
	v_mfma_f32_16x16x32_bf16 v[12:15], v[146:149], v[190:193], 0
	v_mfma_f32_16x16x32_bf16 v[8:11], v[154:157], v[190:193], 0
	v_mfma_f32_16x16x32_bf16 v[4:7], v[146:149], v[198:201], 0
	v_mfma_f32_16x16x32_bf16 v[0:3], v[154:157], v[198:201], 0
	v_mfma_f32_16x16x32_bf16 v[28:31], v[150:153], v[178:181], v[28:31]
	v_mfma_f32_16x16x32_bf16 v[24:27], v[158:161], v[178:181], v[24:27]
	v_mfma_f32_16x16x32_bf16 v[20:23], v[150:153], v[186:189], v[20:23]
	v_mfma_f32_16x16x32_bf16 v[16:19], v[158:161], v[186:189], v[16:19]
	v_mfma_f32_16x16x32_bf16 v[12:15], v[150:153], v[194:197], v[12:15]
	v_mfma_f32_16x16x32_bf16 v[8:11], v[158:161], v[194:197], v[8:11]
	v_mfma_f32_16x16x32_bf16 v[4:7], v[150:153], v[202:205], v[4:7]
	v_mfma_f32_16x16x32_bf16 v[0:3], v[158:161], v[202:205], v[0:3]
	s_setprio 0
	s_barrier
	s_branch .Lpeel_mid_7711
; #define PG8_STAGE(bufoff, gbase, voff, p64) do { _Pragma("unroll") for (int _i = 0; _i < 2; ++_i) { \
;         const char* _gb = (const char*)(gbase) + (size_t)_i * (p64); const unsigned _la = ldsbase + (unsigned)(bufoff) + (unsigned)_i * 8192u; \
;         asm volatile("s_mov_b32 m0, %0\n\ts_nop 0\n\tglobal_load_lds_dwordx4 %1, %2" :: "s"(_la), "v"(voff), "s"(_gb) : "memory"); } } while (0)
; #define PG8_LDA(dst, b, h) do { _Pragma("unroll") for (int m = 0; m < 4; ++m) _Pragma("unroll") for (int k = 0; k < 2; ++k) dst[m][k] = *(const LAS bf16x8*)(lds + PG8_SA(b, h) + aoff + m * 2048 + k * 1024); } while (0)
; #define PG8_LDB(dst, b, h) do { _Pragma("unroll") for (int n = 0; n < 2; ++n) _Pragma("unroll") for (int k = 0; k < 2; ++k) dst[n][k] = *(const LAS bf16x8*)(lds + PG8_SB(b, h) + boff + n * 2048 + k * 1024); } while (0)
; #define PG8_MMA(ai, bj, At, Bt) do { __builtin_amdgcn_s_setprio(1); _Pragma("unroll") for (int m = 0; m < 4; ++m) _Pragma("unroll") for (int n = 0; n < 2; ++n) _Pragma("unroll") for (int k = 0; k < 2; ++k) \
;         acc[ai][bj][m][n] = __builtin_amdgcn_mfma_f32_16x16x32_bf16(Bt[n][k], At[m][k], acc[ai][bj][m][n], 0, 0, 0); __builtin_amdgcn_s_setprio(0); } while (0)
; #define PG8_WAIT_V(n) asm volatile("s_waitcnt vmcnt(" #n ")" ::: "memory")
; #define PG8_WAIT_L(n) asm volatile("s_waitcnt lgkmcnt(" #n ")" ::: "memory")
; #define PG8_BAR __builtin_amdgcn_s_barrier()
; #define PG8_SCHED __builtin_amdgcn_sched_barrier(0)
; template <class Epi, class Sched>
; __device__ __forceinline__ void gemm_phase(LAS unsigned char* lds, const Sched& S, const Epi& E) {
;     ...
;             PG8_LDB(B0, 0, 0); PG8_LDB(B1, 0, 1); PG8_SCHED; PG8_LDA(At, 0, 0); PG8_STAGE(PG8_SA(1, 1), a1 + hA, voffA, hA / 2);
;             PG8_WAIT_V(8); PG8_WAIT_L(0); PG8_BAR; PG8_MMA(0, 0, At, B0); PG8_MMA(0, 1, At, B1); PG8_BAR; PG8_SCHED;
;             PG8_LDA(At, 0, 1); PG8_STAGE(PG8_SB(0, 0), b2, vB2, hB2 / 2); PG8_STAGE(PG8_SB(0, 1), b2 + hB2, vB2, hB2 / 2); PG8_STAGE(PG8_SA(0, 0), a2, vA2, hA2 / 2);
;             PG8_WAIT_V(8); PG8_WAIT_L(0); PG8_BAR; PG8_MMA(1, 0, At, B0); PG8_MMA(1, 1, At, B1); PG8_BAR; PG8_SCHED;
.LBB0_398:
	ds_read_b128 v[130:133], v164
	ds_read_b128 v[134:137], v164 offset:1024
	ds_read_b128 v[138:141], v164 offset:2048
	ds_read_b128 v[142:145], v164 offset:3072
	ds_read_b128 v[146:149], v165
	ds_read_b128 v[150:153], v165 offset:1024
	ds_read_b128 v[154:157], v165 offset:2048
	ds_read_b128 v[158:161], v165 offset:3072
	s_add_i32 s73, s38, 2
	s_cmp_eq_u32 s68, s38
	s_cselect_b32 s38, s67, s69
	s_cselect_b32 s39, s66, s70
	s_cselect_b32 s42, s45, s71
	s_cselect_b32 s43, s44, s72
	s_add_u32 s40, s38, 0x80
	s_addc_u32 s41, s39, 0
	ds_read_b128 v[170:173], v166
	ds_read_b128 v[178:181], v166 offset:1024
	ds_read_b128 v[182:185], v166 offset:2048
	ds_read_b128 v[186:189], v166 offset:3072
	ds_read_b128 v[190:193], v166 offset:4096
	ds_read_b128 v[194:197], v166 offset:5120
	ds_read_b128 v[198:201], v166 offset:6144
	ds_read_b128 v[202:205], v166 offset:7168
	s_add_u32 s74, s69, 0xaff80
	s_mov_b32 m0, s59
	s_addc_u32 s75, s70, 0
	global_load_lds_dwordx4 v128, s[74:75]
	s_add_u32 s74, s69, 0x107f80
	s_mov_b32 m0, s60
	s_addc_u32 s75, s70, 0
	global_load_lds_dwordx4 v128, s[74:75]
	s_waitcnt vmcnt(8) lgkmcnt(0)
	s_barrier
	s_setprio 1
	v_mfma_f32_16x16x32_bf16 v[124:127], v[130:133], v[170:173], v[124:127]
	v_mfma_f32_16x16x32_bf16 v[120:123], v[138:141], v[170:173], v[120:123]
	v_mfma_f32_16x16x32_bf16 v[116:119], v[130:133], v[182:185], v[116:119]
	v_mfma_f32_16x16x32_bf16 v[112:115], v[138:141], v[182:185], v[112:115]
	v_mfma_f32_16x16x32_bf16 v[108:111], v[130:133], v[190:193], v[108:111]
	v_mfma_f32_16x16x32_bf16 v[104:107], v[138:141], v[190:193], v[104:107]
	v_mfma_f32_16x16x32_bf16 v[100:103], v[130:133], v[198:201], v[100:103]
	v_mfma_f32_16x16x32_bf16 v[96:99], v[138:141], v[198:201], v[96:99]
	v_mfma_f32_16x16x32_bf16 v[124:127], v[134:137], v[178:181], v[124:127]
	v_mfma_f32_16x16x32_bf16 v[120:123], v[142:145], v[178:181], v[120:123]
	v_mfma_f32_16x16x32_bf16 v[116:119], v[134:137], v[186:189], v[116:119]
	v_mfma_f32_16x16x32_bf16 v[112:115], v[142:145], v[186:189], v[112:115]
	v_mfma_f32_16x16x32_bf16 v[108:111], v[134:137], v[194:197], v[108:111]
	v_mfma_f32_16x16x32_bf16 v[104:107], v[142:145], v[194:197], v[104:107]
	v_mfma_f32_16x16x32_bf16 v[100:103], v[134:137], v[202:205], v[100:103]
	v_mfma_f32_16x16x32_bf16 v[96:99], v[142:145], v[202:205], v[96:99]
	v_mfma_f32_16x16x32_bf16 v[60:63], v[146:149], v[170:173], v[60:63]
	v_mfma_f32_16x16x32_bf16 v[56:59], v[154:157], v[170:173], v[56:59]
	v_mfma_f32_16x16x32_bf16 v[52:55], v[146:149], v[182:185], v[52:55]
	v_mfma_f32_16x16x32_bf16 v[48:51], v[154:157], v[182:185], v[48:51]
	v_mfma_f32_16x16x32_bf16 v[44:47], v[146:149], v[190:193], v[44:47]
	v_mfma_f32_16x16x32_bf16 v[40:43], v[154:157], v[190:193], v[40:43]
	v_mfma_f32_16x16x32_bf16 v[36:39], v[146:149], v[198:201], v[36:39]
	v_mfma_f32_16x16x32_bf16 v[32:35], v[154:157], v[198:201], v[32:35]
	v_mfma_f32_16x16x32_bf16 v[60:63], v[150:153], v[178:181], v[60:63]
	v_mfma_f32_16x16x32_bf16 v[56:59], v[158:161], v[178:181], v[56:59]
	v_mfma_f32_16x16x32_bf16 v[52:55], v[150:153], v[186:189], v[52:55]
	v_mfma_f32_16x16x32_bf16 v[48:51], v[158:161], v[186:189], v[48:51]
	v_mfma_f32_16x16x32_bf16 v[44:47], v[150:153], v[194:197], v[44:47]
	v_mfma_f32_16x16x32_bf16 v[40:43], v[158:161], v[194:197], v[40:43]
	v_mfma_f32_16x16x32_bf16 v[36:39], v[150:153], v[202:205], v[36:39]
	v_mfma_f32_16x16x32_bf16 v[32:35], v[158:161], v[202:205], v[32:35]
	s_add_u32 s69, s69, 0x100
	s_addc_u32 s70, s70, 0
	s_add_u32 s71, s71, 0x100
	s_addc_u32 s72, s72, 0
	s_setprio 0
	s_barrier
	s_add_u32 s74, s42, 0x58000
	ds_read_b128 v[170:173], v166 offset:16384
	ds_read_b128 v[178:181], v166 offset:17408
	ds_read_b128 v[182:185], v166 offset:18432
	ds_read_b128 v[186:189], v166 offset:19456
	ds_read_b128 v[190:193], v166 offset:20480
	ds_read_b128 v[194:197], v166 offset:21504
	ds_read_b128 v[198:201], v166 offset:22528
	ds_read_b128 v[202:205], v166 offset:23552
	s_mov_b32 m0, s15
	s_nop 0
	global_load_lds_dwordx4 v129, s[42:43]
	s_mov_b32 m0, s33
	s_addc_u32 s75, s43, 0
	global_load_lds_dwordx4 v129, s[74:75]
	s_add_u32 s74, s42, 0xb0000
	s_mov_b32 m0, s34
	s_addc_u32 s75, s43, 0
	global_load_lds_dwordx4 v129, s[74:75]
	s_add_u32 s74, s42, 0x108000
	s_mov_b32 m0, s35
	s_addc_u32 s75, s43, 0
	global_load_lds_dwordx4 v129, s[74:75]
	s_mov_b32 m0, s14
	s_nop 0
	global_load_lds_dwordx4 v128, s[38:39]
	s_add_u32 s74, s38, 0x58000
	s_mov_b32 m0, s36
	s_addc_u32 s75, s39, 0
	global_load_lds_dwordx4 v128, s[74:75]
	s_waitcnt vmcnt(8) lgkmcnt(0)
	s_barrier
	s_setprio 1
	v_mfma_f32_16x16x32_bf16 v[92:95], v[130:133], v[170:173], v[92:95]
	v_mfma_f32_16x16x32_bf16 v[88:91], v[138:141], v[170:173], v[88:91]
	v_mfma_f32_16x16x32_bf16 v[84:87], v[130:133], v[182:185], v[84:87]
	v_mfma_f32_16x16x32_bf16 v[80:83], v[138:141], v[182:185], v[80:83]
	v_mfma_f32_16x16x32_bf16 v[76:79], v[130:133], v[190:193], v[76:79]
	v_mfma_f32_16x16x32_bf16 v[72:75], v[138:141], v[190:193], v[72:75]
	v_mfma_f32_16x16x32_bf16 v[68:71], v[130:133], v[198:201], v[68:71]
	v_mfma_f32_16x16x32_bf16 v[64:67], v[138:141], v[198:201], v[64:67]
	v_mfma_f32_16x16x32_bf16 v[92:95], v[134:137], v[178:181], v[92:95]
	v_mfma_f32_16x16x32_bf16 v[88:91], v[142:145], v[178:181], v[88:91]
	v_mfma_f32_16x16x32_bf16 v[84:87], v[134:137], v[186:189], v[84:87]
	v_mfma_f32_16x16x32_bf16 v[80:83], v[142:145], v[186:189], v[80:83]
	v_mfma_f32_16x16x32_bf16 v[76:79], v[134:137], v[194:197], v[76:79]
	v_mfma_f32_16x16x32_bf16 v[72:75], v[142:145], v[194:197], v[72:75]
	v_mfma_f32_16x16x32_bf16 v[68:71], v[134:137], v[202:205], v[68:71]
	v_mfma_f32_16x16x32_bf16 v[64:67], v[142:145], v[202:205], v[64:67]
	v_mfma_f32_16x16x32_bf16 v[28:31], v[146:149], v[170:173], v[28:31]
	v_mfma_f32_16x16x32_bf16 v[24:27], v[154:157], v[170:173], v[24:27]
	v_mfma_f32_16x16x32_bf16 v[20:23], v[146:149], v[182:185], v[20:23]
	v_mfma_f32_16x16x32_bf16 v[16:19], v[154:157], v[182:185], v[16:19]
	v_mfma_f32_16x16x32_bf16 v[12:15], v[146:149], v[190:193], v[12:15]
	v_mfma_f32_16x16x32_bf16 v[8:11], v[154:157], v[190:193], v[8:11]
	v_mfma_f32_16x16x32_bf16 v[4:7], v[146:149], v[198:201], v[4:7]
	v_mfma_f32_16x16x32_bf16 v[0:3], v[154:157], v[198:201], v[0:3]
	v_mfma_f32_16x16x32_bf16 v[28:31], v[150:153], v[178:181], v[28:31]
	v_mfma_f32_16x16x32_bf16 v[24:27], v[158:161], v[178:181], v[24:27]
	v_mfma_f32_16x16x32_bf16 v[20:23], v[150:153], v[186:189], v[20:23]
	v_mfma_f32_16x16x32_bf16 v[16:19], v[158:161], v[186:189], v[16:19]
	v_mfma_f32_16x16x32_bf16 v[12:15], v[150:153], v[194:197], v[12:15]
	v_mfma_f32_16x16x32_bf16 v[8:11], v[158:161], v[194:197], v[8:11]
	v_mfma_f32_16x16x32_bf16 v[4:7], v[150:153], v[202:205], v[4:7]
	v_mfma_f32_16x16x32_bf16 v[0:3], v[158:161], v[202:205], v[0:3]
	s_setprio 0
	s_barrier
; #define PG8_STAGE(bufoff, gbase, voff, p64) do { _Pragma("unroll") for (int _i = 0; _i < 2; ++_i) { \
;         const char* _gb = (const char*)(gbase) + (size_t)_i * (p64); const unsigned _la = ldsbase + (unsigned)(bufoff) + (unsigned)_i * 8192u; \
;         asm volatile("s_mov_b32 m0, %0\n\ts_nop 0\n\tglobal_load_lds_dwordx4 %1, %2" :: "s"(_la), "v"(voff), "s"(_gb) : "memory"); } } while (0)
; #define PG8_LDA(dst, b, h) do { _Pragma("unroll") for (int m = 0; m < 4; ++m) _Pragma("unroll") for (int k = 0; k < 2; ++k) dst[m][k] = *(const LAS bf16x8*)(lds + PG8_SA(b, h) + aoff + m * 2048 + k * 1024); } while (0)
; #define PG8_LDB(dst, b, h) do { _Pragma("unroll") for (int n = 0; n < 2; ++n) _Pragma("unroll") for (int k = 0; k < 2; ++k) dst[n][k] = *(const LAS bf16x8*)(lds + PG8_SB(b, h) + boff + n * 2048 + k * 1024); } while (0)
; #define PG8_MMA(ai, bj, At, Bt) do { __builtin_amdgcn_s_setprio(1); _Pragma("unroll") for (int m = 0; m < 4; ++m) _Pragma("unroll") for (int n = 0; n < 2; ++n) _Pragma("unroll") for (int k = 0; k < 2; ++k) \
;         acc[ai][bj][m][n] = __builtin_amdgcn_mfma_f32_16x16x32_bf16(Bt[n][k], At[m][k], acc[ai][bj][m][n], 0, 0, 0); __builtin_amdgcn_s_setprio(0); } while (0)
; #define PG8_WAIT_V(n) asm volatile("s_waitcnt vmcnt(" #n ")" ::: "memory")
; #define PG8_WAIT_L(n) asm volatile("s_waitcnt lgkmcnt(" #n ")" ::: "memory")
; #define PG8_BAR __builtin_amdgcn_s_barrier()
; #define PG8_SCHED __builtin_amdgcn_sched_barrier(0)
; template <class Epi, class Sched>
; __device__ __forceinline__ void gemm_phase(LAS unsigned char* lds, const Sched& S, const Epi& E) {
;     ...
;             PG8_LDB(B0, 1, 0); PG8_LDB(B1, 1, 1); PG8_SCHED; PG8_LDA(At, 1, 0); PG8_STAGE(PG8_SA(0, 1), a2 + hA2, vA2, hA2 / 2);
;             PG8_WAIT_V(8); PG8_WAIT_L(0); PG8_BAR; PG8_MMA(0, 0, At, B0); PG8_MMA(0, 1, At, B1); PG8_BAR; PG8_SCHED;
;             PG8_LDA(At, 1, 1); PG8_STAGE(PG8_SB(1, 0), b3, vB2, hB2 / 2); PG8_STAGE(PG8_SB(1, 1), b3 + hB2, vB2, hB2 / 2); PG8_STAGE(PG8_SA(1, 0), a3, vA2, hA2 / 2);
;             PG8_WAIT_V(8); PG8_WAIT_L(0); PG8_BAR; PG8_MMA(1, 0, At, B0); PG8_MMA(1, 1, At, B1); PG8_BAR; PG8_SCHED;
;         }
;         if (wr == 0) PG8_BAR;
.Lpeel_mid_7711:
	ds_read_b128 v[130:133], v167
	ds_read_b128 v[134:137], v167 offset:1024
	ds_read_b128 v[138:141], v167 offset:2048
	ds_read_b128 v[142:145], v167 offset:3072
	ds_read_b128 v[146:149], v168
	ds_read_b128 v[150:153], v168 offset:1024
	ds_read_b128 v[154:157], v168 offset:2048
	ds_read_b128 v[158:161], v168 offset:3072
	ds_read_b128 v[170:173], v166 offset:32768
	ds_read_b128 v[178:181], v166 offset:33792
	ds_read_b128 v[182:185], v166 offset:34816
	ds_read_b128 v[186:189], v166 offset:35840
	ds_read_b128 v[190:193], v166 offset:36864
	ds_read_b128 v[194:197], v166 offset:37888
	ds_read_b128 v[198:201], v166 offset:38912
	ds_read_b128 v[202:205], v166 offset:39936
	s_add_u32 s74, s38, 0xb0000
	s_mov_b32 m0, s37
	s_addc_u32 s75, s39, 0
	global_load_lds_dwordx4 v128, s[74:75]
	s_add_u32 s74, s38, 0x108000
	s_mov_b32 m0, s46
	s_addc_u32 s75, s39, 0
	global_load_lds_dwordx4 v128, s[74:75]
	s_waitcnt vmcnt(8) lgkmcnt(0)
	s_barrier
	s_setprio 1
	v_mfma_f32_16x16x32_bf16 v[124:127], v[130:133], v[170:173], v[124:127]
	v_mfma_f32_16x16x32_bf16 v[120:123], v[138:141], v[170:173], v[120:123]
	v_mfma_f32_16x16x32_bf16 v[116:119], v[130:133], v[182:185], v[116:119]
	v_mfma_f32_16x16x32_bf16 v[112:115], v[138:141], v[182:185], v[112:115]
	v_mfma_f32_16x16x32_bf16 v[108:111], v[130:133], v[190:193], v[108:111]
	v_mfma_f32_16x16x32_bf16 v[104:107], v[138:141], v[190:193], v[104:107]
	v_mfma_f32_16x16x32_bf16 v[100:103], v[130:133], v[198:201], v[100:103]
	v_mfma_f32_16x16x32_bf16 v[96:99], v[138:141], v[198:201], v[96:99]
	v_mfma_f32_16x16x32_bf16 v[124:127], v[134:137], v[178:181], v[124:127]
	v_mfma_f32_16x16x32_bf16 v[120:123], v[142:145], v[178:181], v[120:123]
	v_mfma_f32_16x16x32_bf16 v[116:119], v[134:137], v[186:189], v[116:119]
	v_mfma_f32_16x16x32_bf16 v[112:115], v[142:145], v[186:189], v[112:115]
	v_mfma_f32_16x16x32_bf16 v[108:111], v[134:137], v[194:197], v[108:111]
	v_mfma_f32_16x16x32_bf16 v[104:107], v[142:145], v[194:197], v[104:107]
	v_mfma_f32_16x16x32_bf16 v[100:103], v[134:137], v[202:205], v[100:103]
	v_mfma_f32_16x16x32_bf16 v[96:99], v[142:145], v[202:205], v[96:99]
	v_mfma_f32_16x16x32_bf16 v[60:63], v[146:149], v[170:173], v[60:63]
	v_mfma_f32_16x16x32_bf16 v[56:59], v[154:157], v[170:173], v[56:59]
	v_mfma_f32_16x16x32_bf16 v[52:55], v[146:149], v[182:185], v[52:55]
	v_mfma_f32_16x16x32_bf16 v[48:51], v[154:157], v[182:185], v[48:51]
	v_mfma_f32_16x16x32_bf16 v[44:47], v[146:149], v[190:193], v[44:47]
	v_mfma_f32_16x16x32_bf16 v[40:43], v[154:157], v[190:193], v[40:43]
	v_mfma_f32_16x16x32_bf16 v[36:39], v[146:149], v[198:201], v[36:39]
	v_mfma_f32_16x16x32_bf16 v[32:35], v[154:157], v[198:201], v[32:35]
	v_mfma_f32_16x16x32_bf16 v[60:63], v[150:153], v[178:181], v[60:63]
	v_mfma_f32_16x16x32_bf16 v[56:59], v[158:161], v[178:181], v[56:59]
	v_mfma_f32_16x16x32_bf16 v[52:55], v[150:153], v[186:189], v[52:55]
	v_mfma_f32_16x16x32_bf16 v[48:51], v[158:161], v[186:189], v[48:51]
	v_mfma_f32_16x16x32_bf16 v[44:47], v[150:153], v[194:197], v[44:47]
	v_mfma_f32_16x16x32_bf16 v[40:43], v[158:161], v[194:197], v[40:43]
	v_mfma_f32_16x16x32_bf16 v[36:39], v[150:153], v[202:205], v[36:39]
	v_mfma_f32_16x16x32_bf16 v[32:35], v[158:161], v[202:205], v[32:35]
	s_setprio 0
	s_barrier
	s_add_u32 s74, s42, 0x80
	s_addc_u32 s75, s43, 0
	ds_read_b128 v[170:173], v166 offset:49152
	ds_read_b128 v[178:181], v166 offset:50176
	ds_read_b128 v[182:185], v166 offset:51200
	ds_read_b128 v[186:189], v166 offset:52224
	ds_read_b128 v[190:193], v166 offset:53248
	ds_read_b128 v[194:197], v166 offset:54272
	ds_read_b128 v[198:201], v166 offset:55296
	ds_read_b128 v[202:205], v166 offset:56320
	s_mov_b32 m0, s53
	s_nop 0
	global_load_lds_dwordx4 v129, s[74:75]
	s_add_u32 s74, s42, 0x58080
	s_mov_b32 m0, s54
	s_addc_u32 s75, s43, 0
	global_load_lds_dwordx4 v129, s[74:75]
	s_add_u32 s74, s42, 0xb0080
	s_mov_b32 m0, s57
	s_addc_u32 s75, s43, 0
	global_load_lds_dwordx4 v129, s[74:75]
	s_add_u32 s42, s42, 0x108080
	s_mov_b32 m0, s58
	s_addc_u32 s43, s43, 0
	global_load_lds_dwordx4 v129, s[42:43]
	s_mov_b32 m0, s55
	s_nop 0
	global_load_lds_dwordx4 v128, s[40:41]
	s_add_u32 s38, s38, 0x58080
	s_mov_b32 m0, s56
	s_addc_u32 s39, s39, 0
	global_load_lds_dwordx4 v128, s[38:39]
	s_waitcnt vmcnt(8) lgkmcnt(0)
	s_barrier
	s_setprio 1
	v_mfma_f32_16x16x32_bf16 v[92:95], v[130:133], v[170:173], v[92:95]
	v_mfma_f32_16x16x32_bf16 v[88:91], v[138:141], v[170:173], v[88:91]
	v_mfma_f32_16x16x32_bf16 v[84:87], v[130:133], v[182:185], v[84:87]
	v_mfma_f32_16x16x32_bf16 v[80:83], v[138:141], v[182:185], v[80:83]
	v_mfma_f32_16x16x32_bf16 v[76:79], v[130:133], v[190:193], v[76:79]
	v_mfma_f32_16x16x32_bf16 v[72:75], v[138:141], v[190:193], v[72:75]
	v_mfma_f32_16x16x32_bf16 v[68:71], v[130:133], v[198:201], v[68:71]
	v_mfma_f32_16x16x32_bf16 v[64:67], v[138:141], v[198:201], v[64:67]
	v_mfma_f32_16x16x32_bf16 v[92:95], v[134:137], v[178:181], v[92:95]
	v_mfma_f32_16x16x32_bf16 v[88:91], v[142:145], v[178:181], v[88:91]
	v_mfma_f32_16x16x32_bf16 v[84:87], v[134:137], v[186:189], v[84:87]
	v_mfma_f32_16x16x32_bf16 v[80:83], v[142:145], v[186:189], v[80:83]
	v_mfma_f32_16x16x32_bf16 v[76:79], v[134:137], v[194:197], v[76:79]
	v_mfma_f32_16x16x32_bf16 v[72:75], v[142:145], v[194:197], v[72:75]
	v_mfma_f32_16x16x32_bf16 v[68:71], v[134:137], v[202:205], v[68:71]
	v_mfma_f32_16x16x32_bf16 v[64:67], v[142:145], v[202:205], v[64:67]
	v_mfma_f32_16x16x32_bf16 v[28:31], v[146:149], v[170:173], v[28:31]
	v_mfma_f32_16x16x32_bf16 v[24:27], v[154:157], v[170:173], v[24:27]
	v_mfma_f32_16x16x32_bf16 v[20:23], v[146:149], v[182:185], v[20:23]
	v_mfma_f32_16x16x32_bf16 v[16:19], v[154:157], v[182:185], v[16:19]
	v_mfma_f32_16x16x32_bf16 v[12:15], v[146:149], v[190:193], v[12:15]
	v_mfma_f32_16x16x32_bf16 v[8:11], v[154:157], v[190:193], v[8:11]
	v_mfma_f32_16x16x32_bf16 v[4:7], v[146:149], v[198:201], v[4:7]
	v_mfma_f32_16x16x32_bf16 v[0:3], v[154:157], v[198:201], v[0:3]
	v_mfma_f32_16x16x32_bf16 v[28:31], v[150:153], v[178:181], v[28:31]
	v_mfma_f32_16x16x32_bf16 v[24:27], v[158:161], v[178:181], v[24:27]
	v_mfma_f32_16x16x32_bf16 v[20:23], v[150:153], v[186:189], v[20:23]
	v_mfma_f32_16x16x32_bf16 v[16:19], v[158:161], v[186:189], v[16:19]
	v_mfma_f32_16x16x32_bf16 v[12:15], v[150:153], v[194:197], v[12:15]
	v_mfma_f32_16x16x32_bf16 v[8:11], v[158:161], v[194:197], v[8:11]
	v_mfma_f32_16x16x32_bf16 v[4:7], v[150:153], v[202:205], v[4:7]
	v_mfma_f32_16x16x32_bf16 v[0:3], v[158:161], v[202:205], v[0:3]
	s_setprio 0
	s_barrier
	s_cmp_ge_i32 s73, s21
	s_mov_b32 s38, s73
	s_cbranch_scc0 .LBB0_398
	s_and_b64 vcc, exec, s[18:19]
	s_cbranch_vccz .LBB0_401
	s_barrier

; #define PG8_STAGE(bufoff, gbase, voff, p64) do { _Pragma("unroll") for (int _i = 0; _i < 2; ++_i) { \
;         const char* _gb = (const char*)(gbase) + (size_t)_i * (p64); const unsigned _la = ldsbase + (unsigned)(bufoff) + (unsigned)_i * 8192u; \
;         asm volatile("s_mov_b32 m0, %0\n\ts_nop 0\n\tglobal_load_lds_dwordx4 %1, %2" :: "s"(_la), "v"(voff), "s"(_gb) : "memory"); } } while (0)
; #define PG8_LDA(dst, b, h) do { _Pragma("unroll") for (int m = 0; m < 4; ++m) _Pragma("unroll") for (int k = 0; k < 2; ++k) dst[m][k] = *(const LAS bf16x8*)(lds + PG8_SA(b, h) + aoff + m * 2048 + k * 1024); } while (0)
; #define PG8_LDB(dst, b, h) do { _Pragma("unroll") for (int n = 0; n < 2; ++n) _Pragma("unroll") for (int k = 0; k < 2; ++k) dst[n][k] = *(const LAS bf16x8*)(lds + PG8_SB(b, h) + boff + n * 2048 + k * 1024); } while (0)
; #define PG8_MMA(ai, bj, At, Bt) do { __builtin_amdgcn_s_setprio(1); _Pragma("unroll") for (int m = 0; m < 4; ++m) _Pragma("unroll") for (int n = 0; n < 2; ++n) _Pragma("unroll") for (int k = 0; k < 2; ++k) \
;         acc[ai][bj][m][n] = __builtin_amdgcn_mfma_f32_16x16x32_bf16(Bt[n][k], At[m][k], acc[ai][bj][m][n], 0, 0, 0); __builtin_amdgcn_s_setprio(0); } while (0)
; #define PG8_WAIT_V(n) asm volatile("s_waitcnt vmcnt(" #n ")" ::: "memory")
; #define PG8_WAIT_L(n) asm volatile("s_waitcnt lgkmcnt(" #n ")" ::: "memory")
; #define PG8_BAR __builtin_amdgcn_s_barrier()
; template <class Epi, class Sched>
; __device__ __forceinline__ void gemm_phase(LAS unsigned char* lds, const Sched& S, const Epi& E) {
;     ...
; #pragma unroll
;     for (int a = 0; a < 2; ++a)
; #pragma unroll
;         for (int b = 0; b < 2; ++b)
; #pragma unroll
;             for (int m = 0; m < 4; ++m)
; #pragma unroll
;                 for (int n = 0; n < 2; ++n) acc[a][b][m][n] = (f32x4){0.f, 0.f, 0.f, 0.f};
;     ...
;             PG8_LDB(B0, 0, 0); PG8_LDB(B1, 0, 1); PG8_SCHED; PG8_LDA(At, 0, 0); PG8_STAGE(PG8_SA(1, 1), a1 + hA, voffA, hA / 2);
;             PG8_WAIT_V(8); PG8_WAIT_L(0); PG8_BAR; PG8_MMA(0, 0, At, B0); PG8_MMA(0, 1, At, B1); PG8_BAR; PG8_SCHED;
;             PG8_LDA(At, 0, 1); PG8_STAGE(PG8_SB(0, 0), b2, vB2, hB2 / 2); PG8_STAGE(PG8_SB(0, 1), b2 + hB2, vB2, hB2 / 2); PG8_STAGE(PG8_SA(0, 0), a2, vA2, hA2 / 2);
;             PG8_WAIT_V(8); PG8_WAIT_L(0); PG8_BAR; PG8_MMA(1, 0, At, B0); PG8_MMA(1, 1, At, B1); PG8_BAR; PG8_SCHED;
.LBB0_552:
	s_add_u32 s74, s22, 0x40080
	s_addc_u32 s75, s23, 0
	s_add_u32 s57, s16, 0x100
	s_addc_u32 s80, s17, 0
	s_mov_b32 s81, -2
	s_waitcnt vmcnt(2)
	s_waitcnt vmcnt(0)
	v_add_u32_e32 v128, 0x10000, v154
	ds_read_b128 v[138:141], v128
	ds_read_b128 v[142:145], v128 offset:1024
	ds_read_b128 v[146:149], v128 offset:2048
	ds_read_b128 v[172:175], v128 offset:3072
	v_add_u32_e32 v128, 0x14000, v154
	ds_read_b128 v[178:181], v128
	ds_read_b128 v[182:185], v128 offset:1024
	ds_read_b128 v[186:189], v128 offset:2048
	ds_read_b128 v[190:193], v128 offset:3072
	s_add_u32 s16, s74, 0xfffc0080
	s_addc_u32 s17, s75, -1
	s_cmp_eq_u32 s81, 12
	s_cselect_b32 s16, s58, s16
	s_cselect_b32 s17, s59, s17
	s_cselect_b32 s76, s62, s57
	s_cselect_b32 s77, s63, s80
	s_add_u32 s22, s16, 0x80
	s_addc_u32 s23, s17, 0
	ds_read_b128 v[194:197], v155
	ds_read_b128 v[198:201], v155 offset:1024
	ds_read_b128 v[202:205], v155 offset:2048
	ds_read_b128 v[206:209], v155 offset:3072
	ds_read_b128 v[210:213], v155 offset:4096
	ds_read_b128 v[214:217], v155 offset:5120
	ds_read_b128 v[218:221], v155 offset:6144
	ds_read_b128 v[222:225], v155 offset:7168
	s_mov_b32 m0, s67
	s_nop 0
	global_load_lds_dwordx4 v150, s[74:75]
	s_add_u32 s82, s74, 0x20000
	s_mov_b32 m0, s69
	s_addc_u32 s83, s75, 0
	global_load_lds_dwordx4 v150, s[82:83]
	s_waitcnt vmcnt(8) lgkmcnt(0)
	s_barrier
	s_setprio 1
	v_mfma_f32_16x16x32_bf16 v[124:127], v[138:141], v[194:197], 0
	v_mfma_f32_16x16x32_bf16 v[120:123], v[146:149], v[194:197], 0
	v_mfma_f32_16x16x32_bf16 v[112:115], v[138:141], v[202:205], 0
	v_mfma_f32_16x16x32_bf16 v[104:107], v[146:149], v[202:205], 0
	v_mfma_f32_16x16x32_bf16 v[96:99], v[138:141], v[210:213], 0
	v_mfma_f32_16x16x32_bf16 v[88:91], v[146:149], v[210:213], 0
	v_mfma_f32_16x16x32_bf16 v[80:83], v[138:141], v[218:221], 0
	v_mfma_f32_16x16x32_bf16 v[72:75], v[146:149], v[218:221], 0
	v_mfma_f32_16x16x32_bf16 v[124:127], v[142:145], v[198:201], v[124:127]
	v_mfma_f32_16x16x32_bf16 v[120:123], v[172:175], v[198:201], v[120:123]
	v_mfma_f32_16x16x32_bf16 v[112:115], v[142:145], v[206:209], v[112:115]
	v_mfma_f32_16x16x32_bf16 v[104:107], v[172:175], v[206:209], v[104:107]
	v_mfma_f32_16x16x32_bf16 v[96:99], v[142:145], v[214:217], v[96:99]
	v_mfma_f32_16x16x32_bf16 v[88:91], v[172:175], v[214:217], v[88:91]
	v_mfma_f32_16x16x32_bf16 v[80:83], v[142:145], v[222:225], v[80:83]
	v_mfma_f32_16x16x32_bf16 v[72:75], v[172:175], v[222:225], v[72:75]
	v_mfma_f32_16x16x32_bf16 v[116:119], v[178:181], v[194:197], 0
	v_mfma_f32_16x16x32_bf16 v[108:111], v[186:189], v[194:197], 0
	v_mfma_f32_16x16x32_bf16 v[100:103], v[178:181], v[202:205], 0
	v_mfma_f32_16x16x32_bf16 v[92:95], v[186:189], v[202:205], 0
	v_mfma_f32_16x16x32_bf16 v[84:87], v[178:181], v[210:213], 0
	v_mfma_f32_16x16x32_bf16 v[76:79], v[186:189], v[210:213], 0
	v_mfma_f32_16x16x32_bf16 v[68:71], v[178:181], v[218:221], 0
	v_mfma_f32_16x16x32_bf16 v[64:67], v[186:189], v[218:221], 0
	v_mfma_f32_16x16x32_bf16 v[116:119], v[182:185], v[198:201], v[116:119]
	v_mfma_f32_16x16x32_bf16 v[108:111], v[190:193], v[198:201], v[108:111]
	v_mfma_f32_16x16x32_bf16 v[100:103], v[182:185], v[206:209], v[100:103]
	v_mfma_f32_16x16x32_bf16 v[92:95], v[190:193], v[206:209], v[92:95]
	v_mfma_f32_16x16x32_bf16 v[84:87], v[182:185], v[214:217], v[84:87]
	v_mfma_f32_16x16x32_bf16 v[76:79], v[190:193], v[214:217], v[76:79]
	v_mfma_f32_16x16x32_bf16 v[68:71], v[182:185], v[222:225], v[68:71]
	v_mfma_f32_16x16x32_bf16 v[64:67], v[190:193], v[222:225], v[64:67]
	s_add_i32 s81, s81, 2
	s_add_u32 s74, s74, 0x100
	s_addc_u32 s75, s75, 0
	s_add_u32 s57, s57, 0x100
	s_addc_u32 s80, s80, 0
	s_setprio 0
	s_barrier
	s_add_u32 s82, s76, 0x20000
	ds_read_b128 v[194:197], v155 offset:16384
	ds_read_b128 v[198:201], v155 offset:17408
	ds_read_b128 v[202:205], v155 offset:18432
	ds_read_b128 v[206:209], v155 offset:19456
	ds_read_b128 v[210:213], v155 offset:20480
	ds_read_b128 v[214:217], v155 offset:21504
	ds_read_b128 v[218:221], v155 offset:22528
	ds_read_b128 v[222:225], v155 offset:23552
	s_mov_b32 m0, s24
	s_nop 0
	global_load_lds_dwordx4 v151, s[76:77]
	s_mov_b32 m0, s33
	s_addc_u32 s83, s77, 0
	global_load_lds_dwordx4 v151, s[82:83]
	s_add_u32 s82, s76, 0x40000
	s_mov_b32 m0, s34
	s_addc_u32 s83, s77, 0
	global_load_lds_dwordx4 v151, s[82:83]
	s_add_u32 s82, s76, 0x60000
	s_mov_b32 m0, s35
	s_addc_u32 s83, s77, 0
	global_load_lds_dwordx4 v151, s[82:83]
	s_mov_b32 m0, s15
	s_nop 0
	global_load_lds_dwordx4 v150, s[16:17]
	s_add_u32 s82, s16, 0x20000
	s_mov_b32 m0, s36
	s_addc_u32 s83, s17, 0
	global_load_lds_dwordx4 v150, s[82:83]
	s_waitcnt vmcnt(8) lgkmcnt(0)
	s_barrier
	s_setprio 1
	v_mfma_f32_16x16x32_bf16 v[60:63], v[138:141], v[194:197], 0
	v_mfma_f32_16x16x32_bf16 v[56:59], v[146:149], v[194:197], 0
	v_mfma_f32_16x16x32_bf16 v[48:51], v[138:141], v[202:205], 0
	v_mfma_f32_16x16x32_bf16 v[40:43], v[146:149], v[202:205], 0
	v_mfma_f32_16x16x32_bf16 v[32:35], v[138:141], v[210:213], 0
	v_mfma_f32_16x16x32_bf16 v[24:27], v[146:149], v[210:213], 0
	v_mfma_f32_16x16x32_bf16 v[16:19], v[138:141], v[218:221], 0
	v_mfma_f32_16x16x32_bf16 v[8:11], v[146:149], v[218:221], 0
	v_mfma_f32_16x16x32_bf16 v[60:63], v[142:145], v[198:201], v[60:63]
	v_mfma_f32_16x16x32_bf16 v[56:59], v[172:175], v[198:201], v[56:59]
	v_mfma_f32_16x16x32_bf16 v[48:51], v[142:145], v[206:209], v[48:51]
	v_mfma_f32_16x16x32_bf16 v[40:43], v[172:175], v[206:209], v[40:43]
	v_mfma_f32_16x16x32_bf16 v[32:35], v[142:145], v[214:217], v[32:35]
	v_mfma_f32_16x16x32_bf16 v[24:27], v[172:175], v[214:217], v[24:27]
	v_mfma_f32_16x16x32_bf16 v[16:19], v[142:145], v[222:225], v[16:19]
	v_mfma_f32_16x16x32_bf16 v[8:11], v[172:175], v[222:225], v[8:11]
	v_mfma_f32_16x16x32_bf16 v[52:55], v[178:181], v[194:197], 0
	v_mfma_f32_16x16x32_bf16 v[44:47], v[186:189], v[194:197], 0
	v_mfma_f32_16x16x32_bf16 v[36:39], v[178:181], v[202:205], 0
	v_mfma_f32_16x16x32_bf16 v[28:31], v[186:189], v[202:205], 0
	v_mfma_f32_16x16x32_bf16 v[20:23], v[178:181], v[210:213], 0
	v_mfma_f32_16x16x32_bf16 v[12:15], v[186:189], v[210:213], 0
	v_mfma_f32_16x16x32_bf16 v[4:7], v[178:181], v[218:221], 0
	v_mfma_f32_16x16x32_bf16 v[0:3], v[186:189], v[218:221], 0
	v_mfma_f32_16x16x32_bf16 v[52:55], v[182:185], v[198:201], v[52:55]
	v_mfma_f32_16x16x32_bf16 v[44:47], v[190:193], v[198:201], v[44:47]
	v_mfma_f32_16x16x32_bf16 v[36:39], v[182:185], v[206:209], v[36:39]
	v_mfma_f32_16x16x32_bf16 v[28:31], v[190:193], v[206:209], v[28:31]
	v_mfma_f32_16x16x32_bf16 v[20:23], v[182:185], v[214:217], v[20:23]
	v_mfma_f32_16x16x32_bf16 v[12:15], v[190:193], v[214:217], v[12:15]
	v_mfma_f32_16x16x32_bf16 v[4:7], v[182:185], v[222:225], v[4:7]
	v_mfma_f32_16x16x32_bf16 v[0:3], v[190:193], v[222:225], v[0:3]
	s_setprio 0
	s_barrier
	s_branch .Lpeel_mid_11724
; #define PG8_STAGE(bufoff, gbase, voff, p64) do { _Pragma("unroll") for (int _i = 0; _i < 2; ++_i) { \
;         const char* _gb = (const char*)(gbase) + (size_t)_i * (p64); const unsigned _la = ldsbase + (unsigned)(bufoff) + (unsigned)_i * 8192u; \
;         asm volatile("s_mov_b32 m0, %0\n\ts_nop 0\n\tglobal_load_lds_dwordx4 %1, %2" :: "s"(_la), "v"(voff), "s"(_gb) : "memory"); } } while (0)
; #define PG8_LDA(dst, b, h) do { _Pragma("unroll") for (int m = 0; m < 4; ++m) _Pragma("unroll") for (int k = 0; k < 2; ++k) dst[m][k] = *(const LAS bf16x8*)(lds + PG8_SA(b, h) + aoff + m * 2048 + k * 1024); } while (0)
; #define PG8_LDB(dst, b, h) do { _Pragma("unroll") for (int n = 0; n < 2; ++n) _Pragma("unroll") for (int k = 0; k < 2; ++k) dst[n][k] = *(const LAS bf16x8*)(lds + PG8_SB(b, h) + boff + n * 2048 + k * 1024); } while (0)
; #define PG8_MMA(ai, bj, At, Bt) do { __builtin_amdgcn_s_setprio(1); _Pragma("unroll") for (int m = 0; m < 4; ++m) _Pragma("unroll") for (int n = 0; n < 2; ++n) _Pragma("unroll") for (int k = 0; k < 2; ++k) \
;         acc[ai][bj][m][n] = __builtin_amdgcn_mfma_f32_16x16x32_bf16(Bt[n][k], At[m][k], acc[ai][bj][m][n], 0, 0, 0); __builtin_amdgcn_s_setprio(0); } while (0)
; #define PG8_WAIT_V(n) asm volatile("s_waitcnt vmcnt(" #n ")" ::: "memory")
; #define PG8_WAIT_L(n) asm volatile("s_waitcnt lgkmcnt(" #n ")" ::: "memory")
; #define PG8_BAR __builtin_amdgcn_s_barrier()
; #define PG8_SCHED __builtin_amdgcn_sched_barrier(0)
; template <class Epi, class Sched>
; __device__ __forceinline__ void gemm_phase(LAS unsigned char* lds, const Sched& S, const Epi& E) {
;     ...
;             PG8_LDB(B0, 0, 0); PG8_LDB(B1, 0, 1); PG8_SCHED; PG8_LDA(At, 0, 0); PG8_STAGE(PG8_SA(1, 1), a1 + hA, voffA, hA / 2);
;             PG8_WAIT_V(8); PG8_WAIT_L(0); PG8_BAR; PG8_MMA(0, 0, At, B0); PG8_MMA(0, 1, At, B1); PG8_BAR; PG8_SCHED;
;             PG8_LDA(At, 0, 1); PG8_STAGE(PG8_SB(0, 0), b2, vB2, hB2 / 2); PG8_STAGE(PG8_SB(0, 1), b2 + hB2, vB2, hB2 / 2); PG8_STAGE(PG8_SA(0, 0), a2, vA2, hA2 / 2);
;             PG8_WAIT_V(8); PG8_WAIT_L(0); PG8_BAR; PG8_MMA(1, 0, At, B0); PG8_MMA(1, 1, At, B1); PG8_BAR; PG8_SCHED;
.LBB0_553:
	v_add_u32_e32 v128, 0x10000, v154
	ds_read_b128 v[138:141], v128
	ds_read_b128 v[142:145], v128 offset:1024
	ds_read_b128 v[146:149], v128 offset:2048
	ds_read_b128 v[172:175], v128 offset:3072
	v_add_u32_e32 v128, 0x14000, v154
	ds_read_b128 v[178:181], v128
	ds_read_b128 v[182:185], v128 offset:1024
	ds_read_b128 v[186:189], v128 offset:2048
	ds_read_b128 v[190:193], v128 offset:3072
	s_add_u32 s16, s74, 0xfffc0080
	s_addc_u32 s17, s75, -1
	s_cmp_eq_u32 s81, 12
	s_cselect_b32 s16, s58, s16
	s_cselect_b32 s17, s59, s17
	s_cselect_b32 s76, s62, s57
	s_cselect_b32 s77, s63, s80
	s_add_u32 s22, s16, 0x80
	s_addc_u32 s23, s17, 0
	ds_read_b128 v[194:197], v155
	ds_read_b128 v[198:201], v155 offset:1024
	ds_read_b128 v[202:205], v155 offset:2048
	ds_read_b128 v[206:209], v155 offset:3072
	ds_read_b128 v[210:213], v155 offset:4096
	ds_read_b128 v[214:217], v155 offset:5120
	ds_read_b128 v[218:221], v155 offset:6144
	ds_read_b128 v[222:225], v155 offset:7168
	s_mov_b32 m0, s67
	s_nop 0
	global_load_lds_dwordx4 v150, s[74:75]
	s_add_u32 s82, s74, 0x20000
	s_mov_b32 m0, s69
	s_addc_u32 s83, s75, 0
	global_load_lds_dwordx4 v150, s[82:83]
	s_waitcnt vmcnt(8) lgkmcnt(0)
	s_barrier
	s_setprio 1
	v_mfma_f32_16x16x32_bf16 v[124:127], v[138:141], v[194:197], v[124:127]
	v_mfma_f32_16x16x32_bf16 v[120:123], v[146:149], v[194:197], v[120:123]
	v_mfma_f32_16x16x32_bf16 v[112:115], v[138:141], v[202:205], v[112:115]
	v_mfma_f32_16x16x32_bf16 v[104:107], v[146:149], v[202:205], v[104:107]
	v_mfma_f32_16x16x32_bf16 v[96:99], v[138:141], v[210:213], v[96:99]
	v_mfma_f32_16x16x32_bf16 v[88:91], v[146:149], v[210:213], v[88:91]
	v_mfma_f32_16x16x32_bf16 v[80:83], v[138:141], v[218:221], v[80:83]
	v_mfma_f32_16x16x32_bf16 v[72:75], v[146:149], v[218:221], v[72:75]
	v_mfma_f32_16x16x32_bf16 v[124:127], v[142:145], v[198:201], v[124:127]
	v_mfma_f32_16x16x32_bf16 v[120:123], v[172:175], v[198:201], v[120:123]
	v_mfma_f32_16x16x32_bf16 v[112:115], v[142:145], v[206:209], v[112:115]
	v_mfma_f32_16x16x32_bf16 v[104:107], v[172:175], v[206:209], v[104:107]
	v_mfma_f32_16x16x32_bf16 v[96:99], v[142:145], v[214:217], v[96:99]
	v_mfma_f32_16x16x32_bf16 v[88:91], v[172:175], v[214:217], v[88:91]
	v_mfma_f32_16x16x32_bf16 v[80:83], v[142:145], v[222:225], v[80:83]
	v_mfma_f32_16x16x32_bf16 v[72:75], v[172:175], v[222:225], v[72:75]
	v_mfma_f32_16x16x32_bf16 v[116:119], v[178:181], v[194:197], v[116:119]
	v_mfma_f32_16x16x32_bf16 v[108:111], v[186:189], v[194:197], v[108:111]
	v_mfma_f32_16x16x32_bf16 v[100:103], v[178:181], v[202:205], v[100:103]
	v_mfma_f32_16x16x32_bf16 v[92:95], v[186:189], v[202:205], v[92:95]
	v_mfma_f32_16x16x32_bf16 v[84:87], v[178:181], v[210:213], v[84:87]
	v_mfma_f32_16x16x32_bf16 v[76:79], v[186:189], v[210:213], v[76:79]
	v_mfma_f32_16x16x32_bf16 v[68:71], v[178:181], v[218:221], v[68:71]
	v_mfma_f32_16x16x32_bf16 v[64:67], v[186:189], v[218:221], v[64:67]
	v_mfma_f32_16x16x32_bf16 v[116:119], v[182:185], v[198:201], v[116:119]
	v_mfma_f32_16x16x32_bf16 v[108:111], v[190:193], v[198:201], v[108:111]
	v_mfma_f32_16x16x32_bf16 v[100:103], v[182:185], v[206:209], v[100:103]
	v_mfma_f32_16x16x32_bf16 v[92:95], v[190:193], v[206:209], v[92:95]
	v_mfma_f32_16x16x32_bf16 v[84:87], v[182:185], v[214:217], v[84:87]
	v_mfma_f32_16x16x32_bf16 v[76:79], v[190:193], v[214:217], v[76:79]
	v_mfma_f32_16x16x32_bf16 v[68:71], v[182:185], v[222:225], v[68:71]
	v_mfma_f32_16x16x32_bf16 v[64:67], v[190:193], v[222:225], v[64:67]
	s_add_i32 s81, s81, 2
	s_add_u32 s74, s74, 0x100
	s_addc_u32 s75, s75, 0
	s_add_u32 s57, s57, 0x100
	s_addc_u32 s80, s80, 0
	s_setprio 0
	s_barrier
	s_add_u32 s82, s76, 0x20000
	ds_read_b128 v[194:197], v155 offset:16384
	ds_read_b128 v[198:201], v155 offset:17408
	ds_read_b128 v[202:205], v155 offset:18432
	ds_read_b128 v[206:209], v155 offset:19456
	ds_read_b128 v[210:213], v155 offset:20480
	ds_read_b128 v[214:217], v155 offset:21504
	ds_read_b128 v[218:221], v155 offset:22528
	ds_read_b128 v[222:225], v155 offset:23552
	s_mov_b32 m0, s24
	s_nop 0
	global_load_lds_dwordx4 v151, s[76:77]
	s_mov_b32 m0, s33
	s_addc_u32 s83, s77, 0
	global_load_lds_dwordx4 v151, s[82:83]
	s_add_u32 s82, s76, 0x40000
	s_mov_b32 m0, s34
	s_addc_u32 s83, s77, 0
	global_load_lds_dwordx4 v151, s[82:83]
	s_add_u32 s82, s76, 0x60000
	s_mov_b32 m0, s35
	s_addc_u32 s83, s77, 0
	global_load_lds_dwordx4 v151, s[82:83]
	s_mov_b32 m0, s15
	s_nop 0
	global_load_lds_dwordx4 v150, s[16:17]
	s_add_u32 s82, s16, 0x20000
	s_mov_b32 m0, s36
	s_addc_u32 s83, s17, 0
	global_load_lds_dwordx4 v150, s[82:83]
	s_waitcnt vmcnt(8) lgkmcnt(0)
	s_barrier
	s_setprio 1
	v_mfma_f32_16x16x32_bf16 v[60:63], v[138:141], v[194:197], v[60:63]
	v_mfma_f32_16x16x32_bf16 v[56:59], v[146:149], v[194:197], v[56:59]
	v_mfma_f32_16x16x32_bf16 v[48:51], v[138:141], v[202:205], v[48:51]
	v_mfma_f32_16x16x32_bf16 v[40:43], v[146:149], v[202:205], v[40:43]
	v_mfma_f32_16x16x32_bf16 v[32:35], v[138:141], v[210:213], v[32:35]
	v_mfma_f32_16x16x32_bf16 v[24:27], v[146:149], v[210:213], v[24:27]
	v_mfma_f32_16x16x32_bf16 v[16:19], v[138:141], v[218:221], v[16:19]
	v_mfma_f32_16x16x32_bf16 v[8:11], v[146:149], v[218:221], v[8:11]
	v_mfma_f32_16x16x32_bf16 v[60:63], v[142:145], v[198:201], v[60:63]
	v_mfma_f32_16x16x32_bf16 v[56:59], v[172:175], v[198:201], v[56:59]
	v_mfma_f32_16x16x32_bf16 v[48:51], v[142:145], v[206:209], v[48:51]
	v_mfma_f32_16x16x32_bf16 v[40:43], v[172:175], v[206:209], v[40:43]
	v_mfma_f32_16x16x32_bf16 v[32:35], v[142:145], v[214:217], v[32:35]
	v_mfma_f32_16x16x32_bf16 v[24:27], v[172:175], v[214:217], v[24:27]
	v_mfma_f32_16x16x32_bf16 v[16:19], v[142:145], v[222:225], v[16:19]
	v_mfma_f32_16x16x32_bf16 v[8:11], v[172:175], v[222:225], v[8:11]
	v_mfma_f32_16x16x32_bf16 v[52:55], v[178:181], v[194:197], v[52:55]
	v_mfma_f32_16x16x32_bf16 v[44:47], v[186:189], v[194:197], v[44:47]
	v_mfma_f32_16x16x32_bf16 v[36:39], v[178:181], v[202:205], v[36:39]
	v_mfma_f32_16x16x32_bf16 v[28:31], v[186:189], v[202:205], v[28:31]
	v_mfma_f32_16x16x32_bf16 v[20:23], v[178:181], v[210:213], v[20:23]
	v_mfma_f32_16x16x32_bf16 v[12:15], v[186:189], v[210:213], v[12:15]
	v_mfma_f32_16x16x32_bf16 v[4:7], v[178:181], v[218:221], v[4:7]
	v_mfma_f32_16x16x32_bf16 v[0:3], v[186:189], v[218:221], v[0:3]
	v_mfma_f32_16x16x32_bf16 v[52:55], v[182:185], v[198:201], v[52:55]
	v_mfma_f32_16x16x32_bf16 v[44:47], v[190:193], v[198:201], v[44:47]
	v_mfma_f32_16x16x32_bf16 v[36:39], v[182:185], v[206:209], v[36:39]
	v_mfma_f32_16x16x32_bf16 v[28:31], v[190:193], v[206:209], v[28:31]
	v_mfma_f32_16x16x32_bf16 v[20:23], v[182:185], v[214:217], v[20:23]
	v_mfma_f32_16x16x32_bf16 v[12:15], v[190:193], v[214:217], v[12:15]
	v_mfma_f32_16x16x32_bf16 v[4:7], v[182:185], v[222:225], v[4:7]
	v_mfma_f32_16x16x32_bf16 v[0:3], v[190:193], v[222:225], v[0:3]
	s_setprio 0
	s_barrier
; #define PG8_STAGE(bufoff, gbase, voff, p64) do { _Pragma("unroll") for (int _i = 0; _i < 2; ++_i) { \
;         const char* _gb = (const char*)(gbase) + (size_t)_i * (p64); const unsigned _la = ldsbase + (unsigned)(bufoff) + (unsigned)_i * 8192u; \
;         asm volatile("s_mov_b32 m0, %0\n\ts_nop 0\n\tglobal_load_lds_dwordx4 %1, %2" :: "s"(_la), "v"(voff), "s"(_gb) : "memory"); } } while (0)
; #define PG8_LDA(dst, b, h) do { _Pragma("unroll") for (int m = 0; m < 4; ++m) _Pragma("unroll") for (int k = 0; k < 2; ++k) dst[m][k] = *(const LAS bf16x8*)(lds + PG8_SA(b, h) + aoff + m * 2048 + k * 1024); } while (0)
; #define PG8_LDB(dst, b, h) do { _Pragma("unroll") for (int n = 0; n < 2; ++n) _Pragma("unroll") for (int k = 0; k < 2; ++k) dst[n][k] = *(const LAS bf16x8*)(lds + PG8_SB(b, h) + boff + n * 2048 + k * 1024); } while (0)
; #define PG8_MMA(ai, bj, At, Bt) do { __builtin_amdgcn_s_setprio(1); _Pragma("unroll") for (int m = 0; m < 4; ++m) _Pragma("unroll") for (int n = 0; n < 2; ++n) _Pragma("unroll") for (int k = 0; k < 2; ++k) \
;         acc[ai][bj][m][n] = __builtin_amdgcn_mfma_f32_16x16x32_bf16(Bt[n][k], At[m][k], acc[ai][bj][m][n], 0, 0, 0); __builtin_amdgcn_s_setprio(0); } while (0)
; #define PG8_WAIT_V(n) asm volatile("s_waitcnt vmcnt(" #n ")" ::: "memory")
; #define PG8_WAIT_L(n) asm volatile("s_waitcnt lgkmcnt(" #n ")" ::: "memory")
; #define PG8_BAR __builtin_amdgcn_s_barrier()
; #define PG8_SCHED __builtin_amdgcn_sched_barrier(0)
; template <class Epi, class Sched>
; __device__ __forceinline__ void gemm_phase(LAS unsigned char* lds, const Sched& S, const Epi& E) {
;     ...
;             PG8_LDB(B0, 1, 0); PG8_LDB(B1, 1, 1); PG8_SCHED; PG8_LDA(At, 1, 0); PG8_STAGE(PG8_SA(0, 1), a2 + hA2, vA2, hA2 / 2);
;             PG8_WAIT_V(8); PG8_WAIT_L(0); PG8_BAR; PG8_MMA(0, 0, At, B0); PG8_MMA(0, 1, At, B1); PG8_BAR; PG8_SCHED;
;             PG8_LDA(At, 1, 1); PG8_STAGE(PG8_SB(1, 0), b3, vB2, hB2 / 2); PG8_STAGE(PG8_SB(1, 1), b3 + hB2, vB2, hB2 / 2); PG8_STAGE(PG8_SA(1, 0), a3, vA2, hA2 / 2);
;             PG8_WAIT_V(8); PG8_WAIT_L(0); PG8_BAR; PG8_MMA(1, 0, At, B0); PG8_MMA(1, 1, At, B1); PG8_BAR; PG8_SCHED;
;         }
;         if (wr == 0) PG8_BAR;
.Lpeel_mid_11724:
	v_add_u32_e32 v128, 0x18000, v154
	ds_read_b128 v[138:141], v128
	ds_read_b128 v[142:145], v128 offset:1024
	ds_read_b128 v[146:149], v128 offset:2048
	ds_read_b128 v[172:175], v128 offset:3072
	v_add_u32_e32 v128, 0x1c000, v154
	ds_read_b128 v[178:181], v128
	ds_read_b128 v[182:185], v128 offset:1024
	ds_read_b128 v[186:189], v128 offset:2048
	ds_read_b128 v[190:193], v128 offset:3072
	ds_read_b128 v[194:197], v155 offset:32768
	ds_read_b128 v[198:201], v155 offset:33792
	ds_read_b128 v[202:205], v155 offset:34816
	ds_read_b128 v[206:209], v155 offset:35840
	ds_read_b128 v[210:213], v155 offset:36864
	ds_read_b128 v[214:217], v155 offset:37888
	ds_read_b128 v[218:221], v155 offset:38912
	ds_read_b128 v[222:225], v155 offset:39936
	s_add_u32 s82, s16, 0x40000
	s_mov_b32 m0, s37
	s_addc_u32 s83, s17, 0
	global_load_lds_dwordx4 v150, s[82:83]
	s_add_u32 s82, s16, 0x60000
	s_mov_b32 m0, s42
	s_addc_u32 s83, s17, 0
	global_load_lds_dwordx4 v150, s[82:83]
	s_waitcnt vmcnt(8) lgkmcnt(0)
	s_barrier
	s_setprio 1
	v_mfma_f32_16x16x32_bf16 v[124:127], v[138:141], v[194:197], v[124:127]
	v_mfma_f32_16x16x32_bf16 v[120:123], v[146:149], v[194:197], v[120:123]
	v_mfma_f32_16x16x32_bf16 v[112:115], v[138:141], v[202:205], v[112:115]
	v_mfma_f32_16x16x32_bf16 v[104:107], v[146:149], v[202:205], v[104:107]
	v_mfma_f32_16x16x32_bf16 v[96:99], v[138:141], v[210:213], v[96:99]
	v_mfma_f32_16x16x32_bf16 v[88:91], v[146:149], v[210:213], v[88:91]
	v_mfma_f32_16x16x32_bf16 v[80:83], v[138:141], v[218:221], v[80:83]
	v_mfma_f32_16x16x32_bf16 v[72:75], v[146:149], v[218:221], v[72:75]
	v_mfma_f32_16x16x32_bf16 v[124:127], v[142:145], v[198:201], v[124:127]
	v_mfma_f32_16x16x32_bf16 v[120:123], v[172:175], v[198:201], v[120:123]
	v_mfma_f32_16x16x32_bf16 v[112:115], v[142:145], v[206:209], v[112:115]
	v_mfma_f32_16x16x32_bf16 v[104:107], v[172:175], v[206:209], v[104:107]
	v_mfma_f32_16x16x32_bf16 v[96:99], v[142:145], v[214:217], v[96:99]
	v_mfma_f32_16x16x32_bf16 v[88:91], v[172:175], v[214:217], v[88:91]
	v_mfma_f32_16x16x32_bf16 v[80:83], v[142:145], v[222:225], v[80:83]
	v_mfma_f32_16x16x32_bf16 v[72:75], v[172:175], v[222:225], v[72:75]
	v_mfma_f32_16x16x32_bf16 v[116:119], v[178:181], v[194:197], v[116:119]
	v_mfma_f32_16x16x32_bf16 v[108:111], v[186:189], v[194:197], v[108:111]
	v_mfma_f32_16x16x32_bf16 v[100:103], v[178:181], v[202:205], v[100:103]
	v_mfma_f32_16x16x32_bf16 v[92:95], v[186:189], v[202:205], v[92:95]
	v_mfma_f32_16x16x32_bf16 v[84:87], v[178:181], v[210:213], v[84:87]
	v_mfma_f32_16x16x32_bf16 v[76:79], v[186:189], v[210:213], v[76:79]
	v_mfma_f32_16x16x32_bf16 v[68:71], v[178:181], v[218:221], v[68:71]
	v_mfma_f32_16x16x32_bf16 v[64:67], v[186:189], v[218:221], v[64:67]
	v_mfma_f32_16x16x32_bf16 v[116:119], v[182:185], v[198:201], v[116:119]
	v_mfma_f32_16x16x32_bf16 v[108:111], v[190:193], v[198:201], v[108:111]
	v_mfma_f32_16x16x32_bf16 v[100:103], v[182:185], v[206:209], v[100:103]
	v_mfma_f32_16x16x32_bf16 v[92:95], v[190:193], v[206:209], v[92:95]
	v_mfma_f32_16x16x32_bf16 v[84:87], v[182:185], v[214:217], v[84:87]
	v_mfma_f32_16x16x32_bf16 v[76:79], v[190:193], v[214:217], v[76:79]
	v_mfma_f32_16x16x32_bf16 v[68:71], v[182:185], v[222:225], v[68:71]
	v_mfma_f32_16x16x32_bf16 v[64:67], v[190:193], v[222:225], v[64:67]
	s_setprio 0
	s_barrier
	s_add_u32 s82, s76, 0x80
	s_addc_u32 s83, s77, 0
	ds_read_b128 v[194:197], v155 offset:49152
	ds_read_b128 v[198:201], v155 offset:50176
	ds_read_b128 v[202:205], v155 offset:51200
	ds_read_b128 v[206:209], v155 offset:52224
	ds_read_b128 v[210:213], v155 offset:53248
	ds_read_b128 v[214:217], v155 offset:54272
	ds_read_b128 v[218:221], v155 offset:55296
	ds_read_b128 v[222:225], v155 offset:56320
	s_mov_b32 m0, s50
	s_nop 0
	global_load_lds_dwordx4 v151, s[82:83]
	s_add_u32 s82, s76, 0x20080
	s_mov_b32 m0, s51
	s_addc_u32 s83, s77, 0
	global_load_lds_dwordx4 v151, s[82:83]
	s_add_u32 s82, s76, 0x40080
	s_mov_b32 m0, s65
	s_addc_u32 s83, s77, 0
	global_load_lds_dwordx4 v151, s[82:83]
	s_add_u32 s76, s76, 0x60080
	s_mov_b32 m0, s66
	s_addc_u32 s77, s77, 0
	global_load_lds_dwordx4 v151, s[76:77]
	s_mov_b32 m0, s61
	s_nop 0
	global_load_lds_dwordx4 v150, s[22:23]
	s_add_u32 s16, s16, 0x20080
	s_mov_b32 m0, s64
	s_addc_u32 s17, s17, 0
	global_load_lds_dwordx4 v150, s[16:17]
	s_waitcnt vmcnt(8) lgkmcnt(0)
	s_barrier
	s_setprio 1
	v_mfma_f32_16x16x32_bf16 v[60:63], v[138:141], v[194:197], v[60:63]
	v_mfma_f32_16x16x32_bf16 v[56:59], v[146:149], v[194:197], v[56:59]
	v_mfma_f32_16x16x32_bf16 v[48:51], v[138:141], v[202:205], v[48:51]
	v_mfma_f32_16x16x32_bf16 v[40:43], v[146:149], v[202:205], v[40:43]
	v_mfma_f32_16x16x32_bf16 v[32:35], v[138:141], v[210:213], v[32:35]
	v_mfma_f32_16x16x32_bf16 v[24:27], v[146:149], v[210:213], v[24:27]
	v_mfma_f32_16x16x32_bf16 v[16:19], v[138:141], v[218:221], v[16:19]
	v_mfma_f32_16x16x32_bf16 v[8:11], v[146:149], v[218:221], v[8:11]
	v_mfma_f32_16x16x32_bf16 v[60:63], v[142:145], v[198:201], v[60:63]
	v_mfma_f32_16x16x32_bf16 v[56:59], v[172:175], v[198:201], v[56:59]
	v_mfma_f32_16x16x32_bf16 v[48:51], v[142:145], v[206:209], v[48:51]
	v_mfma_f32_16x16x32_bf16 v[40:43], v[172:175], v[206:209], v[40:43]
	v_mfma_f32_16x16x32_bf16 v[32:35], v[142:145], v[214:217], v[32:35]
	v_mfma_f32_16x16x32_bf16 v[24:27], v[172:175], v[214:217], v[24:27]
	v_mfma_f32_16x16x32_bf16 v[16:19], v[142:145], v[222:225], v[16:19]
	v_mfma_f32_16x16x32_bf16 v[8:11], v[172:175], v[222:225], v[8:11]
	v_mfma_f32_16x16x32_bf16 v[52:55], v[178:181], v[194:197], v[52:55]
	v_mfma_f32_16x16x32_bf16 v[44:47], v[186:189], v[194:197], v[44:47]
	v_mfma_f32_16x16x32_bf16 v[36:39], v[178:181], v[202:205], v[36:39]
	v_mfma_f32_16x16x32_bf16 v[28:31], v[186:189], v[202:205], v[28:31]
	v_mfma_f32_16x16x32_bf16 v[20:23], v[178:181], v[210:213], v[20:23]
	v_mfma_f32_16x16x32_bf16 v[12:15], v[186:189], v[210:213], v[12:15]
	v_mfma_f32_16x16x32_bf16 v[4:7], v[178:181], v[218:221], v[4:7]
	v_mfma_f32_16x16x32_bf16 v[0:3], v[186:189], v[218:221], v[0:3]
	v_mfma_f32_16x16x32_bf16 v[52:55], v[182:185], v[198:201], v[52:55]
	v_mfma_f32_16x16x32_bf16 v[44:47], v[190:193], v[198:201], v[44:47]
	v_mfma_f32_16x16x32_bf16 v[36:39], v[182:185], v[206:209], v[36:39]
	v_mfma_f32_16x16x32_bf16 v[28:31], v[190:193], v[206:209], v[28:31]
	v_mfma_f32_16x16x32_bf16 v[20:23], v[182:185], v[214:217], v[20:23]
	v_mfma_f32_16x16x32_bf16 v[12:15], v[190:193], v[214:217], v[12:15]
	v_mfma_f32_16x16x32_bf16 v[4:7], v[182:185], v[222:225], v[4:7]
	v_mfma_f32_16x16x32_bf16 v[0:3], v[190:193], v[222:225], v[0:3]
	s_setprio 0
	s_barrier
	s_cmp_gt_u32 s81, 13
	s_cbranch_scc0 .LBB0_553
	s_and_b64 vcc, exec, s[6:7]
	s_cbranch_vccz .LBB0_556
	s_barrier

; #define PG8_STAGE(bufoff, gbase, voff, p64) do { _Pragma("unroll") for (int _i = 0; _i < 2; ++_i) { \
;         const char* _gb = (const char*)(gbase) + (size_t)_i * (p64); const unsigned _la = ldsbase + (unsigned)(bufoff) + (unsigned)_i * 8192u; \
;         asm volatile("s_mov_b32 m0, %0\n\ts_nop 0\n\tglobal_load_lds_dwordx4 %1, %2" :: "s"(_la), "v"(voff), "s"(_gb) : "memory"); } } while (0)
; #define PG8_LDA(dst, b, h) do { _Pragma("unroll") for (int m = 0; m < 4; ++m) _Pragma("unroll") for (int k = 0; k < 2; ++k) dst[m][k] = *(const LAS bf16x8*)(lds + PG8_SA(b, h) + aoff + m * 2048 + k * 1024); } while (0)
; #define PG8_LDB(dst, b, h) do { _Pragma("unroll") for (int n = 0; n < 2; ++n) _Pragma("unroll") for (int k = 0; k < 2; ++k) dst[n][k] = *(const LAS bf16x8*)(lds + PG8_SB(b, h) + boff + n * 2048 + k * 1024); } while (0)
; #define PG8_MMA(ai, bj, At, Bt) do { __builtin_amdgcn_s_setprio(1); _Pragma("unroll") for (int m = 0; m < 4; ++m) _Pragma("unroll") for (int n = 0; n < 2; ++n) _Pragma("unroll") for (int k = 0; k < 2; ++k) \
;         acc[ai][bj][m][n] = __builtin_amdgcn_mfma_f32_16x16x32_bf16(Bt[n][k], At[m][k], acc[ai][bj][m][n], 0, 0, 0); __builtin_amdgcn_s_setprio(0); } while (0)
; #define PG8_WAIT_V(n) asm volatile("s_waitcnt vmcnt(" #n ")" ::: "memory")
; #define PG8_WAIT_L(n) asm volatile("s_waitcnt lgkmcnt(" #n ")" ::: "memory")
; #define PG8_BAR __builtin_amdgcn_s_barrier()
; template <class Epi, class Sched>
; __device__ __forceinline__ void gemm_phase(LAS unsigned char* lds, const Sched& S, const Epi& E) {
;     ...
; #pragma unroll
;     for (int a = 0; a < 2; ++a)
; #pragma unroll
;         for (int b = 0; b < 2; ++b)
; #pragma unroll
;             for (int m = 0; m < 4; ++m)
; #pragma unroll
;                 for (int n = 0; n < 2; ++n) acc[a][b][m][n] = (f32x4){0.f, 0.f, 0.f, 0.f};
;     ...
;             PG8_LDB(B0, 0, 0); PG8_LDB(B1, 0, 1); PG8_SCHED; PG8_LDA(At, 0, 0); PG8_STAGE(PG8_SA(1, 1), a1 + hA, voffA, hA / 2);
;             PG8_WAIT_V(8); PG8_WAIT_L(0); PG8_BAR; PG8_MMA(0, 0, At, B0); PG8_MMA(0, 1, At, B1); PG8_BAR; PG8_SCHED;
;             PG8_LDA(At, 0, 1); PG8_STAGE(PG8_SB(0, 0), b2, vB2, hB2 / 2); PG8_STAGE(PG8_SB(0, 1), b2 + hB2, vB2, hB2 / 2); PG8_STAGE(PG8_SA(0, 0), a2, vA2, hA2 / 2);
;             PG8_WAIT_V(8); PG8_WAIT_L(0); PG8_BAR; PG8_MMA(1, 0, At, B0); PG8_MMA(1, 1, At, B1); PG8_BAR; PG8_SCHED;
.LBB0_581:
	s_add_u32 s62, s16, 0x40080
	s_addc_u32 s63, s17, 0
	s_add_u32 s55, s22, 0x100
	s_addc_u32 s74, s23, 0
	s_mov_b32 s75, -2
	s_waitcnt vmcnt(1)
	s_waitcnt vmcnt(0)
	v_add_u32_e32 v130, 0x10000, v153
	ds_read_b128 v[138:141], v130
	ds_read_b128 v[142:145], v130 offset:1024
	ds_read_b128 v[146:149], v130 offset:2048
	ds_read_b128 v[172:175], v130 offset:3072
	v_add_u32_e32 v130, 0x14000, v153
	ds_read_b128 v[178:181], v130
	ds_read_b128 v[182:185], v130 offset:1024
	ds_read_b128 v[186:189], v130 offset:2048
	ds_read_b128 v[190:193], v130 offset:3072
	s_add_u32 s16, s62, 0xfffc0080
	s_addc_u32 s17, s63, -1
	s_cmp_eq_u32 s75, 12
	s_cselect_b32 s16, s56, s16
	s_cselect_b32 s17, s57, s17
	s_cselect_b32 s72, s58, s55
	s_cselect_b32 s73, s59, s74
	s_add_u32 s22, s16, 0x80
	s_addc_u32 s23, s17, 0
	ds_read_b128 v[194:197], v154
	ds_read_b128 v[198:201], v154 offset:1024
	ds_read_b128 v[202:205], v154 offset:2048
	ds_read_b128 v[206:209], v154 offset:3072
	ds_read_b128 v[210:213], v154 offset:4096
	ds_read_b128 v[214:217], v154 offset:5120
	ds_read_b128 v[218:221], v154 offset:6144
	ds_read_b128 v[222:225], v154 offset:7168
	s_mov_b32 m0, s78
	s_nop 0
	global_load_lds_dwordx4 v128, s[62:63]
	s_add_u32 s82, s62, 0x20000
	s_mov_b32 m0, s80
	s_addc_u32 s83, s63, 0
	global_load_lds_dwordx4 v128, s[82:83]
	s_waitcnt vmcnt(8) lgkmcnt(0)
	s_barrier
	s_setprio 1
	v_mfma_f32_16x16x32_bf16 v[124:127], v[138:141], v[194:197], 0
	v_mfma_f32_16x16x32_bf16 v[120:123], v[146:149], v[194:197], 0
	v_mfma_f32_16x16x32_bf16 v[116:119], v[138:141], v[202:205], 0
	v_mfma_f32_16x16x32_bf16 v[108:111], v[146:149], v[202:205], 0
	v_mfma_f32_16x16x32_bf16 v[100:103], v[138:141], v[210:213], 0
	v_mfma_f32_16x16x32_bf16 v[92:95], v[146:149], v[210:213], 0
	v_mfma_f32_16x16x32_bf16 v[84:87], v[138:141], v[218:221], 0
	v_mfma_f32_16x16x32_bf16 v[76:79], v[146:149], v[218:221], 0
	v_mfma_f32_16x16x32_bf16 v[124:127], v[142:145], v[198:201], v[124:127]
	v_mfma_f32_16x16x32_bf16 v[120:123], v[172:175], v[198:201], v[120:123]
	v_mfma_f32_16x16x32_bf16 v[116:119], v[142:145], v[206:209], v[116:119]
	v_mfma_f32_16x16x32_bf16 v[108:111], v[172:175], v[206:209], v[108:111]
	v_mfma_f32_16x16x32_bf16 v[100:103], v[142:145], v[214:217], v[100:103]
	v_mfma_f32_16x16x32_bf16 v[92:95], v[172:175], v[214:217], v[92:95]
	v_mfma_f32_16x16x32_bf16 v[84:87], v[142:145], v[222:225], v[84:87]
	v_mfma_f32_16x16x32_bf16 v[76:79], v[172:175], v[222:225], v[76:79]
	v_mfma_f32_16x16x32_bf16 v[112:115], v[178:181], v[194:197], 0
	v_mfma_f32_16x16x32_bf16 v[104:107], v[186:189], v[194:197], 0
	v_mfma_f32_16x16x32_bf16 v[96:99], v[178:181], v[202:205], 0
	v_mfma_f32_16x16x32_bf16 v[88:91], v[186:189], v[202:205], 0
	v_mfma_f32_16x16x32_bf16 v[80:83], v[178:181], v[210:213], 0
	v_mfma_f32_16x16x32_bf16 v[72:75], v[186:189], v[210:213], 0
	v_mfma_f32_16x16x32_bf16 v[68:71], v[178:181], v[218:221], 0
	v_mfma_f32_16x16x32_bf16 v[64:67], v[186:189], v[218:221], 0
	v_mfma_f32_16x16x32_bf16 v[112:115], v[182:185], v[198:201], v[112:115]
	v_mfma_f32_16x16x32_bf16 v[104:107], v[190:193], v[198:201], v[104:107]
	v_mfma_f32_16x16x32_bf16 v[96:99], v[182:185], v[206:209], v[96:99]
	v_mfma_f32_16x16x32_bf16 v[88:91], v[190:193], v[206:209], v[88:91]
	v_mfma_f32_16x16x32_bf16 v[80:83], v[182:185], v[214:217], v[80:83]
	v_mfma_f32_16x16x32_bf16 v[72:75], v[190:193], v[214:217], v[72:75]
	v_mfma_f32_16x16x32_bf16 v[68:71], v[182:185], v[222:225], v[68:71]
	v_mfma_f32_16x16x32_bf16 v[64:67], v[190:193], v[222:225], v[64:67]
	s_add_i32 s75, s75, 2
	s_add_u32 s62, s62, 0x100
	s_addc_u32 s63, s63, 0
	s_add_u32 s55, s55, 0x100
	s_addc_u32 s74, s74, 0
	s_setprio 0
	s_barrier
	s_add_u32 s82, s72, 0x20000
	ds_read_b128 v[194:197], v154 offset:16384
	ds_read_b128 v[198:201], v154 offset:17408
	ds_read_b128 v[202:205], v154 offset:18432
	ds_read_b128 v[206:209], v154 offset:19456
	ds_read_b128 v[210:213], v154 offset:20480
	ds_read_b128 v[214:217], v154 offset:21504
	ds_read_b128 v[218:221], v154 offset:22528
	ds_read_b128 v[222:225], v154 offset:23552
	s_mov_b32 m0, s20
	s_nop 0
	global_load_lds_dwordx4 v150, s[72:73]
	s_mov_b32 m0, s24
	s_addc_u32 s83, s73, 0
	global_load_lds_dwordx4 v150, s[82:83]
	s_add_u32 s82, s72, 0x40000
	s_mov_b32 m0, s33
	s_addc_u32 s83, s73, 0
	global_load_lds_dwordx4 v150, s[82:83]
	s_add_u32 s82, s72, 0x60000
	s_mov_b32 m0, s34
	s_addc_u32 s83, s73, 0
	global_load_lds_dwordx4 v150, s[82:83]
	s_mov_b32 m0, s15
	s_nop 0
	global_load_lds_dwordx4 v128, s[16:17]
	s_add_u32 s82, s16, 0x20000
	s_mov_b32 m0, s35
	s_addc_u32 s83, s17, 0
	global_load_lds_dwordx4 v128, s[82:83]
	s_waitcnt vmcnt(8) lgkmcnt(0)
	s_barrier
	s_setprio 1
	v_mfma_f32_16x16x32_bf16 v[60:63], v[138:141], v[194:197], 0
	v_mfma_f32_16x16x32_bf16 v[56:59], v[146:149], v[194:197], 0
	v_mfma_f32_16x16x32_bf16 v[52:55], v[138:141], v[202:205], 0
	v_mfma_f32_16x16x32_bf16 v[44:47], v[146:149], v[202:205], 0
	v_mfma_f32_16x16x32_bf16 v[36:39], v[138:141], v[210:213], 0
	v_mfma_f32_16x16x32_bf16 v[28:31], v[146:149], v[210:213], 0
	v_mfma_f32_16x16x32_bf16 v[20:23], v[138:141], v[218:221], 0
	v_mfma_f32_16x16x32_bf16 v[12:15], v[146:149], v[218:221], 0
	v_mfma_f32_16x16x32_bf16 v[60:63], v[142:145], v[198:201], v[60:63]
	v_mfma_f32_16x16x32_bf16 v[56:59], v[172:175], v[198:201], v[56:59]
	v_mfma_f32_16x16x32_bf16 v[52:55], v[142:145], v[206:209], v[52:55]
	v_mfma_f32_16x16x32_bf16 v[44:47], v[172:175], v[206:209], v[44:47]
	v_mfma_f32_16x16x32_bf16 v[36:39], v[142:145], v[214:217], v[36:39]
	v_mfma_f32_16x16x32_bf16 v[28:31], v[172:175], v[214:217], v[28:31]
	v_mfma_f32_16x16x32_bf16 v[20:23], v[142:145], v[222:225], v[20:23]
	v_mfma_f32_16x16x32_bf16 v[12:15], v[172:175], v[222:225], v[12:15]
	v_mfma_f32_16x16x32_bf16 v[48:51], v[178:181], v[194:197], 0
	v_mfma_f32_16x16x32_bf16 v[40:43], v[186:189], v[194:197], 0
	v_mfma_f32_16x16x32_bf16 v[32:35], v[178:181], v[202:205], 0
	v_mfma_f32_16x16x32_bf16 v[24:27], v[186:189], v[202:205], 0
	v_mfma_f32_16x16x32_bf16 v[16:19], v[178:181], v[210:213], 0
	v_mfma_f32_16x16x32_bf16 v[8:11], v[186:189], v[210:213], 0
	v_mfma_f32_16x16x32_bf16 v[4:7], v[178:181], v[218:221], 0
	v_mfma_f32_16x16x32_bf16 v[0:3], v[186:189], v[218:221], 0
	v_mfma_f32_16x16x32_bf16 v[48:51], v[182:185], v[198:201], v[48:51]
	v_mfma_f32_16x16x32_bf16 v[40:43], v[190:193], v[198:201], v[40:43]
	v_mfma_f32_16x16x32_bf16 v[32:35], v[182:185], v[206:209], v[32:35]
	v_mfma_f32_16x16x32_bf16 v[24:27], v[190:193], v[206:209], v[24:27]
	v_mfma_f32_16x16x32_bf16 v[16:19], v[182:185], v[214:217], v[16:19]
	v_mfma_f32_16x16x32_bf16 v[8:11], v[190:193], v[214:217], v[8:11]
	v_mfma_f32_16x16x32_bf16 v[4:7], v[182:185], v[222:225], v[4:7]
	v_mfma_f32_16x16x32_bf16 v[0:3], v[190:193], v[222:225], v[0:3]
	s_setprio 0
	s_barrier
	s_branch .Lpeel_mid_14726
; #define PG8_STAGE(bufoff, gbase, voff, p64) do { _Pragma("unroll") for (int _i = 0; _i < 2; ++_i) { \
;         const char* _gb = (const char*)(gbase) + (size_t)_i * (p64); const unsigned _la = ldsbase + (unsigned)(bufoff) + (unsigned)_i * 8192u; \
;         asm volatile("s_mov_b32 m0, %0\n\ts_nop 0\n\tglobal_load_lds_dwordx4 %1, %2" :: "s"(_la), "v"(voff), "s"(_gb) : "memory"); } } while (0)
; #define PG8_LDA(dst, b, h) do { _Pragma("unroll") for (int m = 0; m < 4; ++m) _Pragma("unroll") for (int k = 0; k < 2; ++k) dst[m][k] = *(const LAS bf16x8*)(lds + PG8_SA(b, h) + aoff + m * 2048 + k * 1024); } while (0)
; #define PG8_LDB(dst, b, h) do { _Pragma("unroll") for (int n = 0; n < 2; ++n) _Pragma("unroll") for (int k = 0; k < 2; ++k) dst[n][k] = *(const LAS bf16x8*)(lds + PG8_SB(b, h) + boff + n * 2048 + k * 1024); } while (0)
; #define PG8_MMA(ai, bj, At, Bt) do { __builtin_amdgcn_s_setprio(1); _Pragma("unroll") for (int m = 0; m < 4; ++m) _Pragma("unroll") for (int n = 0; n < 2; ++n) _Pragma("unroll") for (int k = 0; k < 2; ++k) \
;         acc[ai][bj][m][n] = __builtin_amdgcn_mfma_f32_16x16x32_bf16(Bt[n][k], At[m][k], acc[ai][bj][m][n], 0, 0, 0); __builtin_amdgcn_s_setprio(0); } while (0)
; #define PG8_WAIT_V(n) asm volatile("s_waitcnt vmcnt(" #n ")" ::: "memory")
; #define PG8_WAIT_L(n) asm volatile("s_waitcnt lgkmcnt(" #n ")" ::: "memory")
; #define PG8_BAR __builtin_amdgcn_s_barrier()
; #define PG8_SCHED __builtin_amdgcn_sched_barrier(0)
; template <class Epi, class Sched>
; __device__ __forceinline__ void gemm_phase(LAS unsigned char* lds, const Sched& S, const Epi& E) {
;     ...
;             PG8_LDB(B0, 0, 0); PG8_LDB(B1, 0, 1); PG8_SCHED; PG8_LDA(At, 0, 0); PG8_STAGE(PG8_SA(1, 1), a1 + hA, voffA, hA / 2);
;             PG8_WAIT_V(8); PG8_WAIT_L(0); PG8_BAR; PG8_MMA(0, 0, At, B0); PG8_MMA(0, 1, At, B1); PG8_BAR; PG8_SCHED;
;             PG8_LDA(At, 0, 1); PG8_STAGE(PG8_SB(0, 0), b2, vB2, hB2 / 2); PG8_STAGE(PG8_SB(0, 1), b2 + hB2, vB2, hB2 / 2); PG8_STAGE(PG8_SA(0, 0), a2, vA2, hA2 / 2);
;             PG8_WAIT_V(8); PG8_WAIT_L(0); PG8_BAR; PG8_MMA(1, 0, At, B0); PG8_MMA(1, 1, At, B1); PG8_BAR; PG8_SCHED;
.LBB0_582:
	v_add_u32_e32 v130, 0x10000, v153
	ds_read_b128 v[138:141], v130
	ds_read_b128 v[142:145], v130 offset:1024
	ds_read_b128 v[146:149], v130 offset:2048
	ds_read_b128 v[172:175], v130 offset:3072
	v_add_u32_e32 v130, 0x14000, v153
	ds_read_b128 v[178:181], v130
	ds_read_b128 v[182:185], v130 offset:1024
	ds_read_b128 v[186:189], v130 offset:2048
	ds_read_b128 v[190:193], v130 offset:3072
	s_add_u32 s16, s62, 0xfffc0080
	s_addc_u32 s17, s63, -1
	s_cmp_eq_u32 s75, 12
	s_cselect_b32 s16, s56, s16
	s_cselect_b32 s17, s57, s17
	s_cselect_b32 s72, s58, s55
	s_cselect_b32 s73, s59, s74
	s_add_u32 s22, s16, 0x80
	s_addc_u32 s23, s17, 0
	ds_read_b128 v[194:197], v154
	ds_read_b128 v[198:201], v154 offset:1024
	ds_read_b128 v[202:205], v154 offset:2048
	ds_read_b128 v[206:209], v154 offset:3072
	ds_read_b128 v[210:213], v154 offset:4096
	ds_read_b128 v[214:217], v154 offset:5120
	ds_read_b128 v[218:221], v154 offset:6144
	ds_read_b128 v[222:225], v154 offset:7168
	s_mov_b32 m0, s78
	s_nop 0
	global_load_lds_dwordx4 v128, s[62:63]
	s_add_u32 s82, s62, 0x20000
	s_mov_b32 m0, s80
	s_addc_u32 s83, s63, 0
	global_load_lds_dwordx4 v128, s[82:83]
	s_waitcnt vmcnt(8) lgkmcnt(0)
	s_barrier
	s_setprio 1
	v_mfma_f32_16x16x32_bf16 v[124:127], v[138:141], v[194:197], v[124:127]
	v_mfma_f32_16x16x32_bf16 v[120:123], v[146:149], v[194:197], v[120:123]
	v_mfma_f32_16x16x32_bf16 v[116:119], v[138:141], v[202:205], v[116:119]
	v_mfma_f32_16x16x32_bf16 v[108:111], v[146:149], v[202:205], v[108:111]
	v_mfma_f32_16x16x32_bf16 v[100:103], v[138:141], v[210:213], v[100:103]
	v_mfma_f32_16x16x32_bf16 v[92:95], v[146:149], v[210:213], v[92:95]
	v_mfma_f32_16x16x32_bf16 v[84:87], v[138:141], v[218:221], v[84:87]
	v_mfma_f32_16x16x32_bf16 v[76:79], v[146:149], v[218:221], v[76:79]
	v_mfma_f32_16x16x32_bf16 v[124:127], v[142:145], v[198:201], v[124:127]
	v_mfma_f32_16x16x32_bf16 v[120:123], v[172:175], v[198:201], v[120:123]
	v_mfma_f32_16x16x32_bf16 v[116:119], v[142:145], v[206:209], v[116:119]
	v_mfma_f32_16x16x32_bf16 v[108:111], v[172:175], v[206:209], v[108:111]
	v_mfma_f32_16x16x32_bf16 v[100:103], v[142:145], v[214:217], v[100:103]
	v_mfma_f32_16x16x32_bf16 v[92:95], v[172:175], v[214:217], v[92:95]
	v_mfma_f32_16x16x32_bf16 v[84:87], v[142:145], v[222:225], v[84:87]
	v_mfma_f32_16x16x32_bf16 v[76:79], v[172:175], v[222:225], v[76:79]
	v_mfma_f32_16x16x32_bf16 v[112:115], v[178:181], v[194:197], v[112:115]
	v_mfma_f32_16x16x32_bf16 v[104:107], v[186:189], v[194:197], v[104:107]
	v_mfma_f32_16x16x32_bf16 v[96:99], v[178:181], v[202:205], v[96:99]
	v_mfma_f32_16x16x32_bf16 v[88:91], v[186:189], v[202:205], v[88:91]
	v_mfma_f32_16x16x32_bf16 v[80:83], v[178:181], v[210:213], v[80:83]
	v_mfma_f32_16x16x32_bf16 v[72:75], v[186:189], v[210:213], v[72:75]
	v_mfma_f32_16x16x32_bf16 v[68:71], v[178:181], v[218:221], v[68:71]
	v_mfma_f32_16x16x32_bf16 v[64:67], v[186:189], v[218:221], v[64:67]
	v_mfma_f32_16x16x32_bf16 v[112:115], v[182:185], v[198:201], v[112:115]
	v_mfma_f32_16x16x32_bf16 v[104:107], v[190:193], v[198:201], v[104:107]
	v_mfma_f32_16x16x32_bf16 v[96:99], v[182:185], v[206:209], v[96:99]
	v_mfma_f32_16x16x32_bf16 v[88:91], v[190:193], v[206:209], v[88:91]
	v_mfma_f32_16x16x32_bf16 v[80:83], v[182:185], v[214:217], v[80:83]
	v_mfma_f32_16x16x32_bf16 v[72:75], v[190:193], v[214:217], v[72:75]
	v_mfma_f32_16x16x32_bf16 v[68:71], v[182:185], v[222:225], v[68:71]
	v_mfma_f32_16x16x32_bf16 v[64:67], v[190:193], v[222:225], v[64:67]
	s_add_i32 s75, s75, 2
	s_add_u32 s62, s62, 0x100
	s_addc_u32 s63, s63, 0
	s_add_u32 s55, s55, 0x100
	s_addc_u32 s74, s74, 0
	s_setprio 0
	s_barrier
	s_add_u32 s82, s72, 0x20000
	ds_read_b128 v[194:197], v154 offset:16384
	ds_read_b128 v[198:201], v154 offset:17408
	ds_read_b128 v[202:205], v154 offset:18432
	ds_read_b128 v[206:209], v154 offset:19456
	ds_read_b128 v[210:213], v154 offset:20480
	ds_read_b128 v[214:217], v154 offset:21504
	ds_read_b128 v[218:221], v154 offset:22528
	ds_read_b128 v[222:225], v154 offset:23552
	s_mov_b32 m0, s20
	s_nop 0
	global_load_lds_dwordx4 v150, s[72:73]
	s_mov_b32 m0, s24
	s_addc_u32 s83, s73, 0
	global_load_lds_dwordx4 v150, s[82:83]
	s_add_u32 s82, s72, 0x40000
	s_mov_b32 m0, s33
	s_addc_u32 s83, s73, 0
	global_load_lds_dwordx4 v150, s[82:83]
	s_add_u32 s82, s72, 0x60000
	s_mov_b32 m0, s34
	s_addc_u32 s83, s73, 0
	global_load_lds_dwordx4 v150, s[82:83]
	s_mov_b32 m0, s15
	s_nop 0
	global_load_lds_dwordx4 v128, s[16:17]
	s_add_u32 s82, s16, 0x20000
	s_mov_b32 m0, s35
	s_addc_u32 s83, s17, 0
	global_load_lds_dwordx4 v128, s[82:83]
	s_waitcnt vmcnt(8) lgkmcnt(0)
	s_barrier
	s_setprio 1
	v_mfma_f32_16x16x32_bf16 v[60:63], v[138:141], v[194:197], v[60:63]
	v_mfma_f32_16x16x32_bf16 v[56:59], v[146:149], v[194:197], v[56:59]
	v_mfma_f32_16x16x32_bf16 v[52:55], v[138:141], v[202:205], v[52:55]
	v_mfma_f32_16x16x32_bf16 v[44:47], v[146:149], v[202:205], v[44:47]
	v_mfma_f32_16x16x32_bf16 v[36:39], v[138:141], v[210:213], v[36:39]
	v_mfma_f32_16x16x32_bf16 v[28:31], v[146:149], v[210:213], v[28:31]
	v_mfma_f32_16x16x32_bf16 v[20:23], v[138:141], v[218:221], v[20:23]
	v_mfma_f32_16x16x32_bf16 v[12:15], v[146:149], v[218:221], v[12:15]
	v_mfma_f32_16x16x32_bf16 v[60:63], v[142:145], v[198:201], v[60:63]
	v_mfma_f32_16x16x32_bf16 v[56:59], v[172:175], v[198:201], v[56:59]
	v_mfma_f32_16x16x32_bf16 v[52:55], v[142:145], v[206:209], v[52:55]
	v_mfma_f32_16x16x32_bf16 v[44:47], v[172:175], v[206:209], v[44:47]
	v_mfma_f32_16x16x32_bf16 v[36:39], v[142:145], v[214:217], v[36:39]
	v_mfma_f32_16x16x32_bf16 v[28:31], v[172:175], v[214:217], v[28:31]
	v_mfma_f32_16x16x32_bf16 v[20:23], v[142:145], v[222:225], v[20:23]
	v_mfma_f32_16x16x32_bf16 v[12:15], v[172:175], v[222:225], v[12:15]
	v_mfma_f32_16x16x32_bf16 v[48:51], v[178:181], v[194:197], v[48:51]
	v_mfma_f32_16x16x32_bf16 v[40:43], v[186:189], v[194:197], v[40:43]
	v_mfma_f32_16x16x32_bf16 v[32:35], v[178:181], v[202:205], v[32:35]
	v_mfma_f32_16x16x32_bf16 v[24:27], v[186:189], v[202:205], v[24:27]
	v_mfma_f32_16x16x32_bf16 v[16:19], v[178:181], v[210:213], v[16:19]
	v_mfma_f32_16x16x32_bf16 v[8:11], v[186:189], v[210:213], v[8:11]
	v_mfma_f32_16x16x32_bf16 v[4:7], v[178:181], v[218:221], v[4:7]
	v_mfma_f32_16x16x32_bf16 v[0:3], v[186:189], v[218:221], v[0:3]
	v_mfma_f32_16x16x32_bf16 v[48:51], v[182:185], v[198:201], v[48:51]
	v_mfma_f32_16x16x32_bf16 v[40:43], v[190:193], v[198:201], v[40:43]
	v_mfma_f32_16x16x32_bf16 v[32:35], v[182:185], v[206:209], v[32:35]
	v_mfma_f32_16x16x32_bf16 v[24:27], v[190:193], v[206:209], v[24:27]
	v_mfma_f32_16x16x32_bf16 v[16:19], v[182:185], v[214:217], v[16:19]
	v_mfma_f32_16x16x32_bf16 v[8:11], v[190:193], v[214:217], v[8:11]
	v_mfma_f32_16x16x32_bf16 v[4:7], v[182:185], v[222:225], v[4:7]
	v_mfma_f32_16x16x32_bf16 v[0:3], v[190:193], v[222:225], v[0:3]
	s_setprio 0
	s_barrier
; #define PG8_STAGE(bufoff, gbase, voff, p64) do { _Pragma("unroll") for (int _i = 0; _i < 2; ++_i) { \
;         const char* _gb = (const char*)(gbase) + (size_t)_i * (p64); const unsigned _la = ldsbase + (unsigned)(bufoff) + (unsigned)_i * 8192u; \
;         asm volatile("s_mov_b32 m0, %0\n\ts_nop 0\n\tglobal_load_lds_dwordx4 %1, %2" :: "s"(_la), "v"(voff), "s"(_gb) : "memory"); } } while (0)
; #define PG8_LDA(dst, b, h) do { _Pragma("unroll") for (int m = 0; m < 4; ++m) _Pragma("unroll") for (int k = 0; k < 2; ++k) dst[m][k] = *(const LAS bf16x8*)(lds + PG8_SA(b, h) + aoff + m * 2048 + k * 1024); } while (0)
; #define PG8_LDB(dst, b, h) do { _Pragma("unroll") for (int n = 0; n < 2; ++n) _Pragma("unroll") for (int k = 0; k < 2; ++k) dst[n][k] = *(const LAS bf16x8*)(lds + PG8_SB(b, h) + boff + n * 2048 + k * 1024); } while (0)
; #define PG8_MMA(ai, bj, At, Bt) do { __builtin_amdgcn_s_setprio(1); _Pragma("unroll") for (int m = 0; m < 4; ++m) _Pragma("unroll") for (int n = 0; n < 2; ++n) _Pragma("unroll") for (int k = 0; k < 2; ++k) \
;         acc[ai][bj][m][n] = __builtin_amdgcn_mfma_f32_16x16x32_bf16(Bt[n][k], At[m][k], acc[ai][bj][m][n], 0, 0, 0); __builtin_amdgcn_s_setprio(0); } while (0)
; #define PG8_WAIT_V(n) asm volatile("s_waitcnt vmcnt(" #n ")" ::: "memory")
; #define PG8_WAIT_L(n) asm volatile("s_waitcnt lgkmcnt(" #n ")" ::: "memory")
; #define PG8_BAR __builtin_amdgcn_s_barrier()
; #define PG8_SCHED __builtin_amdgcn_sched_barrier(0)
; template <class Epi, class Sched>
; __device__ __forceinline__ void gemm_phase(LAS unsigned char* lds, const Sched& S, const Epi& E) {
;     ...
;             PG8_LDB(B0, 1, 0); PG8_LDB(B1, 1, 1); PG8_SCHED; PG8_LDA(At, 1, 0); PG8_STAGE(PG8_SA(0, 1), a2 + hA2, vA2, hA2 / 2);
;             PG8_WAIT_V(8); PG8_WAIT_L(0); PG8_BAR; PG8_MMA(0, 0, At, B0); PG8_MMA(0, 1, At, B1); PG8_BAR; PG8_SCHED;
;             PG8_LDA(At, 1, 1); PG8_STAGE(PG8_SB(1, 0), b3, vB2, hB2 / 2); PG8_STAGE(PG8_SB(1, 1), b3 + hB2, vB2, hB2 / 2); PG8_STAGE(PG8_SA(1, 0), a3, vA2, hA2 / 2);
;             PG8_WAIT_V(8); PG8_WAIT_L(0); PG8_BAR; PG8_MMA(1, 0, At, B0); PG8_MMA(1, 1, At, B1); PG8_BAR; PG8_SCHED;
;         }
;         if (wr == 0) PG8_BAR;
.Lpeel_mid_14726:
	v_add_u32_e32 v130, 0x18000, v153
	ds_read_b128 v[138:141], v130
	ds_read_b128 v[142:145], v130 offset:1024
	ds_read_b128 v[146:149], v130 offset:2048
	ds_read_b128 v[172:175], v130 offset:3072
	v_add_u32_e32 v130, 0x1c000, v153
	ds_read_b128 v[178:181], v130
	ds_read_b128 v[182:185], v130 offset:1024
	ds_read_b128 v[186:189], v130 offset:2048
	ds_read_b128 v[190:193], v130 offset:3072
	ds_read_b128 v[194:197], v154 offset:32768
	ds_read_b128 v[198:201], v154 offset:33792
	ds_read_b128 v[202:205], v154 offset:34816
	ds_read_b128 v[206:209], v154 offset:35840
	ds_read_b128 v[210:213], v154 offset:36864
	ds_read_b128 v[214:217], v154 offset:37888
	ds_read_b128 v[218:221], v154 offset:38912
	ds_read_b128 v[222:225], v154 offset:39936
	s_add_u32 s82, s16, 0x40000
	s_mov_b32 m0, s36
	s_addc_u32 s83, s17, 0
	global_load_lds_dwordx4 v128, s[82:83]
	s_add_u32 s82, s16, 0x60000
	s_mov_b32 m0, s37
	s_addc_u32 s83, s17, 0
	global_load_lds_dwordx4 v128, s[82:83]
	s_waitcnt vmcnt(8) lgkmcnt(0)
	s_barrier
	s_setprio 1
	v_mfma_f32_16x16x32_bf16 v[124:127], v[138:141], v[194:197], v[124:127]
	v_mfma_f32_16x16x32_bf16 v[120:123], v[146:149], v[194:197], v[120:123]
	v_mfma_f32_16x16x32_bf16 v[116:119], v[138:141], v[202:205], v[116:119]
	v_mfma_f32_16x16x32_bf16 v[108:111], v[146:149], v[202:205], v[108:111]
	v_mfma_f32_16x16x32_bf16 v[100:103], v[138:141], v[210:213], v[100:103]
	v_mfma_f32_16x16x32_bf16 v[92:95], v[146:149], v[210:213], v[92:95]
	v_mfma_f32_16x16x32_bf16 v[84:87], v[138:141], v[218:221], v[84:87]
	v_mfma_f32_16x16x32_bf16 v[76:79], v[146:149], v[218:221], v[76:79]
	v_mfma_f32_16x16x32_bf16 v[124:127], v[142:145], v[198:201], v[124:127]
	v_mfma_f32_16x16x32_bf16 v[120:123], v[172:175], v[198:201], v[120:123]
	v_mfma_f32_16x16x32_bf16 v[116:119], v[142:145], v[206:209], v[116:119]
	v_mfma_f32_16x16x32_bf16 v[108:111], v[172:175], v[206:209], v[108:111]
	v_mfma_f32_16x16x32_bf16 v[100:103], v[142:145], v[214:217], v[100:103]
	v_mfma_f32_16x16x32_bf16 v[92:95], v[172:175], v[214:217], v[92:95]
	v_mfma_f32_16x16x32_bf16 v[84:87], v[142:145], v[222:225], v[84:87]
	v_mfma_f32_16x16x32_bf16 v[76:79], v[172:175], v[222:225], v[76:79]
	v_mfma_f32_16x16x32_bf16 v[112:115], v[178:181], v[194:197], v[112:115]
	v_mfma_f32_16x16x32_bf16 v[104:107], v[186:189], v[194:197], v[104:107]
	v_mfma_f32_16x16x32_bf16 v[96:99], v[178:181], v[202:205], v[96:99]
	v_mfma_f32_16x16x32_bf16 v[88:91], v[186:189], v[202:205], v[88:91]
	v_mfma_f32_16x16x32_bf16 v[80:83], v[178:181], v[210:213], v[80:83]
	v_mfma_f32_16x16x32_bf16 v[72:75], v[186:189], v[210:213], v[72:75]
	v_mfma_f32_16x16x32_bf16 v[68:71], v[178:181], v[218:221], v[68:71]
	v_mfma_f32_16x16x32_bf16 v[64:67], v[186:189], v[218:221], v[64:67]
	v_mfma_f32_16x16x32_bf16 v[112:115], v[182:185], v[198:201], v[112:115]
	v_mfma_f32_16x16x32_bf16 v[104:107], v[190:193], v[198:201], v[104:107]
	v_mfma_f32_16x16x32_bf16 v[96:99], v[182:185], v[206:209], v[96:99]
	v_mfma_f32_16x16x32_bf16 v[88:91], v[190:193], v[206:209], v[88:91]
	v_mfma_f32_16x16x32_bf16 v[80:83], v[182:185], v[214:217], v[80:83]
	v_mfma_f32_16x16x32_bf16 v[72:75], v[190:193], v[214:217], v[72:75]
	v_mfma_f32_16x16x32_bf16 v[68:71], v[182:185], v[222:225], v[68:71]
	v_mfma_f32_16x16x32_bf16 v[64:67], v[190:193], v[222:225], v[64:67]
	s_setprio 0
	s_barrier
	s_add_u32 s82, s72, 0x80
	s_addc_u32 s83, s73, 0
	ds_read_b128 v[194:197], v154 offset:49152
	ds_read_b128 v[198:201], v154 offset:50176
	ds_read_b128 v[202:205], v154 offset:51200
	ds_read_b128 v[206:209], v154 offset:52224
	ds_read_b128 v[210:213], v154 offset:53248
	ds_read_b128 v[214:217], v154 offset:54272
	ds_read_b128 v[218:221], v154 offset:55296
	ds_read_b128 v[222:225], v154 offset:56320
	s_mov_b32 m0, s66
	s_nop 0
	global_load_lds_dwordx4 v150, s[82:83]
	s_add_u32 s82, s72, 0x20080
	s_mov_b32 m0, s67
	s_addc_u32 s83, s73, 0
	global_load_lds_dwordx4 v150, s[82:83]
	s_add_u32 s82, s72, 0x40080
	s_mov_b32 m0, s76
	s_addc_u32 s83, s73, 0
	global_load_lds_dwordx4 v150, s[82:83]
	s_add_u32 s72, s72, 0x60080
	s_mov_b32 m0, s77
	s_addc_u32 s73, s73, 0
	global_load_lds_dwordx4 v150, s[72:73]
	s_mov_b32 m0, s68
	s_nop 0
	global_load_lds_dwordx4 v128, s[22:23]
	s_add_u32 s16, s16, 0x20080
	s_mov_b32 m0, s69
	s_addc_u32 s17, s17, 0
	global_load_lds_dwordx4 v128, s[16:17]
	s_waitcnt vmcnt(8) lgkmcnt(0)
	s_barrier
	s_setprio 1
	v_mfma_f32_16x16x32_bf16 v[60:63], v[138:141], v[194:197], v[60:63]
	v_mfma_f32_16x16x32_bf16 v[56:59], v[146:149], v[194:197], v[56:59]
	v_mfma_f32_16x16x32_bf16 v[52:55], v[138:141], v[202:205], v[52:55]
	v_mfma_f32_16x16x32_bf16 v[44:47], v[146:149], v[202:205], v[44:47]
	v_mfma_f32_16x16x32_bf16 v[36:39], v[138:141], v[210:213], v[36:39]
	v_mfma_f32_16x16x32_bf16 v[28:31], v[146:149], v[210:213], v[28:31]
	v_mfma_f32_16x16x32_bf16 v[20:23], v[138:141], v[218:221], v[20:23]
	v_mfma_f32_16x16x32_bf16 v[12:15], v[146:149], v[218:221], v[12:15]
	v_mfma_f32_16x16x32_bf16 v[60:63], v[142:145], v[198:201], v[60:63]
	v_mfma_f32_16x16x32_bf16 v[56:59], v[172:175], v[198:201], v[56:59]
	v_mfma_f32_16x16x32_bf16 v[52:55], v[142:145], v[206:209], v[52:55]
	v_mfma_f32_16x16x32_bf16 v[44:47], v[172:175], v[206:209], v[44:47]
	v_mfma_f32_16x16x32_bf16 v[36:39], v[142:145], v[214:217], v[36:39]
	v_mfma_f32_16x16x32_bf16 v[28:31], v[172:175], v[214:217], v[28:31]
	v_mfma_f32_16x16x32_bf16 v[20:23], v[142:145], v[222:225], v[20:23]
	v_mfma_f32_16x16x32_bf16 v[12:15], v[172:175], v[222:225], v[12:15]
	v_mfma_f32_16x16x32_bf16 v[48:51], v[178:181], v[194:197], v[48:51]
	v_mfma_f32_16x16x32_bf16 v[40:43], v[186:189], v[194:197], v[40:43]
	v_mfma_f32_16x16x32_bf16 v[32:35], v[178:181], v[202:205], v[32:35]
	v_mfma_f32_16x16x32_bf16 v[24:27], v[186:189], v[202:205], v[24:27]
	v_mfma_f32_16x16x32_bf16 v[16:19], v[178:181], v[210:213], v[16:19]
	v_mfma_f32_16x16x32_bf16 v[8:11], v[186:189], v[210:213], v[8:11]
	v_mfma_f32_16x16x32_bf16 v[4:7], v[178:181], v[218:221], v[4:7]
	v_mfma_f32_16x16x32_bf16 v[0:3], v[186:189], v[218:221], v[0:3]
	v_mfma_f32_16x16x32_bf16 v[48:51], v[182:185], v[198:201], v[48:51]
	v_mfma_f32_16x16x32_bf16 v[40:43], v[190:193], v[198:201], v[40:43]
	v_mfma_f32_16x16x32_bf16 v[32:35], v[182:185], v[206:209], v[32:35]
	v_mfma_f32_16x16x32_bf16 v[24:27], v[190:193], v[206:209], v[24:27]
	v_mfma_f32_16x16x32_bf16 v[16:19], v[182:185], v[214:217], v[16:19]
	v_mfma_f32_16x16x32_bf16 v[8:11], v[190:193], v[214:217], v[8:11]
	v_mfma_f32_16x16x32_bf16 v[4:7], v[182:185], v[222:225], v[4:7]
	v_mfma_f32_16x16x32_bf16 v[0:3], v[190:193], v[222:225], v[0:3]
	s_setprio 0
	s_barrier
	s_cmp_gt_u32 s75, 13
	s_cbranch_scc0 .LBB0_582
	s_and_b64 vcc, exec, s[26:27]
	s_cbranch_vccz .LBB0_585
	s_barrier

; #define PG8_STAGE(bufoff, gbase, voff, p64) do { _Pragma("unroll") for (int _i = 0; _i < 2; ++_i) { \
;         const char* _gb = (const char*)(gbase) + (size_t)_i * (p64); const unsigned _la = ldsbase + (unsigned)(bufoff) + (unsigned)_i * 8192u; \
;         asm volatile("s_mov_b32 m0, %0\n\ts_nop 0\n\tglobal_load_lds_dwordx4 %1, %2" :: "s"(_la), "v"(voff), "s"(_gb) : "memory"); } } while (0)
; #define PG8_LDA(dst, b, h) do { _Pragma("unroll") for (int m = 0; m < 4; ++m) _Pragma("unroll") for (int k = 0; k < 2; ++k) dst[m][k] = *(const LAS bf16x8*)(lds + PG8_SA(b, h) + aoff + m * 2048 + k * 1024); } while (0)
; #define PG8_LDB(dst, b, h) do { _Pragma("unroll") for (int n = 0; n < 2; ++n) _Pragma("unroll") for (int k = 0; k < 2; ++k) dst[n][k] = *(const LAS bf16x8*)(lds + PG8_SB(b, h) + boff + n * 2048 + k * 1024); } while (0)
; #define PG8_MMA(ai, bj, At, Bt) do { __builtin_amdgcn_s_setprio(1); _Pragma("unroll") for (int m = 0; m < 4; ++m) _Pragma("unroll") for (int n = 0; n < 2; ++n) _Pragma("unroll") for (int k = 0; k < 2; ++k) \
;         acc[ai][bj][m][n] = __builtin_amdgcn_mfma_f32_16x16x32_bf16(Bt[n][k], At[m][k], acc[ai][bj][m][n], 0, 0, 0); __builtin_amdgcn_s_setprio(0); } while (0)
; #define PG8_WAIT_V(n) asm volatile("s_waitcnt vmcnt(" #n ")" ::: "memory")
; #define PG8_WAIT_L(n) asm volatile("s_waitcnt lgkmcnt(" #n ")" ::: "memory")
; #define PG8_BAR __builtin_amdgcn_s_barrier()
; template <class Epi, class Sched>
; __device__ __forceinline__ void gemm_phase(LAS unsigned char* lds, const Sched& S, const Epi& E) {
;     ...
;     f32x4 acc[2][2][4][2];
; #pragma unroll
;     for (int a = 0; a < 2; ++a)
; #pragma unroll
;         for (int b = 0; b < 2; ++b)
; #pragma unroll
;             for (int m = 0; m < 4; ++m)
; #pragma unroll
;                 for (int n = 0; n < 2; ++n) acc[a][b][m][n] = (f32x4){0.f, 0.f, 0.f, 0.f};
;     ...
;             PG8_LDB(B0, 0, 0); PG8_LDB(B1, 0, 1); PG8_SCHED; PG8_LDA(At, 0, 0); PG8_STAGE(PG8_SA(1, 1), a1 + hA, voffA, hA / 2);
;             PG8_WAIT_V(8); PG8_WAIT_L(0); PG8_BAR; PG8_MMA(0, 0, At, B0); PG8_MMA(0, 1, At, B1); PG8_BAR; PG8_SCHED;
;             PG8_LDA(At, 0, 1); PG8_STAGE(PG8_SB(0, 0), b2, vB2, hB2 / 2); PG8_STAGE(PG8_SB(0, 1), b2 + hB2, vB2, hB2 / 2); PG8_STAGE(PG8_SA(0, 0), a2, vA2, hA2 / 2);
;             PG8_WAIT_V(8); PG8_WAIT_L(0); PG8_BAR; PG8_MMA(1, 0, At, B0); PG8_MMA(1, 1, At, B1); PG8_BAR; PG8_SCHED;
.LBB0_659:
	s_add_u32 s78, s16, 0x100
	s_addc_u32 s79, s17, 0
	s_mov_b32 s80, -2
	v_add_u32_e32 v130, 0x10000, v143
	ds_read_b128 v[146:149], v130
	ds_read_b128 v[150:153], v130 offset:1024
	ds_read_b128 v[172:175], v130 offset:2048
	ds_read_b128 v[178:181], v130 offset:3072
	v_add_u32_e32 v130, 0x14000, v143
	ds_read_b128 v[182:185], v130
	ds_read_b128 v[186:189], v130 offset:1024
	ds_read_b128 v[190:193], v130 offset:2048
	ds_read_b128 v[194:197], v130 offset:3072
	s_add_u32 s16, s58, 0x100
	s_addc_u32 s17, s59, 0
	s_cmp_eq_u32 s80, 4
	s_cselect_b32 s22, s40, s16
	s_cselect_b32 s23, s41, s17
	s_cselect_b32 s72, s54, s78
	s_cselect_b32 s73, s55, s79
	s_add_u32 s62, s22, 0x80
	s_addc_u32 s63, s23, 0
	ds_read_b128 v[198:201], v144
	ds_read_b128 v[202:205], v144 offset:1024
	ds_read_b128 v[206:209], v144 offset:2048
	ds_read_b128 v[210:213], v144 offset:3072
	ds_read_b128 v[214:217], v144 offset:4096
	ds_read_b128 v[218:221], v144 offset:5120
	ds_read_b128 v[222:225], v144 offset:6144
	ds_read_b128 v[226:229], v144 offset:7168
	s_add_u32 s82, s58, 0x20080
	s_mov_b32 m0, s66
	s_addc_u32 s83, s59, 0
	global_load_lds_dwordx4 v128, s[82:83]
	s_add_u32 s58, s58, 0x30080
	s_mov_b32 m0, s67
	s_addc_u32 s59, s59, 0
	global_load_lds_dwordx4 v128, s[58:59]
	s_waitcnt vmcnt(8) lgkmcnt(0)
	s_barrier
	s_setprio 1
	v_mfma_f32_16x16x32_bf16 v[124:127], v[146:149], v[198:201], 0
	v_mfma_f32_16x16x32_bf16 v[120:123], v[172:175], v[198:201], 0
	v_mfma_f32_16x16x32_bf16 v[116:119], v[146:149], v[206:209], 0
	v_mfma_f32_16x16x32_bf16 v[108:111], v[172:175], v[206:209], 0
	v_mfma_f32_16x16x32_bf16 v[100:103], v[146:149], v[214:217], 0
	v_mfma_f32_16x16x32_bf16 v[92:95], v[172:175], v[214:217], 0
	v_mfma_f32_16x16x32_bf16 v[84:87], v[146:149], v[222:225], 0
	v_mfma_f32_16x16x32_bf16 v[76:79], v[172:175], v[222:225], 0
	v_mfma_f32_16x16x32_bf16 v[124:127], v[150:153], v[202:205], v[124:127]
	v_mfma_f32_16x16x32_bf16 v[120:123], v[178:181], v[202:205], v[120:123]
	v_mfma_f32_16x16x32_bf16 v[116:119], v[150:153], v[210:213], v[116:119]
	v_mfma_f32_16x16x32_bf16 v[108:111], v[178:181], v[210:213], v[108:111]
	v_mfma_f32_16x16x32_bf16 v[100:103], v[150:153], v[218:221], v[100:103]
	v_mfma_f32_16x16x32_bf16 v[92:95], v[178:181], v[218:221], v[92:95]
	v_mfma_f32_16x16x32_bf16 v[84:87], v[150:153], v[226:229], v[84:87]
	v_mfma_f32_16x16x32_bf16 v[76:79], v[178:181], v[226:229], v[76:79]
	v_mfma_f32_16x16x32_bf16 v[112:115], v[182:185], v[198:201], 0
	v_mfma_f32_16x16x32_bf16 v[104:107], v[190:193], v[198:201], 0
	v_mfma_f32_16x16x32_bf16 v[96:99], v[182:185], v[206:209], 0
	v_mfma_f32_16x16x32_bf16 v[88:91], v[190:193], v[206:209], 0
	v_mfma_f32_16x16x32_bf16 v[80:83], v[182:185], v[214:217], 0
	v_mfma_f32_16x16x32_bf16 v[72:75], v[190:193], v[214:217], 0
	v_mfma_f32_16x16x32_bf16 v[68:71], v[182:185], v[222:225], 0
	v_mfma_f32_16x16x32_bf16 v[64:67], v[190:193], v[222:225], 0
	v_mfma_f32_16x16x32_bf16 v[112:115], v[186:189], v[202:205], v[112:115]
	v_mfma_f32_16x16x32_bf16 v[104:107], v[194:197], v[202:205], v[104:107]
	v_mfma_f32_16x16x32_bf16 v[96:99], v[186:189], v[210:213], v[96:99]
	v_mfma_f32_16x16x32_bf16 v[88:91], v[194:197], v[210:213], v[88:91]
	v_mfma_f32_16x16x32_bf16 v[80:83], v[186:189], v[218:221], v[80:83]
	v_mfma_f32_16x16x32_bf16 v[72:75], v[194:197], v[218:221], v[72:75]
	v_mfma_f32_16x16x32_bf16 v[68:71], v[186:189], v[226:229], v[68:71]
	v_mfma_f32_16x16x32_bf16 v[64:67], v[194:197], v[226:229], v[64:67]
	s_add_i32 s80, s80, 2
	s_add_u32 s78, s78, 0x100
	s_addc_u32 s79, s79, 0
	s_setprio 0
	s_barrier
	s_add_u32 s58, s72, 0x10000
	ds_read_b128 v[198:201], v144 offset:16384
	ds_read_b128 v[202:205], v144 offset:17408
	ds_read_b128 v[206:209], v144 offset:18432
	ds_read_b128 v[210:213], v144 offset:19456
	ds_read_b128 v[214:217], v144 offset:20480
	ds_read_b128 v[218:221], v144 offset:21504
	ds_read_b128 v[222:225], v144 offset:22528
	ds_read_b128 v[226:229], v144 offset:23552
	s_mov_b32 m0, s33
	s_nop 0
	global_load_lds_dwordx4 v140, s[72:73]
	s_mov_b32 m0, s34
	s_addc_u32 s59, s73, 0
	global_load_lds_dwordx4 v140, s[58:59]
	s_add_u32 s58, s72, 0x20000
	s_mov_b32 m0, s35
	s_addc_u32 s59, s73, 0
	global_load_lds_dwordx4 v140, s[58:59]
	s_add_u32 s58, s72, 0x30000
	s_mov_b32 m0, s36
	s_addc_u32 s59, s73, 0
	global_load_lds_dwordx4 v140, s[58:59]
	s_mov_b32 m0, s24
	s_nop 0
	global_load_lds_dwordx4 v128, s[22:23]
	s_add_u32 s58, s22, 0x10000
	s_mov_b32 m0, s37
	s_addc_u32 s59, s23, 0
	global_load_lds_dwordx4 v128, s[58:59]
	s_waitcnt vmcnt(8) lgkmcnt(0)
	s_barrier
	s_setprio 1
	v_mfma_f32_16x16x32_bf16 v[60:63], v[146:149], v[198:201], 0
	v_mfma_f32_16x16x32_bf16 v[56:59], v[172:175], v[198:201], 0
	v_mfma_f32_16x16x32_bf16 v[52:55], v[146:149], v[206:209], 0
	v_mfma_f32_16x16x32_bf16 v[44:47], v[172:175], v[206:209], 0
	v_mfma_f32_16x16x32_bf16 v[36:39], v[146:149], v[214:217], 0
	v_mfma_f32_16x16x32_bf16 v[28:31], v[172:175], v[214:217], 0
	v_mfma_f32_16x16x32_bf16 v[20:23], v[146:149], v[222:225], 0
	v_mfma_f32_16x16x32_bf16 v[12:15], v[172:175], v[222:225], 0
	v_mfma_f32_16x16x32_bf16 v[60:63], v[150:153], v[202:205], v[60:63]
	v_mfma_f32_16x16x32_bf16 v[56:59], v[178:181], v[202:205], v[56:59]
	v_mfma_f32_16x16x32_bf16 v[52:55], v[150:153], v[210:213], v[52:55]
	v_mfma_f32_16x16x32_bf16 v[44:47], v[178:181], v[210:213], v[44:47]
	v_mfma_f32_16x16x32_bf16 v[36:39], v[150:153], v[218:221], v[36:39]
	v_mfma_f32_16x16x32_bf16 v[28:31], v[178:181], v[218:221], v[28:31]
	v_mfma_f32_16x16x32_bf16 v[20:23], v[150:153], v[226:229], v[20:23]
	v_mfma_f32_16x16x32_bf16 v[12:15], v[178:181], v[226:229], v[12:15]
	v_mfma_f32_16x16x32_bf16 v[48:51], v[182:185], v[198:201], 0
	v_mfma_f32_16x16x32_bf16 v[40:43], v[190:193], v[198:201], 0
	v_mfma_f32_16x16x32_bf16 v[32:35], v[182:185], v[206:209], 0
	v_mfma_f32_16x16x32_bf16 v[24:27], v[190:193], v[206:209], 0
	v_mfma_f32_16x16x32_bf16 v[16:19], v[182:185], v[214:217], 0
	v_mfma_f32_16x16x32_bf16 v[8:11], v[190:193], v[214:217], 0
	v_mfma_f32_16x16x32_bf16 v[4:7], v[182:185], v[222:225], 0
	v_mfma_f32_16x16x32_bf16 v[0:3], v[190:193], v[222:225], 0
	v_mfma_f32_16x16x32_bf16 v[48:51], v[186:189], v[202:205], v[48:51]
	v_mfma_f32_16x16x32_bf16 v[40:43], v[194:197], v[202:205], v[40:43]
	v_mfma_f32_16x16x32_bf16 v[32:35], v[186:189], v[210:213], v[32:35]
	v_mfma_f32_16x16x32_bf16 v[24:27], v[194:197], v[210:213], v[24:27]
	v_mfma_f32_16x16x32_bf16 v[16:19], v[186:189], v[218:221], v[16:19]
	v_mfma_f32_16x16x32_bf16 v[8:11], v[194:197], v[218:221], v[8:11]
	v_mfma_f32_16x16x32_bf16 v[4:7], v[186:189], v[226:229], v[4:7]
	v_mfma_f32_16x16x32_bf16 v[0:3], v[194:197], v[226:229], v[0:3]
	s_setprio 0
	s_barrier
	s_branch .Lpeel_mid_17324
; #define PG8_STAGE(bufoff, gbase, voff, p64) do { _Pragma("unroll") for (int _i = 0; _i < 2; ++_i) { \
;         const char* _gb = (const char*)(gbase) + (size_t)_i * (p64); const unsigned _la = ldsbase + (unsigned)(bufoff) + (unsigned)_i * 8192u; \
;         asm volatile("s_mov_b32 m0, %0\n\ts_nop 0\n\tglobal_load_lds_dwordx4 %1, %2" :: "s"(_la), "v"(voff), "s"(_gb) : "memory"); } } while (0)
; #define PG8_LDA(dst, b, h) do { _Pragma("unroll") for (int m = 0; m < 4; ++m) _Pragma("unroll") for (int k = 0; k < 2; ++k) dst[m][k] = *(const LAS bf16x8*)(lds + PG8_SA(b, h) + aoff + m * 2048 + k * 1024); } while (0)
; #define PG8_LDB(dst, b, h) do { _Pragma("unroll") for (int n = 0; n < 2; ++n) _Pragma("unroll") for (int k = 0; k < 2; ++k) dst[n][k] = *(const LAS bf16x8*)(lds + PG8_SB(b, h) + boff + n * 2048 + k * 1024); } while (0)
; #define PG8_MMA(ai, bj, At, Bt) do { __builtin_amdgcn_s_setprio(1); _Pragma("unroll") for (int m = 0; m < 4; ++m) _Pragma("unroll") for (int n = 0; n < 2; ++n) _Pragma("unroll") for (int k = 0; k < 2; ++k) \
;         acc[ai][bj][m][n] = __builtin_amdgcn_mfma_f32_16x16x32_bf16(Bt[n][k], At[m][k], acc[ai][bj][m][n], 0, 0, 0); __builtin_amdgcn_s_setprio(0); } while (0)
; #define PG8_WAIT_V(n) asm volatile("s_waitcnt vmcnt(" #n ")" ::: "memory")
; #define PG8_WAIT_L(n) asm volatile("s_waitcnt lgkmcnt(" #n ")" ::: "memory")
; #define PG8_BAR __builtin_amdgcn_s_barrier()
; #define PG8_SCHED __builtin_amdgcn_sched_barrier(0)
; template <class Epi, class Sched>
; __device__ __forceinline__ void gemm_phase(LAS unsigned char* lds, const Sched& S, const Epi& E) {
;     ...
;             PG8_LDB(B0, 0, 0); PG8_LDB(B1, 0, 1); PG8_SCHED; PG8_LDA(At, 0, 0); PG8_STAGE(PG8_SA(1, 1), a1 + hA, voffA, hA / 2);
;             PG8_WAIT_V(8); PG8_WAIT_L(0); PG8_BAR; PG8_MMA(0, 0, At, B0); PG8_MMA(0, 1, At, B1); PG8_BAR; PG8_SCHED;
;             PG8_LDA(At, 0, 1); PG8_STAGE(PG8_SB(0, 0), b2, vB2, hB2 / 2); PG8_STAGE(PG8_SB(0, 1), b2 + hB2, vB2, hB2 / 2); PG8_STAGE(PG8_SA(0, 0), a2, vA2, hA2 / 2);
;             PG8_WAIT_V(8); PG8_WAIT_L(0); PG8_BAR; PG8_MMA(1, 0, At, B0); PG8_MMA(1, 1, At, B1); PG8_BAR; PG8_SCHED;
.LBB0_660:
	v_add_u32_e32 v130, 0x10000, v143
	ds_read_b128 v[146:149], v130
	ds_read_b128 v[150:153], v130 offset:1024
	ds_read_b128 v[172:175], v130 offset:2048
	ds_read_b128 v[178:181], v130 offset:3072
	v_add_u32_e32 v130, 0x14000, v143
	ds_read_b128 v[182:185], v130
	ds_read_b128 v[186:189], v130 offset:1024
	ds_read_b128 v[190:193], v130 offset:2048
	ds_read_b128 v[194:197], v130 offset:3072
	s_add_u32 s16, s58, 0x100
	s_addc_u32 s17, s59, 0
	s_cmp_eq_u32 s80, 4
	s_cselect_b32 s22, s40, s16
	s_cselect_b32 s23, s41, s17
	s_cselect_b32 s72, s54, s78
	s_cselect_b32 s73, s55, s79
	s_add_u32 s62, s22, 0x80
	s_addc_u32 s63, s23, 0
	ds_read_b128 v[198:201], v144
	ds_read_b128 v[202:205], v144 offset:1024
	ds_read_b128 v[206:209], v144 offset:2048
	ds_read_b128 v[210:213], v144 offset:3072
	ds_read_b128 v[214:217], v144 offset:4096
	ds_read_b128 v[218:221], v144 offset:5120
	ds_read_b128 v[222:225], v144 offset:6144
	ds_read_b128 v[226:229], v144 offset:7168
	s_add_u32 s82, s58, 0x20080
	s_mov_b32 m0, s66
	s_addc_u32 s83, s59, 0
	global_load_lds_dwordx4 v128, s[82:83]
	s_add_u32 s58, s58, 0x30080
	s_mov_b32 m0, s67
	s_addc_u32 s59, s59, 0
	global_load_lds_dwordx4 v128, s[58:59]
	s_waitcnt vmcnt(8) lgkmcnt(0)
	s_barrier
	s_setprio 1
	v_mfma_f32_16x16x32_bf16 v[124:127], v[146:149], v[198:201], v[124:127]
	v_mfma_f32_16x16x32_bf16 v[120:123], v[172:175], v[198:201], v[120:123]
	v_mfma_f32_16x16x32_bf16 v[116:119], v[146:149], v[206:209], v[116:119]
	v_mfma_f32_16x16x32_bf16 v[108:111], v[172:175], v[206:209], v[108:111]
	v_mfma_f32_16x16x32_bf16 v[100:103], v[146:149], v[214:217], v[100:103]
	v_mfma_f32_16x16x32_bf16 v[92:95], v[172:175], v[214:217], v[92:95]
	v_mfma_f32_16x16x32_bf16 v[84:87], v[146:149], v[222:225], v[84:87]
	v_mfma_f32_16x16x32_bf16 v[76:79], v[172:175], v[222:225], v[76:79]
	v_mfma_f32_16x16x32_bf16 v[124:127], v[150:153], v[202:205], v[124:127]
	v_mfma_f32_16x16x32_bf16 v[120:123], v[178:181], v[202:205], v[120:123]
	v_mfma_f32_16x16x32_bf16 v[116:119], v[150:153], v[210:213], v[116:119]
	v_mfma_f32_16x16x32_bf16 v[108:111], v[178:181], v[210:213], v[108:111]
	v_mfma_f32_16x16x32_bf16 v[100:103], v[150:153], v[218:221], v[100:103]
	v_mfma_f32_16x16x32_bf16 v[92:95], v[178:181], v[218:221], v[92:95]
	v_mfma_f32_16x16x32_bf16 v[84:87], v[150:153], v[226:229], v[84:87]
	v_mfma_f32_16x16x32_bf16 v[76:79], v[178:181], v[226:229], v[76:79]
	v_mfma_f32_16x16x32_bf16 v[112:115], v[182:185], v[198:201], v[112:115]
	v_mfma_f32_16x16x32_bf16 v[104:107], v[190:193], v[198:201], v[104:107]
	v_mfma_f32_16x16x32_bf16 v[96:99], v[182:185], v[206:209], v[96:99]
	v_mfma_f32_16x16x32_bf16 v[88:91], v[190:193], v[206:209], v[88:91]
	v_mfma_f32_16x16x32_bf16 v[80:83], v[182:185], v[214:217], v[80:83]
	v_mfma_f32_16x16x32_bf16 v[72:75], v[190:193], v[214:217], v[72:75]
	v_mfma_f32_16x16x32_bf16 v[68:71], v[182:185], v[222:225], v[68:71]
	v_mfma_f32_16x16x32_bf16 v[64:67], v[190:193], v[222:225], v[64:67]
	v_mfma_f32_16x16x32_bf16 v[112:115], v[186:189], v[202:205], v[112:115]
	v_mfma_f32_16x16x32_bf16 v[104:107], v[194:197], v[202:205], v[104:107]
	v_mfma_f32_16x16x32_bf16 v[96:99], v[186:189], v[210:213], v[96:99]
	v_mfma_f32_16x16x32_bf16 v[88:91], v[194:197], v[210:213], v[88:91]
	v_mfma_f32_16x16x32_bf16 v[80:83], v[186:189], v[218:221], v[80:83]
	v_mfma_f32_16x16x32_bf16 v[72:75], v[194:197], v[218:221], v[72:75]
	v_mfma_f32_16x16x32_bf16 v[68:71], v[186:189], v[226:229], v[68:71]
	v_mfma_f32_16x16x32_bf16 v[64:67], v[194:197], v[226:229], v[64:67]
	s_add_i32 s80, s80, 2
	s_add_u32 s78, s78, 0x100
	s_addc_u32 s79, s79, 0
	s_setprio 0
	s_barrier
	s_add_u32 s58, s72, 0x10000
	ds_read_b128 v[198:201], v144 offset:16384
	ds_read_b128 v[202:205], v144 offset:17408
	ds_read_b128 v[206:209], v144 offset:18432
	ds_read_b128 v[210:213], v144 offset:19456
	ds_read_b128 v[214:217], v144 offset:20480
	ds_read_b128 v[218:221], v144 offset:21504
	ds_read_b128 v[222:225], v144 offset:22528
	ds_read_b128 v[226:229], v144 offset:23552
	s_mov_b32 m0, s33
	s_nop 0
	global_load_lds_dwordx4 v140, s[72:73]
	s_mov_b32 m0, s34
	s_addc_u32 s59, s73, 0
	global_load_lds_dwordx4 v140, s[58:59]
	s_add_u32 s58, s72, 0x20000
	s_mov_b32 m0, s35
	s_addc_u32 s59, s73, 0
	global_load_lds_dwordx4 v140, s[58:59]
	s_add_u32 s58, s72, 0x30000
	s_mov_b32 m0, s36
	s_addc_u32 s59, s73, 0
	global_load_lds_dwordx4 v140, s[58:59]
	s_mov_b32 m0, s24
	s_nop 0
	global_load_lds_dwordx4 v128, s[22:23]
	s_add_u32 s58, s22, 0x10000
	s_mov_b32 m0, s37
	s_addc_u32 s59, s23, 0
	global_load_lds_dwordx4 v128, s[58:59]
	s_waitcnt vmcnt(8) lgkmcnt(0)
	s_barrier
	s_setprio 1
	v_mfma_f32_16x16x32_bf16 v[60:63], v[146:149], v[198:201], v[60:63]
	v_mfma_f32_16x16x32_bf16 v[56:59], v[172:175], v[198:201], v[56:59]
	v_mfma_f32_16x16x32_bf16 v[52:55], v[146:149], v[206:209], v[52:55]
	v_mfma_f32_16x16x32_bf16 v[44:47], v[172:175], v[206:209], v[44:47]
	v_mfma_f32_16x16x32_bf16 v[36:39], v[146:149], v[214:217], v[36:39]
	v_mfma_f32_16x16x32_bf16 v[28:31], v[172:175], v[214:217], v[28:31]
	v_mfma_f32_16x16x32_bf16 v[20:23], v[146:149], v[222:225], v[20:23]
	v_mfma_f32_16x16x32_bf16 v[12:15], v[172:175], v[222:225], v[12:15]
	v_mfma_f32_16x16x32_bf16 v[60:63], v[150:153], v[202:205], v[60:63]
	v_mfma_f32_16x16x32_bf16 v[56:59], v[178:181], v[202:205], v[56:59]
	v_mfma_f32_16x16x32_bf16 v[52:55], v[150:153], v[210:213], v[52:55]
	v_mfma_f32_16x16x32_bf16 v[44:47], v[178:181], v[210:213], v[44:47]
	v_mfma_f32_16x16x32_bf16 v[36:39], v[150:153], v[218:221], v[36:39]
	v_mfma_f32_16x16x32_bf16 v[28:31], v[178:181], v[218:221], v[28:31]
	v_mfma_f32_16x16x32_bf16 v[20:23], v[150:153], v[226:229], v[20:23]
	v_mfma_f32_16x16x32_bf16 v[12:15], v[178:181], v[226:229], v[12:15]
	v_mfma_f32_16x16x32_bf16 v[48:51], v[182:185], v[198:201], v[48:51]
	v_mfma_f32_16x16x32_bf16 v[40:43], v[190:193], v[198:201], v[40:43]
	v_mfma_f32_16x16x32_bf16 v[32:35], v[182:185], v[206:209], v[32:35]
	v_mfma_f32_16x16x32_bf16 v[24:27], v[190:193], v[206:209], v[24:27]
	v_mfma_f32_16x16x32_bf16 v[16:19], v[182:185], v[214:217], v[16:19]
	v_mfma_f32_16x16x32_bf16 v[8:11], v[190:193], v[214:217], v[8:11]
	v_mfma_f32_16x16x32_bf16 v[4:7], v[182:185], v[222:225], v[4:7]
	v_mfma_f32_16x16x32_bf16 v[0:3], v[190:193], v[222:225], v[0:3]
	v_mfma_f32_16x16x32_bf16 v[48:51], v[186:189], v[202:205], v[48:51]
	v_mfma_f32_16x16x32_bf16 v[40:43], v[194:197], v[202:205], v[40:43]
	v_mfma_f32_16x16x32_bf16 v[32:35], v[186:189], v[210:213], v[32:35]
	v_mfma_f32_16x16x32_bf16 v[24:27], v[194:197], v[210:213], v[24:27]
	v_mfma_f32_16x16x32_bf16 v[16:19], v[186:189], v[218:221], v[16:19]
	v_mfma_f32_16x16x32_bf16 v[8:11], v[194:197], v[218:221], v[8:11]
	v_mfma_f32_16x16x32_bf16 v[4:7], v[186:189], v[226:229], v[4:7]
	v_mfma_f32_16x16x32_bf16 v[0:3], v[194:197], v[226:229], v[0:3]
	s_setprio 0
	s_barrier
; #define PG8_STAGE(bufoff, gbase, voff, p64) do { _Pragma("unroll") for (int _i = 0; _i < 2; ++_i) { \
;         const char* _gb = (const char*)(gbase) + (size_t)_i * (p64); const unsigned _la = ldsbase + (unsigned)(bufoff) + (unsigned)_i * 8192u; \
;         asm volatile("s_mov_b32 m0, %0\n\ts_nop 0\n\tglobal_load_lds_dwordx4 %1, %2" :: "s"(_la), "v"(voff), "s"(_gb) : "memory"); } } while (0)
; #define PG8_LDA(dst, b, h) do { _Pragma("unroll") for (int m = 0; m < 4; ++m) _Pragma("unroll") for (int k = 0; k < 2; ++k) dst[m][k] = *(const LAS bf16x8*)(lds + PG8_SA(b, h) + aoff + m * 2048 + k * 1024); } while (0)
; #define PG8_LDB(dst, b, h) do { _Pragma("unroll") for (int n = 0; n < 2; ++n) _Pragma("unroll") for (int k = 0; k < 2; ++k) dst[n][k] = *(const LAS bf16x8*)(lds + PG8_SB(b, h) + boff + n * 2048 + k * 1024); } while (0)
; #define PG8_MMA(ai, bj, At, Bt) do { __builtin_amdgcn_s_setprio(1); _Pragma("unroll") for (int m = 0; m < 4; ++m) _Pragma("unroll") for (int n = 0; n < 2; ++n) _Pragma("unroll") for (int k = 0; k < 2; ++k) \
;         acc[ai][bj][m][n] = __builtin_amdgcn_mfma_f32_16x16x32_bf16(Bt[n][k], At[m][k], acc[ai][bj][m][n], 0, 0, 0); __builtin_amdgcn_s_setprio(0); } while (0)
; #define PG8_WAIT_V(n) asm volatile("s_waitcnt vmcnt(" #n ")" ::: "memory")
; #define PG8_WAIT_L(n) asm volatile("s_waitcnt lgkmcnt(" #n ")" ::: "memory")
; #define PG8_BAR __builtin_amdgcn_s_barrier()
; #define PG8_SCHED __builtin_amdgcn_sched_barrier(0)
; template <class Epi, class Sched>
; __device__ __forceinline__ void gemm_phase(LAS unsigned char* lds, const Sched& S, const Epi& E) {
;     ...
;             PG8_LDB(B0, 1, 0); PG8_LDB(B1, 1, 1); PG8_SCHED; PG8_LDA(At, 1, 0); PG8_STAGE(PG8_SA(0, 1), a2 + hA2, vA2, hA2 / 2);
;             PG8_WAIT_V(8); PG8_WAIT_L(0); PG8_BAR; PG8_MMA(0, 0, At, B0); PG8_MMA(0, 1, At, B1); PG8_BAR; PG8_SCHED;
;             PG8_LDA(At, 1, 1); PG8_STAGE(PG8_SB(1, 0), b3, vB2, hB2 / 2); PG8_STAGE(PG8_SB(1, 1), b3 + hB2, vB2, hB2 / 2); PG8_STAGE(PG8_SA(1, 0), a3, vA2, hA2 / 2);
;             PG8_WAIT_V(8); PG8_WAIT_L(0); PG8_BAR; PG8_MMA(1, 0, At, B0); PG8_MMA(1, 1, At, B1); PG8_BAR; PG8_SCHED;
;         }
;         if (wr == 0) PG8_BAR;
.Lpeel_mid_17324:
	v_add_u32_e32 v130, 0x18000, v143
	ds_read_b128 v[146:149], v130
	ds_read_b128 v[150:153], v130 offset:1024
	ds_read_b128 v[172:175], v130 offset:2048
	ds_read_b128 v[178:181], v130 offset:3072
	v_add_u32_e32 v130, 0x1c000, v143
	ds_read_b128 v[182:185], v130
	ds_read_b128 v[186:189], v130 offset:1024
	ds_read_b128 v[190:193], v130 offset:2048
	ds_read_b128 v[194:197], v130 offset:3072
	ds_read_b128 v[198:201], v144 offset:32768
	ds_read_b128 v[202:205], v144 offset:33792
	ds_read_b128 v[206:209], v144 offset:34816
	ds_read_b128 v[210:213], v144 offset:35840
	ds_read_b128 v[214:217], v144 offset:36864
	ds_read_b128 v[218:221], v144 offset:37888
	ds_read_b128 v[222:225], v144 offset:38912
	ds_read_b128 v[226:229], v144 offset:39936
	s_add_u32 s58, s22, 0x20000
	s_mov_b32 m0, s42
	s_addc_u32 s59, s23, 0
	global_load_lds_dwordx4 v128, s[58:59]
	s_add_u32 s58, s22, 0x30000
	s_mov_b32 m0, s44
	s_addc_u32 s59, s23, 0
	global_load_lds_dwordx4 v128, s[58:59]
	s_waitcnt vmcnt(8) lgkmcnt(0)
	s_barrier
	s_setprio 1
	v_mfma_f32_16x16x32_bf16 v[124:127], v[146:149], v[198:201], v[124:127]
	v_mfma_f32_16x16x32_bf16 v[120:123], v[172:175], v[198:201], v[120:123]
	v_mfma_f32_16x16x32_bf16 v[116:119], v[146:149], v[206:209], v[116:119]
	v_mfma_f32_16x16x32_bf16 v[108:111], v[172:175], v[206:209], v[108:111]
	v_mfma_f32_16x16x32_bf16 v[100:103], v[146:149], v[214:217], v[100:103]
	v_mfma_f32_16x16x32_bf16 v[92:95], v[172:175], v[214:217], v[92:95]
	v_mfma_f32_16x16x32_bf16 v[84:87], v[146:149], v[222:225], v[84:87]
	v_mfma_f32_16x16x32_bf16 v[76:79], v[172:175], v[222:225], v[76:79]
	v_mfma_f32_16x16x32_bf16 v[124:127], v[150:153], v[202:205], v[124:127]
	v_mfma_f32_16x16x32_bf16 v[120:123], v[178:181], v[202:205], v[120:123]
	v_mfma_f32_16x16x32_bf16 v[116:119], v[150:153], v[210:213], v[116:119]
	v_mfma_f32_16x16x32_bf16 v[108:111], v[178:181], v[210:213], v[108:111]
	v_mfma_f32_16x16x32_bf16 v[100:103], v[150:153], v[218:221], v[100:103]
	v_mfma_f32_16x16x32_bf16 v[92:95], v[178:181], v[218:221], v[92:95]
	v_mfma_f32_16x16x32_bf16 v[84:87], v[150:153], v[226:229], v[84:87]
	v_mfma_f32_16x16x32_bf16 v[76:79], v[178:181], v[226:229], v[76:79]
	v_mfma_f32_16x16x32_bf16 v[112:115], v[182:185], v[198:201], v[112:115]
	v_mfma_f32_16x16x32_bf16 v[104:107], v[190:193], v[198:201], v[104:107]
	v_mfma_f32_16x16x32_bf16 v[96:99], v[182:185], v[206:209], v[96:99]
	v_mfma_f32_16x16x32_bf16 v[88:91], v[190:193], v[206:209], v[88:91]
	v_mfma_f32_16x16x32_bf16 v[80:83], v[182:185], v[214:217], v[80:83]
	v_mfma_f32_16x16x32_bf16 v[72:75], v[190:193], v[214:217], v[72:75]
	v_mfma_f32_16x16x32_bf16 v[68:71], v[182:185], v[222:225], v[68:71]
	v_mfma_f32_16x16x32_bf16 v[64:67], v[190:193], v[222:225], v[64:67]
	v_mfma_f32_16x16x32_bf16 v[112:115], v[186:189], v[202:205], v[112:115]
	v_mfma_f32_16x16x32_bf16 v[104:107], v[194:197], v[202:205], v[104:107]
	v_mfma_f32_16x16x32_bf16 v[96:99], v[186:189], v[210:213], v[96:99]
	v_mfma_f32_16x16x32_bf16 v[88:91], v[194:197], v[210:213], v[88:91]
	v_mfma_f32_16x16x32_bf16 v[80:83], v[186:189], v[218:221], v[80:83]
	v_mfma_f32_16x16x32_bf16 v[72:75], v[194:197], v[218:221], v[72:75]
	v_mfma_f32_16x16x32_bf16 v[68:71], v[186:189], v[226:229], v[68:71]
	v_mfma_f32_16x16x32_bf16 v[64:67], v[194:197], v[226:229], v[64:67]
	s_setprio 0
	s_barrier
	s_add_u32 s58, s72, 0x80
	s_addc_u32 s59, s73, 0
	ds_read_b128 v[198:201], v144 offset:49152
	ds_read_b128 v[202:205], v144 offset:50176
	ds_read_b128 v[206:209], v144 offset:51200
	ds_read_b128 v[210:213], v144 offset:52224
	ds_read_b128 v[214:217], v144 offset:53248
	ds_read_b128 v[218:221], v144 offset:54272
	ds_read_b128 v[222:225], v144 offset:55296
	ds_read_b128 v[226:229], v144 offset:56320
	s_mov_b32 m0, s48
	s_nop 0
	global_load_lds_dwordx4 v140, s[58:59]
	s_add_u32 s58, s72, 0x10080
	s_mov_b32 m0, s50
	s_addc_u32 s59, s73, 0
	global_load_lds_dwordx4 v140, s[58:59]
	s_add_u32 s58, s72, 0x20080
	s_mov_b32 m0, s64
	s_addc_u32 s59, s73, 0
	global_load_lds_dwordx4 v140, s[58:59]
	s_add_u32 s58, s72, 0x30080
	s_mov_b32 m0, s65
	s_addc_u32 s59, s73, 0
	global_load_lds_dwordx4 v140, s[58:59]
	s_mov_b32 m0, s51
	s_nop 0
	global_load_lds_dwordx4 v128, s[62:63]
	s_add_u32 s22, s22, 0x10080
	s_mov_b32 m0, s61
	s_addc_u32 s23, s23, 0
	global_load_lds_dwordx4 v128, s[22:23]
	s_waitcnt vmcnt(8) lgkmcnt(0)
	s_barrier
	s_setprio 1
	v_mfma_f32_16x16x32_bf16 v[60:63], v[146:149], v[198:201], v[60:63]
	v_mfma_f32_16x16x32_bf16 v[56:59], v[172:175], v[198:201], v[56:59]
	v_mfma_f32_16x16x32_bf16 v[52:55], v[146:149], v[206:209], v[52:55]
	v_mfma_f32_16x16x32_bf16 v[44:47], v[172:175], v[206:209], v[44:47]
	v_mfma_f32_16x16x32_bf16 v[36:39], v[146:149], v[214:217], v[36:39]
	v_mfma_f32_16x16x32_bf16 v[28:31], v[172:175], v[214:217], v[28:31]
	v_mfma_f32_16x16x32_bf16 v[20:23], v[146:149], v[222:225], v[20:23]
	v_mfma_f32_16x16x32_bf16 v[12:15], v[172:175], v[222:225], v[12:15]
	v_mfma_f32_16x16x32_bf16 v[60:63], v[150:153], v[202:205], v[60:63]
	v_mfma_f32_16x16x32_bf16 v[56:59], v[178:181], v[202:205], v[56:59]
	v_mfma_f32_16x16x32_bf16 v[52:55], v[150:153], v[210:213], v[52:55]
	v_mfma_f32_16x16x32_bf16 v[44:47], v[178:181], v[210:213], v[44:47]
	v_mfma_f32_16x16x32_bf16 v[36:39], v[150:153], v[218:221], v[36:39]
	v_mfma_f32_16x16x32_bf16 v[28:31], v[178:181], v[218:221], v[28:31]
	v_mfma_f32_16x16x32_bf16 v[20:23], v[150:153], v[226:229], v[20:23]
	v_mfma_f32_16x16x32_bf16 v[12:15], v[178:181], v[226:229], v[12:15]
	v_mfma_f32_16x16x32_bf16 v[48:51], v[182:185], v[198:201], v[48:51]
	v_mfma_f32_16x16x32_bf16 v[40:43], v[190:193], v[198:201], v[40:43]
	v_mfma_f32_16x16x32_bf16 v[32:35], v[182:185], v[206:209], v[32:35]
	v_mfma_f32_16x16x32_bf16 v[24:27], v[190:193], v[206:209], v[24:27]
	v_mfma_f32_16x16x32_bf16 v[16:19], v[182:185], v[214:217], v[16:19]
	v_mfma_f32_16x16x32_bf16 v[8:11], v[190:193], v[214:217], v[8:11]
	v_mfma_f32_16x16x32_bf16 v[4:7], v[182:185], v[222:225], v[4:7]
	v_mfma_f32_16x16x32_bf16 v[0:3], v[190:193], v[222:225], v[0:3]
	v_mfma_f32_16x16x32_bf16 v[48:51], v[186:189], v[202:205], v[48:51]
	v_mfma_f32_16x16x32_bf16 v[40:43], v[194:197], v[202:205], v[40:43]
	v_mfma_f32_16x16x32_bf16 v[32:35], v[186:189], v[210:213], v[32:35]
	v_mfma_f32_16x16x32_bf16 v[24:27], v[194:197], v[210:213], v[24:27]
	v_mfma_f32_16x16x32_bf16 v[16:19], v[186:189], v[218:221], v[16:19]
	v_mfma_f32_16x16x32_bf16 v[8:11], v[194:197], v[218:221], v[8:11]
	v_mfma_f32_16x16x32_bf16 v[4:7], v[186:189], v[226:229], v[4:7]
	v_mfma_f32_16x16x32_bf16 v[0:3], v[194:197], v[226:229], v[0:3]
	s_setprio 0
	s_barrier
	s_cmp_gt_u32 s80, 5
	s_mov_b64 s[58:59], s[16:17]
	s_cbranch_scc0 .LBB0_660
	s_and_b64 vcc, exec, s[38:39]
	s_cbranch_vccz .LBB0_663
	s_barrier

; #define PG8_STAGE(bufoff, gbase, voff, p64) do { _Pragma("unroll") for (int _i = 0; _i < 2; ++_i) { \
;         const char* _gb = (const char*)(gbase) + (size_t)_i * (p64); const unsigned _la = ldsbase + (unsigned)(bufoff) + (unsigned)_i * 8192u; \
;         asm volatile("s_mov_b32 m0, %0\n\ts_nop 0\n\tglobal_load_lds_dwordx4 %1, %2" :: "s"(_la), "v"(voff), "s"(_gb) : "memory"); } } while (0)
; #define PG8_LDA(dst, b, h) do { _Pragma("unroll") for (int m = 0; m < 4; ++m) _Pragma("unroll") for (int k = 0; k < 2; ++k) dst[m][k] = *(const LAS bf16x8*)(lds + PG8_SA(b, h) + aoff + m * 2048 + k * 1024); } while (0)
; #define PG8_LDB(dst, b, h) do { _Pragma("unroll") for (int n = 0; n < 2; ++n) _Pragma("unroll") for (int k = 0; k < 2; ++k) dst[n][k] = *(const LAS bf16x8*)(lds + PG8_SB(b, h) + boff + n * 2048 + k * 1024); } while (0)
; #define PG8_MMA(ai, bj, At, Bt) do { __builtin_amdgcn_s_setprio(1); _Pragma("unroll") for (int m = 0; m < 4; ++m) _Pragma("unroll") for (int n = 0; n < 2; ++n) _Pragma("unroll") for (int k = 0; k < 2; ++k) \
;         acc[ai][bj][m][n] = __builtin_amdgcn_mfma_f32_16x16x32_bf16(Bt[n][k], At[m][k], acc[ai][bj][m][n], 0, 0, 0); __builtin_amdgcn_s_setprio(0); } while (0)
; #define PG8_WAIT_V(n) asm volatile("s_waitcnt vmcnt(" #n ")" ::: "memory")
; #define PG8_WAIT_L(n) asm volatile("s_waitcnt lgkmcnt(" #n ")" ::: "memory")
; #define PG8_BAR __builtin_amdgcn_s_barrier()
; template <class Epi, class Sched>
; __device__ __forceinline__ void gemm_phase(LAS unsigned char* lds, const Sched& S, const Epi& E) {
;     ...
;     f32x4 acc[2][2][4][2];
; #pragma unroll
;     for (int a = 0; a < 2; ++a)
; #pragma unroll
;         for (int b = 0; b < 2; ++b)
; #pragma unroll
;             for (int m = 0; m < 4; ++m)
; #pragma unroll
;                 for (int n = 0; n < 2; ++n) acc[a][b][m][n] = (f32x4){0.f, 0.f, 0.f, 0.f};
;     ...
;             PG8_LDB(B0, 0, 0); PG8_LDB(B1, 0, 1); PG8_SCHED; PG8_LDA(At, 0, 0); PG8_STAGE(PG8_SA(1, 1), a1 + hA, voffA, hA / 2);
;             PG8_WAIT_V(8); PG8_WAIT_L(0); PG8_BAR; PG8_MMA(0, 0, At, B0); PG8_MMA(0, 1, At, B1); PG8_BAR; PG8_SCHED;
;             PG8_LDA(At, 0, 1); PG8_STAGE(PG8_SB(0, 0), b2, vB2, hB2 / 2); PG8_STAGE(PG8_SB(0, 1), b2 + hB2, vB2, hB2 / 2); PG8_STAGE(PG8_SA(0, 0), a2, vA2, hA2 / 2);
;             PG8_WAIT_V(8); PG8_WAIT_L(0); PG8_BAR; PG8_MMA(1, 0, At, B0); PG8_MMA(1, 1, At, B1); PG8_BAR; PG8_SCHED;
.LBB0_756:
	s_add_u32 s56, s22, 0x40080
	s_addc_u32 s57, s23, 0
	s_add_u32 s69, s16, 0x100
	s_addc_u32 s72, s17, 0
	s_mov_b32 s73, -2
	v_add_u32_e32 v128, 0x10000, v146
	ds_read_b128 v[130:133], v128
	ds_read_b128 v[134:137], v128 offset:1024
	ds_read_b128 v[138:141], v128 offset:2048
	ds_read_b128 v[148:151], v128 offset:3072
	v_add_u32_e32 v128, 0x14000, v146
	ds_read_b128 v[152:155], v128
	ds_read_b128 v[158:161], v128 offset:1024
	ds_read_b128 v[162:165], v128 offset:2048
	ds_read_b128 v[172:175], v128 offset:3072
	s_add_u32 s16, s56, 0xfffc0080
	s_addc_u32 s17, s57, -1
	s_cmp_eq_u32 s73, 12
	s_cselect_b32 s16, s40, s16
	s_cselect_b32 s17, s41, s17
	s_cselect_b32 s58, s54, s69
	s_cselect_b32 s59, s55, s72
	s_add_u32 s22, s16, 0x80
	s_addc_u32 s23, s17, 0
	ds_read_b128 v[178:181], v147
	ds_read_b128 v[182:185], v147 offset:1024
	ds_read_b128 v[186:189], v147 offset:2048
	ds_read_b128 v[190:193], v147 offset:3072
	ds_read_b128 v[194:197], v147 offset:4096
	ds_read_b128 v[198:201], v147 offset:5120
	ds_read_b128 v[202:205], v147 offset:6144
	ds_read_b128 v[206:209], v147 offset:7168
	s_mov_b32 m0, s62
	s_nop 0
	global_load_lds_dwordx4 v142, s[56:57]
	s_add_u32 s74, s56, 0x20000
	s_mov_b32 m0, s63
	s_addc_u32 s75, s57, 0
	global_load_lds_dwordx4 v142, s[74:75]
	s_waitcnt vmcnt(8) lgkmcnt(0)
	s_barrier
	s_setprio 1
	v_mfma_f32_16x16x32_bf16 v[124:127], v[130:133], v[178:181], 0
	v_mfma_f32_16x16x32_bf16 v[116:119], v[138:141], v[178:181], 0
	v_mfma_f32_16x16x32_bf16 v[108:111], v[130:133], v[186:189], 0
	v_mfma_f32_16x16x32_bf16 v[100:103], v[138:141], v[186:189], 0
	v_mfma_f32_16x16x32_bf16 v[92:95], v[130:133], v[194:197], 0
	v_mfma_f32_16x16x32_bf16 v[84:87], v[138:141], v[194:197], 0
	v_mfma_f32_16x16x32_bf16 v[76:79], v[130:133], v[202:205], 0
	v_mfma_f32_16x16x32_bf16 v[68:71], v[138:141], v[202:205], 0
	v_mfma_f32_16x16x32_bf16 v[124:127], v[134:137], v[182:185], v[124:127]
	v_mfma_f32_16x16x32_bf16 v[116:119], v[148:151], v[182:185], v[116:119]
	v_mfma_f32_16x16x32_bf16 v[108:111], v[134:137], v[190:193], v[108:111]
	v_mfma_f32_16x16x32_bf16 v[100:103], v[148:151], v[190:193], v[100:103]
	v_mfma_f32_16x16x32_bf16 v[92:95], v[134:137], v[198:201], v[92:95]
	v_mfma_f32_16x16x32_bf16 v[84:87], v[148:151], v[198:201], v[84:87]
	v_mfma_f32_16x16x32_bf16 v[76:79], v[134:137], v[206:209], v[76:79]
	v_mfma_f32_16x16x32_bf16 v[68:71], v[148:151], v[206:209], v[68:71]
	v_mfma_f32_16x16x32_bf16 v[120:123], v[152:155], v[178:181], 0
	v_mfma_f32_16x16x32_bf16 v[112:115], v[162:165], v[178:181], 0
	v_mfma_f32_16x16x32_bf16 v[104:107], v[152:155], v[186:189], 0
	v_mfma_f32_16x16x32_bf16 v[96:99], v[162:165], v[186:189], 0
	v_mfma_f32_16x16x32_bf16 v[88:91], v[152:155], v[194:197], 0
	v_mfma_f32_16x16x32_bf16 v[80:83], v[162:165], v[194:197], 0
	v_mfma_f32_16x16x32_bf16 v[72:75], v[152:155], v[202:205], 0
	v_mfma_f32_16x16x32_bf16 v[64:67], v[162:165], v[202:205], 0
	v_mfma_f32_16x16x32_bf16 v[120:123], v[158:161], v[182:185], v[120:123]
	v_mfma_f32_16x16x32_bf16 v[112:115], v[172:175], v[182:185], v[112:115]
	v_mfma_f32_16x16x32_bf16 v[104:107], v[158:161], v[190:193], v[104:107]
	v_mfma_f32_16x16x32_bf16 v[96:99], v[172:175], v[190:193], v[96:99]
	v_mfma_f32_16x16x32_bf16 v[88:91], v[158:161], v[198:201], v[88:91]
	v_mfma_f32_16x16x32_bf16 v[80:83], v[172:175], v[198:201], v[80:83]
	v_mfma_f32_16x16x32_bf16 v[72:75], v[158:161], v[206:209], v[72:75]
	v_mfma_f32_16x16x32_bf16 v[64:67], v[172:175], v[206:209], v[64:67]
	s_add_i32 s73, s73, 2
	s_add_u32 s56, s56, 0x100
	s_addc_u32 s57, s57, 0
	s_add_u32 s69, s69, 0x100
	s_addc_u32 s72, s72, 0
	s_setprio 0
	s_barrier
	s_add_u32 s74, s58, 0x20000
	ds_read_b128 v[178:181], v147 offset:16384
	ds_read_b128 v[182:185], v147 offset:17408
	ds_read_b128 v[186:189], v147 offset:18432
	ds_read_b128 v[190:193], v147 offset:19456
	ds_read_b128 v[194:197], v147 offset:20480
	ds_read_b128 v[198:201], v147 offset:21504
	ds_read_b128 v[202:205], v147 offset:22528
	ds_read_b128 v[206:209], v147 offset:23552
	s_mov_b32 m0, s20
	s_nop 0
	global_load_lds_dwordx4 v143, s[58:59]
	s_mov_b32 m0, s24
	s_addc_u32 s75, s59, 0
	global_load_lds_dwordx4 v143, s[74:75]
	s_add_u32 s74, s58, 0x40000
	s_mov_b32 m0, s33
	s_addc_u32 s75, s59, 0
	global_load_lds_dwordx4 v143, s[74:75]
	s_add_u32 s74, s58, 0x60000
	s_mov_b32 m0, s34
	s_addc_u32 s75, s59, 0
	global_load_lds_dwordx4 v143, s[74:75]
	s_mov_b32 m0, s15
	s_nop 0
	global_load_lds_dwordx4 v142, s[16:17]
	s_add_u32 s74, s16, 0x20000
	s_mov_b32 m0, s35
	s_addc_u32 s75, s17, 0
	global_load_lds_dwordx4 v142, s[74:75]
	s_waitcnt vmcnt(8) lgkmcnt(0)
	s_barrier
	s_setprio 1
	v_mfma_f32_16x16x32_bf16 v[60:63], v[130:133], v[178:181], 0
	v_mfma_f32_16x16x32_bf16 v[52:55], v[138:141], v[178:181], 0
	v_mfma_f32_16x16x32_bf16 v[44:47], v[130:133], v[186:189], 0
	v_mfma_f32_16x16x32_bf16 v[36:39], v[138:141], v[186:189], 0
	v_mfma_f32_16x16x32_bf16 v[28:31], v[130:133], v[194:197], 0
	v_mfma_f32_16x16x32_bf16 v[20:23], v[138:141], v[194:197], 0
	v_mfma_f32_16x16x32_bf16 v[12:15], v[130:133], v[202:205], 0
	v_mfma_f32_16x16x32_bf16 v[4:7], v[138:141], v[202:205], 0
	v_mfma_f32_16x16x32_bf16 v[60:63], v[134:137], v[182:185], v[60:63]
	v_mfma_f32_16x16x32_bf16 v[52:55], v[148:151], v[182:185], v[52:55]
	v_mfma_f32_16x16x32_bf16 v[44:47], v[134:137], v[190:193], v[44:47]
	v_mfma_f32_16x16x32_bf16 v[36:39], v[148:151], v[190:193], v[36:39]
	v_mfma_f32_16x16x32_bf16 v[28:31], v[134:137], v[198:201], v[28:31]
	v_mfma_f32_16x16x32_bf16 v[20:23], v[148:151], v[198:201], v[20:23]
	v_mfma_f32_16x16x32_bf16 v[12:15], v[134:137], v[206:209], v[12:15]
	v_mfma_f32_16x16x32_bf16 v[4:7], v[148:151], v[206:209], v[4:7]
	v_mfma_f32_16x16x32_bf16 v[56:59], v[152:155], v[178:181], 0
	v_mfma_f32_16x16x32_bf16 v[48:51], v[162:165], v[178:181], 0
	v_mfma_f32_16x16x32_bf16 v[40:43], v[152:155], v[186:189], 0
	v_mfma_f32_16x16x32_bf16 v[32:35], v[162:165], v[186:189], 0
	v_mfma_f32_16x16x32_bf16 v[24:27], v[152:155], v[194:197], 0
	v_mfma_f32_16x16x32_bf16 v[16:19], v[162:165], v[194:197], 0
	v_mfma_f32_16x16x32_bf16 v[8:11], v[152:155], v[202:205], 0
	v_mfma_f32_16x16x32_bf16 v[0:3], v[162:165], v[202:205], 0
	v_mfma_f32_16x16x32_bf16 v[56:59], v[158:161], v[182:185], v[56:59]
	v_mfma_f32_16x16x32_bf16 v[48:51], v[172:175], v[182:185], v[48:51]
	v_mfma_f32_16x16x32_bf16 v[40:43], v[158:161], v[190:193], v[40:43]
	v_mfma_f32_16x16x32_bf16 v[32:35], v[172:175], v[190:193], v[32:35]
	v_mfma_f32_16x16x32_bf16 v[24:27], v[158:161], v[198:201], v[24:27]
	v_mfma_f32_16x16x32_bf16 v[16:19], v[172:175], v[198:201], v[16:19]
	v_mfma_f32_16x16x32_bf16 v[8:11], v[158:161], v[206:209], v[8:11]
	v_mfma_f32_16x16x32_bf16 v[0:3], v[172:175], v[206:209], v[0:3]
	s_setprio 0
	s_barrier
	s_branch .Lpeel_mid_20519
; #define PG8_STAGE(bufoff, gbase, voff, p64) do { _Pragma("unroll") for (int _i = 0; _i < 2; ++_i) { \
;         const char* _gb = (const char*)(gbase) + (size_t)_i * (p64); const unsigned _la = ldsbase + (unsigned)(bufoff) + (unsigned)_i * 8192u; \
;         asm volatile("s_mov_b32 m0, %0\n\ts_nop 0\n\tglobal_load_lds_dwordx4 %1, %2" :: "s"(_la), "v"(voff), "s"(_gb) : "memory"); } } while (0)
; #define PG8_LDA(dst, b, h) do { _Pragma("unroll") for (int m = 0; m < 4; ++m) _Pragma("unroll") for (int k = 0; k < 2; ++k) dst[m][k] = *(const LAS bf16x8*)(lds + PG8_SA(b, h) + aoff + m * 2048 + k * 1024); } while (0)
; #define PG8_LDB(dst, b, h) do { _Pragma("unroll") for (int n = 0; n < 2; ++n) _Pragma("unroll") for (int k = 0; k < 2; ++k) dst[n][k] = *(const LAS bf16x8*)(lds + PG8_SB(b, h) + boff + n * 2048 + k * 1024); } while (0)
; #define PG8_MMA(ai, bj, At, Bt) do { __builtin_amdgcn_s_setprio(1); _Pragma("unroll") for (int m = 0; m < 4; ++m) _Pragma("unroll") for (int n = 0; n < 2; ++n) _Pragma("unroll") for (int k = 0; k < 2; ++k) \
;         acc[ai][bj][m][n] = __builtin_amdgcn_mfma_f32_16x16x32_bf16(Bt[n][k], At[m][k], acc[ai][bj][m][n], 0, 0, 0); __builtin_amdgcn_s_setprio(0); } while (0)
; #define PG8_WAIT_V(n) asm volatile("s_waitcnt vmcnt(" #n ")" ::: "memory")
; #define PG8_WAIT_L(n) asm volatile("s_waitcnt lgkmcnt(" #n ")" ::: "memory")
; #define PG8_BAR __builtin_amdgcn_s_barrier()
; #define PG8_SCHED __builtin_amdgcn_sched_barrier(0)
; template <class Epi, class Sched>
; __device__ __forceinline__ void gemm_phase(LAS unsigned char* lds, const Sched& S, const Epi& E) {
;     ...
;             PG8_LDB(B0, 0, 0); PG8_LDB(B1, 0, 1); PG8_SCHED; PG8_LDA(At, 0, 0); PG8_STAGE(PG8_SA(1, 1), a1 + hA, voffA, hA / 2);
;             PG8_WAIT_V(8); PG8_WAIT_L(0); PG8_BAR; PG8_MMA(0, 0, At, B0); PG8_MMA(0, 1, At, B1); PG8_BAR; PG8_SCHED;
;             PG8_LDA(At, 0, 1); PG8_STAGE(PG8_SB(0, 0), b2, vB2, hB2 / 2); PG8_STAGE(PG8_SB(0, 1), b2 + hB2, vB2, hB2 / 2); PG8_STAGE(PG8_SA(0, 0), a2, vA2, hA2 / 2);
;             PG8_WAIT_V(8); PG8_WAIT_L(0); PG8_BAR; PG8_MMA(1, 0, At, B0); PG8_MMA(1, 1, At, B1); PG8_BAR; PG8_SCHED;
.LBB0_757:
	v_add_u32_e32 v128, 0x10000, v146
	ds_read_b128 v[130:133], v128
	ds_read_b128 v[134:137], v128 offset:1024
	ds_read_b128 v[138:141], v128 offset:2048
	ds_read_b128 v[148:151], v128 offset:3072
	v_add_u32_e32 v128, 0x14000, v146
	ds_read_b128 v[152:155], v128
	ds_read_b128 v[158:161], v128 offset:1024
	ds_read_b128 v[162:165], v128 offset:2048
	ds_read_b128 v[172:175], v128 offset:3072
	s_add_u32 s16, s56, 0xfffc0080
	s_addc_u32 s17, s57, -1
	s_cmp_eq_u32 s73, 12
	s_cselect_b32 s16, s40, s16
	s_cselect_b32 s17, s41, s17
	s_cselect_b32 s58, s54, s69
	s_cselect_b32 s59, s55, s72
	s_add_u32 s22, s16, 0x80
	s_addc_u32 s23, s17, 0
	ds_read_b128 v[178:181], v147
	ds_read_b128 v[182:185], v147 offset:1024
	ds_read_b128 v[186:189], v147 offset:2048
	ds_read_b128 v[190:193], v147 offset:3072
	ds_read_b128 v[194:197], v147 offset:4096
	ds_read_b128 v[198:201], v147 offset:5120
	ds_read_b128 v[202:205], v147 offset:6144
	ds_read_b128 v[206:209], v147 offset:7168
	s_mov_b32 m0, s62
	s_nop 0
	global_load_lds_dwordx4 v142, s[56:57]
	s_add_u32 s74, s56, 0x20000
	s_mov_b32 m0, s63
	s_addc_u32 s75, s57, 0
	global_load_lds_dwordx4 v142, s[74:75]
	s_waitcnt vmcnt(8) lgkmcnt(0)
	s_barrier
	s_setprio 1
	v_mfma_f32_16x16x32_bf16 v[124:127], v[130:133], v[178:181], v[124:127]
	v_mfma_f32_16x16x32_bf16 v[116:119], v[138:141], v[178:181], v[116:119]
	v_mfma_f32_16x16x32_bf16 v[108:111], v[130:133], v[186:189], v[108:111]
	v_mfma_f32_16x16x32_bf16 v[100:103], v[138:141], v[186:189], v[100:103]
	v_mfma_f32_16x16x32_bf16 v[92:95], v[130:133], v[194:197], v[92:95]
	v_mfma_f32_16x16x32_bf16 v[84:87], v[138:141], v[194:197], v[84:87]
	v_mfma_f32_16x16x32_bf16 v[76:79], v[130:133], v[202:205], v[76:79]
	v_mfma_f32_16x16x32_bf16 v[68:71], v[138:141], v[202:205], v[68:71]
	v_mfma_f32_16x16x32_bf16 v[124:127], v[134:137], v[182:185], v[124:127]
	v_mfma_f32_16x16x32_bf16 v[116:119], v[148:151], v[182:185], v[116:119]
	v_mfma_f32_16x16x32_bf16 v[108:111], v[134:137], v[190:193], v[108:111]
	v_mfma_f32_16x16x32_bf16 v[100:103], v[148:151], v[190:193], v[100:103]
	v_mfma_f32_16x16x32_bf16 v[92:95], v[134:137], v[198:201], v[92:95]
	v_mfma_f32_16x16x32_bf16 v[84:87], v[148:151], v[198:201], v[84:87]
	v_mfma_f32_16x16x32_bf16 v[76:79], v[134:137], v[206:209], v[76:79]
	v_mfma_f32_16x16x32_bf16 v[68:71], v[148:151], v[206:209], v[68:71]
	v_mfma_f32_16x16x32_bf16 v[120:123], v[152:155], v[178:181], v[120:123]
	v_mfma_f32_16x16x32_bf16 v[112:115], v[162:165], v[178:181], v[112:115]
	v_mfma_f32_16x16x32_bf16 v[104:107], v[152:155], v[186:189], v[104:107]
	v_mfma_f32_16x16x32_bf16 v[96:99], v[162:165], v[186:189], v[96:99]
	v_mfma_f32_16x16x32_bf16 v[88:91], v[152:155], v[194:197], v[88:91]
	v_mfma_f32_16x16x32_bf16 v[80:83], v[162:165], v[194:197], v[80:83]
	v_mfma_f32_16x16x32_bf16 v[72:75], v[152:155], v[202:205], v[72:75]
	v_mfma_f32_16x16x32_bf16 v[64:67], v[162:165], v[202:205], v[64:67]
	v_mfma_f32_16x16x32_bf16 v[120:123], v[158:161], v[182:185], v[120:123]
	v_mfma_f32_16x16x32_bf16 v[112:115], v[172:175], v[182:185], v[112:115]
	v_mfma_f32_16x16x32_bf16 v[104:107], v[158:161], v[190:193], v[104:107]
	v_mfma_f32_16x16x32_bf16 v[96:99], v[172:175], v[190:193], v[96:99]
	v_mfma_f32_16x16x32_bf16 v[88:91], v[158:161], v[198:201], v[88:91]
	v_mfma_f32_16x16x32_bf16 v[80:83], v[172:175], v[198:201], v[80:83]
	v_mfma_f32_16x16x32_bf16 v[72:75], v[158:161], v[206:209], v[72:75]
	v_mfma_f32_16x16x32_bf16 v[64:67], v[172:175], v[206:209], v[64:67]
	s_add_i32 s73, s73, 2
	s_add_u32 s56, s56, 0x100
	s_addc_u32 s57, s57, 0
	s_add_u32 s69, s69, 0x100
	s_addc_u32 s72, s72, 0
	s_setprio 0
	s_barrier
	s_add_u32 s74, s58, 0x20000
	ds_read_b128 v[178:181], v147 offset:16384
	ds_read_b128 v[182:185], v147 offset:17408
	ds_read_b128 v[186:189], v147 offset:18432
	ds_read_b128 v[190:193], v147 offset:19456
	ds_read_b128 v[194:197], v147 offset:20480
	ds_read_b128 v[198:201], v147 offset:21504
	ds_read_b128 v[202:205], v147 offset:22528
	ds_read_b128 v[206:209], v147 offset:23552
	s_mov_b32 m0, s20
	s_nop 0
	global_load_lds_dwordx4 v143, s[58:59]
	s_mov_b32 m0, s24
	s_addc_u32 s75, s59, 0
	global_load_lds_dwordx4 v143, s[74:75]
	s_add_u32 s74, s58, 0x40000
	s_mov_b32 m0, s33
	s_addc_u32 s75, s59, 0
	global_load_lds_dwordx4 v143, s[74:75]
	s_add_u32 s74, s58, 0x60000
	s_mov_b32 m0, s34
	s_addc_u32 s75, s59, 0
	global_load_lds_dwordx4 v143, s[74:75]
	s_mov_b32 m0, s15
	s_nop 0
	global_load_lds_dwordx4 v142, s[16:17]
	s_add_u32 s74, s16, 0x20000
	s_mov_b32 m0, s35
	s_addc_u32 s75, s17, 0
	global_load_lds_dwordx4 v142, s[74:75]
	s_waitcnt vmcnt(8) lgkmcnt(0)
	s_barrier
	s_setprio 1
	v_mfma_f32_16x16x32_bf16 v[60:63], v[130:133], v[178:181], v[60:63]
	v_mfma_f32_16x16x32_bf16 v[52:55], v[138:141], v[178:181], v[52:55]
	v_mfma_f32_16x16x32_bf16 v[44:47], v[130:133], v[186:189], v[44:47]
	v_mfma_f32_16x16x32_bf16 v[36:39], v[138:141], v[186:189], v[36:39]
	v_mfma_f32_16x16x32_bf16 v[28:31], v[130:133], v[194:197], v[28:31]
	v_mfma_f32_16x16x32_bf16 v[20:23], v[138:141], v[194:197], v[20:23]
	v_mfma_f32_16x16x32_bf16 v[12:15], v[130:133], v[202:205], v[12:15]
	v_mfma_f32_16x16x32_bf16 v[4:7], v[138:141], v[202:205], v[4:7]
	v_mfma_f32_16x16x32_bf16 v[60:63], v[134:137], v[182:185], v[60:63]
	v_mfma_f32_16x16x32_bf16 v[52:55], v[148:151], v[182:185], v[52:55]
	v_mfma_f32_16x16x32_bf16 v[44:47], v[134:137], v[190:193], v[44:47]
	v_mfma_f32_16x16x32_bf16 v[36:39], v[148:151], v[190:193], v[36:39]
	v_mfma_f32_16x16x32_bf16 v[28:31], v[134:137], v[198:201], v[28:31]
	v_mfma_f32_16x16x32_bf16 v[20:23], v[148:151], v[198:201], v[20:23]
	v_mfma_f32_16x16x32_bf16 v[12:15], v[134:137], v[206:209], v[12:15]
	v_mfma_f32_16x16x32_bf16 v[4:7], v[148:151], v[206:209], v[4:7]
	v_mfma_f32_16x16x32_bf16 v[56:59], v[152:155], v[178:181], v[56:59]
	v_mfma_f32_16x16x32_bf16 v[48:51], v[162:165], v[178:181], v[48:51]
	v_mfma_f32_16x16x32_bf16 v[40:43], v[152:155], v[186:189], v[40:43]
	v_mfma_f32_16x16x32_bf16 v[32:35], v[162:165], v[186:189], v[32:35]
	v_mfma_f32_16x16x32_bf16 v[24:27], v[152:155], v[194:197], v[24:27]
	v_mfma_f32_16x16x32_bf16 v[16:19], v[162:165], v[194:197], v[16:19]
	v_mfma_f32_16x16x32_bf16 v[8:11], v[152:155], v[202:205], v[8:11]
	v_mfma_f32_16x16x32_bf16 v[0:3], v[162:165], v[202:205], v[0:3]
	v_mfma_f32_16x16x32_bf16 v[56:59], v[158:161], v[182:185], v[56:59]
	v_mfma_f32_16x16x32_bf16 v[48:51], v[172:175], v[182:185], v[48:51]
	v_mfma_f32_16x16x32_bf16 v[40:43], v[158:161], v[190:193], v[40:43]
	v_mfma_f32_16x16x32_bf16 v[32:35], v[172:175], v[190:193], v[32:35]
	v_mfma_f32_16x16x32_bf16 v[24:27], v[158:161], v[198:201], v[24:27]
	v_mfma_f32_16x16x32_bf16 v[16:19], v[172:175], v[198:201], v[16:19]
	v_mfma_f32_16x16x32_bf16 v[8:11], v[158:161], v[206:209], v[8:11]
	v_mfma_f32_16x16x32_bf16 v[0:3], v[172:175], v[206:209], v[0:3]
	s_setprio 0
	s_barrier
; #define PG8_STAGE(bufoff, gbase, voff, p64) do { _Pragma("unroll") for (int _i = 0; _i < 2; ++_i) { \
;         const char* _gb = (const char*)(gbase) + (size_t)_i * (p64); const unsigned _la = ldsbase + (unsigned)(bufoff) + (unsigned)_i * 8192u; \
;         asm volatile("s_mov_b32 m0, %0\n\ts_nop 0\n\tglobal_load_lds_dwordx4 %1, %2" :: "s"(_la), "v"(voff), "s"(_gb) : "memory"); } } while (0)
; #define PG8_LDA(dst, b, h) do { _Pragma("unroll") for (int m = 0; m < 4; ++m) _Pragma("unroll") for (int k = 0; k < 2; ++k) dst[m][k] = *(const LAS bf16x8*)(lds + PG8_SA(b, h) + aoff + m * 2048 + k * 1024); } while (0)
; #define PG8_LDB(dst, b, h) do { _Pragma("unroll") for (int n = 0; n < 2; ++n) _Pragma("unroll") for (int k = 0; k < 2; ++k) dst[n][k] = *(const LAS bf16x8*)(lds + PG8_SB(b, h) + boff + n * 2048 + k * 1024); } while (0)
; #define PG8_MMA(ai, bj, At, Bt) do { __builtin_amdgcn_s_setprio(1); _Pragma("unroll") for (int m = 0; m < 4; ++m) _Pragma("unroll") for (int n = 0; n < 2; ++n) _Pragma("unroll") for (int k = 0; k < 2; ++k) \
;         acc[ai][bj][m][n] = __builtin_amdgcn_mfma_f32_16x16x32_bf16(Bt[n][k], At[m][k], acc[ai][bj][m][n], 0, 0, 0); __builtin_amdgcn_s_setprio(0); } while (0)
; #define PG8_WAIT_V(n) asm volatile("s_waitcnt vmcnt(" #n ")" ::: "memory")
; #define PG8_WAIT_L(n) asm volatile("s_waitcnt lgkmcnt(" #n ")" ::: "memory")
; #define PG8_BAR __builtin_amdgcn_s_barrier()
; #define PG8_SCHED __builtin_amdgcn_sched_barrier(0)
; template <class Epi, class Sched>
; __device__ __forceinline__ void gemm_phase(LAS unsigned char* lds, const Sched& S, const Epi& E) {
;     ...
;             PG8_LDB(B0, 1, 0); PG8_LDB(B1, 1, 1); PG8_SCHED; PG8_LDA(At, 1, 0); PG8_STAGE(PG8_SA(0, 1), a2 + hA2, vA2, hA2 / 2);
;             PG8_WAIT_V(8); PG8_WAIT_L(0); PG8_BAR; PG8_MMA(0, 0, At, B0); PG8_MMA(0, 1, At, B1); PG8_BAR; PG8_SCHED;
;             PG8_LDA(At, 1, 1); PG8_STAGE(PG8_SB(1, 0), b3, vB2, hB2 / 2); PG8_STAGE(PG8_SB(1, 1), b3 + hB2, vB2, hB2 / 2); PG8_STAGE(PG8_SA(1, 0), a3, vA2, hA2 / 2);
;             PG8_WAIT_V(8); PG8_WAIT_L(0); PG8_BAR; PG8_MMA(1, 0, At, B0); PG8_MMA(1, 1, At, B1); PG8_BAR; PG8_SCHED;
;         }
;         if (wr == 0) PG8_BAR;
.Lpeel_mid_20519:
	v_add_u32_e32 v128, 0x18000, v146
	ds_read_b128 v[130:133], v128
	ds_read_b128 v[134:137], v128 offset:1024
	ds_read_b128 v[138:141], v128 offset:2048
	ds_read_b128 v[148:151], v128 offset:3072
	v_add_u32_e32 v128, 0x1c000, v146
	ds_read_b128 v[152:155], v128
	ds_read_b128 v[158:161], v128 offset:1024
	ds_read_b128 v[162:165], v128 offset:2048
	ds_read_b128 v[172:175], v128 offset:3072
	ds_read_b128 v[178:181], v147 offset:32768
	ds_read_b128 v[182:185], v147 offset:33792
	ds_read_b128 v[186:189], v147 offset:34816
	ds_read_b128 v[190:193], v147 offset:35840
	ds_read_b128 v[194:197], v147 offset:36864
	ds_read_b128 v[198:201], v147 offset:37888
	ds_read_b128 v[202:205], v147 offset:38912
	ds_read_b128 v[206:209], v147 offset:39936
	s_add_u32 s74, s16, 0x40000
	s_mov_b32 m0, s36
	s_addc_u32 s75, s17, 0
	global_load_lds_dwordx4 v142, s[74:75]
	s_add_u32 s74, s16, 0x60000
	s_mov_b32 m0, s37
	s_addc_u32 s75, s17, 0
	global_load_lds_dwordx4 v142, s[74:75]
	s_waitcnt vmcnt(8) lgkmcnt(0)
	s_barrier
	s_setprio 1
	v_mfma_f32_16x16x32_bf16 v[124:127], v[130:133], v[178:181], v[124:127]
	v_mfma_f32_16x16x32_bf16 v[116:119], v[138:141], v[178:181], v[116:119]
	v_mfma_f32_16x16x32_bf16 v[108:111], v[130:133], v[186:189], v[108:111]
	v_mfma_f32_16x16x32_bf16 v[100:103], v[138:141], v[186:189], v[100:103]
	v_mfma_f32_16x16x32_bf16 v[92:95], v[130:133], v[194:197], v[92:95]
	v_mfma_f32_16x16x32_bf16 v[84:87], v[138:141], v[194:197], v[84:87]
	v_mfma_f32_16x16x32_bf16 v[76:79], v[130:133], v[202:205], v[76:79]
	v_mfma_f32_16x16x32_bf16 v[68:71], v[138:141], v[202:205], v[68:71]
	v_mfma_f32_16x16x32_bf16 v[124:127], v[134:137], v[182:185], v[124:127]
	v_mfma_f32_16x16x32_bf16 v[116:119], v[148:151], v[182:185], v[116:119]
	v_mfma_f32_16x16x32_bf16 v[108:111], v[134:137], v[190:193], v[108:111]
	v_mfma_f32_16x16x32_bf16 v[100:103], v[148:151], v[190:193], v[100:103]
	v_mfma_f32_16x16x32_bf16 v[92:95], v[134:137], v[198:201], v[92:95]
	v_mfma_f32_16x16x32_bf16 v[84:87], v[148:151], v[198:201], v[84:87]
	v_mfma_f32_16x16x32_bf16 v[76:79], v[134:137], v[206:209], v[76:79]
	v_mfma_f32_16x16x32_bf16 v[68:71], v[148:151], v[206:209], v[68:71]
	v_mfma_f32_16x16x32_bf16 v[120:123], v[152:155], v[178:181], v[120:123]
	v_mfma_f32_16x16x32_bf16 v[112:115], v[162:165], v[178:181], v[112:115]
	v_mfma_f32_16x16x32_bf16 v[104:107], v[152:155], v[186:189], v[104:107]
	v_mfma_f32_16x16x32_bf16 v[96:99], v[162:165], v[186:189], v[96:99]
	v_mfma_f32_16x16x32_bf16 v[88:91], v[152:155], v[194:197], v[88:91]
	v_mfma_f32_16x16x32_bf16 v[80:83], v[162:165], v[194:197], v[80:83]
	v_mfma_f32_16x16x32_bf16 v[72:75], v[152:155], v[202:205], v[72:75]
	v_mfma_f32_16x16x32_bf16 v[64:67], v[162:165], v[202:205], v[64:67]
	v_mfma_f32_16x16x32_bf16 v[120:123], v[158:161], v[182:185], v[120:123]
	v_mfma_f32_16x16x32_bf16 v[112:115], v[172:175], v[182:185], v[112:115]
	v_mfma_f32_16x16x32_bf16 v[104:107], v[158:161], v[190:193], v[104:107]
	v_mfma_f32_16x16x32_bf16 v[96:99], v[172:175], v[190:193], v[96:99]
	v_mfma_f32_16x16x32_bf16 v[88:91], v[158:161], v[198:201], v[88:91]
	v_mfma_f32_16x16x32_bf16 v[80:83], v[172:175], v[198:201], v[80:83]
	v_mfma_f32_16x16x32_bf16 v[72:75], v[158:161], v[206:209], v[72:75]
	v_mfma_f32_16x16x32_bf16 v[64:67], v[172:175], v[206:209], v[64:67]
	s_setprio 0
	s_barrier
	s_add_u32 s74, s58, 0x80
	s_addc_u32 s75, s59, 0
	ds_read_b128 v[178:181], v147 offset:49152
	ds_read_b128 v[182:185], v147 offset:50176
	ds_read_b128 v[186:189], v147 offset:51200
	ds_read_b128 v[190:193], v147 offset:52224
	ds_read_b128 v[194:197], v147 offset:53248
	ds_read_b128 v[198:201], v147 offset:54272
	ds_read_b128 v[202:205], v147 offset:55296
	ds_read_b128 v[206:209], v147 offset:56320
	s_mov_b32 m0, s45
	s_nop 0
	global_load_lds_dwordx4 v143, s[74:75]
	s_add_u32 s74, s58, 0x20080
	s_mov_b32 m0, s47
	s_addc_u32 s75, s59, 0
	global_load_lds_dwordx4 v143, s[74:75]
	s_add_u32 s74, s58, 0x40080
	s_mov_b32 m0, s51
	s_addc_u32 s75, s59, 0
	global_load_lds_dwordx4 v143, s[74:75]
	s_add_u32 s58, s58, 0x60080
	s_mov_b32 m0, s61
	s_addc_u32 s59, s59, 0
	global_load_lds_dwordx4 v143, s[58:59]
	s_mov_b32 m0, s48
	s_nop 0
	global_load_lds_dwordx4 v142, s[22:23]
	s_add_u32 s16, s16, 0x20080
	s_mov_b32 m0, s50
	s_addc_u32 s17, s17, 0
	global_load_lds_dwordx4 v142, s[16:17]
	s_waitcnt vmcnt(8) lgkmcnt(0)
	s_barrier
	s_setprio 1
	v_mfma_f32_16x16x32_bf16 v[60:63], v[130:133], v[178:181], v[60:63]
	v_mfma_f32_16x16x32_bf16 v[52:55], v[138:141], v[178:181], v[52:55]
	v_mfma_f32_16x16x32_bf16 v[44:47], v[130:133], v[186:189], v[44:47]
	v_mfma_f32_16x16x32_bf16 v[36:39], v[138:141], v[186:189], v[36:39]
	v_mfma_f32_16x16x32_bf16 v[28:31], v[130:133], v[194:197], v[28:31]
	v_mfma_f32_16x16x32_bf16 v[20:23], v[138:141], v[194:197], v[20:23]
	v_mfma_f32_16x16x32_bf16 v[12:15], v[130:133], v[202:205], v[12:15]
	v_mfma_f32_16x16x32_bf16 v[4:7], v[138:141], v[202:205], v[4:7]
	v_mfma_f32_16x16x32_bf16 v[60:63], v[134:137], v[182:185], v[60:63]
	v_mfma_f32_16x16x32_bf16 v[52:55], v[148:151], v[182:185], v[52:55]
	v_mfma_f32_16x16x32_bf16 v[44:47], v[134:137], v[190:193], v[44:47]
	v_mfma_f32_16x16x32_bf16 v[36:39], v[148:151], v[190:193], v[36:39]
	v_mfma_f32_16x16x32_bf16 v[28:31], v[134:137], v[198:201], v[28:31]
	v_mfma_f32_16x16x32_bf16 v[20:23], v[148:151], v[198:201], v[20:23]
	v_mfma_f32_16x16x32_bf16 v[12:15], v[134:137], v[206:209], v[12:15]
	v_mfma_f32_16x16x32_bf16 v[4:7], v[148:151], v[206:209], v[4:7]
	v_mfma_f32_16x16x32_bf16 v[56:59], v[152:155], v[178:181], v[56:59]
	v_mfma_f32_16x16x32_bf16 v[48:51], v[162:165], v[178:181], v[48:51]
	v_mfma_f32_16x16x32_bf16 v[40:43], v[152:155], v[186:189], v[40:43]
	v_mfma_f32_16x16x32_bf16 v[32:35], v[162:165], v[186:189], v[32:35]
	v_mfma_f32_16x16x32_bf16 v[24:27], v[152:155], v[194:197], v[24:27]
	v_mfma_f32_16x16x32_bf16 v[16:19], v[162:165], v[194:197], v[16:19]
	v_mfma_f32_16x16x32_bf16 v[8:11], v[152:155], v[202:205], v[8:11]
	v_mfma_f32_16x16x32_bf16 v[0:3], v[162:165], v[202:205], v[0:3]
	v_mfma_f32_16x16x32_bf16 v[56:59], v[158:161], v[182:185], v[56:59]
	v_mfma_f32_16x16x32_bf16 v[48:51], v[172:175], v[182:185], v[48:51]
	v_mfma_f32_16x16x32_bf16 v[40:43], v[158:161], v[190:193], v[40:43]
	v_mfma_f32_16x16x32_bf16 v[32:35], v[172:175], v[190:193], v[32:35]
	v_mfma_f32_16x16x32_bf16 v[24:27], v[158:161], v[198:201], v[24:27]
	v_mfma_f32_16x16x32_bf16 v[16:19], v[172:175], v[198:201], v[16:19]
	v_mfma_f32_16x16x32_bf16 v[8:11], v[158:161], v[206:209], v[8:11]
	v_mfma_f32_16x16x32_bf16 v[0:3], v[172:175], v[206:209], v[0:3]
	s_setprio 0
	s_barrier
	s_cmp_gt_u32 s73, 13
	s_cbranch_scc0 .LBB0_757
	s_and_b64 vcc, exec, s[38:39]
	s_cbranch_vccz .LBB0_760
	s_barrier

; #define PG8_STAGE(bufoff, gbase, voff, p64) do { _Pragma("unroll") for (int _i = 0; _i < 2; ++_i) { \
;         const char* _gb = (const char*)(gbase) + (size_t)_i * (p64); const unsigned _la = ldsbase + (unsigned)(bufoff) + (unsigned)_i * 8192u; \
;         asm volatile("s_mov_b32 m0, %0\n\ts_nop 0\n\tglobal_load_lds_dwordx4 %1, %2" :: "s"(_la), "v"(voff), "s"(_gb) : "memory"); } } while (0)
; #define PG8_LDA(dst, b, h) do { _Pragma("unroll") for (int m = 0; m < 4; ++m) _Pragma("unroll") for (int k = 0; k < 2; ++k) dst[m][k] = *(const LAS bf16x8*)(lds + PG8_SA(b, h) + aoff + m * 2048 + k * 1024); } while (0)
; #define PG8_LDB(dst, b, h) do { _Pragma("unroll") for (int n = 0; n < 2; ++n) _Pragma("unroll") for (int k = 0; k < 2; ++k) dst[n][k] = *(const LAS bf16x8*)(lds + PG8_SB(b, h) + boff + n * 2048 + k * 1024); } while (0)
; #define PG8_MMA(ai, bj, At, Bt) do { __builtin_amdgcn_s_setprio(1); _Pragma("unroll") for (int m = 0; m < 4; ++m) _Pragma("unroll") for (int n = 0; n < 2; ++n) _Pragma("unroll") for (int k = 0; k < 2; ++k) \
;         acc[ai][bj][m][n] = __builtin_amdgcn_mfma_f32_16x16x32_bf16(Bt[n][k], At[m][k], acc[ai][bj][m][n], 0, 0, 0); __builtin_amdgcn_s_setprio(0); } while (0)
; #define PG8_WAIT_V(n) asm volatile("s_waitcnt vmcnt(" #n ")" ::: "memory")
; #define PG8_WAIT_L(n) asm volatile("s_waitcnt lgkmcnt(" #n ")" ::: "memory")
; #define PG8_BAR __builtin_amdgcn_s_barrier()
; #define PG8_SCHED __builtin_amdgcn_sched_barrier(0)
; template <class Epi, class Sched>
; __device__ __forceinline__ void gemm_phase(LAS unsigned char* lds, const Sched& S, const Epi& E) {
;     ...
;             PG8_LDB(B0, 0, 0); PG8_LDB(B1, 0, 1); PG8_SCHED; PG8_LDA(At, 0, 0); PG8_STAGE(PG8_SA(1, 1), a1 + hA, voffA, hA / 2);
;             PG8_WAIT_V(8); PG8_WAIT_L(0); PG8_BAR; PG8_MMA(0, 0, At, B0); PG8_MMA(0, 1, At, B1); PG8_BAR; PG8_SCHED;
;             PG8_LDA(At, 0, 1); PG8_STAGE(PG8_SB(0, 0), b2, vB2, hB2 / 2); PG8_STAGE(PG8_SB(0, 1), b2 + hB2, vB2, hB2 / 2); PG8_STAGE(PG8_SA(0, 0), a2, vA2, hA2 / 2);
;             PG8_WAIT_V(8); PG8_WAIT_L(0); PG8_BAR; PG8_MMA(1, 0, At, B0); PG8_MMA(1, 1, At, B1); PG8_BAR; PG8_SCHED;
.LBB0_844:
	v_add_u32_e32 v142, 0x10000, v175
	v_add_u32_e32 v154, 0x14000, v175
	ds_read_b128 v[130:133], v142
	ds_read_b128 v[134:137], v142 offset:1024
	ds_read_b128 v[138:141], v142 offset:2048
	ds_read_b128 v[142:145], v142 offset:3072
	ds_read_b128 v[146:149], v154
	ds_read_b128 v[150:153], v154 offset:1024
	ds_read_b128 v[158:161], v154 offset:2048
	ds_read_b128 v[162:165], v154 offset:3072
	s_add_i32 s80, s8, 2
	s_cmp_eq_u32 s73, s8
	s_cselect_b32 s8, s56, s76
	s_cselect_b32 s9, s57, s77
	s_cselect_b32 s22, s58, s78
	s_cselect_b32 s23, s59, s79
	s_add_u32 s16, s8, 0x80
	s_addc_u32 s17, s9, 0
	ds_read_b128 v[180:183], v177
	ds_read_b128 v[184:187], v177 offset:1024
	ds_read_b128 v[188:191], v177 offset:2048
	ds_read_b128 v[192:195], v177 offset:3072
	ds_read_b128 v[196:199], v177 offset:4096
	ds_read_b128 v[200:203], v177 offset:5120
	ds_read_b128 v[204:207], v177 offset:6144
	ds_read_b128 v[208:211], v177 offset:7168
	s_add_u32 s30, s76, 0x3ff80
	s_mov_b32 m0, s66
	s_addc_u32 s31, s77, 0
	global_load_lds_dwordx4 v172, s[30:31]
	s_add_u32 s30, s76, 0x5ff80
	s_mov_b32 m0, s67
	s_addc_u32 s31, s77, 0
	global_load_lds_dwordx4 v172, s[30:31]
	s_waitcnt vmcnt(8) lgkmcnt(0)
	s_barrier
	s_setprio 1
	v_mfma_f32_16x16x32_bf16 v[124:127], v[130:133], v[180:183], v[124:127]
	v_mfma_f32_16x16x32_bf16 v[120:123], v[138:141], v[180:183], v[120:123]
	v_mfma_f32_16x16x32_bf16 v[116:119], v[130:133], v[188:191], v[116:119]
	v_mfma_f32_16x16x32_bf16 v[112:115], v[138:141], v[188:191], v[112:115]
	v_mfma_f32_16x16x32_bf16 v[108:111], v[130:133], v[196:199], v[108:111]
	v_mfma_f32_16x16x32_bf16 v[104:107], v[138:141], v[196:199], v[104:107]
	v_mfma_f32_16x16x32_bf16 v[100:103], v[130:133], v[204:207], v[100:103]
	v_mfma_f32_16x16x32_bf16 v[96:99], v[138:141], v[204:207], v[96:99]
	v_mfma_f32_16x16x32_bf16 v[124:127], v[134:137], v[184:187], v[124:127]
	v_mfma_f32_16x16x32_bf16 v[120:123], v[142:145], v[184:187], v[120:123]
	v_mfma_f32_16x16x32_bf16 v[116:119], v[134:137], v[192:195], v[116:119]
	v_mfma_f32_16x16x32_bf16 v[112:115], v[142:145], v[192:195], v[112:115]
	v_mfma_f32_16x16x32_bf16 v[108:111], v[134:137], v[200:203], v[108:111]
	v_mfma_f32_16x16x32_bf16 v[104:107], v[142:145], v[200:203], v[104:107]
	v_mfma_f32_16x16x32_bf16 v[100:103], v[134:137], v[208:211], v[100:103]
	v_mfma_f32_16x16x32_bf16 v[96:99], v[142:145], v[208:211], v[96:99]
	v_mfma_f32_16x16x32_bf16 v[92:95], v[146:149], v[180:183], v[92:95]
	v_mfma_f32_16x16x32_bf16 v[88:91], v[158:161], v[180:183], v[88:91]
	v_mfma_f32_16x16x32_bf16 v[84:87], v[146:149], v[188:191], v[84:87]
	v_mfma_f32_16x16x32_bf16 v[80:83], v[158:161], v[188:191], v[80:83]
	v_mfma_f32_16x16x32_bf16 v[76:79], v[146:149], v[196:199], v[76:79]
	v_mfma_f32_16x16x32_bf16 v[72:75], v[158:161], v[196:199], v[72:75]
	v_mfma_f32_16x16x32_bf16 v[68:71], v[146:149], v[204:207], v[68:71]
	v_mfma_f32_16x16x32_bf16 v[64:67], v[158:161], v[204:207], v[64:67]
	v_mfma_f32_16x16x32_bf16 v[92:95], v[150:153], v[184:187], v[92:95]
	v_mfma_f32_16x16x32_bf16 v[88:91], v[162:165], v[184:187], v[88:91]
	v_mfma_f32_16x16x32_bf16 v[84:87], v[150:153], v[192:195], v[84:87]
	v_mfma_f32_16x16x32_bf16 v[80:83], v[162:165], v[192:195], v[80:83]
	v_mfma_f32_16x16x32_bf16 v[76:79], v[150:153], v[200:203], v[76:79]
	v_mfma_f32_16x16x32_bf16 v[72:75], v[162:165], v[200:203], v[72:75]
	v_mfma_f32_16x16x32_bf16 v[68:71], v[150:153], v[208:211], v[68:71]
	v_mfma_f32_16x16x32_bf16 v[64:67], v[162:165], v[208:211], v[64:67]
	s_add_u32 s76, s76, 0x100
	s_addc_u32 s77, s77, 0
	s_add_u32 s78, s78, 0x100
	s_addc_u32 s79, s79, 0
	s_setprio 0
	s_barrier
	s_add_u32 s30, s22, 0x10000
	ds_read_b128 v[180:183], v177 offset:16384
	ds_read_b128 v[184:187], v177 offset:17408
	ds_read_b128 v[188:191], v177 offset:18432
	ds_read_b128 v[192:195], v177 offset:19456
	ds_read_b128 v[196:199], v177 offset:20480
	ds_read_b128 v[200:203], v177 offset:21504
	ds_read_b128 v[204:207], v177 offset:22528
	ds_read_b128 v[208:211], v177 offset:23552
	s_mov_b32 m0, s5
	s_nop 0
	global_load_lds_dwordx4 v128, s[22:23]
	s_mov_b32 m0, s12
	s_addc_u32 s31, s23, 0
	global_load_lds_dwordx4 v128, s[30:31]
	s_add_u32 s30, s22, 0x20000
	s_mov_b32 m0, s14
	s_addc_u32 s31, s23, 0
	global_load_lds_dwordx4 v128, s[30:31]
	s_add_u32 s30, s22, 0x30000
	s_mov_b32 m0, s15
	s_addc_u32 s31, s23, 0
	global_load_lds_dwordx4 v128, s[30:31]
	s_mov_b32 m0, s4
	s_nop 0
	global_load_lds_dwordx4 v172, s[8:9]
	s_add_u32 s30, s8, 0x20000
	s_mov_b32 m0, s24
	s_addc_u32 s31, s9, 0
	global_load_lds_dwordx4 v172, s[30:31]
	s_waitcnt vmcnt(8) lgkmcnt(0)
	s_barrier
; #define PG8_STAGE(bufoff, gbase, voff, p64) do { _Pragma("unroll") for (int _i = 0; _i < 2; ++_i) { \
;         const char* _gb = (const char*)(gbase) + (size_t)_i * (p64); const unsigned _la = ldsbase + (unsigned)(bufoff) + (unsigned)_i * 8192u; \
;         asm volatile("s_mov_b32 m0, %0\n\ts_nop 0\n\tglobal_load_lds_dwordx4 %1, %2" :: "s"(_la), "v"(voff), "s"(_gb) : "memory"); } } while (0)
; #define PG8_LDA(dst, b, h) do { _Pragma("unroll") for (int m = 0; m < 4; ++m) _Pragma("unroll") for (int k = 0; k < 2; ++k) dst[m][k] = *(const LAS bf16x8*)(lds + PG8_SA(b, h) + aoff + m * 2048 + k * 1024); } while (0)
; #define PG8_LDB(dst, b, h) do { _Pragma("unroll") for (int n = 0; n < 2; ++n) _Pragma("unroll") for (int k = 0; k < 2; ++k) dst[n][k] = *(const LAS bf16x8*)(lds + PG8_SB(b, h) + boff + n * 2048 + k * 1024); } while (0)
; #define PG8_MMA(ai, bj, At, Bt) do { __builtin_amdgcn_s_setprio(1); _Pragma("unroll") for (int m = 0; m < 4; ++m) _Pragma("unroll") for (int n = 0; n < 2; ++n) _Pragma("unroll") for (int k = 0; k < 2; ++k) \
;         acc[ai][bj][m][n] = __builtin_amdgcn_mfma_f32_16x16x32_bf16(Bt[n][k], At[m][k], acc[ai][bj][m][n], 0, 0, 0); __builtin_amdgcn_s_setprio(0); } while (0)
; #define PG8_WAIT_V(n) asm volatile("s_waitcnt vmcnt(" #n ")" ::: "memory")
; #define PG8_WAIT_L(n) asm volatile("s_waitcnt lgkmcnt(" #n ")" ::: "memory")
; #define PG8_BAR __builtin_amdgcn_s_barrier()
; #define PG8_SCHED __builtin_amdgcn_sched_barrier(0)
; template <class Epi, class Sched>
; __device__ __forceinline__ void gemm_phase(LAS unsigned char* lds, const Sched& S, const Epi& E) {
;     ...
;             PG8_WAIT_V(8); PG8_WAIT_L(0); PG8_BAR; PG8_MMA(1, 0, At, B0); PG8_MMA(1, 1, At, B1); PG8_BAR; PG8_SCHED;
;             PG8_LDB(B0, 1, 0); PG8_LDB(B1, 1, 1); PG8_SCHED; PG8_LDA(At, 1, 0); PG8_STAGE(PG8_SA(0, 1), a2 + hA2, vA2, hA2 / 2);
;             PG8_WAIT_V(8); PG8_WAIT_L(0); PG8_BAR; PG8_MMA(0, 0, At, B0); PG8_MMA(0, 1, At, B1); PG8_BAR; PG8_SCHED;
;             PG8_LDA(At, 1, 1); PG8_STAGE(PG8_SB(1, 0), b3, vB2, hB2 / 2); PG8_STAGE(PG8_SB(1, 1), b3 + hB2, vB2, hB2 / 2); PG8_STAGE(PG8_SA(1, 0), a3, vA2, hA2 / 2);
	s_setprio 1
	v_mfma_f32_16x16x32_bf16 v[60:63], v[130:133], v[180:183], v[60:63]
	v_mfma_f32_16x16x32_bf16 v[56:59], v[138:141], v[180:183], v[56:59]
	v_mfma_f32_16x16x32_bf16 v[52:55], v[130:133], v[188:191], v[52:55]
	v_mfma_f32_16x16x32_bf16 v[48:51], v[138:141], v[188:191], v[48:51]
	v_mfma_f32_16x16x32_bf16 v[44:47], v[130:133], v[196:199], v[44:47]
	v_mfma_f32_16x16x32_bf16 v[40:43], v[138:141], v[196:199], v[40:43]
	v_mfma_f32_16x16x32_bf16 v[36:39], v[130:133], v[204:207], v[36:39]
	v_mfma_f32_16x16x32_bf16 v[32:35], v[138:141], v[204:207], v[32:35]
	v_mfma_f32_16x16x32_bf16 v[60:63], v[134:137], v[184:187], v[60:63]
	v_mfma_f32_16x16x32_bf16 v[56:59], v[142:145], v[184:187], v[56:59]
	v_mfma_f32_16x16x32_bf16 v[52:55], v[134:137], v[192:195], v[52:55]
	v_mfma_f32_16x16x32_bf16 v[48:51], v[142:145], v[192:195], v[48:51]
	v_mfma_f32_16x16x32_bf16 v[44:47], v[134:137], v[200:203], v[44:47]
	v_mfma_f32_16x16x32_bf16 v[40:43], v[142:145], v[200:203], v[40:43]
	v_mfma_f32_16x16x32_bf16 v[36:39], v[134:137], v[208:211], v[36:39]
	v_mfma_f32_16x16x32_bf16 v[32:35], v[142:145], v[208:211], v[32:35]
	v_mfma_f32_16x16x32_bf16 v[28:31], v[146:149], v[180:183], v[28:31]
	v_mfma_f32_16x16x32_bf16 v[24:27], v[158:161], v[180:183], v[24:27]
	v_mfma_f32_16x16x32_bf16 v[20:23], v[146:149], v[188:191], v[20:23]
	v_mfma_f32_16x16x32_bf16 v[16:19], v[158:161], v[188:191], v[16:19]
	v_mfma_f32_16x16x32_bf16 v[12:15], v[146:149], v[196:199], v[12:15]
	v_mfma_f32_16x16x32_bf16 v[8:11], v[158:161], v[196:199], v[8:11]
	v_mfma_f32_16x16x32_bf16 v[4:7], v[146:149], v[204:207], v[4:7]
	v_mfma_f32_16x16x32_bf16 v[0:3], v[158:161], v[204:207], v[0:3]
	v_mfma_f32_16x16x32_bf16 v[28:31], v[150:153], v[184:187], v[28:31]
	v_mfma_f32_16x16x32_bf16 v[24:27], v[162:165], v[184:187], v[24:27]
	v_mfma_f32_16x16x32_bf16 v[20:23], v[150:153], v[192:195], v[20:23]
	v_mfma_f32_16x16x32_bf16 v[16:19], v[162:165], v[192:195], v[16:19]
	v_mfma_f32_16x16x32_bf16 v[12:15], v[150:153], v[200:203], v[12:15]
	v_mfma_f32_16x16x32_bf16 v[8:11], v[162:165], v[200:203], v[8:11]
	v_mfma_f32_16x16x32_bf16 v[4:7], v[150:153], v[208:211], v[4:7]
	v_mfma_f32_16x16x32_bf16 v[0:3], v[162:165], v[208:211], v[0:3]
	s_setprio 0
	s_barrier
	v_add_u32_e32 v142, 0x18000, v175
	v_add_u32_e32 v154, 0x1c000, v175
	ds_read_b128 v[130:133], v142
	ds_read_b128 v[134:137], v142 offset:1024
	ds_read_b128 v[138:141], v142 offset:2048
	ds_read_b128 v[142:145], v142 offset:3072
	ds_read_b128 v[146:149], v154
	ds_read_b128 v[150:153], v154 offset:1024
	ds_read_b128 v[158:161], v154 offset:2048
	ds_read_b128 v[162:165], v154 offset:3072
	ds_read_b128 v[180:183], v177 offset:32768
	ds_read_b128 v[184:187], v177 offset:33792
	ds_read_b128 v[188:191], v177 offset:34816
	ds_read_b128 v[192:195], v177 offset:35840
	ds_read_b128 v[196:199], v177 offset:36864
	ds_read_b128 v[200:203], v177 offset:37888
	ds_read_b128 v[204:207], v177 offset:38912
	ds_read_b128 v[208:211], v177 offset:39936
	s_add_u32 s30, s8, 0x40000
	s_mov_b32 m0, s33
	s_addc_u32 s31, s9, 0
	global_load_lds_dwordx4 v172, s[30:31]
	s_add_u32 s30, s8, 0x60000
	s_mov_b32 m0, s34
	s_addc_u32 s31, s9, 0
	global_load_lds_dwordx4 v172, s[30:31]
	s_waitcnt vmcnt(8) lgkmcnt(0)
	s_barrier
	s_setprio 1
	v_mfma_f32_16x16x32_bf16 v[124:127], v[130:133], v[180:183], v[124:127]
	v_mfma_f32_16x16x32_bf16 v[120:123], v[138:141], v[180:183], v[120:123]
	v_mfma_f32_16x16x32_bf16 v[116:119], v[130:133], v[188:191], v[116:119]
	v_mfma_f32_16x16x32_bf16 v[112:115], v[138:141], v[188:191], v[112:115]
	v_mfma_f32_16x16x32_bf16 v[108:111], v[130:133], v[196:199], v[108:111]
	v_mfma_f32_16x16x32_bf16 v[104:107], v[138:141], v[196:199], v[104:107]
	v_mfma_f32_16x16x32_bf16 v[100:103], v[130:133], v[204:207], v[100:103]
	v_mfma_f32_16x16x32_bf16 v[96:99], v[138:141], v[204:207], v[96:99]
	v_mfma_f32_16x16x32_bf16 v[124:127], v[134:137], v[184:187], v[124:127]
	v_mfma_f32_16x16x32_bf16 v[120:123], v[142:145], v[184:187], v[120:123]
	v_mfma_f32_16x16x32_bf16 v[116:119], v[134:137], v[192:195], v[116:119]
	v_mfma_f32_16x16x32_bf16 v[112:115], v[142:145], v[192:195], v[112:115]
	v_mfma_f32_16x16x32_bf16 v[108:111], v[134:137], v[200:203], v[108:111]
	v_mfma_f32_16x16x32_bf16 v[104:107], v[142:145], v[200:203], v[104:107]
	v_mfma_f32_16x16x32_bf16 v[100:103], v[134:137], v[208:211], v[100:103]
	v_mfma_f32_16x16x32_bf16 v[96:99], v[142:145], v[208:211], v[96:99]
	v_mfma_f32_16x16x32_bf16 v[92:95], v[146:149], v[180:183], v[92:95]
	v_mfma_f32_16x16x32_bf16 v[88:91], v[158:161], v[180:183], v[88:91]
	v_mfma_f32_16x16x32_bf16 v[84:87], v[146:149], v[188:191], v[84:87]
	v_mfma_f32_16x16x32_bf16 v[80:83], v[158:161], v[188:191], v[80:83]
	v_mfma_f32_16x16x32_bf16 v[76:79], v[146:149], v[196:199], v[76:79]
	v_mfma_f32_16x16x32_bf16 v[72:75], v[158:161], v[196:199], v[72:75]
	v_mfma_f32_16x16x32_bf16 v[68:71], v[146:149], v[204:207], v[68:71]
	v_mfma_f32_16x16x32_bf16 v[64:67], v[158:161], v[204:207], v[64:67]
	v_mfma_f32_16x16x32_bf16 v[92:95], v[150:153], v[184:187], v[92:95]
	v_mfma_f32_16x16x32_bf16 v[88:91], v[162:165], v[184:187], v[88:91]
	v_mfma_f32_16x16x32_bf16 v[84:87], v[150:153], v[192:195], v[84:87]
	v_mfma_f32_16x16x32_bf16 v[80:83], v[162:165], v[192:195], v[80:83]
	v_mfma_f32_16x16x32_bf16 v[76:79], v[150:153], v[200:203], v[76:79]
	v_mfma_f32_16x16x32_bf16 v[72:75], v[162:165], v[200:203], v[72:75]
	v_mfma_f32_16x16x32_bf16 v[68:71], v[150:153], v[208:211], v[68:71]
	v_mfma_f32_16x16x32_bf16 v[64:67], v[162:165], v[208:211], v[64:67]
	s_setprio 0
	s_barrier
; #define PG8_STAGE(bufoff, gbase, voff, p64) do { _Pragma("unroll") for (int _i = 0; _i < 2; ++_i) { \
;         const char* _gb = (const char*)(gbase) + (size_t)_i * (p64); const unsigned _la = ldsbase + (unsigned)(bufoff) + (unsigned)_i * 8192u; \
;         asm volatile("s_mov_b32 m0, %0\n\ts_nop 0\n\tglobal_load_lds_dwordx4 %1, %2" :: "s"(_la), "v"(voff), "s"(_gb) : "memory"); } } while (0)
; #define PG8_LDA(dst, b, h) do { _Pragma("unroll") for (int m = 0; m < 4; ++m) _Pragma("unroll") for (int k = 0; k < 2; ++k) dst[m][k] = *(const LAS bf16x8*)(lds + PG8_SA(b, h) + aoff + m * 2048 + k * 1024); } while (0)
; #define PG8_MMA(ai, bj, At, Bt) do { __builtin_amdgcn_s_setprio(1); _Pragma("unroll") for (int m = 0; m < 4; ++m) _Pragma("unroll") for (int n = 0; n < 2; ++n) _Pragma("unroll") for (int k = 0; k < 2; ++k) \
;         acc[ai][bj][m][n] = __builtin_amdgcn_mfma_f32_16x16x32_bf16(Bt[n][k], At[m][k], acc[ai][bj][m][n], 0, 0, 0); __builtin_amdgcn_s_setprio(0); } while (0)
; #define PG8_WAIT_V(n) asm volatile("s_waitcnt vmcnt(" #n ")" ::: "memory")
; #define PG8_WAIT_L(n) asm volatile("s_waitcnt lgkmcnt(" #n ")" ::: "memory")
; #define PG8_BAR __builtin_amdgcn_s_barrier()
; #define PG8_SCHED __builtin_amdgcn_sched_barrier(0)
; template <class Epi, class Sched>
; __device__ __forceinline__ void gemm_phase(LAS unsigned char* lds, const Sched& S, const Epi& E) {
;     ...
;             PG8_LDA(At, 1, 1); PG8_STAGE(PG8_SB(1, 0), b3, vB2, hB2 / 2); PG8_STAGE(PG8_SB(1, 1), b3 + hB2, vB2, hB2 / 2); PG8_STAGE(PG8_SA(1, 0), a3, vA2, hA2 / 2);
;             PG8_WAIT_V(8); PG8_WAIT_L(0); PG8_BAR; PG8_MMA(1, 0, At, B0); PG8_MMA(1, 1, At, B1); PG8_BAR; PG8_SCHED;
;         }
;         if (wr == 0) PG8_BAR;
	s_add_u32 s30, s22, 0x80
	s_addc_u32 s31, s23, 0
	ds_read_b128 v[180:183], v177 offset:49152
	ds_read_b128 v[184:187], v177 offset:50176
	ds_read_b128 v[188:191], v177 offset:51200
	ds_read_b128 v[192:195], v177 offset:52224
	ds_read_b128 v[196:199], v177 offset:53248
	ds_read_b128 v[200:203], v177 offset:54272
	ds_read_b128 v[204:207], v177 offset:55296
	ds_read_b128 v[208:211], v177 offset:56320
	s_mov_b32 m0, s51
	s_nop 0
	global_load_lds_dwordx4 v128, s[30:31]
	s_add_u32 s30, s22, 0x10080
	s_mov_b32 m0, s61
	s_addc_u32 s31, s23, 0
	global_load_lds_dwordx4 v128, s[30:31]
	s_add_u32 s30, s22, 0x20080
	s_mov_b32 m0, s64
	s_addc_u32 s31, s23, 0
	global_load_lds_dwordx4 v128, s[30:31]
	s_add_u32 s22, s22, 0x30080
	s_mov_b32 m0, s65
	s_addc_u32 s23, s23, 0
	global_load_lds_dwordx4 v128, s[22:23]
	s_mov_b32 m0, s62
	s_nop 0
	global_load_lds_dwordx4 v172, s[16:17]
	s_add_u32 s8, s8, 0x20080
	s_mov_b32 m0, s63
	s_addc_u32 s9, s9, 0
	global_load_lds_dwordx4 v172, s[8:9]
	s_waitcnt vmcnt(8) lgkmcnt(0)
	s_barrier
	s_setprio 1
	v_mfma_f32_16x16x32_bf16 v[60:63], v[130:133], v[180:183], v[60:63]
	v_mfma_f32_16x16x32_bf16 v[56:59], v[138:141], v[180:183], v[56:59]
	v_mfma_f32_16x16x32_bf16 v[52:55], v[130:133], v[188:191], v[52:55]
	v_mfma_f32_16x16x32_bf16 v[48:51], v[138:141], v[188:191], v[48:51]
	v_mfma_f32_16x16x32_bf16 v[44:47], v[130:133], v[196:199], v[44:47]
	v_mfma_f32_16x16x32_bf16 v[40:43], v[138:141], v[196:199], v[40:43]
	v_mfma_f32_16x16x32_bf16 v[36:39], v[130:133], v[204:207], v[36:39]
	v_mfma_f32_16x16x32_bf16 v[32:35], v[138:141], v[204:207], v[32:35]
	v_mfma_f32_16x16x32_bf16 v[60:63], v[134:137], v[184:187], v[60:63]
	v_mfma_f32_16x16x32_bf16 v[56:59], v[142:145], v[184:187], v[56:59]
	v_mfma_f32_16x16x32_bf16 v[52:55], v[134:137], v[192:195], v[52:55]
	v_mfma_f32_16x16x32_bf16 v[48:51], v[142:145], v[192:195], v[48:51]
	v_mfma_f32_16x16x32_bf16 v[44:47], v[134:137], v[200:203], v[44:47]
	v_mfma_f32_16x16x32_bf16 v[40:43], v[142:145], v[200:203], v[40:43]
	v_mfma_f32_16x16x32_bf16 v[36:39], v[134:137], v[208:211], v[36:39]
	v_mfma_f32_16x16x32_bf16 v[32:35], v[142:145], v[208:211], v[32:35]
	v_mfma_f32_16x16x32_bf16 v[28:31], v[146:149], v[180:183], v[28:31]
	v_mfma_f32_16x16x32_bf16 v[24:27], v[158:161], v[180:183], v[24:27]
	v_mfma_f32_16x16x32_bf16 v[20:23], v[146:149], v[188:191], v[20:23]
	v_mfma_f32_16x16x32_bf16 v[16:19], v[158:161], v[188:191], v[16:19]
	v_mfma_f32_16x16x32_bf16 v[12:15], v[146:149], v[196:199], v[12:15]
	v_mfma_f32_16x16x32_bf16 v[8:11], v[158:161], v[196:199], v[8:11]
	v_mfma_f32_16x16x32_bf16 v[4:7], v[146:149], v[204:207], v[4:7]
	v_mfma_f32_16x16x32_bf16 v[0:3], v[158:161], v[204:207], v[0:3]
	v_mfma_f32_16x16x32_bf16 v[28:31], v[150:153], v[184:187], v[28:31]
	v_mfma_f32_16x16x32_bf16 v[24:27], v[162:165], v[184:187], v[24:27]
	v_mfma_f32_16x16x32_bf16 v[20:23], v[150:153], v[192:195], v[20:23]
	v_mfma_f32_16x16x32_bf16 v[16:19], v[162:165], v[192:195], v[16:19]
	v_mfma_f32_16x16x32_bf16 v[12:15], v[150:153], v[200:203], v[12:15]
	v_mfma_f32_16x16x32_bf16 v[8:11], v[162:165], v[200:203], v[8:11]
	v_mfma_f32_16x16x32_bf16 v[4:7], v[150:153], v[208:211], v[4:7]
	v_mfma_f32_16x16x32_bf16 v[0:3], v[162:165], v[208:211], v[0:3]
	s_setprio 0
	s_barrier
	s_cmp_ge_u32 s80, s7
	s_mov_b32 s8, s80
	s_cbranch_scc0 .LBB0_844
	s_and_b64 vcc, exec, s[10:11]
	s_cbranch_vccz .LBB0_847
	s_barrier

; __device__ __forceinline__ float ex2(float x) { return __builtin_amdgcn_exp2f(x); }
;     __device__ __forceinline__ bool operator()(EPI_ARGS) const {
;         const int h = u.z; const float lgf = dec[h], lgb = dec[4 + h];
;         const float c1 = u.kind == 1 ? lgf : 0.f, c2 = u.kind == 1 ? -lgb : (u.kind == 2 ? lgb : 0.f);
; #pragma unroll
;         for (int ai = 0; ai < 2; ++ai)
; #pragma unroll
;             for (int m = 0; m < 4; ++m) {
;                 const int i = u.pm * 256 + ROWLOC(ai, m);
;                 const float s = ex2((float)(i + 1) * c1 + (float)(CH - i) * c2);
; #pragma unroll
;                 for (int bj = 0; bj < 2; ++bj)
; #pragma unroll
;                     for (int n = 0; n < 2; ++n)
; #pragma unroll
;                         for (int e = 0; e < 4; ++e) asm("s_nop 0\n\tv_mul_f32 %0, %0, %1" : "+v"(acc[ai][bj][m][n][e]) : "v"(s));
;             }
.LBB0_849:
	s_ashr_i32 s73, s72, 31
	s_lshl_b64 s[8:9], s[72:73], 2
	s_add_u32 s8, s44, s8
	s_addc_u32 s9, s45, s9
	global_load_dword v130, v129, s[8:9]
	global_load_dword v131, v129, s[8:9] offset:16
	s_cmp_eq_u32 s68, 1
	s_cselect_b64 vcc, -1, 0
	s_cmp_eq_u32 s68, 2
	s_cselect_b64 s[8:9], -1, 0
	v_add_u32_e32 v138, s47, v138
	s_lshl_b32 s16, s50, 8
	v_add_u32_e32 v140, 16, v138
	v_add_u32_e32 v142, 32, v138
	v_add_u32_e32 v144, 48, v138
	v_add_u32_e32 v146, 0x80, v138
	v_add_u32_e32 v148, 0x90, v138
	v_add_u32_e32 v150, 0xa0, v138
	v_add_u32_e32 v152, 0xb0, v138
	s_cmp_eq_u32 s68, 3
	s_waitcnt vmcnt(1)
	v_cndmask_b32_e32 v141, 0, v130, vcc
	s_waitcnt vmcnt(0)
	v_cndmask_b32_e64 v130, 0, v131, s[8:9]
	v_cndmask_b32_e64 v143, v130, -v131, vcc
	v_add_u32_e32 v130, s16, v138
	v_add_u32_e32 v131, 1, v130
	v_sub_u32_e32 v130, 0x200, v130
	v_cvt_f32_i32_e32 v130, v130
	v_cvt_f32_i32_e32 v131, v131
	s_cselect_b64 s[8:9], -1, 0
	s_cmp_lg_u32 s68, 3
	v_mul_f32_e32 v130, v143, v130
	v_fmac_f32_e32 v130, v141, v131
	v_exp_f32_e32 v130, v130
	s_nop 0
	v_pk_mul_f32 v[124:125], v[124:125], v[130:131] op_sel_hi:[1,0]
	v_pk_mul_f32 v[126:127], v[126:127], v[130:131] op_sel_hi:[1,0]
	v_pk_mul_f32 v[120:121], v[120:121], v[130:131] op_sel_hi:[1,0]
	v_pk_mul_f32 v[122:123], v[122:123], v[130:131] op_sel_hi:[1,0]
	v_pk_mul_f32 v[92:93], v[92:93], v[130:131] op_sel_hi:[1,0]
	v_pk_mul_f32 v[94:95], v[94:95], v[130:131] op_sel_hi:[1,0]
	v_pk_mul_f32 v[88:89], v[88:89], v[130:131] op_sel_hi:[1,0]
	v_pk_mul_f32 v[90:91], v[90:91], v[130:131] op_sel_hi:[1,0]
	v_add_u32_e32 v130, s16, v140
	v_add_u32_e32 v131, 1, v130
	v_sub_u32_e32 v130, 0x200, v130
	v_cvt_f32_i32_e32 v130, v130
	v_cvt_f32_i32_e32 v131, v131
	v_mul_f32_e32 v130, v143, v130
	v_fmac_f32_e32 v130, v141, v131
	v_exp_f32_e32 v130, v130
	s_nop 0
	v_pk_mul_f32 v[116:117], v[116:117], v[130:131] op_sel_hi:[1,0]
	v_pk_mul_f32 v[118:119], v[118:119], v[130:131] op_sel_hi:[1,0]
	v_pk_mul_f32 v[112:113], v[112:113], v[130:131] op_sel_hi:[1,0]
	v_pk_mul_f32 v[114:115], v[114:115], v[130:131] op_sel_hi:[1,0]
	v_pk_mul_f32 v[84:85], v[84:85], v[130:131] op_sel_hi:[1,0]
	v_pk_mul_f32 v[86:87], v[86:87], v[130:131] op_sel_hi:[1,0]
	v_pk_mul_f32 v[80:81], v[80:81], v[130:131] op_sel_hi:[1,0]
	v_pk_mul_f32 v[82:83], v[82:83], v[130:131] op_sel_hi:[1,0]
	v_add_u32_e32 v130, s16, v142
	v_add_u32_e32 v131, 1, v130
	v_sub_u32_e32 v130, 0x200, v130
	v_cvt_f32_i32_e32 v130, v130
	v_cvt_f32_i32_e32 v131, v131
	v_mul_f32_e32 v130, v143, v130
	v_fmac_f32_e32 v130, v141, v131
	v_exp_f32_e32 v130, v130
	s_nop 0
	v_pk_mul_f32 v[108:109], v[108:109], v[130:131] op_sel_hi:[1,0]
	v_pk_mul_f32 v[110:111], v[110:111], v[130:131] op_sel_hi:[1,0]
	v_pk_mul_f32 v[104:105], v[104:105], v[130:131] op_sel_hi:[1,0]
	v_pk_mul_f32 v[106:107], v[106:107], v[130:131] op_sel_hi:[1,0]
	v_pk_mul_f32 v[76:77], v[76:77], v[130:131] op_sel_hi:[1,0]
	v_pk_mul_f32 v[78:79], v[78:79], v[130:131] op_sel_hi:[1,0]
	v_pk_mul_f32 v[72:73], v[72:73], v[130:131] op_sel_hi:[1,0]
	v_pk_mul_f32 v[74:75], v[74:75], v[130:131] op_sel_hi:[1,0]
	v_add_u32_e32 v130, s16, v144
	v_add_u32_e32 v131, 1, v130
	v_sub_u32_e32 v130, 0x200, v130
	v_cvt_f32_i32_e32 v130, v130
	v_cvt_f32_i32_e32 v131, v131
	v_mul_f32_e32 v130, v143, v130
	v_fmac_f32_e32 v130, v141, v131
	v_exp_f32_e32 v130, v130
	s_nop 0
	v_pk_mul_f32 v[100:101], v[100:101], v[130:131] op_sel_hi:[1,0]
	v_pk_mul_f32 v[102:103], v[102:103], v[130:131] op_sel_hi:[1,0]
	v_pk_mul_f32 v[96:97], v[96:97], v[130:131] op_sel_hi:[1,0]
	v_pk_mul_f32 v[98:99], v[98:99], v[130:131] op_sel_hi:[1,0]
	v_pk_mul_f32 v[68:69], v[68:69], v[130:131] op_sel_hi:[1,0]
	v_pk_mul_f32 v[70:71], v[70:71], v[130:131] op_sel_hi:[1,0]
	v_pk_mul_f32 v[64:65], v[64:65], v[130:131] op_sel_hi:[1,0]
	v_pk_mul_f32 v[66:67], v[66:67], v[130:131] op_sel_hi:[1,0]
	v_add_u32_e32 v130, s16, v146
	v_add_u32_e32 v131, 1, v130
	v_sub_u32_e32 v130, 0x200, v130
	v_cvt_f32_i32_e32 v130, v130
	v_cvt_f32_i32_e32 v131, v131
	v_mul_f32_e32 v130, v143, v130
	v_fmac_f32_e32 v130, v141, v131
	v_exp_f32_e32 v130, v130
	s_nop 0
	v_pk_mul_f32 v[60:61], v[60:61], v[130:131] op_sel_hi:[1,0]
	v_pk_mul_f32 v[62:63], v[62:63], v[130:131] op_sel_hi:[1,0]
	v_pk_mul_f32 v[56:57], v[56:57], v[130:131] op_sel_hi:[1,0]
	v_pk_mul_f32 v[58:59], v[58:59], v[130:131] op_sel_hi:[1,0]
	v_pk_mul_f32 v[28:29], v[28:29], v[130:131] op_sel_hi:[1,0]
	v_pk_mul_f32 v[30:31], v[30:31], v[130:131] op_sel_hi:[1,0]
	v_pk_mul_f32 v[24:25], v[24:25], v[130:131] op_sel_hi:[1,0]
	v_pk_mul_f32 v[26:27], v[26:27], v[130:131] op_sel_hi:[1,0]
	v_add_u32_e32 v130, s16, v148
	v_add_u32_e32 v131, 1, v130
	v_sub_u32_e32 v130, 0x200, v130
	v_cvt_f32_i32_e32 v130, v130
	v_cvt_f32_i32_e32 v131, v131
	v_mul_f32_e32 v130, v143, v130
	v_fmac_f32_e32 v130, v141, v131
	v_exp_f32_e32 v130, v130
	s_nop 0
	v_pk_mul_f32 v[52:53], v[52:53], v[130:131] op_sel_hi:[1,0]
	v_pk_mul_f32 v[54:55], v[54:55], v[130:131] op_sel_hi:[1,0]
	v_pk_mul_f32 v[48:49], v[48:49], v[130:131] op_sel_hi:[1,0]
	v_pk_mul_f32 v[50:51], v[50:51], v[130:131] op_sel_hi:[1,0]
	v_pk_mul_f32 v[20:21], v[20:21], v[130:131] op_sel_hi:[1,0]
	v_pk_mul_f32 v[22:23], v[22:23], v[130:131] op_sel_hi:[1,0]
	v_pk_mul_f32 v[16:17], v[16:17], v[130:131] op_sel_hi:[1,0]
	v_pk_mul_f32 v[18:19], v[18:19], v[130:131] op_sel_hi:[1,0]
	v_add_u32_e32 v130, s16, v150
	v_add_u32_e32 v131, 1, v130
	v_sub_u32_e32 v130, 0x200, v130
	v_cvt_f32_i32_e32 v130, v130
	v_cvt_f32_i32_e32 v131, v131
	v_mul_f32_e32 v130, v143, v130
	v_fmac_f32_e32 v130, v141, v131
	v_exp_f32_e32 v130, v130
	s_nop 0
	v_pk_mul_f32 v[44:45], v[44:45], v[130:131] op_sel_hi:[1,0]
	v_pk_mul_f32 v[46:47], v[46:47], v[130:131] op_sel_hi:[1,0]
	v_pk_mul_f32 v[40:41], v[40:41], v[130:131] op_sel_hi:[1,0]
	v_pk_mul_f32 v[42:43], v[42:43], v[130:131] op_sel_hi:[1,0]
	v_pk_mul_f32 v[12:13], v[12:13], v[130:131] op_sel_hi:[1,0]
	v_pk_mul_f32 v[14:15], v[14:15], v[130:131] op_sel_hi:[1,0]
	v_pk_mul_f32 v[8:9], v[8:9], v[130:131] op_sel_hi:[1,0]
	v_pk_mul_f32 v[10:11], v[10:11], v[130:131] op_sel_hi:[1,0]
	v_add_u32_e32 v130, s16, v152
	v_add_u32_e32 v131, 1, v130
	v_sub_u32_e32 v130, 0x200, v130
	v_cvt_f32_i32_e32 v130, v130
	v_cvt_f32_i32_e32 v131, v131
	v_mul_f32_e32 v130, v143, v130
	v_fmac_f32_e32 v130, v141, v131
	v_exp_f32_e32 v130, v130
	s_nop 0
	v_pk_mul_f32 v[36:37], v[36:37], v[130:131] op_sel_hi:[1,0]
	v_pk_mul_f32 v[38:39], v[38:39], v[130:131] op_sel_hi:[1,0]
	v_pk_mul_f32 v[32:33], v[32:33], v[130:131] op_sel_hi:[1,0]
	v_pk_mul_f32 v[34:35], v[34:35], v[130:131] op_sel_hi:[1,0]
	v_pk_mul_f32 v[4:5], v[4:5], v[130:131] op_sel_hi:[1,0]
	v_pk_mul_f32 v[6:7], v[6:7], v[130:131] op_sel_hi:[1,0]
	v_pk_mul_f32 v[0:1], v[0:1], v[130:131] op_sel_hi:[1,0]
	v_pk_mul_f32 v[2:3], v[2:3], v[130:131] op_sel_hi:[1,0]
	s_cbranch_scc1 .LBB0_851
; __device__ __forceinline__ u32x4 pack8(const f32x4 a, const f32x4 b) { u32x4 w; w.x = pk2(a[0], a[1]); w.y = pk2(a[2], a[3]); w.z = pk2(b[0], b[1]); w.w = pk2(b[2], b[3]); return w; }
;     __device__ __forceinline__ bool operator()(EPI_ARGS) const {
;     ...
;         if (u.kind == 3) {
; #pragma unroll
;             for (int ai = 0; ai < 2; ++ai)
; #pragma unroll
;                 for (int m = 0; m < 4; ++m) {
;                     const size_t row = (size_t)u.pn * CH + u.pm * 256 + ROWLOC(ai, m);
; #pragma unroll
;                     for (int bj = 0; bj < 2; ++bj) *(u32x4*)(o + row * 2048 + h * 512 + u.w * 256 + COLLOC(bj)) = pack8(acc[ai][bj][m][0], acc[ai][bj][m][1]);
;                 }
	s_lshl_b32 s22, s72, 9
	s_ashr_i32 s7, s6, 31
	s_ashr_i32 s23, s22, 31
	s_lshl_b64 s[30:31], s[6:7], 9
	s_ashr_i32 s7, s16, 31
	s_add_u32 s16, s30, s16
	v_lshl_add_u32 v134, v139, 3, s48
	v_ashrrev_i32_e32 v139, 31, v138
	s_addc_u32 s17, s31, s7
	v_lshl_add_u64 v[130:131], s[16:17], 0, v[138:139]
	v_lshlrev_b64 v[136:137], 12, v[130:131]
	v_lshlrev_b32_e32 v138, 8, v178
	v_lshl_add_u64 v[136:137], s[54:55], 0, v[136:137]
	s_lshl_b64 s[22:23], s[22:23], 1
	v_ashrrev_i32_e32 v139, 31, v138
	v_lshl_add_u64 v[136:137], v[136:137], 0, s[22:23]
	v_lshlrev_b64 v[138:139], 1, v[138:139]
	v_ashrrev_i32_e32 v135, 31, v134
	v_lshl_add_u64 v[136:137], v[136:137], 0, v[138:139]
	v_lshlrev_b64 v[154:155], 1, v[134:135]
	v_cvt_pk_bf16_f32 v130, v124, v125
	v_cvt_pk_bf16_f32 v131, v126, v127
	v_lshl_add_u64 v[134:135], v[136:137], 0, v[154:155]
	v_cvt_pk_bf16_f32 v132, v120, v121
	v_cvt_pk_bf16_f32 v133, v122, v123
	global_store_dwordx4 v[134:135], v[130:133], off
	v_ashrrev_i32_e32 v141, 31, v140
	v_ashrrev_i32_e32 v143, 31, v142
	v_cvt_pk_bf16_f32 v130, v92, v93
	v_cvt_pk_bf16_f32 v131, v94, v95
	v_cvt_pk_bf16_f32 v132, v88, v89
	v_cvt_pk_bf16_f32 v133, v90, v91
	global_store_dwordx4 v[134:135], v[130:133], off offset:256
	v_ashrrev_i32_e32 v145, 31, v144
	v_ashrrev_i32_e32 v147, 31, v146
	v_lshl_add_u64 v[130:131], s[16:17], 0, v[140:141]
	v_lshlrev_b64 v[134:135], 12, v[130:131]
	v_lshl_add_u64 v[134:135], s[54:55], 0, v[134:135]
	v_lshl_add_u64 v[134:135], v[134:135], 0, s[22:23]
	v_lshl_add_u64 v[134:135], v[134:135], 0, v[138:139]
	v_cvt_pk_bf16_f32 v130, v116, v117
	v_cvt_pk_bf16_f32 v131, v118, v119
	v_lshl_add_u64 v[134:135], v[134:135], 0, v[154:155]
	v_cvt_pk_bf16_f32 v132, v112, v113
	v_cvt_pk_bf16_f32 v133, v114, v115
	global_store_dwordx4 v[134:135], v[130:133], off
	v_ashrrev_i32_e32 v149, 31, v148
	v_ashrrev_i32_e32 v151, 31, v150
	v_cvt_pk_bf16_f32 v130, v84, v85
	v_cvt_pk_bf16_f32 v131, v86, v87
	v_cvt_pk_bf16_f32 v132, v80, v81
	v_cvt_pk_bf16_f32 v133, v82, v83
	global_store_dwordx4 v[134:135], v[130:133], off offset:256
	v_ashrrev_i32_e32 v153, 31, v152
	s_nop 0
	v_lshl_add_u64 v[130:131], s[16:17], 0, v[142:143]
	v_lshlrev_b64 v[134:135], 12, v[130:131]
	v_lshl_add_u64 v[134:135], s[54:55], 0, v[134:135]
	v_lshl_add_u64 v[134:135], v[134:135], 0, s[22:23]
	v_lshl_add_u64 v[134:135], v[134:135], 0, v[138:139]
	v_cvt_pk_bf16_f32 v130, v108, v109
	v_cvt_pk_bf16_f32 v131, v110, v111
	v_lshl_add_u64 v[134:135], v[134:135], 0, v[154:155]
	v_cvt_pk_bf16_f32 v132, v104, v105
	v_cvt_pk_bf16_f32 v133, v106, v107
	global_store_dwordx4 v[134:135], v[130:133], off
	s_nop 1
	v_cvt_pk_bf16_f32 v130, v76, v77
	v_cvt_pk_bf16_f32 v131, v78, v79
	v_cvt_pk_bf16_f32 v132, v72, v73
	v_cvt_pk_bf16_f32 v133, v74, v75
	global_store_dwordx4 v[134:135], v[130:133], off offset:256
	s_nop 1
	v_lshl_add_u64 v[130:131], s[16:17], 0, v[144:145]
	v_lshlrev_b64 v[134:135], 12, v[130:131]
	v_lshl_add_u64 v[134:135], s[54:55], 0, v[134:135]
	v_lshl_add_u64 v[134:135], v[134:135], 0, s[22:23]
	v_lshl_add_u64 v[134:135], v[134:135], 0, v[138:139]
	v_cvt_pk_bf16_f32 v130, v100, v101
	v_cvt_pk_bf16_f32 v131, v102, v103
	v_lshl_add_u64 v[134:135], v[134:135], 0, v[154:155]
	v_cvt_pk_bf16_f32 v132, v96, v97
	v_cvt_pk_bf16_f32 v133, v98, v99
	global_store_dwordx4 v[134:135], v[130:133], off
	s_nop 1
	v_cvt_pk_bf16_f32 v130, v68, v69
	v_cvt_pk_bf16_f32 v131, v70, v71
	v_cvt_pk_bf16_f32 v132, v64, v65
	v_cvt_pk_bf16_f32 v133, v66, v67
	global_store_dwordx4 v[134:135], v[130:133], off offset:256
	s_nop 1
	v_lshl_add_u64 v[130:131], s[16:17], 0, v[146:147]
	v_lshlrev_b64 v[134:135], 12, v[130:131]
	v_lshl_add_u64 v[134:135], s[54:55], 0, v[134:135]
	v_lshl_add_u64 v[134:135], v[134:135], 0, s[22:23]
	v_lshl_add_u64 v[134:135], v[134:135], 0, v[138:139]
	v_cvt_pk_bf16_f32 v130, v60, v61
	v_cvt_pk_bf16_f32 v131, v62, v63
	v_lshl_add_u64 v[134:135], v[134:135], 0, v[154:155]
	v_cvt_pk_bf16_f32 v132, v56, v57
	v_cvt_pk_bf16_f32 v133, v58, v59
	global_store_dwordx4 v[134:135], v[130:133], off
	s_nop 1
	v_cvt_pk_bf16_f32 v130, v28, v29
	v_cvt_pk_bf16_f32 v131, v30, v31
	v_cvt_pk_bf16_f32 v132, v24, v25
	v_cvt_pk_bf16_f32 v133, v26, v27
	global_store_dwordx4 v[134:135], v[130:133], off offset:256
	s_nop 1
	v_lshl_add_u64 v[130:131], s[16:17], 0, v[148:149]
	v_lshlrev_b64 v[134:135], 12, v[130:131]
	v_lshl_add_u64 v[134:135], s[54:55], 0, v[134:135]
	v_lshl_add_u64 v[134:135], v[134:135], 0, s[22:23]
	v_lshl_add_u64 v[134:135], v[134:135], 0, v[138:139]
	v_cvt_pk_bf16_f32 v130, v52, v53
	v_cvt_pk_bf16_f32 v131, v54, v55
	v_lshl_add_u64 v[134:135], v[134:135], 0, v[154:155]
	v_cvt_pk_bf16_f32 v132, v48, v49
	v_cvt_pk_bf16_f32 v133, v50, v51
	global_store_dwordx4 v[134:135], v[130:133], off
	s_nop 1
	v_cvt_pk_bf16_f32 v130, v20, v21
	v_cvt_pk_bf16_f32 v131, v22, v23
	v_cvt_pk_bf16_f32 v132, v16, v17
	v_cvt_pk_bf16_f32 v133, v18, v19
	global_store_dwordx4 v[134:135], v[130:133], off offset:256
	s_nop 1
	v_lshl_add_u64 v[130:131], s[16:17], 0, v[150:151]
	v_lshlrev_b64 v[134:135], 12, v[130:131]
	v_lshl_add_u64 v[134:135], s[54:55], 0, v[134:135]
	v_lshl_add_u64 v[134:135], v[134:135], 0, s[22:23]
	v_lshl_add_u64 v[134:135], v[134:135], 0, v[138:139]
	v_cvt_pk_bf16_f32 v130, v44, v45
	v_cvt_pk_bf16_f32 v131, v46, v47
	v_lshl_add_u64 v[134:135], v[134:135], 0, v[154:155]
	v_cvt_pk_bf16_f32 v132, v40, v41
	v_cvt_pk_bf16_f32 v133, v42, v43
	global_store_dwordx4 v[134:135], v[130:133], off
	s_nop 1
	v_cvt_pk_bf16_f32 v130, v12, v13
	v_cvt_pk_bf16_f32 v131, v14, v15
	v_cvt_pk_bf16_f32 v132, v8, v9
	v_cvt_pk_bf16_f32 v133, v10, v11
	global_store_dwordx4 v[134:135], v[130:133], off offset:256
	s_nop 1
	v_lshl_add_u64 v[130:131], s[16:17], 0, v[152:153]
	v_lshlrev_b64 v[134:135], 12, v[130:131]
	v_lshl_add_u64 v[134:135], s[54:55], 0, v[134:135]
	v_lshl_add_u64 v[134:135], v[134:135], 0, s[22:23]
	v_lshl_add_u64 v[134:135], v[134:135], 0, v[138:139]
	v_cvt_pk_bf16_f32 v130, v36, v37
	v_cvt_pk_bf16_f32 v131, v38, v39
	v_cvt_pk_bf16_f32 v132, v32, v33
	v_cvt_pk_bf16_f32 v133, v34, v35
	v_lshl_add_u64 v[134:135], v[134:135], 0, v[154:155]
	global_store_dwordx4 v[134:135], v[130:133], off
	s_nop 1
	v_cvt_pk_bf16_f32 v130, v4, v5
	v_cvt_pk_bf16_f32 v131, v6, v7
	v_cvt_pk_bf16_f32 v132, v0, v1
	v_cvt_pk_bf16_f32 v133, v2, v3
	global_store_dwordx4 v[134:135], v[130:133], off offset:256

; #define PG8_STAGE(bufoff, gbase, voff, p64) do { _Pragma("unroll") for (int _i = 0; _i < 2; ++_i) { \
;         const char* _gb = (const char*)(gbase) + (size_t)_i * (p64); const unsigned _la = ldsbase + (unsigned)(bufoff) + (unsigned)_i * 8192u; \
;         asm volatile("s_mov_b32 m0, %0\n\ts_nop 0\n\tglobal_load_lds_dwordx4 %1, %2" :: "s"(_la), "v"(voff), "s"(_gb) : "memory"); } } while (0)
; #define PG8_LDA(dst, b, h) do { _Pragma("unroll") for (int m = 0; m < 4; ++m) _Pragma("unroll") for (int k = 0; k < 2; ++k) dst[m][k] = *(const LAS bf16x8*)(lds + PG8_SA(b, h) + aoff + m * 2048 + k * 1024); } while (0)
; #define PG8_LDB(dst, b, h) do { _Pragma("unroll") for (int n = 0; n < 2; ++n) _Pragma("unroll") for (int k = 0; k < 2; ++k) dst[n][k] = *(const LAS bf16x8*)(lds + PG8_SB(b, h) + boff + n * 2048 + k * 1024); } while (0)
; #define PG8_MMA(ai, bj, At, Bt) do { __builtin_amdgcn_s_setprio(1); _Pragma("unroll") for (int m = 0; m < 4; ++m) _Pragma("unroll") for (int n = 0; n < 2; ++n) _Pragma("unroll") for (int k = 0; k < 2; ++k) \
;         acc[ai][bj][m][n] = __builtin_amdgcn_mfma_f32_16x16x32_bf16(Bt[n][k], At[m][k], acc[ai][bj][m][n], 0, 0, 0); __builtin_amdgcn_s_setprio(0); } while (0)
; #define PG8_WAIT_V(n) asm volatile("s_waitcnt vmcnt(" #n ")" ::: "memory")
; #define PG8_WAIT_L(n) asm volatile("s_waitcnt lgkmcnt(" #n ")" ::: "memory")
; #define PG8_BAR __builtin_amdgcn_s_barrier()
; template <class Epi, class Sched>
; __device__ __forceinline__ void gemm_phase(LAS unsigned char* lds, const Sched& S, const Epi& E) {
;     ...
;     f32x4 acc[2][2][4][2];
; #pragma unroll
;     for (int a = 0; a < 2; ++a)
; #pragma unroll
;         for (int b = 0; b < 2; ++b)
; #pragma unroll
;             for (int m = 0; m < 4; ++m)
; #pragma unroll
;                 for (int n = 0; n < 2; ++n) acc[a][b][m][n] = (f32x4){0.f, 0.f, 0.f, 0.f};
;     ...
;             PG8_LDB(B0, 0, 0); PG8_LDB(B1, 0, 1); PG8_SCHED; PG8_LDA(At, 0, 0); PG8_STAGE(PG8_SA(1, 1), a1 + hA, voffA, hA / 2);
;             PG8_WAIT_V(8); PG8_WAIT_L(0); PG8_BAR; PG8_MMA(0, 0, At, B0); PG8_MMA(0, 1, At, B1); PG8_BAR; PG8_SCHED;
;             PG8_LDA(At, 0, 1); PG8_STAGE(PG8_SB(0, 0), b2, vB2, hB2 / 2); PG8_STAGE(PG8_SB(0, 1), b2 + hB2, vB2, hB2 / 2); PG8_STAGE(PG8_SA(0, 0), a2, vA2, hA2 / 2);
;             PG8_WAIT_V(8); PG8_WAIT_L(0); PG8_BAR; PG8_MMA(1, 0, At, B0); PG8_MMA(1, 1, At, B1); PG8_BAR; PG8_SCHED;
.LBB0_980:
	s_add_u32 s26, s26, 0x40080
	s_addc_u32 s27, s27, 0
	s_add_u32 s62, s38, 0x100
	s_addc_u32 s63, s39, 0
	s_mov_b32 s65, -2
	s_waitcnt vmcnt(3)
	s_waitcnt vmcnt(2)
	s_waitcnt vmcnt(1)
	s_waitcnt vmcnt(0)
	ds_read_b128 v[112:115], v162
	ds_read_b128 v[116:119], v162 offset:1024
	ds_read_b128 v[140:143], v162 offset:2048
	ds_read_b128 v[144:147], v162 offset:3072
	ds_read_b128 v[148:151], v163
	ds_read_b128 v[152:155], v163 offset:1024
	ds_read_b128 v[168:171], v163 offset:2048
	ds_read_b128 v[172:175], v163 offset:3072
	s_add_u32 s30, s26, 0xfffc0080
	s_addc_u32 s38, s27, -1
	s_cmp_eq_u32 s65, 12
	s_cselect_b32 s39, s23, s38
	s_cselect_b32 s38, s22, s30
	s_cselect_b32 s42, s24, s62
	s_cselect_b32 s43, s25, s63
	s_add_u32 s40, s38, 0x80
	s_addc_u32 s41, s39, 0
	ds_read_b128 v[178:181], v164
	ds_read_b128 v[182:185], v164 offset:1024
	ds_read_b128 v[186:189], v164 offset:2048
	ds_read_b128 v[190:193], v164 offset:3072
	ds_read_b128 v[194:197], v164 offset:4096
	ds_read_b128 v[198:201], v164 offset:5120
	ds_read_b128 v[202:205], v164 offset:6144
	ds_read_b128 v[206:209], v164 offset:7168
	s_mov_b32 m0, s58
	s_nop 0
	global_load_lds_dwordx4 v158, s[26:27]
	s_add_u32 s66, s26, 0x20000
	s_mov_b32 m0, s59
	s_addc_u32 s67, s27, 0
	global_load_lds_dwordx4 v158, s[66:67]
	s_waitcnt vmcnt(8) lgkmcnt(0)
	s_barrier
	s_setprio 1
	v_mfma_f32_16x16x32_bf16 v[132:135], v[112:115], v[178:181], 0
	v_mfma_f32_16x16x32_bf16 v[128:131], v[140:143], v[178:181], 0
	v_mfma_f32_16x16x32_bf16 v[124:127], v[112:115], v[186:189], 0
	v_mfma_f32_16x16x32_bf16 v[120:123], v[140:143], v[186:189], 0
	v_mfma_f32_16x16x32_bf16 v[108:111], v[112:115], v[194:197], 0
	v_mfma_f32_16x16x32_bf16 v[104:107], v[140:143], v[194:197], 0
	v_mfma_f32_16x16x32_bf16 v[100:103], v[112:115], v[202:205], 0
	v_mfma_f32_16x16x32_bf16 v[96:99], v[140:143], v[202:205], 0
	v_mfma_f32_16x16x32_bf16 v[132:135], v[116:119], v[182:185], v[132:135]
	v_mfma_f32_16x16x32_bf16 v[128:131], v[144:147], v[182:185], v[128:131]
	v_mfma_f32_16x16x32_bf16 v[124:127], v[116:119], v[190:193], v[124:127]
	v_mfma_f32_16x16x32_bf16 v[120:123], v[144:147], v[190:193], v[120:123]
	v_mfma_f32_16x16x32_bf16 v[108:111], v[116:119], v[198:201], v[108:111]
	v_mfma_f32_16x16x32_bf16 v[104:107], v[144:147], v[198:201], v[104:107]
	v_mfma_f32_16x16x32_bf16 v[100:103], v[116:119], v[206:209], v[100:103]
	v_mfma_f32_16x16x32_bf16 v[96:99], v[144:147], v[206:209], v[96:99]
	v_mfma_f32_16x16x32_bf16 v[60:63], v[148:151], v[178:181], 0
	v_mfma_f32_16x16x32_bf16 v[56:59], v[168:171], v[178:181], 0
	v_mfma_f32_16x16x32_bf16 v[52:55], v[148:151], v[186:189], 0
	v_mfma_f32_16x16x32_bf16 v[48:51], v[168:171], v[186:189], 0
	v_mfma_f32_16x16x32_bf16 v[44:47], v[148:151], v[194:197], 0
	v_mfma_f32_16x16x32_bf16 v[40:43], v[168:171], v[194:197], 0
	v_mfma_f32_16x16x32_bf16 v[36:39], v[148:151], v[202:205], 0
	v_mfma_f32_16x16x32_bf16 v[32:35], v[168:171], v[202:205], 0
	v_mfma_f32_16x16x32_bf16 v[60:63], v[152:155], v[182:185], v[60:63]
	v_mfma_f32_16x16x32_bf16 v[56:59], v[172:175], v[182:185], v[56:59]
	v_mfma_f32_16x16x32_bf16 v[52:55], v[152:155], v[190:193], v[52:55]
	v_mfma_f32_16x16x32_bf16 v[48:51], v[172:175], v[190:193], v[48:51]
	v_mfma_f32_16x16x32_bf16 v[44:47], v[152:155], v[198:201], v[44:47]
	v_mfma_f32_16x16x32_bf16 v[40:43], v[172:175], v[198:201], v[40:43]
	v_mfma_f32_16x16x32_bf16 v[36:39], v[152:155], v[206:209], v[36:39]
	v_mfma_f32_16x16x32_bf16 v[32:35], v[172:175], v[206:209], v[32:35]
	s_add_i32 s65, s65, 2
	s_add_u32 s26, s26, 0x100
	s_addc_u32 s27, s27, 0
	s_add_u32 s62, s62, 0x100
	s_addc_u32 s63, s63, 0
	s_setprio 0
	s_barrier
	s_add_u32 s66, s42, 0x20000
	ds_read_b128 v[178:181], v164 offset:16384
	ds_read_b128 v[182:185], v164 offset:17408
	ds_read_b128 v[186:189], v164 offset:18432
	ds_read_b128 v[190:193], v164 offset:19456
	ds_read_b128 v[194:197], v164 offset:20480
	ds_read_b128 v[198:201], v164 offset:21504
	ds_read_b128 v[202:205], v164 offset:22528
	ds_read_b128 v[206:209], v164 offset:23552
	s_mov_b32 m0, s35
	s_nop 0
	global_load_lds_dwordx4 v159, s[42:43]
	s_mov_b32 m0, s36
	s_addc_u32 s67, s43, 0
	global_load_lds_dwordx4 v159, s[66:67]
	s_add_u32 s66, s42, 0x40000
	s_mov_b32 m0, s37
	s_addc_u32 s67, s43, 0
	global_load_lds_dwordx4 v159, s[66:67]
	s_add_u32 s66, s42, 0x60000
	s_mov_b32 m0, s44
	s_addc_u32 s67, s43, 0
	global_load_lds_dwordx4 v159, s[66:67]
	s_mov_b32 m0, s34
	s_nop 0
	global_load_lds_dwordx4 v158, s[38:39]
	s_add_u32 s66, s38, 0x20000
	s_mov_b32 m0, s45
	s_addc_u32 s67, s39, 0
	global_load_lds_dwordx4 v158, s[66:67]
	s_waitcnt vmcnt(8) lgkmcnt(0)
	s_barrier
	s_setprio 1
	v_mfma_f32_16x16x32_bf16 v[92:95], v[112:115], v[178:181], 0
	v_mfma_f32_16x16x32_bf16 v[88:91], v[140:143], v[178:181], 0
	v_mfma_f32_16x16x32_bf16 v[84:87], v[112:115], v[186:189], 0
	v_mfma_f32_16x16x32_bf16 v[80:83], v[140:143], v[186:189], 0
	v_mfma_f32_16x16x32_bf16 v[76:79], v[112:115], v[194:197], 0
	v_mfma_f32_16x16x32_bf16 v[72:75], v[140:143], v[194:197], 0
	v_mfma_f32_16x16x32_bf16 v[68:71], v[112:115], v[202:205], 0
	v_mfma_f32_16x16x32_bf16 v[64:67], v[140:143], v[202:205], 0
	v_mfma_f32_16x16x32_bf16 v[92:95], v[116:119], v[182:185], v[92:95]
	v_mfma_f32_16x16x32_bf16 v[88:91], v[144:147], v[182:185], v[88:91]
	v_mfma_f32_16x16x32_bf16 v[84:87], v[116:119], v[190:193], v[84:87]
	v_mfma_f32_16x16x32_bf16 v[80:83], v[144:147], v[190:193], v[80:83]
	v_mfma_f32_16x16x32_bf16 v[76:79], v[116:119], v[198:201], v[76:79]
	v_mfma_f32_16x16x32_bf16 v[72:75], v[144:147], v[198:201], v[72:75]
	v_mfma_f32_16x16x32_bf16 v[68:71], v[116:119], v[206:209], v[68:71]
	v_mfma_f32_16x16x32_bf16 v[64:67], v[144:147], v[206:209], v[64:67]
	v_mfma_f32_16x16x32_bf16 v[28:31], v[148:151], v[178:181], 0
	v_mfma_f32_16x16x32_bf16 v[24:27], v[168:171], v[178:181], 0
	v_mfma_f32_16x16x32_bf16 v[20:23], v[148:151], v[186:189], 0
	v_mfma_f32_16x16x32_bf16 v[16:19], v[168:171], v[186:189], 0
	v_mfma_f32_16x16x32_bf16 v[12:15], v[148:151], v[194:197], 0
	v_mfma_f32_16x16x32_bf16 v[8:11], v[168:171], v[194:197], 0
	v_mfma_f32_16x16x32_bf16 v[4:7], v[148:151], v[202:205], 0
	v_mfma_f32_16x16x32_bf16 v[0:3], v[168:171], v[202:205], 0
	v_mfma_f32_16x16x32_bf16 v[28:31], v[152:155], v[182:185], v[28:31]
	v_mfma_f32_16x16x32_bf16 v[24:27], v[172:175], v[182:185], v[24:27]
	v_mfma_f32_16x16x32_bf16 v[20:23], v[152:155], v[190:193], v[20:23]
	v_mfma_f32_16x16x32_bf16 v[16:19], v[172:175], v[190:193], v[16:19]
	v_mfma_f32_16x16x32_bf16 v[12:15], v[152:155], v[198:201], v[12:15]
	v_mfma_f32_16x16x32_bf16 v[8:11], v[172:175], v[198:201], v[8:11]
	v_mfma_f32_16x16x32_bf16 v[4:7], v[152:155], v[206:209], v[4:7]
	v_mfma_f32_16x16x32_bf16 v[0:3], v[172:175], v[206:209], v[0:3]
	s_setprio 0
	s_barrier
	s_branch .Lpeel_mid_28770
; #define PG8_STAGE(bufoff, gbase, voff, p64) do { _Pragma("unroll") for (int _i = 0; _i < 2; ++_i) { \
;         const char* _gb = (const char*)(gbase) + (size_t)_i * (p64); const unsigned _la = ldsbase + (unsigned)(bufoff) + (unsigned)_i * 8192u; \
;         asm volatile("s_mov_b32 m0, %0\n\ts_nop 0\n\tglobal_load_lds_dwordx4 %1, %2" :: "s"(_la), "v"(voff), "s"(_gb) : "memory"); } } while (0)
; #define PG8_LDA(dst, b, h) do { _Pragma("unroll") for (int m = 0; m < 4; ++m) _Pragma("unroll") for (int k = 0; k < 2; ++k) dst[m][k] = *(const LAS bf16x8*)(lds + PG8_SA(b, h) + aoff + m * 2048 + k * 1024); } while (0)
; #define PG8_LDB(dst, b, h) do { _Pragma("unroll") for (int n = 0; n < 2; ++n) _Pragma("unroll") for (int k = 0; k < 2; ++k) dst[n][k] = *(const LAS bf16x8*)(lds + PG8_SB(b, h) + boff + n * 2048 + k * 1024); } while (0)
; #define PG8_MMA(ai, bj, At, Bt) do { __builtin_amdgcn_s_setprio(1); _Pragma("unroll") for (int m = 0; m < 4; ++m) _Pragma("unroll") for (int n = 0; n < 2; ++n) _Pragma("unroll") for (int k = 0; k < 2; ++k) \
;         acc[ai][bj][m][n] = __builtin_amdgcn_mfma_f32_16x16x32_bf16(Bt[n][k], At[m][k], acc[ai][bj][m][n], 0, 0, 0); __builtin_amdgcn_s_setprio(0); } while (0)
; #define PG8_WAIT_V(n) asm volatile("s_waitcnt vmcnt(" #n ")" ::: "memory")
; #define PG8_WAIT_L(n) asm volatile("s_waitcnt lgkmcnt(" #n ")" ::: "memory")
; #define PG8_BAR __builtin_amdgcn_s_barrier()
; #define PG8_SCHED __builtin_amdgcn_sched_barrier(0)
; template <class Epi, class Sched>
; __device__ __forceinline__ void gemm_phase(LAS unsigned char* lds, const Sched& S, const Epi& E) {
;     ...
;             PG8_LDB(B0, 0, 0); PG8_LDB(B1, 0, 1); PG8_SCHED; PG8_LDA(At, 0, 0); PG8_STAGE(PG8_SA(1, 1), a1 + hA, voffA, hA / 2);
;             PG8_WAIT_V(8); PG8_WAIT_L(0); PG8_BAR; PG8_MMA(0, 0, At, B0); PG8_MMA(0, 1, At, B1); PG8_BAR; PG8_SCHED;
;             PG8_LDA(At, 0, 1); PG8_STAGE(PG8_SB(0, 0), b2, vB2, hB2 / 2); PG8_STAGE(PG8_SB(0, 1), b2 + hB2, vB2, hB2 / 2); PG8_STAGE(PG8_SA(0, 0), a2, vA2, hA2 / 2);
;             PG8_WAIT_V(8); PG8_WAIT_L(0); PG8_BAR; PG8_MMA(1, 0, At, B0); PG8_MMA(1, 1, At, B1); PG8_BAR; PG8_SCHED;
.LBB0_981:
	ds_read_b128 v[112:115], v162
	ds_read_b128 v[116:119], v162 offset:1024
	ds_read_b128 v[140:143], v162 offset:2048
	ds_read_b128 v[144:147], v162 offset:3072
	ds_read_b128 v[148:151], v163
	ds_read_b128 v[152:155], v163 offset:1024
	ds_read_b128 v[168:171], v163 offset:2048
	ds_read_b128 v[172:175], v163 offset:3072
	s_add_u32 s30, s26, 0xfffc0080
	s_addc_u32 s38, s27, -1
	s_cmp_eq_u32 s65, 12
	s_cselect_b32 s39, s23, s38
	s_cselect_b32 s38, s22, s30
	s_cselect_b32 s42, s24, s62
	s_cselect_b32 s43, s25, s63
	s_add_u32 s40, s38, 0x80
	s_addc_u32 s41, s39, 0
	ds_read_b128 v[178:181], v164
	ds_read_b128 v[182:185], v164 offset:1024
	ds_read_b128 v[186:189], v164 offset:2048
	ds_read_b128 v[190:193], v164 offset:3072
	ds_read_b128 v[194:197], v164 offset:4096
	ds_read_b128 v[198:201], v164 offset:5120
	ds_read_b128 v[202:205], v164 offset:6144
	ds_read_b128 v[206:209], v164 offset:7168
	s_mov_b32 m0, s58
	s_nop 0
	global_load_lds_dwordx4 v158, s[26:27]
	s_add_u32 s66, s26, 0x20000
	s_mov_b32 m0, s59
	s_addc_u32 s67, s27, 0
	global_load_lds_dwordx4 v158, s[66:67]
	s_waitcnt vmcnt(8) lgkmcnt(0)
	s_barrier
	s_setprio 1
	v_mfma_f32_16x16x32_bf16 v[132:135], v[112:115], v[178:181], v[132:135]
	v_mfma_f32_16x16x32_bf16 v[128:131], v[140:143], v[178:181], v[128:131]
	v_mfma_f32_16x16x32_bf16 v[124:127], v[112:115], v[186:189], v[124:127]
	v_mfma_f32_16x16x32_bf16 v[120:123], v[140:143], v[186:189], v[120:123]
	v_mfma_f32_16x16x32_bf16 v[108:111], v[112:115], v[194:197], v[108:111]
	v_mfma_f32_16x16x32_bf16 v[104:107], v[140:143], v[194:197], v[104:107]
	v_mfma_f32_16x16x32_bf16 v[100:103], v[112:115], v[202:205], v[100:103]
	v_mfma_f32_16x16x32_bf16 v[96:99], v[140:143], v[202:205], v[96:99]
	v_mfma_f32_16x16x32_bf16 v[132:135], v[116:119], v[182:185], v[132:135]
	v_mfma_f32_16x16x32_bf16 v[128:131], v[144:147], v[182:185], v[128:131]
	v_mfma_f32_16x16x32_bf16 v[124:127], v[116:119], v[190:193], v[124:127]
	v_mfma_f32_16x16x32_bf16 v[120:123], v[144:147], v[190:193], v[120:123]
	v_mfma_f32_16x16x32_bf16 v[108:111], v[116:119], v[198:201], v[108:111]
	v_mfma_f32_16x16x32_bf16 v[104:107], v[144:147], v[198:201], v[104:107]
	v_mfma_f32_16x16x32_bf16 v[100:103], v[116:119], v[206:209], v[100:103]
	v_mfma_f32_16x16x32_bf16 v[96:99], v[144:147], v[206:209], v[96:99]
	v_mfma_f32_16x16x32_bf16 v[60:63], v[148:151], v[178:181], v[60:63]
	v_mfma_f32_16x16x32_bf16 v[56:59], v[168:171], v[178:181], v[56:59]
	v_mfma_f32_16x16x32_bf16 v[52:55], v[148:151], v[186:189], v[52:55]
	v_mfma_f32_16x16x32_bf16 v[48:51], v[168:171], v[186:189], v[48:51]
	v_mfma_f32_16x16x32_bf16 v[44:47], v[148:151], v[194:197], v[44:47]
	v_mfma_f32_16x16x32_bf16 v[40:43], v[168:171], v[194:197], v[40:43]
	v_mfma_f32_16x16x32_bf16 v[36:39], v[148:151], v[202:205], v[36:39]
	v_mfma_f32_16x16x32_bf16 v[32:35], v[168:171], v[202:205], v[32:35]
	v_mfma_f32_16x16x32_bf16 v[60:63], v[152:155], v[182:185], v[60:63]
	v_mfma_f32_16x16x32_bf16 v[56:59], v[172:175], v[182:185], v[56:59]
	v_mfma_f32_16x16x32_bf16 v[52:55], v[152:155], v[190:193], v[52:55]
	v_mfma_f32_16x16x32_bf16 v[48:51], v[172:175], v[190:193], v[48:51]
	v_mfma_f32_16x16x32_bf16 v[44:47], v[152:155], v[198:201], v[44:47]
	v_mfma_f32_16x16x32_bf16 v[40:43], v[172:175], v[198:201], v[40:43]
	v_mfma_f32_16x16x32_bf16 v[36:39], v[152:155], v[206:209], v[36:39]
	v_mfma_f32_16x16x32_bf16 v[32:35], v[172:175], v[206:209], v[32:35]
	s_add_i32 s65, s65, 2
	s_add_u32 s26, s26, 0x100
	s_addc_u32 s27, s27, 0
	s_add_u32 s62, s62, 0x100
	s_addc_u32 s63, s63, 0
	s_setprio 0
	s_barrier
	s_add_u32 s66, s42, 0x20000
	ds_read_b128 v[178:181], v164 offset:16384
	ds_read_b128 v[182:185], v164 offset:17408
	ds_read_b128 v[186:189], v164 offset:18432
	ds_read_b128 v[190:193], v164 offset:19456
	ds_read_b128 v[194:197], v164 offset:20480
	ds_read_b128 v[198:201], v164 offset:21504
	ds_read_b128 v[202:205], v164 offset:22528
	ds_read_b128 v[206:209], v164 offset:23552
	s_mov_b32 m0, s35
	s_nop 0
	global_load_lds_dwordx4 v159, s[42:43]
	s_mov_b32 m0, s36
	s_addc_u32 s67, s43, 0
	global_load_lds_dwordx4 v159, s[66:67]
	s_add_u32 s66, s42, 0x40000
	s_mov_b32 m0, s37
	s_addc_u32 s67, s43, 0
	global_load_lds_dwordx4 v159, s[66:67]
	s_add_u32 s66, s42, 0x60000
	s_mov_b32 m0, s44
	s_addc_u32 s67, s43, 0
	global_load_lds_dwordx4 v159, s[66:67]
	s_mov_b32 m0, s34
	s_nop 0
	global_load_lds_dwordx4 v158, s[38:39]
	s_add_u32 s66, s38, 0x20000
	s_mov_b32 m0, s45
	s_addc_u32 s67, s39, 0
	global_load_lds_dwordx4 v158, s[66:67]
	s_waitcnt vmcnt(8) lgkmcnt(0)
	s_barrier
	s_setprio 1
	v_mfma_f32_16x16x32_bf16 v[92:95], v[112:115], v[178:181], v[92:95]
	v_mfma_f32_16x16x32_bf16 v[88:91], v[140:143], v[178:181], v[88:91]
	v_mfma_f32_16x16x32_bf16 v[84:87], v[112:115], v[186:189], v[84:87]
	v_mfma_f32_16x16x32_bf16 v[80:83], v[140:143], v[186:189], v[80:83]
	v_mfma_f32_16x16x32_bf16 v[76:79], v[112:115], v[194:197], v[76:79]
	v_mfma_f32_16x16x32_bf16 v[72:75], v[140:143], v[194:197], v[72:75]
	v_mfma_f32_16x16x32_bf16 v[68:71], v[112:115], v[202:205], v[68:71]
	v_mfma_f32_16x16x32_bf16 v[64:67], v[140:143], v[202:205], v[64:67]
	v_mfma_f32_16x16x32_bf16 v[92:95], v[116:119], v[182:185], v[92:95]
	v_mfma_f32_16x16x32_bf16 v[88:91], v[144:147], v[182:185], v[88:91]
	v_mfma_f32_16x16x32_bf16 v[84:87], v[116:119], v[190:193], v[84:87]
	v_mfma_f32_16x16x32_bf16 v[80:83], v[144:147], v[190:193], v[80:83]
	v_mfma_f32_16x16x32_bf16 v[76:79], v[116:119], v[198:201], v[76:79]
	v_mfma_f32_16x16x32_bf16 v[72:75], v[144:147], v[198:201], v[72:75]
	v_mfma_f32_16x16x32_bf16 v[68:71], v[116:119], v[206:209], v[68:71]
	v_mfma_f32_16x16x32_bf16 v[64:67], v[144:147], v[206:209], v[64:67]
	v_mfma_f32_16x16x32_bf16 v[28:31], v[148:151], v[178:181], v[28:31]
	v_mfma_f32_16x16x32_bf16 v[24:27], v[168:171], v[178:181], v[24:27]
	v_mfma_f32_16x16x32_bf16 v[20:23], v[148:151], v[186:189], v[20:23]
	v_mfma_f32_16x16x32_bf16 v[16:19], v[168:171], v[186:189], v[16:19]
	v_mfma_f32_16x16x32_bf16 v[12:15], v[148:151], v[194:197], v[12:15]
	v_mfma_f32_16x16x32_bf16 v[8:11], v[168:171], v[194:197], v[8:11]
	v_mfma_f32_16x16x32_bf16 v[4:7], v[148:151], v[202:205], v[4:7]
	v_mfma_f32_16x16x32_bf16 v[0:3], v[168:171], v[202:205], v[0:3]
	v_mfma_f32_16x16x32_bf16 v[28:31], v[152:155], v[182:185], v[28:31]
	v_mfma_f32_16x16x32_bf16 v[24:27], v[172:175], v[182:185], v[24:27]
	v_mfma_f32_16x16x32_bf16 v[20:23], v[152:155], v[190:193], v[20:23]
	v_mfma_f32_16x16x32_bf16 v[16:19], v[172:175], v[190:193], v[16:19]
	v_mfma_f32_16x16x32_bf16 v[12:15], v[152:155], v[198:201], v[12:15]
	v_mfma_f32_16x16x32_bf16 v[8:11], v[172:175], v[198:201], v[8:11]
	v_mfma_f32_16x16x32_bf16 v[4:7], v[152:155], v[206:209], v[4:7]
	v_mfma_f32_16x16x32_bf16 v[0:3], v[172:175], v[206:209], v[0:3]
	s_setprio 0
	s_barrier
; #define PG8_STAGE(bufoff, gbase, voff, p64) do { _Pragma("unroll") for (int _i = 0; _i < 2; ++_i) { \
;         const char* _gb = (const char*)(gbase) + (size_t)_i * (p64); const unsigned _la = ldsbase + (unsigned)(bufoff) + (unsigned)_i * 8192u; \
;         asm volatile("s_mov_b32 m0, %0\n\ts_nop 0\n\tglobal_load_lds_dwordx4 %1, %2" :: "s"(_la), "v"(voff), "s"(_gb) : "memory"); } } while (0)
; #define PG8_LDA(dst, b, h) do { _Pragma("unroll") for (int m = 0; m < 4; ++m) _Pragma("unroll") for (int k = 0; k < 2; ++k) dst[m][k] = *(const LAS bf16x8*)(lds + PG8_SA(b, h) + aoff + m * 2048 + k * 1024); } while (0)
; #define PG8_LDB(dst, b, h) do { _Pragma("unroll") for (int n = 0; n < 2; ++n) _Pragma("unroll") for (int k = 0; k < 2; ++k) dst[n][k] = *(const LAS bf16x8*)(lds + PG8_SB(b, h) + boff + n * 2048 + k * 1024); } while (0)
; #define PG8_MMA(ai, bj, At, Bt) do { __builtin_amdgcn_s_setprio(1); _Pragma("unroll") for (int m = 0; m < 4; ++m) _Pragma("unroll") for (int n = 0; n < 2; ++n) _Pragma("unroll") for (int k = 0; k < 2; ++k) \
;         acc[ai][bj][m][n] = __builtin_amdgcn_mfma_f32_16x16x32_bf16(Bt[n][k], At[m][k], acc[ai][bj][m][n], 0, 0, 0); __builtin_amdgcn_s_setprio(0); } while (0)
; #define PG8_WAIT_V(n) asm volatile("s_waitcnt vmcnt(" #n ")" ::: "memory")
; #define PG8_WAIT_L(n) asm volatile("s_waitcnt lgkmcnt(" #n ")" ::: "memory")
; #define PG8_BAR __builtin_amdgcn_s_barrier()
; #define PG8_SCHED __builtin_amdgcn_sched_barrier(0)
; template <class Epi, class Sched>
; __device__ __forceinline__ void gemm_phase(LAS unsigned char* lds, const Sched& S, const Epi& E) {
;     ...
;             PG8_LDB(B0, 1, 0); PG8_LDB(B1, 1, 1); PG8_SCHED; PG8_LDA(At, 1, 0); PG8_STAGE(PG8_SA(0, 1), a2 + hA2, vA2, hA2 / 2);
;             PG8_WAIT_V(8); PG8_WAIT_L(0); PG8_BAR; PG8_MMA(0, 0, At, B0); PG8_MMA(0, 1, At, B1); PG8_BAR; PG8_SCHED;
;             PG8_LDA(At, 1, 1); PG8_STAGE(PG8_SB(1, 0), b3, vB2, hB2 / 2); PG8_STAGE(PG8_SB(1, 1), b3 + hB2, vB2, hB2 / 2); PG8_STAGE(PG8_SA(1, 0), a3, vA2, hA2 / 2);
;             PG8_WAIT_V(8); PG8_WAIT_L(0); PG8_BAR; PG8_MMA(1, 0, At, B0); PG8_MMA(1, 1, At, B1); PG8_BAR; PG8_SCHED;
;         }
;         if (wr == 0) PG8_BAR;
.Lpeel_mid_28770:
	ds_read_b128 v[112:115], v165
	ds_read_b128 v[116:119], v165 offset:1024
	ds_read_b128 v[140:143], v165 offset:2048
	ds_read_b128 v[144:147], v165 offset:3072
	ds_read_b128 v[148:151], v166
	ds_read_b128 v[152:155], v166 offset:1024
	ds_read_b128 v[168:171], v166 offset:2048
	ds_read_b128 v[172:175], v166 offset:3072
	ds_read_b128 v[178:181], v164 offset:32768
	ds_read_b128 v[182:185], v164 offset:33792
	ds_read_b128 v[186:189], v164 offset:34816
	ds_read_b128 v[190:193], v164 offset:35840
	ds_read_b128 v[194:197], v164 offset:36864
	ds_read_b128 v[198:201], v164 offset:37888
	ds_read_b128 v[202:205], v164 offset:38912
	ds_read_b128 v[206:209], v164 offset:39936
	s_add_u32 s66, s38, 0x40000
	s_mov_b32 m0, s46
	s_addc_u32 s67, s39, 0
	global_load_lds_dwordx4 v158, s[66:67]
	s_add_u32 s66, s38, 0x60000
	s_mov_b32 m0, s47
	s_addc_u32 s67, s39, 0
	global_load_lds_dwordx4 v158, s[66:67]
	s_waitcnt vmcnt(8) lgkmcnt(0)
	s_barrier
	s_setprio 1
	v_mfma_f32_16x16x32_bf16 v[132:135], v[112:115], v[178:181], v[132:135]
	v_mfma_f32_16x16x32_bf16 v[128:131], v[140:143], v[178:181], v[128:131]
	v_mfma_f32_16x16x32_bf16 v[124:127], v[112:115], v[186:189], v[124:127]
	v_mfma_f32_16x16x32_bf16 v[120:123], v[140:143], v[186:189], v[120:123]
	v_mfma_f32_16x16x32_bf16 v[108:111], v[112:115], v[194:197], v[108:111]
	v_mfma_f32_16x16x32_bf16 v[104:107], v[140:143], v[194:197], v[104:107]
	v_mfma_f32_16x16x32_bf16 v[100:103], v[112:115], v[202:205], v[100:103]
	v_mfma_f32_16x16x32_bf16 v[96:99], v[140:143], v[202:205], v[96:99]
	v_mfma_f32_16x16x32_bf16 v[132:135], v[116:119], v[182:185], v[132:135]
	v_mfma_f32_16x16x32_bf16 v[128:131], v[144:147], v[182:185], v[128:131]
	v_mfma_f32_16x16x32_bf16 v[124:127], v[116:119], v[190:193], v[124:127]
	v_mfma_f32_16x16x32_bf16 v[120:123], v[144:147], v[190:193], v[120:123]
	v_mfma_f32_16x16x32_bf16 v[108:111], v[116:119], v[198:201], v[108:111]
	v_mfma_f32_16x16x32_bf16 v[104:107], v[144:147], v[198:201], v[104:107]
	v_mfma_f32_16x16x32_bf16 v[100:103], v[116:119], v[206:209], v[100:103]
	v_mfma_f32_16x16x32_bf16 v[96:99], v[144:147], v[206:209], v[96:99]
	v_mfma_f32_16x16x32_bf16 v[60:63], v[148:151], v[178:181], v[60:63]
	v_mfma_f32_16x16x32_bf16 v[56:59], v[168:171], v[178:181], v[56:59]
	v_mfma_f32_16x16x32_bf16 v[52:55], v[148:151], v[186:189], v[52:55]
	v_mfma_f32_16x16x32_bf16 v[48:51], v[168:171], v[186:189], v[48:51]
	v_mfma_f32_16x16x32_bf16 v[44:47], v[148:151], v[194:197], v[44:47]
	v_mfma_f32_16x16x32_bf16 v[40:43], v[168:171], v[194:197], v[40:43]
	v_mfma_f32_16x16x32_bf16 v[36:39], v[148:151], v[202:205], v[36:39]
	v_mfma_f32_16x16x32_bf16 v[32:35], v[168:171], v[202:205], v[32:35]
	v_mfma_f32_16x16x32_bf16 v[60:63], v[152:155], v[182:185], v[60:63]
	v_mfma_f32_16x16x32_bf16 v[56:59], v[172:175], v[182:185], v[56:59]
	v_mfma_f32_16x16x32_bf16 v[52:55], v[152:155], v[190:193], v[52:55]
	v_mfma_f32_16x16x32_bf16 v[48:51], v[172:175], v[190:193], v[48:51]
	v_mfma_f32_16x16x32_bf16 v[44:47], v[152:155], v[198:201], v[44:47]
	v_mfma_f32_16x16x32_bf16 v[40:43], v[172:175], v[198:201], v[40:43]
	v_mfma_f32_16x16x32_bf16 v[36:39], v[152:155], v[206:209], v[36:39]
	v_mfma_f32_16x16x32_bf16 v[32:35], v[172:175], v[206:209], v[32:35]
	s_setprio 0
	s_barrier
	s_add_u32 s66, s42, 0x80
	s_addc_u32 s67, s43, 0
	ds_read_b128 v[178:181], v164 offset:49152
	ds_read_b128 v[182:185], v164 offset:50176
	ds_read_b128 v[186:189], v164 offset:51200
	ds_read_b128 v[190:193], v164 offset:52224
	ds_read_b128 v[194:197], v164 offset:53248
	ds_read_b128 v[198:201], v164 offset:54272
	ds_read_b128 v[202:205], v164 offset:55296
	ds_read_b128 v[206:209], v164 offset:56320
	s_mov_b32 m0, s52
	s_nop 0
	global_load_lds_dwordx4 v159, s[66:67]
	s_add_u32 s66, s42, 0x20080
	s_mov_b32 m0, s53
	s_addc_u32 s67, s43, 0
	global_load_lds_dwordx4 v159, s[66:67]
	s_add_u32 s66, s42, 0x40080
	s_mov_b32 m0, s56
	s_addc_u32 s67, s43, 0
	global_load_lds_dwordx4 v159, s[66:67]
	s_add_u32 s42, s42, 0x60080
	s_mov_b32 m0, s57
	s_addc_u32 s43, s43, 0
	global_load_lds_dwordx4 v159, s[42:43]
	s_mov_b32 m0, s54
	s_nop 0
	global_load_lds_dwordx4 v158, s[40:41]
	s_add_u32 s38, s38, 0x20080
	s_mov_b32 m0, s55
	s_addc_u32 s39, s39, 0
	global_load_lds_dwordx4 v158, s[38:39]
	s_waitcnt vmcnt(8) lgkmcnt(0)
	s_barrier
	s_setprio 1
	v_mfma_f32_16x16x32_bf16 v[92:95], v[112:115], v[178:181], v[92:95]
	v_mfma_f32_16x16x32_bf16 v[88:91], v[140:143], v[178:181], v[88:91]
	v_mfma_f32_16x16x32_bf16 v[84:87], v[112:115], v[186:189], v[84:87]
	v_mfma_f32_16x16x32_bf16 v[80:83], v[140:143], v[186:189], v[80:83]
	v_mfma_f32_16x16x32_bf16 v[76:79], v[112:115], v[194:197], v[76:79]
	v_mfma_f32_16x16x32_bf16 v[72:75], v[140:143], v[194:197], v[72:75]
	v_mfma_f32_16x16x32_bf16 v[68:71], v[112:115], v[202:205], v[68:71]
	v_mfma_f32_16x16x32_bf16 v[64:67], v[140:143], v[202:205], v[64:67]
	v_mfma_f32_16x16x32_bf16 v[92:95], v[116:119], v[182:185], v[92:95]
	v_mfma_f32_16x16x32_bf16 v[88:91], v[144:147], v[182:185], v[88:91]
	v_mfma_f32_16x16x32_bf16 v[84:87], v[116:119], v[190:193], v[84:87]
	v_mfma_f32_16x16x32_bf16 v[80:83], v[144:147], v[190:193], v[80:83]
	v_mfma_f32_16x16x32_bf16 v[76:79], v[116:119], v[198:201], v[76:79]
	v_mfma_f32_16x16x32_bf16 v[72:75], v[144:147], v[198:201], v[72:75]
	v_mfma_f32_16x16x32_bf16 v[68:71], v[116:119], v[206:209], v[68:71]
	v_mfma_f32_16x16x32_bf16 v[64:67], v[144:147], v[206:209], v[64:67]
	v_mfma_f32_16x16x32_bf16 v[28:31], v[148:151], v[178:181], v[28:31]
	v_mfma_f32_16x16x32_bf16 v[24:27], v[168:171], v[178:181], v[24:27]
	v_mfma_f32_16x16x32_bf16 v[20:23], v[148:151], v[186:189], v[20:23]
	v_mfma_f32_16x16x32_bf16 v[16:19], v[168:171], v[186:189], v[16:19]
	v_mfma_f32_16x16x32_bf16 v[12:15], v[148:151], v[194:197], v[12:15]
	v_mfma_f32_16x16x32_bf16 v[8:11], v[168:171], v[194:197], v[8:11]
	v_mfma_f32_16x16x32_bf16 v[4:7], v[148:151], v[202:205], v[4:7]
	v_mfma_f32_16x16x32_bf16 v[0:3], v[168:171], v[202:205], v[0:3]
	v_mfma_f32_16x16x32_bf16 v[28:31], v[152:155], v[182:185], v[28:31]
	v_mfma_f32_16x16x32_bf16 v[24:27], v[172:175], v[182:185], v[24:27]
	v_mfma_f32_16x16x32_bf16 v[20:23], v[152:155], v[190:193], v[20:23]
	v_mfma_f32_16x16x32_bf16 v[16:19], v[172:175], v[190:193], v[16:19]
	v_mfma_f32_16x16x32_bf16 v[12:15], v[152:155], v[198:201], v[12:15]
	v_mfma_f32_16x16x32_bf16 v[8:11], v[172:175], v[198:201], v[8:11]
	v_mfma_f32_16x16x32_bf16 v[4:7], v[152:155], v[206:209], v[4:7]
	v_mfma_f32_16x16x32_bf16 v[0:3], v[172:175], v[206:209], v[0:3]
	s_setprio 0
	s_barrier
	s_cmp_gt_u32 s65, 13
	s_cbranch_scc0 .LBB0_981
	s_and_b64 vcc, exec, s[14:15]
	s_cbranch_vccz .LBB0_984
	s_barrier

; #define PG8_STAGE(bufoff, gbase, voff, p64) do { _Pragma("unroll") for (int _i = 0; _i < 2; ++_i) { \
;         const char* _gb = (const char*)(gbase) + (size_t)_i * (p64); const unsigned _la = ldsbase + (unsigned)(bufoff) + (unsigned)_i * 8192u; \
;         asm volatile("s_mov_b32 m0, %0\n\ts_nop 0\n\tglobal_load_lds_dwordx4 %1, %2" :: "s"(_la), "v"(voff), "s"(_gb) : "memory"); } } while (0)
; #define PG8_LDA(dst, b, h) do { _Pragma("unroll") for (int m = 0; m < 4; ++m) _Pragma("unroll") for (int k = 0; k < 2; ++k) dst[m][k] = *(const LAS bf16x8*)(lds + PG8_SA(b, h) + aoff + m * 2048 + k * 1024); } while (0)
; #define PG8_LDB(dst, b, h) do { _Pragma("unroll") for (int n = 0; n < 2; ++n) _Pragma("unroll") for (int k = 0; k < 2; ++k) dst[n][k] = *(const LAS bf16x8*)(lds + PG8_SB(b, h) + boff + n * 2048 + k * 1024); } while (0)
; #define PG8_MMA(ai, bj, At, Bt) do { __builtin_amdgcn_s_setprio(1); _Pragma("unroll") for (int m = 0; m < 4; ++m) _Pragma("unroll") for (int n = 0; n < 2; ++n) _Pragma("unroll") for (int k = 0; k < 2; ++k) \
;         acc[ai][bj][m][n] = __builtin_amdgcn_mfma_f32_16x16x32_bf16(Bt[n][k], At[m][k], acc[ai][bj][m][n], 0, 0, 0); __builtin_amdgcn_s_setprio(0); } while (0)
; #define PG8_WAIT_V(n) asm volatile("s_waitcnt vmcnt(" #n ")" ::: "memory")
; #define PG8_WAIT_L(n) asm volatile("s_waitcnt lgkmcnt(" #n ")" ::: "memory")
; #define PG8_BAR __builtin_amdgcn_s_barrier()
; template <class Epi, class Sched>
; __device__ __forceinline__ void gemm_phase(LAS unsigned char* lds, const Sched& S, const Epi& E) {
;     ...
;     f32x4 acc[2][2][4][2];
; #pragma unroll
;     for (int a = 0; a < 2; ++a)
; #pragma unroll
;         for (int b = 0; b < 2; ++b)
; #pragma unroll
;             for (int m = 0; m < 4; ++m)
; #pragma unroll
;                 for (int n = 0; n < 2; ++n) acc[a][b][m][n] = (f32x4){0.f, 0.f, 0.f, 0.f};
;     ...
;             PG8_LDB(B0, 0, 0); PG8_LDB(B1, 0, 1); PG8_SCHED; PG8_LDA(At, 0, 0); PG8_STAGE(PG8_SA(1, 1), a1 + hA, voffA, hA / 2);
;             PG8_WAIT_V(8); PG8_WAIT_L(0); PG8_BAR; PG8_MMA(0, 0, At, B0); PG8_MMA(0, 1, At, B1); PG8_BAR; PG8_SCHED;
;             PG8_LDA(At, 0, 1); PG8_STAGE(PG8_SB(0, 0), b2, vB2, hB2 / 2); PG8_STAGE(PG8_SB(0, 1), b2 + hB2, vB2, hB2 / 2); PG8_STAGE(PG8_SA(0, 0), a2, vA2, hA2 / 2);
;             PG8_WAIT_V(8); PG8_WAIT_L(0); PG8_BAR; PG8_MMA(1, 0, At, B0); PG8_MMA(1, 1, At, B1); PG8_BAR; PG8_SCHED;
.LBB0_1010:
	s_add_u32 s26, s26, 0x40080
	s_addc_u32 s27, s27, 0
	s_add_u32 s61, s38, 0x100
	s_addc_u32 s62, s39, 0
	s_mov_b32 s63, -2
	ds_read_b128 v[144:147], v138
	ds_read_b128 v[148:151], v138 offset:1024
	ds_read_b128 v[152:155], v138 offset:2048
	ds_read_b128 v[156:159], v138 offset:3072
	ds_read_b128 v[160:163], v139
	ds_read_b128 v[164:167], v139 offset:1024
	ds_read_b128 v[168:171], v139 offset:2048
	ds_read_b128 v[172:175], v139 offset:3072
	s_add_u32 s30, s26, 0xfffc0080
	s_addc_u32 s38, s27, -1
	s_cmp_eq_u32 s63, 12
	s_cselect_b32 s39, s23, s38
	s_cselect_b32 s38, s22, s30
	s_cselect_b32 s42, s24, s61
	s_cselect_b32 s43, s25, s62
	s_add_u32 s40, s38, 0x80
	s_addc_u32 s41, s39, 0
	ds_read_b128 v[178:181], v140
	ds_read_b128 v[182:185], v140 offset:1024
	ds_read_b128 v[186:189], v140 offset:2048
	ds_read_b128 v[190:193], v140 offset:3072
	ds_read_b128 v[194:197], v140 offset:4096
	ds_read_b128 v[198:201], v140 offset:5120
	ds_read_b128 v[202:205], v140 offset:6144
	ds_read_b128 v[206:209], v140 offset:7168
	s_mov_b32 m0, s57
	s_nop 0
	global_load_lds_dwordx4 v134, s[26:27]
	s_add_u32 s66, s26, 0x20000
	s_mov_b32 m0, s58
	s_addc_u32 s67, s27, 0
	global_load_lds_dwordx4 v134, s[66:67]
	s_waitcnt vmcnt(8) lgkmcnt(0)
	s_barrier
	s_setprio 1
	v_mfma_f32_16x16x32_bf16 v[120:123], v[144:147], v[178:181], 0
	v_mfma_f32_16x16x32_bf16 v[116:119], v[152:155], v[178:181], 0
	v_mfma_f32_16x16x32_bf16 v[104:107], v[144:147], v[186:189], 0
	v_mfma_f32_16x16x32_bf16 v[100:103], v[152:155], v[186:189], 0
	v_mfma_f32_16x16x32_bf16 v[88:91], v[144:147], v[194:197], 0
	v_mfma_f32_16x16x32_bf16 v[84:87], v[152:155], v[194:197], 0
	v_mfma_f32_16x16x32_bf16 v[72:75], v[144:147], v[202:205], 0
	v_mfma_f32_16x16x32_bf16 v[68:71], v[152:155], v[202:205], 0
	v_mfma_f32_16x16x32_bf16 v[120:123], v[148:151], v[182:185], v[120:123]
	v_mfma_f32_16x16x32_bf16 v[116:119], v[156:159], v[182:185], v[116:119]
	v_mfma_f32_16x16x32_bf16 v[104:107], v[148:151], v[190:193], v[104:107]
	v_mfma_f32_16x16x32_bf16 v[100:103], v[156:159], v[190:193], v[100:103]
	v_mfma_f32_16x16x32_bf16 v[88:91], v[148:151], v[198:201], v[88:91]
	v_mfma_f32_16x16x32_bf16 v[84:87], v[156:159], v[198:201], v[84:87]
	v_mfma_f32_16x16x32_bf16 v[72:75], v[148:151], v[206:209], v[72:75]
	v_mfma_f32_16x16x32_bf16 v[68:71], v[156:159], v[206:209], v[68:71]
	v_mfma_f32_16x16x32_bf16 v[124:127], v[160:163], v[178:181], 0
	v_mfma_f32_16x16x32_bf16 v[112:115], v[168:171], v[178:181], 0
	v_mfma_f32_16x16x32_bf16 v[108:111], v[160:163], v[186:189], 0
	v_mfma_f32_16x16x32_bf16 v[96:99], v[168:171], v[186:189], 0
	v_mfma_f32_16x16x32_bf16 v[92:95], v[160:163], v[194:197], 0
	v_mfma_f32_16x16x32_bf16 v[80:83], v[168:171], v[194:197], 0
	v_mfma_f32_16x16x32_bf16 v[76:79], v[160:163], v[202:205], 0
	v_mfma_f32_16x16x32_bf16 v[64:67], v[168:171], v[202:205], 0
	v_mfma_f32_16x16x32_bf16 v[124:127], v[164:167], v[182:185], v[124:127]
	v_mfma_f32_16x16x32_bf16 v[112:115], v[172:175], v[182:185], v[112:115]
	v_mfma_f32_16x16x32_bf16 v[108:111], v[164:167], v[190:193], v[108:111]
	v_mfma_f32_16x16x32_bf16 v[96:99], v[172:175], v[190:193], v[96:99]
	v_mfma_f32_16x16x32_bf16 v[92:95], v[164:167], v[198:201], v[92:95]
	v_mfma_f32_16x16x32_bf16 v[80:83], v[172:175], v[198:201], v[80:83]
	v_mfma_f32_16x16x32_bf16 v[76:79], v[164:167], v[206:209], v[76:79]
	v_mfma_f32_16x16x32_bf16 v[64:67], v[172:175], v[206:209], v[64:67]
	s_add_i32 s63, s63, 2
	s_add_u32 s26, s26, 0x100
	s_addc_u32 s27, s27, 0
	s_add_u32 s61, s61, 0x100
	s_addc_u32 s62, s62, 0
	s_setprio 0
	s_barrier
	s_add_u32 s66, s42, 0x20000
	ds_read_b128 v[178:181], v140 offset:16384
	ds_read_b128 v[182:185], v140 offset:17408
	ds_read_b128 v[186:189], v140 offset:18432
	ds_read_b128 v[190:193], v140 offset:19456
	ds_read_b128 v[194:197], v140 offset:20480
	ds_read_b128 v[198:201], v140 offset:21504
	ds_read_b128 v[202:205], v140 offset:22528
	ds_read_b128 v[206:209], v140 offset:23552
	s_mov_b32 m0, s35
	s_nop 0
	global_load_lds_dwordx4 v135, s[42:43]
	s_mov_b32 m0, s36
	s_addc_u32 s67, s43, 0
	global_load_lds_dwordx4 v135, s[66:67]
	s_add_u32 s66, s42, 0x40000
	s_mov_b32 m0, s37
	s_addc_u32 s67, s43, 0
	global_load_lds_dwordx4 v135, s[66:67]
	s_add_u32 s66, s42, 0x60000
	s_mov_b32 m0, s44
	s_addc_u32 s67, s43, 0
	global_load_lds_dwordx4 v135, s[66:67]
	s_mov_b32 m0, s34
	s_nop 0
	global_load_lds_dwordx4 v134, s[38:39]
	s_add_u32 s66, s38, 0x20000
	s_mov_b32 m0, s45
	s_addc_u32 s67, s39, 0
	global_load_lds_dwordx4 v134, s[66:67]
	s_waitcnt vmcnt(8) lgkmcnt(0)
	s_barrier
	s_setprio 1
	v_mfma_f32_16x16x32_bf16 v[56:59], v[144:147], v[178:181], 0
	v_mfma_f32_16x16x32_bf16 v[52:55], v[152:155], v[178:181], 0
	v_mfma_f32_16x16x32_bf16 v[40:43], v[144:147], v[186:189], 0
	v_mfma_f32_16x16x32_bf16 v[36:39], v[152:155], v[186:189], 0
	v_mfma_f32_16x16x32_bf16 v[24:27], v[144:147], v[194:197], 0
	v_mfma_f32_16x16x32_bf16 v[20:23], v[152:155], v[194:197], 0
	v_mfma_f32_16x16x32_bf16 v[8:11], v[144:147], v[202:205], 0
	v_mfma_f32_16x16x32_bf16 v[4:7], v[152:155], v[202:205], 0
	v_mfma_f32_16x16x32_bf16 v[56:59], v[148:151], v[182:185], v[56:59]
	v_mfma_f32_16x16x32_bf16 v[52:55], v[156:159], v[182:185], v[52:55]
	v_mfma_f32_16x16x32_bf16 v[40:43], v[148:151], v[190:193], v[40:43]
	v_mfma_f32_16x16x32_bf16 v[36:39], v[156:159], v[190:193], v[36:39]
	v_mfma_f32_16x16x32_bf16 v[24:27], v[148:151], v[198:201], v[24:27]
	v_mfma_f32_16x16x32_bf16 v[20:23], v[156:159], v[198:201], v[20:23]
	v_mfma_f32_16x16x32_bf16 v[8:11], v[148:151], v[206:209], v[8:11]
	v_mfma_f32_16x16x32_bf16 v[4:7], v[156:159], v[206:209], v[4:7]
	v_mfma_f32_16x16x32_bf16 v[60:63], v[160:163], v[178:181], 0
	v_mfma_f32_16x16x32_bf16 v[48:51], v[168:171], v[178:181], 0
	v_mfma_f32_16x16x32_bf16 v[44:47], v[160:163], v[186:189], 0
	v_mfma_f32_16x16x32_bf16 v[32:35], v[168:171], v[186:189], 0
	v_mfma_f32_16x16x32_bf16 v[28:31], v[160:163], v[194:197], 0
	v_mfma_f32_16x16x32_bf16 v[16:19], v[168:171], v[194:197], 0
	v_mfma_f32_16x16x32_bf16 v[12:15], v[160:163], v[202:205], 0
	v_mfma_f32_16x16x32_bf16 v[0:3], v[168:171], v[202:205], 0
	v_mfma_f32_16x16x32_bf16 v[60:63], v[164:167], v[182:185], v[60:63]
	v_mfma_f32_16x16x32_bf16 v[48:51], v[172:175], v[182:185], v[48:51]
	v_mfma_f32_16x16x32_bf16 v[44:47], v[164:167], v[190:193], v[44:47]
	v_mfma_f32_16x16x32_bf16 v[32:35], v[172:175], v[190:193], v[32:35]
	v_mfma_f32_16x16x32_bf16 v[28:31], v[164:167], v[198:201], v[28:31]
	v_mfma_f32_16x16x32_bf16 v[16:19], v[172:175], v[198:201], v[16:19]
	v_mfma_f32_16x16x32_bf16 v[12:15], v[164:167], v[206:209], v[12:15]
	v_mfma_f32_16x16x32_bf16 v[0:3], v[172:175], v[206:209], v[0:3]
	s_setprio 0
	s_barrier
	s_branch .Lpeel_mid_30674
; #define PG8_STAGE(bufoff, gbase, voff, p64) do { _Pragma("unroll") for (int _i = 0; _i < 2; ++_i) { \
;         const char* _gb = (const char*)(gbase) + (size_t)_i * (p64); const unsigned _la = ldsbase + (unsigned)(bufoff) + (unsigned)_i * 8192u; \
;         asm volatile("s_mov_b32 m0, %0\n\ts_nop 0\n\tglobal_load_lds_dwordx4 %1, %2" :: "s"(_la), "v"(voff), "s"(_gb) : "memory"); } } while (0)
; #define PG8_LDA(dst, b, h) do { _Pragma("unroll") for (int m = 0; m < 4; ++m) _Pragma("unroll") for (int k = 0; k < 2; ++k) dst[m][k] = *(const LAS bf16x8*)(lds + PG8_SA(b, h) + aoff + m * 2048 + k * 1024); } while (0)
; #define PG8_LDB(dst, b, h) do { _Pragma("unroll") for (int n = 0; n < 2; ++n) _Pragma("unroll") for (int k = 0; k < 2; ++k) dst[n][k] = *(const LAS bf16x8*)(lds + PG8_SB(b, h) + boff + n * 2048 + k * 1024); } while (0)
; #define PG8_MMA(ai, bj, At, Bt) do { __builtin_amdgcn_s_setprio(1); _Pragma("unroll") for (int m = 0; m < 4; ++m) _Pragma("unroll") for (int n = 0; n < 2; ++n) _Pragma("unroll") for (int k = 0; k < 2; ++k) \
;         acc[ai][bj][m][n] = __builtin_amdgcn_mfma_f32_16x16x32_bf16(Bt[n][k], At[m][k], acc[ai][bj][m][n], 0, 0, 0); __builtin_amdgcn_s_setprio(0); } while (0)
; #define PG8_WAIT_V(n) asm volatile("s_waitcnt vmcnt(" #n ")" ::: "memory")
; #define PG8_WAIT_L(n) asm volatile("s_waitcnt lgkmcnt(" #n ")" ::: "memory")
; #define PG8_BAR __builtin_amdgcn_s_barrier()
; #define PG8_SCHED __builtin_amdgcn_sched_barrier(0)
; template <class Epi, class Sched>
; __device__ __forceinline__ void gemm_phase(LAS unsigned char* lds, const Sched& S, const Epi& E) {
;     ...
;             PG8_LDB(B0, 0, 0); PG8_LDB(B1, 0, 1); PG8_SCHED; PG8_LDA(At, 0, 0); PG8_STAGE(PG8_SA(1, 1), a1 + hA, voffA, hA / 2);
;             PG8_WAIT_V(8); PG8_WAIT_L(0); PG8_BAR; PG8_MMA(0, 0, At, B0); PG8_MMA(0, 1, At, B1); PG8_BAR; PG8_SCHED;
;             PG8_LDA(At, 0, 1); PG8_STAGE(PG8_SB(0, 0), b2, vB2, hB2 / 2); PG8_STAGE(PG8_SB(0, 1), b2 + hB2, vB2, hB2 / 2); PG8_STAGE(PG8_SA(0, 0), a2, vA2, hA2 / 2);
;             PG8_WAIT_V(8); PG8_WAIT_L(0); PG8_BAR; PG8_MMA(1, 0, At, B0); PG8_MMA(1, 1, At, B1); PG8_BAR; PG8_SCHED;
.LBB0_1011:
	ds_read_b128 v[144:147], v138
	ds_read_b128 v[148:151], v138 offset:1024
	ds_read_b128 v[152:155], v138 offset:2048
	ds_read_b128 v[156:159], v138 offset:3072
	ds_read_b128 v[160:163], v139
	ds_read_b128 v[164:167], v139 offset:1024
	ds_read_b128 v[168:171], v139 offset:2048
	ds_read_b128 v[172:175], v139 offset:3072
	s_add_u32 s30, s26, 0xfffc0080
	s_addc_u32 s38, s27, -1
	s_cmp_eq_u32 s63, 12
	s_cselect_b32 s39, s23, s38
	s_cselect_b32 s38, s22, s30
	s_cselect_b32 s42, s24, s61
	s_cselect_b32 s43, s25, s62
	s_add_u32 s40, s38, 0x80
	s_addc_u32 s41, s39, 0
	ds_read_b128 v[178:181], v140
	ds_read_b128 v[182:185], v140 offset:1024
	ds_read_b128 v[186:189], v140 offset:2048
	ds_read_b128 v[190:193], v140 offset:3072
	ds_read_b128 v[194:197], v140 offset:4096
	ds_read_b128 v[198:201], v140 offset:5120
	ds_read_b128 v[202:205], v140 offset:6144
	ds_read_b128 v[206:209], v140 offset:7168
	s_mov_b32 m0, s57
	s_nop 0
	global_load_lds_dwordx4 v134, s[26:27]
	s_add_u32 s66, s26, 0x20000
	s_mov_b32 m0, s58
	s_addc_u32 s67, s27, 0
	global_load_lds_dwordx4 v134, s[66:67]
	s_waitcnt vmcnt(8) lgkmcnt(0)
	s_barrier
	s_setprio 1
	v_mfma_f32_16x16x32_bf16 v[120:123], v[144:147], v[178:181], v[120:123]
	v_mfma_f32_16x16x32_bf16 v[116:119], v[152:155], v[178:181], v[116:119]
	v_mfma_f32_16x16x32_bf16 v[104:107], v[144:147], v[186:189], v[104:107]
	v_mfma_f32_16x16x32_bf16 v[100:103], v[152:155], v[186:189], v[100:103]
	v_mfma_f32_16x16x32_bf16 v[88:91], v[144:147], v[194:197], v[88:91]
	v_mfma_f32_16x16x32_bf16 v[84:87], v[152:155], v[194:197], v[84:87]
	v_mfma_f32_16x16x32_bf16 v[72:75], v[144:147], v[202:205], v[72:75]
	v_mfma_f32_16x16x32_bf16 v[68:71], v[152:155], v[202:205], v[68:71]
	v_mfma_f32_16x16x32_bf16 v[120:123], v[148:151], v[182:185], v[120:123]
	v_mfma_f32_16x16x32_bf16 v[116:119], v[156:159], v[182:185], v[116:119]
	v_mfma_f32_16x16x32_bf16 v[104:107], v[148:151], v[190:193], v[104:107]
	v_mfma_f32_16x16x32_bf16 v[100:103], v[156:159], v[190:193], v[100:103]
	v_mfma_f32_16x16x32_bf16 v[88:91], v[148:151], v[198:201], v[88:91]
	v_mfma_f32_16x16x32_bf16 v[84:87], v[156:159], v[198:201], v[84:87]
	v_mfma_f32_16x16x32_bf16 v[72:75], v[148:151], v[206:209], v[72:75]
	v_mfma_f32_16x16x32_bf16 v[68:71], v[156:159], v[206:209], v[68:71]
	v_mfma_f32_16x16x32_bf16 v[124:127], v[160:163], v[178:181], v[124:127]
	v_mfma_f32_16x16x32_bf16 v[112:115], v[168:171], v[178:181], v[112:115]
	v_mfma_f32_16x16x32_bf16 v[108:111], v[160:163], v[186:189], v[108:111]
	v_mfma_f32_16x16x32_bf16 v[96:99], v[168:171], v[186:189], v[96:99]
	v_mfma_f32_16x16x32_bf16 v[92:95], v[160:163], v[194:197], v[92:95]
	v_mfma_f32_16x16x32_bf16 v[80:83], v[168:171], v[194:197], v[80:83]
	v_mfma_f32_16x16x32_bf16 v[76:79], v[160:163], v[202:205], v[76:79]
	v_mfma_f32_16x16x32_bf16 v[64:67], v[168:171], v[202:205], v[64:67]
	v_mfma_f32_16x16x32_bf16 v[124:127], v[164:167], v[182:185], v[124:127]
	v_mfma_f32_16x16x32_bf16 v[112:115], v[172:175], v[182:185], v[112:115]
	v_mfma_f32_16x16x32_bf16 v[108:111], v[164:167], v[190:193], v[108:111]
	v_mfma_f32_16x16x32_bf16 v[96:99], v[172:175], v[190:193], v[96:99]
	v_mfma_f32_16x16x32_bf16 v[92:95], v[164:167], v[198:201], v[92:95]
	v_mfma_f32_16x16x32_bf16 v[80:83], v[172:175], v[198:201], v[80:83]
	v_mfma_f32_16x16x32_bf16 v[76:79], v[164:167], v[206:209], v[76:79]
	v_mfma_f32_16x16x32_bf16 v[64:67], v[172:175], v[206:209], v[64:67]
	s_add_i32 s63, s63, 2
	s_add_u32 s26, s26, 0x100
	s_addc_u32 s27, s27, 0
	s_add_u32 s61, s61, 0x100
	s_addc_u32 s62, s62, 0
	s_setprio 0
	s_barrier
	s_add_u32 s66, s42, 0x20000
	ds_read_b128 v[178:181], v140 offset:16384
	ds_read_b128 v[182:185], v140 offset:17408
	ds_read_b128 v[186:189], v140 offset:18432
	ds_read_b128 v[190:193], v140 offset:19456
	ds_read_b128 v[194:197], v140 offset:20480
	ds_read_b128 v[198:201], v140 offset:21504
	ds_read_b128 v[202:205], v140 offset:22528
	ds_read_b128 v[206:209], v140 offset:23552
	s_mov_b32 m0, s35
	s_nop 0
	global_load_lds_dwordx4 v135, s[42:43]
	s_mov_b32 m0, s36
	s_addc_u32 s67, s43, 0
	global_load_lds_dwordx4 v135, s[66:67]
	s_add_u32 s66, s42, 0x40000
	s_mov_b32 m0, s37
	s_addc_u32 s67, s43, 0
	global_load_lds_dwordx4 v135, s[66:67]
	s_add_u32 s66, s42, 0x60000
	s_mov_b32 m0, s44
	s_addc_u32 s67, s43, 0
	global_load_lds_dwordx4 v135, s[66:67]
	s_mov_b32 m0, s34
	s_nop 0
	global_load_lds_dwordx4 v134, s[38:39]
	s_add_u32 s66, s38, 0x20000
	s_mov_b32 m0, s45
	s_addc_u32 s67, s39, 0
	global_load_lds_dwordx4 v134, s[66:67]
	s_waitcnt vmcnt(8) lgkmcnt(0)
	s_barrier
	s_setprio 1
	v_mfma_f32_16x16x32_bf16 v[56:59], v[144:147], v[178:181], v[56:59]
	v_mfma_f32_16x16x32_bf16 v[52:55], v[152:155], v[178:181], v[52:55]
	v_mfma_f32_16x16x32_bf16 v[40:43], v[144:147], v[186:189], v[40:43]
	v_mfma_f32_16x16x32_bf16 v[36:39], v[152:155], v[186:189], v[36:39]
	v_mfma_f32_16x16x32_bf16 v[24:27], v[144:147], v[194:197], v[24:27]
	v_mfma_f32_16x16x32_bf16 v[20:23], v[152:155], v[194:197], v[20:23]
	v_mfma_f32_16x16x32_bf16 v[8:11], v[144:147], v[202:205], v[8:11]
	v_mfma_f32_16x16x32_bf16 v[4:7], v[152:155], v[202:205], v[4:7]
	v_mfma_f32_16x16x32_bf16 v[56:59], v[148:151], v[182:185], v[56:59]
	v_mfma_f32_16x16x32_bf16 v[52:55], v[156:159], v[182:185], v[52:55]
	v_mfma_f32_16x16x32_bf16 v[40:43], v[148:151], v[190:193], v[40:43]
	v_mfma_f32_16x16x32_bf16 v[36:39], v[156:159], v[190:193], v[36:39]
	v_mfma_f32_16x16x32_bf16 v[24:27], v[148:151], v[198:201], v[24:27]
	v_mfma_f32_16x16x32_bf16 v[20:23], v[156:159], v[198:201], v[20:23]
	v_mfma_f32_16x16x32_bf16 v[8:11], v[148:151], v[206:209], v[8:11]
	v_mfma_f32_16x16x32_bf16 v[4:7], v[156:159], v[206:209], v[4:7]
	v_mfma_f32_16x16x32_bf16 v[60:63], v[160:163], v[178:181], v[60:63]
	v_mfma_f32_16x16x32_bf16 v[48:51], v[168:171], v[178:181], v[48:51]
	v_mfma_f32_16x16x32_bf16 v[44:47], v[160:163], v[186:189], v[44:47]
	v_mfma_f32_16x16x32_bf16 v[32:35], v[168:171], v[186:189], v[32:35]
	v_mfma_f32_16x16x32_bf16 v[28:31], v[160:163], v[194:197], v[28:31]
	v_mfma_f32_16x16x32_bf16 v[16:19], v[168:171], v[194:197], v[16:19]
	v_mfma_f32_16x16x32_bf16 v[12:15], v[160:163], v[202:205], v[12:15]
	v_mfma_f32_16x16x32_bf16 v[0:3], v[168:171], v[202:205], v[0:3]
	v_mfma_f32_16x16x32_bf16 v[60:63], v[164:167], v[182:185], v[60:63]
	v_mfma_f32_16x16x32_bf16 v[48:51], v[172:175], v[182:185], v[48:51]
	v_mfma_f32_16x16x32_bf16 v[44:47], v[164:167], v[190:193], v[44:47]
	v_mfma_f32_16x16x32_bf16 v[32:35], v[172:175], v[190:193], v[32:35]
	v_mfma_f32_16x16x32_bf16 v[28:31], v[164:167], v[198:201], v[28:31]
	v_mfma_f32_16x16x32_bf16 v[16:19], v[172:175], v[198:201], v[16:19]
	v_mfma_f32_16x16x32_bf16 v[12:15], v[164:167], v[206:209], v[12:15]
	v_mfma_f32_16x16x32_bf16 v[0:3], v[172:175], v[206:209], v[0:3]
	s_setprio 0
	s_barrier
; #define PG8_STAGE(bufoff, gbase, voff, p64) do { _Pragma("unroll") for (int _i = 0; _i < 2; ++_i) { \
;         const char* _gb = (const char*)(gbase) + (size_t)_i * (p64); const unsigned _la = ldsbase + (unsigned)(bufoff) + (unsigned)_i * 8192u; \
;         asm volatile("s_mov_b32 m0, %0\n\ts_nop 0\n\tglobal_load_lds_dwordx4 %1, %2" :: "s"(_la), "v"(voff), "s"(_gb) : "memory"); } } while (0)
; #define PG8_LDA(dst, b, h) do { _Pragma("unroll") for (int m = 0; m < 4; ++m) _Pragma("unroll") for (int k = 0; k < 2; ++k) dst[m][k] = *(const LAS bf16x8*)(lds + PG8_SA(b, h) + aoff + m * 2048 + k * 1024); } while (0)
; #define PG8_LDB(dst, b, h) do { _Pragma("unroll") for (int n = 0; n < 2; ++n) _Pragma("unroll") for (int k = 0; k < 2; ++k) dst[n][k] = *(const LAS bf16x8*)(lds + PG8_SB(b, h) + boff + n * 2048 + k * 1024); } while (0)
; #define PG8_MMA(ai, bj, At, Bt) do { __builtin_amdgcn_s_setprio(1); _Pragma("unroll") for (int m = 0; m < 4; ++m) _Pragma("unroll") for (int n = 0; n < 2; ++n) _Pragma("unroll") for (int k = 0; k < 2; ++k) \
;         acc[ai][bj][m][n] = __builtin_amdgcn_mfma_f32_16x16x32_bf16(Bt[n][k], At[m][k], acc[ai][bj][m][n], 0, 0, 0); __builtin_amdgcn_s_setprio(0); } while (0)
; #define PG8_WAIT_V(n) asm volatile("s_waitcnt vmcnt(" #n ")" ::: "memory")
; #define PG8_WAIT_L(n) asm volatile("s_waitcnt lgkmcnt(" #n ")" ::: "memory")
; #define PG8_BAR __builtin_amdgcn_s_barrier()
; #define PG8_SCHED __builtin_amdgcn_sched_barrier(0)
; template <class Epi, class Sched>
; __device__ __forceinline__ void gemm_phase(LAS unsigned char* lds, const Sched& S, const Epi& E) {
;     ...
;             PG8_LDB(B0, 1, 0); PG8_LDB(B1, 1, 1); PG8_SCHED; PG8_LDA(At, 1, 0); PG8_STAGE(PG8_SA(0, 1), a2 + hA2, vA2, hA2 / 2);
;             PG8_WAIT_V(8); PG8_WAIT_L(0); PG8_BAR; PG8_MMA(0, 0, At, B0); PG8_MMA(0, 1, At, B1); PG8_BAR; PG8_SCHED;
;             PG8_LDA(At, 1, 1); PG8_STAGE(PG8_SB(1, 0), b3, vB2, hB2 / 2); PG8_STAGE(PG8_SB(1, 1), b3 + hB2, vB2, hB2 / 2); PG8_STAGE(PG8_SA(1, 0), a3, vA2, hA2 / 2);
;             PG8_WAIT_V(8); PG8_WAIT_L(0); PG8_BAR; PG8_MMA(1, 0, At, B0); PG8_MMA(1, 1, At, B1); PG8_BAR; PG8_SCHED;
;         }
;         if (wr == 0) PG8_BAR;
.Lpeel_mid_30674:
	ds_read_b128 v[144:147], v141
	ds_read_b128 v[148:151], v141 offset:1024
	ds_read_b128 v[152:155], v141 offset:2048
	ds_read_b128 v[156:159], v141 offset:3072
	ds_read_b128 v[160:163], v142
	ds_read_b128 v[164:167], v142 offset:1024
	ds_read_b128 v[168:171], v142 offset:2048
	ds_read_b128 v[172:175], v142 offset:3072
	ds_read_b128 v[178:181], v140 offset:32768
	ds_read_b128 v[182:185], v140 offset:33792
	ds_read_b128 v[186:189], v140 offset:34816
	ds_read_b128 v[190:193], v140 offset:35840
	ds_read_b128 v[194:197], v140 offset:36864
	ds_read_b128 v[198:201], v140 offset:37888
	ds_read_b128 v[202:205], v140 offset:38912
	ds_read_b128 v[206:209], v140 offset:39936
	s_add_u32 s66, s38, 0x40000
	s_mov_b32 m0, s46
	s_addc_u32 s67, s39, 0
	global_load_lds_dwordx4 v134, s[66:67]
	s_add_u32 s66, s38, 0x60000
	s_mov_b32 m0, s47
	s_addc_u32 s67, s39, 0
	global_load_lds_dwordx4 v134, s[66:67]
	s_waitcnt vmcnt(8) lgkmcnt(0)
	s_barrier
	s_setprio 1
	v_mfma_f32_16x16x32_bf16 v[120:123], v[144:147], v[178:181], v[120:123]
	v_mfma_f32_16x16x32_bf16 v[116:119], v[152:155], v[178:181], v[116:119]
	v_mfma_f32_16x16x32_bf16 v[104:107], v[144:147], v[186:189], v[104:107]
	v_mfma_f32_16x16x32_bf16 v[100:103], v[152:155], v[186:189], v[100:103]
	v_mfma_f32_16x16x32_bf16 v[88:91], v[144:147], v[194:197], v[88:91]
	v_mfma_f32_16x16x32_bf16 v[84:87], v[152:155], v[194:197], v[84:87]
	v_mfma_f32_16x16x32_bf16 v[72:75], v[144:147], v[202:205], v[72:75]
	v_mfma_f32_16x16x32_bf16 v[68:71], v[152:155], v[202:205], v[68:71]
	v_mfma_f32_16x16x32_bf16 v[120:123], v[148:151], v[182:185], v[120:123]
	v_mfma_f32_16x16x32_bf16 v[116:119], v[156:159], v[182:185], v[116:119]
	v_mfma_f32_16x16x32_bf16 v[104:107], v[148:151], v[190:193], v[104:107]
	v_mfma_f32_16x16x32_bf16 v[100:103], v[156:159], v[190:193], v[100:103]
	v_mfma_f32_16x16x32_bf16 v[88:91], v[148:151], v[198:201], v[88:91]
	v_mfma_f32_16x16x32_bf16 v[84:87], v[156:159], v[198:201], v[84:87]
	v_mfma_f32_16x16x32_bf16 v[72:75], v[148:151], v[206:209], v[72:75]
	v_mfma_f32_16x16x32_bf16 v[68:71], v[156:159], v[206:209], v[68:71]
	v_mfma_f32_16x16x32_bf16 v[124:127], v[160:163], v[178:181], v[124:127]
	v_mfma_f32_16x16x32_bf16 v[112:115], v[168:171], v[178:181], v[112:115]
	v_mfma_f32_16x16x32_bf16 v[108:111], v[160:163], v[186:189], v[108:111]
	v_mfma_f32_16x16x32_bf16 v[96:99], v[168:171], v[186:189], v[96:99]
	v_mfma_f32_16x16x32_bf16 v[92:95], v[160:163], v[194:197], v[92:95]
	v_mfma_f32_16x16x32_bf16 v[80:83], v[168:171], v[194:197], v[80:83]
	v_mfma_f32_16x16x32_bf16 v[76:79], v[160:163], v[202:205], v[76:79]
	v_mfma_f32_16x16x32_bf16 v[64:67], v[168:171], v[202:205], v[64:67]
	v_mfma_f32_16x16x32_bf16 v[124:127], v[164:167], v[182:185], v[124:127]
	v_mfma_f32_16x16x32_bf16 v[112:115], v[172:175], v[182:185], v[112:115]
	v_mfma_f32_16x16x32_bf16 v[108:111], v[164:167], v[190:193], v[108:111]
	v_mfma_f32_16x16x32_bf16 v[96:99], v[172:175], v[190:193], v[96:99]
	v_mfma_f32_16x16x32_bf16 v[92:95], v[164:167], v[198:201], v[92:95]
	v_mfma_f32_16x16x32_bf16 v[80:83], v[172:175], v[198:201], v[80:83]
	v_mfma_f32_16x16x32_bf16 v[76:79], v[164:167], v[206:209], v[76:79]
	v_mfma_f32_16x16x32_bf16 v[64:67], v[172:175], v[206:209], v[64:67]
	s_setprio 0
	s_barrier
	s_add_u32 s66, s42, 0x80
	s_addc_u32 s67, s43, 0
	ds_read_b128 v[178:181], v140 offset:49152
	ds_read_b128 v[182:185], v140 offset:50176
	ds_read_b128 v[186:189], v140 offset:51200
	ds_read_b128 v[190:193], v140 offset:52224
	ds_read_b128 v[194:197], v140 offset:53248
	ds_read_b128 v[198:201], v140 offset:54272
	ds_read_b128 v[202:205], v140 offset:55296
	ds_read_b128 v[206:209], v140 offset:56320
	s_mov_b32 m0, s51
	s_nop 0
	global_load_lds_dwordx4 v135, s[66:67]
	s_add_u32 s66, s42, 0x20080
	s_mov_b32 m0, s52
	s_addc_u32 s67, s43, 0
	global_load_lds_dwordx4 v135, s[66:67]
	s_add_u32 s66, s42, 0x40080
	s_mov_b32 m0, s55
	s_addc_u32 s67, s43, 0
	global_load_lds_dwordx4 v135, s[66:67]
	s_add_u32 s42, s42, 0x60080
	s_mov_b32 m0, s56
	s_addc_u32 s43, s43, 0
	global_load_lds_dwordx4 v135, s[42:43]
	s_mov_b32 m0, s53
	s_nop 0
	global_load_lds_dwordx4 v134, s[40:41]
	s_add_u32 s38, s38, 0x20080
	s_mov_b32 m0, s54
	s_addc_u32 s39, s39, 0
	global_load_lds_dwordx4 v134, s[38:39]
	s_waitcnt vmcnt(8) lgkmcnt(0)
	s_barrier
	s_setprio 1
	v_mfma_f32_16x16x32_bf16 v[56:59], v[144:147], v[178:181], v[56:59]
	v_mfma_f32_16x16x32_bf16 v[52:55], v[152:155], v[178:181], v[52:55]
	v_mfma_f32_16x16x32_bf16 v[40:43], v[144:147], v[186:189], v[40:43]
	v_mfma_f32_16x16x32_bf16 v[36:39], v[152:155], v[186:189], v[36:39]
	v_mfma_f32_16x16x32_bf16 v[24:27], v[144:147], v[194:197], v[24:27]
	v_mfma_f32_16x16x32_bf16 v[20:23], v[152:155], v[194:197], v[20:23]
	v_mfma_f32_16x16x32_bf16 v[8:11], v[144:147], v[202:205], v[8:11]
	v_mfma_f32_16x16x32_bf16 v[4:7], v[152:155], v[202:205], v[4:7]
	v_mfma_f32_16x16x32_bf16 v[56:59], v[148:151], v[182:185], v[56:59]
	v_mfma_f32_16x16x32_bf16 v[52:55], v[156:159], v[182:185], v[52:55]
	v_mfma_f32_16x16x32_bf16 v[40:43], v[148:151], v[190:193], v[40:43]
	v_mfma_f32_16x16x32_bf16 v[36:39], v[156:159], v[190:193], v[36:39]
	v_mfma_f32_16x16x32_bf16 v[24:27], v[148:151], v[198:201], v[24:27]
	v_mfma_f32_16x16x32_bf16 v[20:23], v[156:159], v[198:201], v[20:23]
	v_mfma_f32_16x16x32_bf16 v[8:11], v[148:151], v[206:209], v[8:11]
	v_mfma_f32_16x16x32_bf16 v[4:7], v[156:159], v[206:209], v[4:7]
	v_mfma_f32_16x16x32_bf16 v[60:63], v[160:163], v[178:181], v[60:63]
	v_mfma_f32_16x16x32_bf16 v[48:51], v[168:171], v[178:181], v[48:51]
	v_mfma_f32_16x16x32_bf16 v[44:47], v[160:163], v[186:189], v[44:47]
	v_mfma_f32_16x16x32_bf16 v[32:35], v[168:171], v[186:189], v[32:35]
	v_mfma_f32_16x16x32_bf16 v[28:31], v[160:163], v[194:197], v[28:31]
	v_mfma_f32_16x16x32_bf16 v[16:19], v[168:171], v[194:197], v[16:19]
	v_mfma_f32_16x16x32_bf16 v[12:15], v[160:163], v[202:205], v[12:15]
	v_mfma_f32_16x16x32_bf16 v[0:3], v[168:171], v[202:205], v[0:3]
	v_mfma_f32_16x16x32_bf16 v[60:63], v[164:167], v[182:185], v[60:63]
	v_mfma_f32_16x16x32_bf16 v[48:51], v[172:175], v[182:185], v[48:51]
	v_mfma_f32_16x16x32_bf16 v[44:47], v[164:167], v[190:193], v[44:47]
	v_mfma_f32_16x16x32_bf16 v[32:35], v[172:175], v[190:193], v[32:35]
	v_mfma_f32_16x16x32_bf16 v[28:31], v[164:167], v[198:201], v[28:31]
	v_mfma_f32_16x16x32_bf16 v[16:19], v[172:175], v[198:201], v[16:19]
	v_mfma_f32_16x16x32_bf16 v[12:15], v[164:167], v[206:209], v[12:15]
	v_mfma_f32_16x16x32_bf16 v[0:3], v[172:175], v[206:209], v[0:3]
	s_setprio 0
	s_barrier
	s_cmp_gt_u32 s63, 13
	s_cbranch_scc0 .LBB0_1011
	s_and_b64 vcc, exec, s[14:15]
	s_cbranch_vccz .LBB0_1014
	s_barrier

; #define PG8_STAGE(bufoff, gbase, voff, p64) do { _Pragma("unroll") for (int _i = 0; _i < 2; ++_i) { \
;         const char* _gb = (const char*)(gbase) + (size_t)_i * (p64); const unsigned _la = ldsbase + (unsigned)(bufoff) + (unsigned)_i * 8192u; \
;         asm volatile("s_mov_b32 m0, %0\n\ts_nop 0\n\tglobal_load_lds_dwordx4 %1, %2" :: "s"(_la), "v"(voff), "s"(_gb) : "memory"); } } while (0)
; #define PG8_LDA(dst, b, h) do { _Pragma("unroll") for (int m = 0; m < 4; ++m) _Pragma("unroll") for (int k = 0; k < 2; ++k) dst[m][k] = *(const LAS bf16x8*)(lds + PG8_SA(b, h) + aoff + m * 2048 + k * 1024); } while (0)
; #define PG8_LDB(dst, b, h) do { _Pragma("unroll") for (int n = 0; n < 2; ++n) _Pragma("unroll") for (int k = 0; k < 2; ++k) dst[n][k] = *(const LAS bf16x8*)(lds + PG8_SB(b, h) + boff + n * 2048 + k * 1024); } while (0)
; #define PG8_WAIT_V(n) asm volatile("s_waitcnt vmcnt(" #n ")" ::: "memory")
; #define PG8_BAR __builtin_amdgcn_s_barrier()
; template <class Epi, class Sched>
; __device__ __forceinline__ void gemm_phase(LAS unsigned char* lds, const Sched& S, const Epi& E) {
;     ...
;         for (int t = 0; t < nt; t += 2) {
;             const bool last = (t == nt - 2);
;             const char* a1 = cA + (size_t)(t + 1) * kstep;
;             const char* a2 = last ? nA : cA + (size_t)(t + 2) * kstep; const char* b2 = last ? nB : cB + (size_t)(t + 2) * kstep;
;             const char* a3 = a2 + kstep; const char* b3 = b2 + kstep;
;             const unsigned vA2 = voffA, vB2 = voffB, hA2 = hA, hB2 = hB;
;             PG8_LDB(B0, 0, 0); PG8_LDB(B1, 0, 1); PG8_SCHED; PG8_LDA(At, 0, 0); PG8_STAGE(PG8_SA(1, 1), a1 + hA, voffA, hA / 2);
;             PG8_WAIT_V(8); PG8_WAIT_L(0); PG8_BAR; PG8_MMA(0, 0, At, B0); PG8_MMA(0, 1, At, B1); PG8_BAR; PG8_SCHED;
;             PG8_LDA(At, 0, 1); PG8_STAGE(PG8_SB(0, 0), b2, vB2, hB2 / 2); PG8_STAGE(PG8_SB(0, 1), b2 + hB2, vB2, hB2 / 2); PG8_STAGE(PG8_SA(0, 0), a2, vA2, hA2 / 2);
;             PG8_WAIT_V(8); PG8_WAIT_L(0); PG8_BAR; PG8_MMA(1, 0, At, B0); PG8_MMA(1, 1, At, B1); PG8_BAR; PG8_SCHED;
;     ...
; #pragma unroll
;             for (int a = 0; a < 2; ++a)
; #pragma unroll
;                 for (int b = 0; b < 2; ++b)
; #pragma unroll
;                     for (int m = 0; m < 4; ++m)
; #pragma unroll
;                         for (int n = 0; n < 2; ++n) acc[a][b][m][n] = (f32x4){0.f, 0.f, 0.f, 0.f};
.LBB0_1088:
	s_add_u32 s38, s38, 0x80080
	s_addc_u32 s39, s39, 0
	s_add_u32 s60, s40, 0x100
	s_addc_u32 s61, s41, 0
	s_mov_b32 s62, -2
	ds_read_b128 v[144:147], v138
	ds_read_b128 v[148:151], v138 offset:1024
	ds_read_b128 v[152:155], v138 offset:2048
	ds_read_b128 v[156:159], v138 offset:3072
	ds_read_b128 v[160:163], v139
	ds_read_b128 v[164:167], v139 offset:1024
	ds_read_b128 v[168:171], v139 offset:2048
	ds_read_b128 v[172:175], v139 offset:3072
	s_add_u32 s30, s38, 0xfff80080
	s_addc_u32 s40, s39, -1
	s_cmp_eq_u32 s62, 28
	s_cselect_b32 s41, s25, s40
	s_cselect_b32 s40, s24, s30
	s_cselect_b32 s44, s26, s60
	s_cselect_b32 s45, s27, s61
	s_add_u32 s42, s40, 0x80
	s_addc_u32 s43, s41, 0
	ds_read_b128 v[178:181], v140
	ds_read_b128 v[182:185], v140 offset:1024
	ds_read_b128 v[186:189], v140 offset:2048
	ds_read_b128 v[190:193], v140 offset:3072
	ds_read_b128 v[194:197], v140 offset:4096
	ds_read_b128 v[198:201], v140 offset:5120
	ds_read_b128 v[202:205], v140 offset:6144
	ds_read_b128 v[206:209], v140 offset:7168
	s_mov_b32 m0, s56
	s_nop 0
	global_load_lds_dwordx4 v134, s[38:39]
	s_add_u32 s66, s38, 0x40000
	s_mov_b32 m0, s57
	s_addc_u32 s67, s39, 0
	global_load_lds_dwordx4 v134, s[66:67]
	s_waitcnt vmcnt(8) lgkmcnt(0)
	s_barrier
	s_setprio 1
	v_mfma_f32_16x16x32_bf16 v[124:127], v[144:147], v[178:181], 0
	v_mfma_f32_16x16x32_bf16 v[120:123], v[152:155], v[178:181], 0
	v_mfma_f32_16x16x32_bf16 v[116:119], v[144:147], v[186:189], 0
	v_mfma_f32_16x16x32_bf16 v[108:111], v[152:155], v[186:189], 0
	v_mfma_f32_16x16x32_bf16 v[100:103], v[144:147], v[194:197], 0
	v_mfma_f32_16x16x32_bf16 v[92:95], v[152:155], v[194:197], 0
	v_mfma_f32_16x16x32_bf16 v[84:87], v[144:147], v[202:205], 0
	v_mfma_f32_16x16x32_bf16 v[76:79], v[152:155], v[202:205], 0
	v_mfma_f32_16x16x32_bf16 v[124:127], v[148:151], v[182:185], v[124:127]
	v_mfma_f32_16x16x32_bf16 v[120:123], v[156:159], v[182:185], v[120:123]
	v_mfma_f32_16x16x32_bf16 v[116:119], v[148:151], v[190:193], v[116:119]
	v_mfma_f32_16x16x32_bf16 v[108:111], v[156:159], v[190:193], v[108:111]
	v_mfma_f32_16x16x32_bf16 v[100:103], v[148:151], v[198:201], v[100:103]
	v_mfma_f32_16x16x32_bf16 v[92:95], v[156:159], v[198:201], v[92:95]
	v_mfma_f32_16x16x32_bf16 v[84:87], v[148:151], v[206:209], v[84:87]
	v_mfma_f32_16x16x32_bf16 v[76:79], v[156:159], v[206:209], v[76:79]
	v_mfma_f32_16x16x32_bf16 v[112:115], v[160:163], v[178:181], 0
	v_mfma_f32_16x16x32_bf16 v[104:107], v[168:171], v[178:181], 0
	v_mfma_f32_16x16x32_bf16 v[96:99], v[160:163], v[186:189], 0
	v_mfma_f32_16x16x32_bf16 v[88:91], v[168:171], v[186:189], 0
	v_mfma_f32_16x16x32_bf16 v[80:83], v[160:163], v[194:197], 0
	v_mfma_f32_16x16x32_bf16 v[72:75], v[168:171], v[194:197], 0
	v_mfma_f32_16x16x32_bf16 v[68:71], v[160:163], v[202:205], 0
	v_mfma_f32_16x16x32_bf16 v[64:67], v[168:171], v[202:205], 0
	v_mfma_f32_16x16x32_bf16 v[112:115], v[164:167], v[182:185], v[112:115]
	v_mfma_f32_16x16x32_bf16 v[104:107], v[172:175], v[182:185], v[104:107]
	v_mfma_f32_16x16x32_bf16 v[96:99], v[164:167], v[190:193], v[96:99]
	v_mfma_f32_16x16x32_bf16 v[88:91], v[172:175], v[190:193], v[88:91]
	v_mfma_f32_16x16x32_bf16 v[80:83], v[164:167], v[198:201], v[80:83]
	v_mfma_f32_16x16x32_bf16 v[72:75], v[172:175], v[198:201], v[72:75]
	v_mfma_f32_16x16x32_bf16 v[68:71], v[164:167], v[206:209], v[68:71]
	v_mfma_f32_16x16x32_bf16 v[64:67], v[172:175], v[206:209], v[64:67]
	s_add_i32 s62, s62, 2
	s_add_u32 s38, s38, 0x100
	s_addc_u32 s39, s39, 0
	s_add_u32 s60, s60, 0x100
	s_addc_u32 s61, s61, 0
	s_setprio 0
	s_barrier
	s_add_u32 s66, s44, 0x40000
	ds_read_b128 v[178:181], v140 offset:16384
	ds_read_b128 v[182:185], v140 offset:17408
	ds_read_b128 v[186:189], v140 offset:18432
	ds_read_b128 v[190:193], v140 offset:19456
	ds_read_b128 v[194:197], v140 offset:20480
	ds_read_b128 v[198:201], v140 offset:21504
	ds_read_b128 v[202:205], v140 offset:22528
	ds_read_b128 v[206:209], v140 offset:23552
	s_mov_b32 m0, s33
	s_nop 0
	global_load_lds_dwordx4 v135, s[44:45]
	s_mov_b32 m0, s34
	s_addc_u32 s67, s45, 0
	global_load_lds_dwordx4 v135, s[66:67]
	s_add_u32 s66, s44, 0x80000
	s_mov_b32 m0, s35
	s_addc_u32 s67, s45, 0
	global_load_lds_dwordx4 v135, s[66:67]
	s_add_u32 s66, s44, 0xc0000
	s_mov_b32 m0, s36
	s_addc_u32 s67, s45, 0
	global_load_lds_dwordx4 v135, s[66:67]
	s_mov_b32 m0, s31
	s_nop 0
	global_load_lds_dwordx4 v134, s[40:41]
	s_add_u32 s66, s40, 0x40000
	s_mov_b32 m0, s37
	s_addc_u32 s67, s41, 0
	global_load_lds_dwordx4 v134, s[66:67]
	s_waitcnt vmcnt(8) lgkmcnt(0)
	s_barrier
	s_setprio 1
	v_mfma_f32_16x16x32_bf16 v[60:63], v[144:147], v[178:181], 0
	v_mfma_f32_16x16x32_bf16 v[56:59], v[152:155], v[178:181], 0
	v_mfma_f32_16x16x32_bf16 v[52:55], v[144:147], v[186:189], 0
	v_mfma_f32_16x16x32_bf16 v[44:47], v[152:155], v[186:189], 0
	v_mfma_f32_16x16x32_bf16 v[36:39], v[144:147], v[194:197], 0
	v_mfma_f32_16x16x32_bf16 v[28:31], v[152:155], v[194:197], 0
	v_mfma_f32_16x16x32_bf16 v[20:23], v[144:147], v[202:205], 0
	v_mfma_f32_16x16x32_bf16 v[12:15], v[152:155], v[202:205], 0
	v_mfma_f32_16x16x32_bf16 v[60:63], v[148:151], v[182:185], v[60:63]
	v_mfma_f32_16x16x32_bf16 v[56:59], v[156:159], v[182:185], v[56:59]
	v_mfma_f32_16x16x32_bf16 v[52:55], v[148:151], v[190:193], v[52:55]
	v_mfma_f32_16x16x32_bf16 v[44:47], v[156:159], v[190:193], v[44:47]
	v_mfma_f32_16x16x32_bf16 v[36:39], v[148:151], v[198:201], v[36:39]
	v_mfma_f32_16x16x32_bf16 v[28:31], v[156:159], v[198:201], v[28:31]
	v_mfma_f32_16x16x32_bf16 v[20:23], v[148:151], v[206:209], v[20:23]
	v_mfma_f32_16x16x32_bf16 v[12:15], v[156:159], v[206:209], v[12:15]
	v_mfma_f32_16x16x32_bf16 v[48:51], v[160:163], v[178:181], 0
	v_mfma_f32_16x16x32_bf16 v[40:43], v[168:171], v[178:181], 0
	v_mfma_f32_16x16x32_bf16 v[32:35], v[160:163], v[186:189], 0
	v_mfma_f32_16x16x32_bf16 v[24:27], v[168:171], v[186:189], 0
	v_mfma_f32_16x16x32_bf16 v[16:19], v[160:163], v[194:197], 0
	v_mfma_f32_16x16x32_bf16 v[8:11], v[168:171], v[194:197], 0
	v_mfma_f32_16x16x32_bf16 v[4:7], v[160:163], v[202:205], 0
	v_mfma_f32_16x16x32_bf16 v[0:3], v[168:171], v[202:205], 0
	v_mfma_f32_16x16x32_bf16 v[48:51], v[164:167], v[182:185], v[48:51]
	v_mfma_f32_16x16x32_bf16 v[40:43], v[172:175], v[182:185], v[40:43]
	v_mfma_f32_16x16x32_bf16 v[32:35], v[164:167], v[190:193], v[32:35]
	v_mfma_f32_16x16x32_bf16 v[24:27], v[172:175], v[190:193], v[24:27]
	v_mfma_f32_16x16x32_bf16 v[16:19], v[164:167], v[198:201], v[16:19]
	v_mfma_f32_16x16x32_bf16 v[8:11], v[172:175], v[198:201], v[8:11]
	v_mfma_f32_16x16x32_bf16 v[4:7], v[164:167], v[206:209], v[4:7]
	v_mfma_f32_16x16x32_bf16 v[0:3], v[172:175], v[206:209], v[0:3]
	s_setprio 0
	s_barrier
	s_branch .Lpeel_mid_32521
; #define PG8_STAGE(bufoff, gbase, voff, p64) do { _Pragma("unroll") for (int _i = 0; _i < 2; ++_i) { \
;         const char* _gb = (const char*)(gbase) + (size_t)_i * (p64); const unsigned _la = ldsbase + (unsigned)(bufoff) + (unsigned)_i * 8192u; \
;         asm volatile("s_mov_b32 m0, %0\n\ts_nop 0\n\tglobal_load_lds_dwordx4 %1, %2" :: "s"(_la), "v"(voff), "s"(_gb) : "memory"); } } while (0)
; #define PG8_LDA(dst, b, h) do { _Pragma("unroll") for (int m = 0; m < 4; ++m) _Pragma("unroll") for (int k = 0; k < 2; ++k) dst[m][k] = *(const LAS bf16x8*)(lds + PG8_SA(b, h) + aoff + m * 2048 + k * 1024); } while (0)
; #define PG8_LDB(dst, b, h) do { _Pragma("unroll") for (int n = 0; n < 2; ++n) _Pragma("unroll") for (int k = 0; k < 2; ++k) dst[n][k] = *(const LAS bf16x8*)(lds + PG8_SB(b, h) + boff + n * 2048 + k * 1024); } while (0)
; #define PG8_MMA(ai, bj, At, Bt) do { __builtin_amdgcn_s_setprio(1); _Pragma("unroll") for (int m = 0; m < 4; ++m) _Pragma("unroll") for (int n = 0; n < 2; ++n) _Pragma("unroll") for (int k = 0; k < 2; ++k) \
;         acc[ai][bj][m][n] = __builtin_amdgcn_mfma_f32_16x16x32_bf16(Bt[n][k], At[m][k], acc[ai][bj][m][n], 0, 0, 0); __builtin_amdgcn_s_setprio(0); } while (0)
; #define PG8_WAIT_V(n) asm volatile("s_waitcnt vmcnt(" #n ")" ::: "memory")
; template <class Epi, class Sched>
; __device__ __forceinline__ void gemm_phase(LAS unsigned char* lds, const Sched& S, const Epi& E) {
;     ...
;         for (int t = 0; t < nt; t += 2) {
;             const bool last = (t == nt - 2);
;             const char* a1 = cA + (size_t)(t + 1) * kstep;
;             const char* a2 = last ? nA : cA + (size_t)(t + 2) * kstep; const char* b2 = last ? nB : cB + (size_t)(t + 2) * kstep;
;             const char* a3 = a2 + kstep; const char* b3 = b2 + kstep;
;             const unsigned vA2 = voffA, vB2 = voffB, hA2 = hA, hB2 = hB;
;             PG8_LDB(B0, 0, 0); PG8_LDB(B1, 0, 1); PG8_SCHED; PG8_LDA(At, 0, 0); PG8_STAGE(PG8_SA(1, 1), a1 + hA, voffA, hA / 2);
;             PG8_WAIT_V(8); PG8_WAIT_L(0); PG8_BAR; PG8_MMA(0, 0, At, B0); PG8_MMA(0, 1, At, B1); PG8_BAR; PG8_SCHED;
;             PG8_LDA(At, 0, 1); PG8_STAGE(PG8_SB(0, 0), b2, vB2, hB2 / 2); PG8_STAGE(PG8_SB(0, 1), b2 + hB2, vB2, hB2 / 2); PG8_STAGE(PG8_SA(0, 0), a2, vA2, hA2 / 2);
;             PG8_WAIT_V(8); PG8_WAIT_L(0); PG8_BAR; PG8_MMA(1, 0, At, B0); PG8_MMA(1, 1, At, B1); PG8_BAR; PG8_SCHED;
.LBB0_1089:
	ds_read_b128 v[144:147], v138
	ds_read_b128 v[148:151], v138 offset:1024
	ds_read_b128 v[152:155], v138 offset:2048
	ds_read_b128 v[156:159], v138 offset:3072
	ds_read_b128 v[160:163], v139
	ds_read_b128 v[164:167], v139 offset:1024
	ds_read_b128 v[168:171], v139 offset:2048
	ds_read_b128 v[172:175], v139 offset:3072
	s_add_u32 s30, s38, 0xfff80080
	s_addc_u32 s40, s39, -1
	s_cmp_eq_u32 s62, 28
	s_cselect_b32 s41, s25, s40
	s_cselect_b32 s40, s24, s30
	s_cselect_b32 s44, s26, s60
	s_cselect_b32 s45, s27, s61
	s_add_u32 s42, s40, 0x80
	s_addc_u32 s43, s41, 0
	ds_read_b128 v[178:181], v140
	ds_read_b128 v[182:185], v140 offset:1024
	ds_read_b128 v[186:189], v140 offset:2048
	ds_read_b128 v[190:193], v140 offset:3072
	ds_read_b128 v[194:197], v140 offset:4096
	ds_read_b128 v[198:201], v140 offset:5120
	ds_read_b128 v[202:205], v140 offset:6144
	ds_read_b128 v[206:209], v140 offset:7168
	s_mov_b32 m0, s56
	s_nop 0
	global_load_lds_dwordx4 v134, s[38:39]
	s_add_u32 s66, s38, 0x40000
	s_mov_b32 m0, s57
	s_addc_u32 s67, s39, 0
	global_load_lds_dwordx4 v134, s[66:67]
	s_waitcnt vmcnt(8) lgkmcnt(0)
	s_barrier
	s_setprio 1
	v_mfma_f32_16x16x32_bf16 v[124:127], v[144:147], v[178:181], v[124:127]
	v_mfma_f32_16x16x32_bf16 v[120:123], v[152:155], v[178:181], v[120:123]
	v_mfma_f32_16x16x32_bf16 v[116:119], v[144:147], v[186:189], v[116:119]
	v_mfma_f32_16x16x32_bf16 v[108:111], v[152:155], v[186:189], v[108:111]
	v_mfma_f32_16x16x32_bf16 v[100:103], v[144:147], v[194:197], v[100:103]
	v_mfma_f32_16x16x32_bf16 v[92:95], v[152:155], v[194:197], v[92:95]
	v_mfma_f32_16x16x32_bf16 v[84:87], v[144:147], v[202:205], v[84:87]
	v_mfma_f32_16x16x32_bf16 v[76:79], v[152:155], v[202:205], v[76:79]
	v_mfma_f32_16x16x32_bf16 v[124:127], v[148:151], v[182:185], v[124:127]
	v_mfma_f32_16x16x32_bf16 v[120:123], v[156:159], v[182:185], v[120:123]
	v_mfma_f32_16x16x32_bf16 v[116:119], v[148:151], v[190:193], v[116:119]
	v_mfma_f32_16x16x32_bf16 v[108:111], v[156:159], v[190:193], v[108:111]
	v_mfma_f32_16x16x32_bf16 v[100:103], v[148:151], v[198:201], v[100:103]
	v_mfma_f32_16x16x32_bf16 v[92:95], v[156:159], v[198:201], v[92:95]
	v_mfma_f32_16x16x32_bf16 v[84:87], v[148:151], v[206:209], v[84:87]
	v_mfma_f32_16x16x32_bf16 v[76:79], v[156:159], v[206:209], v[76:79]
	v_mfma_f32_16x16x32_bf16 v[112:115], v[160:163], v[178:181], v[112:115]
	v_mfma_f32_16x16x32_bf16 v[104:107], v[168:171], v[178:181], v[104:107]
	v_mfma_f32_16x16x32_bf16 v[96:99], v[160:163], v[186:189], v[96:99]
	v_mfma_f32_16x16x32_bf16 v[88:91], v[168:171], v[186:189], v[88:91]
	v_mfma_f32_16x16x32_bf16 v[80:83], v[160:163], v[194:197], v[80:83]
	v_mfma_f32_16x16x32_bf16 v[72:75], v[168:171], v[194:197], v[72:75]
	v_mfma_f32_16x16x32_bf16 v[68:71], v[160:163], v[202:205], v[68:71]
	v_mfma_f32_16x16x32_bf16 v[64:67], v[168:171], v[202:205], v[64:67]
	v_mfma_f32_16x16x32_bf16 v[112:115], v[164:167], v[182:185], v[112:115]
	v_mfma_f32_16x16x32_bf16 v[104:107], v[172:175], v[182:185], v[104:107]
	v_mfma_f32_16x16x32_bf16 v[96:99], v[164:167], v[190:193], v[96:99]
	v_mfma_f32_16x16x32_bf16 v[88:91], v[172:175], v[190:193], v[88:91]
	v_mfma_f32_16x16x32_bf16 v[80:83], v[164:167], v[198:201], v[80:83]
	v_mfma_f32_16x16x32_bf16 v[72:75], v[172:175], v[198:201], v[72:75]
	v_mfma_f32_16x16x32_bf16 v[68:71], v[164:167], v[206:209], v[68:71]
	v_mfma_f32_16x16x32_bf16 v[64:67], v[172:175], v[206:209], v[64:67]
	s_add_i32 s62, s62, 2
	s_add_u32 s38, s38, 0x100
	s_addc_u32 s39, s39, 0
	s_add_u32 s60, s60, 0x100
	s_addc_u32 s61, s61, 0
	s_setprio 0
	s_barrier
	s_add_u32 s66, s44, 0x40000
	ds_read_b128 v[178:181], v140 offset:16384
	ds_read_b128 v[182:185], v140 offset:17408
	ds_read_b128 v[186:189], v140 offset:18432
	ds_read_b128 v[190:193], v140 offset:19456
	ds_read_b128 v[194:197], v140 offset:20480
	ds_read_b128 v[198:201], v140 offset:21504
	ds_read_b128 v[202:205], v140 offset:22528
	ds_read_b128 v[206:209], v140 offset:23552
	s_mov_b32 m0, s33
	s_nop 0
	global_load_lds_dwordx4 v135, s[44:45]
	s_mov_b32 m0, s34
	s_addc_u32 s67, s45, 0
	global_load_lds_dwordx4 v135, s[66:67]
	s_add_u32 s66, s44, 0x80000
	s_mov_b32 m0, s35
	s_addc_u32 s67, s45, 0
	global_load_lds_dwordx4 v135, s[66:67]
	s_add_u32 s66, s44, 0xc0000
	s_mov_b32 m0, s36
	s_addc_u32 s67, s45, 0
	global_load_lds_dwordx4 v135, s[66:67]
	s_mov_b32 m0, s31
	s_nop 0
	global_load_lds_dwordx4 v134, s[40:41]
	s_add_u32 s66, s40, 0x40000
	s_mov_b32 m0, s37
	s_addc_u32 s67, s41, 0
	global_load_lds_dwordx4 v134, s[66:67]
	s_waitcnt vmcnt(8) lgkmcnt(0)
	s_barrier
	s_setprio 1
	v_mfma_f32_16x16x32_bf16 v[60:63], v[144:147], v[178:181], v[60:63]
	v_mfma_f32_16x16x32_bf16 v[56:59], v[152:155], v[178:181], v[56:59]
	v_mfma_f32_16x16x32_bf16 v[52:55], v[144:147], v[186:189], v[52:55]
	v_mfma_f32_16x16x32_bf16 v[44:47], v[152:155], v[186:189], v[44:47]
	v_mfma_f32_16x16x32_bf16 v[36:39], v[144:147], v[194:197], v[36:39]
	v_mfma_f32_16x16x32_bf16 v[28:31], v[152:155], v[194:197], v[28:31]
	v_mfma_f32_16x16x32_bf16 v[20:23], v[144:147], v[202:205], v[20:23]
	v_mfma_f32_16x16x32_bf16 v[12:15], v[152:155], v[202:205], v[12:15]
	v_mfma_f32_16x16x32_bf16 v[60:63], v[148:151], v[182:185], v[60:63]
	v_mfma_f32_16x16x32_bf16 v[56:59], v[156:159], v[182:185], v[56:59]
	v_mfma_f32_16x16x32_bf16 v[52:55], v[148:151], v[190:193], v[52:55]
	v_mfma_f32_16x16x32_bf16 v[44:47], v[156:159], v[190:193], v[44:47]
	v_mfma_f32_16x16x32_bf16 v[36:39], v[148:151], v[198:201], v[36:39]
	v_mfma_f32_16x16x32_bf16 v[28:31], v[156:159], v[198:201], v[28:31]
	v_mfma_f32_16x16x32_bf16 v[20:23], v[148:151], v[206:209], v[20:23]
	v_mfma_f32_16x16x32_bf16 v[12:15], v[156:159], v[206:209], v[12:15]
	v_mfma_f32_16x16x32_bf16 v[48:51], v[160:163], v[178:181], v[48:51]
	v_mfma_f32_16x16x32_bf16 v[40:43], v[168:171], v[178:181], v[40:43]
	v_mfma_f32_16x16x32_bf16 v[32:35], v[160:163], v[186:189], v[32:35]
	v_mfma_f32_16x16x32_bf16 v[24:27], v[168:171], v[186:189], v[24:27]
	v_mfma_f32_16x16x32_bf16 v[16:19], v[160:163], v[194:197], v[16:19]
	v_mfma_f32_16x16x32_bf16 v[8:11], v[168:171], v[194:197], v[8:11]
	v_mfma_f32_16x16x32_bf16 v[4:7], v[160:163], v[202:205], v[4:7]
	v_mfma_f32_16x16x32_bf16 v[0:3], v[168:171], v[202:205], v[0:3]
	v_mfma_f32_16x16x32_bf16 v[48:51], v[164:167], v[182:185], v[48:51]
	v_mfma_f32_16x16x32_bf16 v[40:43], v[172:175], v[182:185], v[40:43]
	v_mfma_f32_16x16x32_bf16 v[32:35], v[164:167], v[190:193], v[32:35]
	v_mfma_f32_16x16x32_bf16 v[24:27], v[172:175], v[190:193], v[24:27]
	v_mfma_f32_16x16x32_bf16 v[16:19], v[164:167], v[198:201], v[16:19]
	v_mfma_f32_16x16x32_bf16 v[8:11], v[172:175], v[198:201], v[8:11]
	v_mfma_f32_16x16x32_bf16 v[4:7], v[164:167], v[206:209], v[4:7]
	v_mfma_f32_16x16x32_bf16 v[0:3], v[172:175], v[206:209], v[0:3]
	s_setprio 0
	s_barrier
; #define PG8_STAGE(bufoff, gbase, voff, p64) do { _Pragma("unroll") for (int _i = 0; _i < 2; ++_i) { \
;         const char* _gb = (const char*)(gbase) + (size_t)_i * (p64); const unsigned _la = ldsbase + (unsigned)(bufoff) + (unsigned)_i * 8192u; \
;         asm volatile("s_mov_b32 m0, %0\n\ts_nop 0\n\tglobal_load_lds_dwordx4 %1, %2" :: "s"(_la), "v"(voff), "s"(_gb) : "memory"); } } while (0)
; #define PG8_LDA(dst, b, h) do { _Pragma("unroll") for (int m = 0; m < 4; ++m) _Pragma("unroll") for (int k = 0; k < 2; ++k) dst[m][k] = *(const LAS bf16x8*)(lds + PG8_SA(b, h) + aoff + m * 2048 + k * 1024); } while (0)
; #define PG8_LDB(dst, b, h) do { _Pragma("unroll") for (int n = 0; n < 2; ++n) _Pragma("unroll") for (int k = 0; k < 2; ++k) dst[n][k] = *(const LAS bf16x8*)(lds + PG8_SB(b, h) + boff + n * 2048 + k * 1024); } while (0)
; #define PG8_MMA(ai, bj, At, Bt) do { __builtin_amdgcn_s_setprio(1); _Pragma("unroll") for (int m = 0; m < 4; ++m) _Pragma("unroll") for (int n = 0; n < 2; ++n) _Pragma("unroll") for (int k = 0; k < 2; ++k) \
;         acc[ai][bj][m][n] = __builtin_amdgcn_mfma_f32_16x16x32_bf16(Bt[n][k], At[m][k], acc[ai][bj][m][n], 0, 0, 0); __builtin_amdgcn_s_setprio(0); } while (0)
; #define PG8_WAIT_V(n) asm volatile("s_waitcnt vmcnt(" #n ")" ::: "memory")
; #define PG8_WAIT_L(n) asm volatile("s_waitcnt lgkmcnt(" #n ")" ::: "memory")
; #define PG8_BAR __builtin_amdgcn_s_barrier()
; #define PG8_SCHED __builtin_amdgcn_sched_barrier(0)
; template <class Epi, class Sched>
; __device__ __forceinline__ void gemm_phase(LAS unsigned char* lds, const Sched& S, const Epi& E) {
;     ...
;             PG8_LDB(B0, 1, 0); PG8_LDB(B1, 1, 1); PG8_SCHED; PG8_LDA(At, 1, 0); PG8_STAGE(PG8_SA(0, 1), a2 + hA2, vA2, hA2 / 2);
;             PG8_WAIT_V(8); PG8_WAIT_L(0); PG8_BAR; PG8_MMA(0, 0, At, B0); PG8_MMA(0, 1, At, B1); PG8_BAR; PG8_SCHED;
;             PG8_LDA(At, 1, 1); PG8_STAGE(PG8_SB(1, 0), b3, vB2, hB2 / 2); PG8_STAGE(PG8_SB(1, 1), b3 + hB2, vB2, hB2 / 2); PG8_STAGE(PG8_SA(1, 0), a3, vA2, hA2 / 2);
;             PG8_WAIT_V(8); PG8_WAIT_L(0); PG8_BAR; PG8_MMA(1, 0, At, B0); PG8_MMA(1, 1, At, B1); PG8_BAR; PG8_SCHED;
;         }
;         if (wr == 0) PG8_BAR;
.Lpeel_mid_32521:
	ds_read_b128 v[144:147], v141
	ds_read_b128 v[148:151], v141 offset:1024
	ds_read_b128 v[152:155], v141 offset:2048
	ds_read_b128 v[156:159], v141 offset:3072
	ds_read_b128 v[160:163], v142
	ds_read_b128 v[164:167], v142 offset:1024
	ds_read_b128 v[168:171], v142 offset:2048
	ds_read_b128 v[172:175], v142 offset:3072
	ds_read_b128 v[178:181], v140 offset:32768
	ds_read_b128 v[182:185], v140 offset:33792
	ds_read_b128 v[186:189], v140 offset:34816
	ds_read_b128 v[190:193], v140 offset:35840
	ds_read_b128 v[194:197], v140 offset:36864
	ds_read_b128 v[198:201], v140 offset:37888
	ds_read_b128 v[202:205], v140 offset:38912
	ds_read_b128 v[206:209], v140 offset:39936
	s_add_u32 s66, s40, 0x80000
	s_mov_b32 m0, s46
	s_addc_u32 s67, s41, 0
	global_load_lds_dwordx4 v134, s[66:67]
	s_add_u32 s66, s40, 0xc0000
	s_mov_b32 m0, s47
	s_addc_u32 s67, s41, 0
	global_load_lds_dwordx4 v134, s[66:67]
	s_waitcnt vmcnt(8) lgkmcnt(0)
	s_barrier
	s_setprio 1
	v_mfma_f32_16x16x32_bf16 v[124:127], v[144:147], v[178:181], v[124:127]
	v_mfma_f32_16x16x32_bf16 v[120:123], v[152:155], v[178:181], v[120:123]
	v_mfma_f32_16x16x32_bf16 v[116:119], v[144:147], v[186:189], v[116:119]
	v_mfma_f32_16x16x32_bf16 v[108:111], v[152:155], v[186:189], v[108:111]
	v_mfma_f32_16x16x32_bf16 v[100:103], v[144:147], v[194:197], v[100:103]
	v_mfma_f32_16x16x32_bf16 v[92:95], v[152:155], v[194:197], v[92:95]
	v_mfma_f32_16x16x32_bf16 v[84:87], v[144:147], v[202:205], v[84:87]
	v_mfma_f32_16x16x32_bf16 v[76:79], v[152:155], v[202:205], v[76:79]
	v_mfma_f32_16x16x32_bf16 v[124:127], v[148:151], v[182:185], v[124:127]
	v_mfma_f32_16x16x32_bf16 v[120:123], v[156:159], v[182:185], v[120:123]
	v_mfma_f32_16x16x32_bf16 v[116:119], v[148:151], v[190:193], v[116:119]
	v_mfma_f32_16x16x32_bf16 v[108:111], v[156:159], v[190:193], v[108:111]
	v_mfma_f32_16x16x32_bf16 v[100:103], v[148:151], v[198:201], v[100:103]
	v_mfma_f32_16x16x32_bf16 v[92:95], v[156:159], v[198:201], v[92:95]
	v_mfma_f32_16x16x32_bf16 v[84:87], v[148:151], v[206:209], v[84:87]
	v_mfma_f32_16x16x32_bf16 v[76:79], v[156:159], v[206:209], v[76:79]
	v_mfma_f32_16x16x32_bf16 v[112:115], v[160:163], v[178:181], v[112:115]
	v_mfma_f32_16x16x32_bf16 v[104:107], v[168:171], v[178:181], v[104:107]
	v_mfma_f32_16x16x32_bf16 v[96:99], v[160:163], v[186:189], v[96:99]
	v_mfma_f32_16x16x32_bf16 v[88:91], v[168:171], v[186:189], v[88:91]
	v_mfma_f32_16x16x32_bf16 v[80:83], v[160:163], v[194:197], v[80:83]
	v_mfma_f32_16x16x32_bf16 v[72:75], v[168:171], v[194:197], v[72:75]
	v_mfma_f32_16x16x32_bf16 v[68:71], v[160:163], v[202:205], v[68:71]
	v_mfma_f32_16x16x32_bf16 v[64:67], v[168:171], v[202:205], v[64:67]
	v_mfma_f32_16x16x32_bf16 v[112:115], v[164:167], v[182:185], v[112:115]
	v_mfma_f32_16x16x32_bf16 v[104:107], v[172:175], v[182:185], v[104:107]
	v_mfma_f32_16x16x32_bf16 v[96:99], v[164:167], v[190:193], v[96:99]
	v_mfma_f32_16x16x32_bf16 v[88:91], v[172:175], v[190:193], v[88:91]
	v_mfma_f32_16x16x32_bf16 v[80:83], v[164:167], v[198:201], v[80:83]
	v_mfma_f32_16x16x32_bf16 v[72:75], v[172:175], v[198:201], v[72:75]
	v_mfma_f32_16x16x32_bf16 v[68:71], v[164:167], v[206:209], v[68:71]
	v_mfma_f32_16x16x32_bf16 v[64:67], v[172:175], v[206:209], v[64:67]
	s_setprio 0
	s_barrier
	s_add_u32 s66, s44, 0x80
	s_addc_u32 s67, s45, 0
	ds_read_b128 v[178:181], v140 offset:49152
	ds_read_b128 v[182:185], v140 offset:50176
	ds_read_b128 v[186:189], v140 offset:51200
	ds_read_b128 v[190:193], v140 offset:52224
	ds_read_b128 v[194:197], v140 offset:53248
	ds_read_b128 v[198:201], v140 offset:54272
	ds_read_b128 v[202:205], v140 offset:55296
	ds_read_b128 v[206:209], v140 offset:56320
	s_mov_b32 m0, s50
	s_nop 0
	global_load_lds_dwordx4 v135, s[66:67]
	s_add_u32 s66, s44, 0x40080
	s_mov_b32 m0, s51
	s_addc_u32 s67, s45, 0
	global_load_lds_dwordx4 v135, s[66:67]
	s_add_u32 s66, s44, 0x80080
	s_mov_b32 m0, s54
	s_addc_u32 s67, s45, 0
	global_load_lds_dwordx4 v135, s[66:67]
	s_add_u32 s44, s44, 0xc0080
	s_mov_b32 m0, s55
	s_addc_u32 s45, s45, 0
	global_load_lds_dwordx4 v135, s[44:45]
	s_mov_b32 m0, s52
	s_nop 0
	global_load_lds_dwordx4 v134, s[42:43]
	s_add_u32 s40, s40, 0x40080
	s_mov_b32 m0, s53
	s_addc_u32 s41, s41, 0
	global_load_lds_dwordx4 v134, s[40:41]
	s_waitcnt vmcnt(8) lgkmcnt(0)
	s_barrier
	s_setprio 1
	v_mfma_f32_16x16x32_bf16 v[60:63], v[144:147], v[178:181], v[60:63]
	v_mfma_f32_16x16x32_bf16 v[56:59], v[152:155], v[178:181], v[56:59]
	v_mfma_f32_16x16x32_bf16 v[52:55], v[144:147], v[186:189], v[52:55]
	v_mfma_f32_16x16x32_bf16 v[44:47], v[152:155], v[186:189], v[44:47]
	v_mfma_f32_16x16x32_bf16 v[36:39], v[144:147], v[194:197], v[36:39]
	v_mfma_f32_16x16x32_bf16 v[28:31], v[152:155], v[194:197], v[28:31]
	v_mfma_f32_16x16x32_bf16 v[20:23], v[144:147], v[202:205], v[20:23]
	v_mfma_f32_16x16x32_bf16 v[12:15], v[152:155], v[202:205], v[12:15]
	v_mfma_f32_16x16x32_bf16 v[60:63], v[148:151], v[182:185], v[60:63]
	v_mfma_f32_16x16x32_bf16 v[56:59], v[156:159], v[182:185], v[56:59]
	v_mfma_f32_16x16x32_bf16 v[52:55], v[148:151], v[190:193], v[52:55]
	v_mfma_f32_16x16x32_bf16 v[44:47], v[156:159], v[190:193], v[44:47]
	v_mfma_f32_16x16x32_bf16 v[36:39], v[148:151], v[198:201], v[36:39]
	v_mfma_f32_16x16x32_bf16 v[28:31], v[156:159], v[198:201], v[28:31]
	v_mfma_f32_16x16x32_bf16 v[20:23], v[148:151], v[206:209], v[20:23]
	v_mfma_f32_16x16x32_bf16 v[12:15], v[156:159], v[206:209], v[12:15]
	v_mfma_f32_16x16x32_bf16 v[48:51], v[160:163], v[178:181], v[48:51]
	v_mfma_f32_16x16x32_bf16 v[40:43], v[168:171], v[178:181], v[40:43]
	v_mfma_f32_16x16x32_bf16 v[32:35], v[160:163], v[186:189], v[32:35]
	v_mfma_f32_16x16x32_bf16 v[24:27], v[168:171], v[186:189], v[24:27]
	v_mfma_f32_16x16x32_bf16 v[16:19], v[160:163], v[194:197], v[16:19]
	v_mfma_f32_16x16x32_bf16 v[8:11], v[168:171], v[194:197], v[8:11]
	v_mfma_f32_16x16x32_bf16 v[4:7], v[160:163], v[202:205], v[4:7]
	v_mfma_f32_16x16x32_bf16 v[0:3], v[168:171], v[202:205], v[0:3]
	v_mfma_f32_16x16x32_bf16 v[48:51], v[164:167], v[182:185], v[48:51]
	v_mfma_f32_16x16x32_bf16 v[40:43], v[172:175], v[182:185], v[40:43]
	v_mfma_f32_16x16x32_bf16 v[32:35], v[164:167], v[190:193], v[32:35]
	v_mfma_f32_16x16x32_bf16 v[24:27], v[172:175], v[190:193], v[24:27]
	v_mfma_f32_16x16x32_bf16 v[16:19], v[164:167], v[198:201], v[16:19]
	v_mfma_f32_16x16x32_bf16 v[8:11], v[172:175], v[198:201], v[8:11]
	v_mfma_f32_16x16x32_bf16 v[4:7], v[164:167], v[206:209], v[4:7]
	v_mfma_f32_16x16x32_bf16 v[0:3], v[172:175], v[206:209], v[0:3]
	s_setprio 0
	s_barrier
	s_cmp_gt_u32 s62, 29
	s_cbranch_scc0 .LBB0_1089
	s_and_b64 vcc, exec, s[18:19]
	s_cbranch_vccz .LBB0_1092
	s_barrier

; #define PG8_STAGE(bufoff, gbase, voff, p64) do { _Pragma("unroll") for (int _i = 0; _i < 2; ++_i) { \
;         const char* _gb = (const char*)(gbase) + (size_t)_i * (p64); const unsigned _la = ldsbase + (unsigned)(bufoff) + (unsigned)_i * 8192u; \
;         asm volatile("s_mov_b32 m0, %0\n\ts_nop 0\n\tglobal_load_lds_dwordx4 %1, %2" :: "s"(_la), "v"(voff), "s"(_gb) : "memory"); } } while (0)
; #define PG8_LDA(dst, b, h) do { _Pragma("unroll") for (int m = 0; m < 4; ++m) _Pragma("unroll") for (int k = 0; k < 2; ++k) dst[m][k] = *(const LAS bf16x8*)(lds + PG8_SA(b, h) + aoff + m * 2048 + k * 1024); } while (0)
; #define PG8_LDB(dst, b, h) do { _Pragma("unroll") for (int n = 0; n < 2; ++n) _Pragma("unroll") for (int k = 0; k < 2; ++k) dst[n][k] = *(const LAS bf16x8*)(lds + PG8_SB(b, h) + boff + n * 2048 + k * 1024); } while (0)
; #define PG8_WAIT_V(n) asm volatile("s_waitcnt vmcnt(" #n ")" ::: "memory")
; #define PG8_BAR __builtin_amdgcn_s_barrier()
; template <class Epi, class Sched>
; __device__ __forceinline__ void gemm_phase(LAS unsigned char* lds, const Sched& S, const Epi& E) {
;     ...
;         for (int t = 0; t < nt; t += 2) {
;             const bool last = (t == nt - 2);
;             const char* a1 = cA + (size_t)(t + 1) * kstep;
;             const char* a2 = last ? nA : cA + (size_t)(t + 2) * kstep; const char* b2 = last ? nB : cB + (size_t)(t + 2) * kstep;
;             const char* a3 = a2 + kstep; const char* b3 = b2 + kstep;
;             const unsigned vA2 = voffA, vB2 = voffB, hA2 = hA, hB2 = hB;
;             PG8_LDB(B0, 0, 0); PG8_LDB(B1, 0, 1); PG8_SCHED; PG8_LDA(At, 0, 0); PG8_STAGE(PG8_SA(1, 1), a1 + hA, voffA, hA / 2);
;             PG8_WAIT_V(8); PG8_WAIT_L(0); PG8_BAR; PG8_MMA(0, 0, At, B0); PG8_MMA(0, 1, At, B1); PG8_BAR; PG8_SCHED;
;             PG8_LDA(At, 0, 1); PG8_STAGE(PG8_SB(0, 0), b2, vB2, hB2 / 2); PG8_STAGE(PG8_SB(0, 1), b2 + hB2, vB2, hB2 / 2); PG8_STAGE(PG8_SA(0, 0), a2, vA2, hA2 / 2);
;             PG8_WAIT_V(8); PG8_WAIT_L(0); PG8_BAR; PG8_MMA(1, 0, At, B0); PG8_MMA(1, 1, At, B1); PG8_BAR; PG8_SCHED;
;     ...
; #pragma unroll
;             for (int a = 0; a < 2; ++a)
; #pragma unroll
;                 for (int b = 0; b < 2; ++b)
; #pragma unroll
;                     for (int m = 0; m < 4; ++m)
; #pragma unroll
;                         for (int n = 0; n < 2; ++n) acc[a][b][m][n] = (f32x4){0.f, 0.f, 0.f, 0.f};
.LBB0_1191:
	s_add_u32 s24, s24, 0x40080
	s_addc_u32 s25, s25, 0
	s_add_u32 s58, s26, 0x100
	s_addc_u32 s59, s27, 0
	s_mov_b32 s60, -2
	ds_read_b128 v[144:147], v138
	ds_read_b128 v[148:151], v138 offset:1024
	ds_read_b128 v[152:155], v138 offset:2048
	ds_read_b128 v[156:159], v138 offset:3072
	ds_read_b128 v[160:163], v139
	ds_read_b128 v[164:167], v139 offset:1024
	ds_read_b128 v[168:171], v139 offset:2048
	ds_read_b128 v[172:175], v139 offset:3072
	s_add_u32 s26, s24, 0xfffc0080
	s_addc_u32 s27, s25, -1
	s_cmp_eq_u32 s60, 12
	s_cselect_b32 s26, s20, s26
	s_cselect_b32 s27, s21, s27
	s_cselect_b32 s40, s22, s58
	s_cselect_b32 s41, s23, s59
	s_add_u32 s38, s26, 0x80
	s_addc_u32 s39, s27, 0
	ds_read_b128 v[178:181], v140
	ds_read_b128 v[182:185], v140 offset:1024
	ds_read_b128 v[186:189], v140 offset:2048
	ds_read_b128 v[190:193], v140 offset:3072
	ds_read_b128 v[194:197], v140 offset:4096
	ds_read_b128 v[198:201], v140 offset:5120
	ds_read_b128 v[202:205], v140 offset:6144
	ds_read_b128 v[206:209], v140 offset:7168
	s_mov_b32 m0, s54
	s_nop 0
	global_load_lds_dwordx4 v134, s[24:25]
	s_add_u32 s62, s24, 0x20000
	s_mov_b32 m0, s55
	s_addc_u32 s63, s25, 0
	global_load_lds_dwordx4 v134, s[62:63]
	s_waitcnt vmcnt(8) lgkmcnt(0)
	s_barrier
	s_setprio 1
	v_mfma_f32_16x16x32_bf16 v[124:127], v[144:147], v[178:181], 0
	v_mfma_f32_16x16x32_bf16 v[120:123], v[152:155], v[178:181], 0
	v_mfma_f32_16x16x32_bf16 v[116:119], v[144:147], v[186:189], 0
	v_mfma_f32_16x16x32_bf16 v[108:111], v[152:155], v[186:189], 0
	v_mfma_f32_16x16x32_bf16 v[100:103], v[144:147], v[194:197], 0
	v_mfma_f32_16x16x32_bf16 v[92:95], v[152:155], v[194:197], 0
	v_mfma_f32_16x16x32_bf16 v[84:87], v[144:147], v[202:205], 0
	v_mfma_f32_16x16x32_bf16 v[76:79], v[152:155], v[202:205], 0
	v_mfma_f32_16x16x32_bf16 v[124:127], v[148:151], v[182:185], v[124:127]
	v_mfma_f32_16x16x32_bf16 v[120:123], v[156:159], v[182:185], v[120:123]
	v_mfma_f32_16x16x32_bf16 v[116:119], v[148:151], v[190:193], v[116:119]
	v_mfma_f32_16x16x32_bf16 v[108:111], v[156:159], v[190:193], v[108:111]
	v_mfma_f32_16x16x32_bf16 v[100:103], v[148:151], v[198:201], v[100:103]
	v_mfma_f32_16x16x32_bf16 v[92:95], v[156:159], v[198:201], v[92:95]
	v_mfma_f32_16x16x32_bf16 v[84:87], v[148:151], v[206:209], v[84:87]
	v_mfma_f32_16x16x32_bf16 v[76:79], v[156:159], v[206:209], v[76:79]
	v_mfma_f32_16x16x32_bf16 v[112:115], v[160:163], v[178:181], 0
	v_mfma_f32_16x16x32_bf16 v[104:107], v[168:171], v[178:181], 0
	v_mfma_f32_16x16x32_bf16 v[96:99], v[160:163], v[186:189], 0
	v_mfma_f32_16x16x32_bf16 v[88:91], v[168:171], v[186:189], 0
	v_mfma_f32_16x16x32_bf16 v[80:83], v[160:163], v[194:197], 0
	v_mfma_f32_16x16x32_bf16 v[72:75], v[168:171], v[194:197], 0
	v_mfma_f32_16x16x32_bf16 v[68:71], v[160:163], v[202:205], 0
	v_mfma_f32_16x16x32_bf16 v[64:67], v[168:171], v[202:205], 0
	v_mfma_f32_16x16x32_bf16 v[112:115], v[164:167], v[182:185], v[112:115]
	v_mfma_f32_16x16x32_bf16 v[104:107], v[172:175], v[182:185], v[104:107]
	v_mfma_f32_16x16x32_bf16 v[96:99], v[164:167], v[190:193], v[96:99]
	v_mfma_f32_16x16x32_bf16 v[88:91], v[172:175], v[190:193], v[88:91]
	v_mfma_f32_16x16x32_bf16 v[80:83], v[164:167], v[198:201], v[80:83]
	v_mfma_f32_16x16x32_bf16 v[72:75], v[172:175], v[198:201], v[72:75]
	v_mfma_f32_16x16x32_bf16 v[68:71], v[164:167], v[206:209], v[68:71]
	v_mfma_f32_16x16x32_bf16 v[64:67], v[172:175], v[206:209], v[64:67]
	s_add_i32 s60, s60, 2
	s_add_u32 s24, s24, 0x100
	s_addc_u32 s25, s25, 0
	s_add_u32 s58, s58, 0x100
	s_addc_u32 s59, s59, 0
	s_setprio 0
	s_barrier
	s_add_u32 s62, s40, 0x20000
	ds_read_b128 v[178:181], v140 offset:16384
	ds_read_b128 v[182:185], v140 offset:17408
	ds_read_b128 v[186:189], v140 offset:18432
	ds_read_b128 v[190:193], v140 offset:19456
	ds_read_b128 v[194:197], v140 offset:20480
	ds_read_b128 v[198:201], v140 offset:21504
	ds_read_b128 v[202:205], v140 offset:22528
	ds_read_b128 v[206:209], v140 offset:23552
	s_mov_b32 m0, s35
	s_nop 0
	global_load_lds_dwordx4 v135, s[40:41]
	s_mov_b32 m0, s36
	s_addc_u32 s63, s41, 0
	global_load_lds_dwordx4 v135, s[62:63]
	s_add_u32 s62, s40, 0x40000
	s_mov_b32 m0, s37
	s_addc_u32 s63, s41, 0
	global_load_lds_dwordx4 v135, s[62:63]
	s_add_u32 s62, s40, 0x60000
	s_mov_b32 m0, s42
	s_addc_u32 s63, s41, 0
	global_load_lds_dwordx4 v135, s[62:63]
	s_mov_b32 m0, s34
	s_nop 0
	global_load_lds_dwordx4 v134, s[26:27]
	s_add_u32 s62, s26, 0x20000
	s_mov_b32 m0, s43
	s_addc_u32 s63, s27, 0
	global_load_lds_dwordx4 v134, s[62:63]
	s_waitcnt vmcnt(8) lgkmcnt(0)
	s_barrier
	s_setprio 1
	v_mfma_f32_16x16x32_bf16 v[60:63], v[144:147], v[178:181], 0
	v_mfma_f32_16x16x32_bf16 v[56:59], v[152:155], v[178:181], 0
	v_mfma_f32_16x16x32_bf16 v[52:55], v[144:147], v[186:189], 0
	v_mfma_f32_16x16x32_bf16 v[44:47], v[152:155], v[186:189], 0
	v_mfma_f32_16x16x32_bf16 v[36:39], v[144:147], v[194:197], 0
	v_mfma_f32_16x16x32_bf16 v[28:31], v[152:155], v[194:197], 0
	v_mfma_f32_16x16x32_bf16 v[20:23], v[144:147], v[202:205], 0
	v_mfma_f32_16x16x32_bf16 v[12:15], v[152:155], v[202:205], 0
	v_mfma_f32_16x16x32_bf16 v[60:63], v[148:151], v[182:185], v[60:63]
	v_mfma_f32_16x16x32_bf16 v[56:59], v[156:159], v[182:185], v[56:59]
	v_mfma_f32_16x16x32_bf16 v[52:55], v[148:151], v[190:193], v[52:55]
	v_mfma_f32_16x16x32_bf16 v[44:47], v[156:159], v[190:193], v[44:47]
	v_mfma_f32_16x16x32_bf16 v[36:39], v[148:151], v[198:201], v[36:39]
	v_mfma_f32_16x16x32_bf16 v[28:31], v[156:159], v[198:201], v[28:31]
	v_mfma_f32_16x16x32_bf16 v[20:23], v[148:151], v[206:209], v[20:23]
	v_mfma_f32_16x16x32_bf16 v[12:15], v[156:159], v[206:209], v[12:15]
	v_mfma_f32_16x16x32_bf16 v[48:51], v[160:163], v[178:181], 0
	v_mfma_f32_16x16x32_bf16 v[40:43], v[168:171], v[178:181], 0
	v_mfma_f32_16x16x32_bf16 v[32:35], v[160:163], v[186:189], 0
	v_mfma_f32_16x16x32_bf16 v[24:27], v[168:171], v[186:189], 0
	v_mfma_f32_16x16x32_bf16 v[16:19], v[160:163], v[194:197], 0
	v_mfma_f32_16x16x32_bf16 v[8:11], v[168:171], v[194:197], 0
	v_mfma_f32_16x16x32_bf16 v[4:7], v[160:163], v[202:205], 0
	v_mfma_f32_16x16x32_bf16 v[0:3], v[168:171], v[202:205], 0
	v_mfma_f32_16x16x32_bf16 v[48:51], v[164:167], v[182:185], v[48:51]
	v_mfma_f32_16x16x32_bf16 v[40:43], v[172:175], v[182:185], v[40:43]
	v_mfma_f32_16x16x32_bf16 v[32:35], v[164:167], v[190:193], v[32:35]
	v_mfma_f32_16x16x32_bf16 v[24:27], v[172:175], v[190:193], v[24:27]
	v_mfma_f32_16x16x32_bf16 v[16:19], v[164:167], v[198:201], v[16:19]
	v_mfma_f32_16x16x32_bf16 v[8:11], v[172:175], v[198:201], v[8:11]
	v_mfma_f32_16x16x32_bf16 v[4:7], v[164:167], v[206:209], v[4:7]
	v_mfma_f32_16x16x32_bf16 v[0:3], v[172:175], v[206:209], v[0:3]
	s_setprio 0
	s_barrier
	s_branch .Lpeel_mid_36225
; #define PG8_STAGE(bufoff, gbase, voff, p64) do { _Pragma("unroll") for (int _i = 0; _i < 2; ++_i) { \
;         const char* _gb = (const char*)(gbase) + (size_t)_i * (p64); const unsigned _la = ldsbase + (unsigned)(bufoff) + (unsigned)_i * 8192u; \
;         asm volatile("s_mov_b32 m0, %0\n\ts_nop 0\n\tglobal_load_lds_dwordx4 %1, %2" :: "s"(_la), "v"(voff), "s"(_gb) : "memory"); } } while (0)
; #define PG8_LDA(dst, b, h) do { _Pragma("unroll") for (int m = 0; m < 4; ++m) _Pragma("unroll") for (int k = 0; k < 2; ++k) dst[m][k] = *(const LAS bf16x8*)(lds + PG8_SA(b, h) + aoff + m * 2048 + k * 1024); } while (0)
; #define PG8_LDB(dst, b, h) do { _Pragma("unroll") for (int n = 0; n < 2; ++n) _Pragma("unroll") for (int k = 0; k < 2; ++k) dst[n][k] = *(const LAS bf16x8*)(lds + PG8_SB(b, h) + boff + n * 2048 + k * 1024); } while (0)
; #define PG8_MMA(ai, bj, At, Bt) do { __builtin_amdgcn_s_setprio(1); _Pragma("unroll") for (int m = 0; m < 4; ++m) _Pragma("unroll") for (int n = 0; n < 2; ++n) _Pragma("unroll") for (int k = 0; k < 2; ++k) \
;         acc[ai][bj][m][n] = __builtin_amdgcn_mfma_f32_16x16x32_bf16(Bt[n][k], At[m][k], acc[ai][bj][m][n], 0, 0, 0); __builtin_amdgcn_s_setprio(0); } while (0)
; #define PG8_WAIT_V(n) asm volatile("s_waitcnt vmcnt(" #n ")" ::: "memory")
; template <class Epi, class Sched>
; __device__ __forceinline__ void gemm_phase(LAS unsigned char* lds, const Sched& S, const Epi& E) {
;     ...
;         for (int t = 0; t < nt; t += 2) {
;             const bool last = (t == nt - 2);
;             const char* a1 = cA + (size_t)(t + 1) * kstep;
;             const char* a2 = last ? nA : cA + (size_t)(t + 2) * kstep; const char* b2 = last ? nB : cB + (size_t)(t + 2) * kstep;
;             const char* a3 = a2 + kstep; const char* b3 = b2 + kstep;
;             const unsigned vA2 = voffA, vB2 = voffB, hA2 = hA, hB2 = hB;
;             PG8_LDB(B0, 0, 0); PG8_LDB(B1, 0, 1); PG8_SCHED; PG8_LDA(At, 0, 0); PG8_STAGE(PG8_SA(1, 1), a1 + hA, voffA, hA / 2);
;             PG8_WAIT_V(8); PG8_WAIT_L(0); PG8_BAR; PG8_MMA(0, 0, At, B0); PG8_MMA(0, 1, At, B1); PG8_BAR; PG8_SCHED;
;             PG8_LDA(At, 0, 1); PG8_STAGE(PG8_SB(0, 0), b2, vB2, hB2 / 2); PG8_STAGE(PG8_SB(0, 1), b2 + hB2, vB2, hB2 / 2); PG8_STAGE(PG8_SA(0, 0), a2, vA2, hA2 / 2);
;             PG8_WAIT_V(8); PG8_WAIT_L(0); PG8_BAR; PG8_MMA(1, 0, At, B0); PG8_MMA(1, 1, At, B1); PG8_BAR; PG8_SCHED;
.LBB0_1192:
	ds_read_b128 v[144:147], v138
	ds_read_b128 v[148:151], v138 offset:1024
	ds_read_b128 v[152:155], v138 offset:2048
	ds_read_b128 v[156:159], v138 offset:3072
	ds_read_b128 v[160:163], v139
	ds_read_b128 v[164:167], v139 offset:1024
	ds_read_b128 v[168:171], v139 offset:2048
	ds_read_b128 v[172:175], v139 offset:3072
	s_add_u32 s26, s24, 0xfffc0080
	s_addc_u32 s27, s25, -1
	s_cmp_eq_u32 s60, 12
	s_cselect_b32 s26, s20, s26
	s_cselect_b32 s27, s21, s27
	s_cselect_b32 s40, s22, s58
	s_cselect_b32 s41, s23, s59
	s_add_u32 s38, s26, 0x80
	s_addc_u32 s39, s27, 0
	ds_read_b128 v[178:181], v140
	ds_read_b128 v[182:185], v140 offset:1024
	ds_read_b128 v[186:189], v140 offset:2048
	ds_read_b128 v[190:193], v140 offset:3072
	ds_read_b128 v[194:197], v140 offset:4096
	ds_read_b128 v[198:201], v140 offset:5120
	ds_read_b128 v[202:205], v140 offset:6144
	ds_read_b128 v[206:209], v140 offset:7168
	s_mov_b32 m0, s54
	s_nop 0
	global_load_lds_dwordx4 v134, s[24:25]
	s_add_u32 s62, s24, 0x20000
	s_mov_b32 m0, s55
	s_addc_u32 s63, s25, 0
	global_load_lds_dwordx4 v134, s[62:63]
	s_waitcnt vmcnt(8) lgkmcnt(0)
	s_barrier
	s_setprio 1
	v_mfma_f32_16x16x32_bf16 v[124:127], v[144:147], v[178:181], v[124:127]
	v_mfma_f32_16x16x32_bf16 v[120:123], v[152:155], v[178:181], v[120:123]
	v_mfma_f32_16x16x32_bf16 v[116:119], v[144:147], v[186:189], v[116:119]
	v_mfma_f32_16x16x32_bf16 v[108:111], v[152:155], v[186:189], v[108:111]
	v_mfma_f32_16x16x32_bf16 v[100:103], v[144:147], v[194:197], v[100:103]
	v_mfma_f32_16x16x32_bf16 v[92:95], v[152:155], v[194:197], v[92:95]
	v_mfma_f32_16x16x32_bf16 v[84:87], v[144:147], v[202:205], v[84:87]
	v_mfma_f32_16x16x32_bf16 v[76:79], v[152:155], v[202:205], v[76:79]
	v_mfma_f32_16x16x32_bf16 v[124:127], v[148:151], v[182:185], v[124:127]
	v_mfma_f32_16x16x32_bf16 v[120:123], v[156:159], v[182:185], v[120:123]
	v_mfma_f32_16x16x32_bf16 v[116:119], v[148:151], v[190:193], v[116:119]
	v_mfma_f32_16x16x32_bf16 v[108:111], v[156:159], v[190:193], v[108:111]
	v_mfma_f32_16x16x32_bf16 v[100:103], v[148:151], v[198:201], v[100:103]
	v_mfma_f32_16x16x32_bf16 v[92:95], v[156:159], v[198:201], v[92:95]
	v_mfma_f32_16x16x32_bf16 v[84:87], v[148:151], v[206:209], v[84:87]
	v_mfma_f32_16x16x32_bf16 v[76:79], v[156:159], v[206:209], v[76:79]
	v_mfma_f32_16x16x32_bf16 v[112:115], v[160:163], v[178:181], v[112:115]
	v_mfma_f32_16x16x32_bf16 v[104:107], v[168:171], v[178:181], v[104:107]
	v_mfma_f32_16x16x32_bf16 v[96:99], v[160:163], v[186:189], v[96:99]
	v_mfma_f32_16x16x32_bf16 v[88:91], v[168:171], v[186:189], v[88:91]
	v_mfma_f32_16x16x32_bf16 v[80:83], v[160:163], v[194:197], v[80:83]
	v_mfma_f32_16x16x32_bf16 v[72:75], v[168:171], v[194:197], v[72:75]
	v_mfma_f32_16x16x32_bf16 v[68:71], v[160:163], v[202:205], v[68:71]
	v_mfma_f32_16x16x32_bf16 v[64:67], v[168:171], v[202:205], v[64:67]
	v_mfma_f32_16x16x32_bf16 v[112:115], v[164:167], v[182:185], v[112:115]
	v_mfma_f32_16x16x32_bf16 v[104:107], v[172:175], v[182:185], v[104:107]
	v_mfma_f32_16x16x32_bf16 v[96:99], v[164:167], v[190:193], v[96:99]
	v_mfma_f32_16x16x32_bf16 v[88:91], v[172:175], v[190:193], v[88:91]
	v_mfma_f32_16x16x32_bf16 v[80:83], v[164:167], v[198:201], v[80:83]
	v_mfma_f32_16x16x32_bf16 v[72:75], v[172:175], v[198:201], v[72:75]
	v_mfma_f32_16x16x32_bf16 v[68:71], v[164:167], v[206:209], v[68:71]
	v_mfma_f32_16x16x32_bf16 v[64:67], v[172:175], v[206:209], v[64:67]
	s_add_i32 s60, s60, 2
	s_add_u32 s24, s24, 0x100
	s_addc_u32 s25, s25, 0
	s_add_u32 s58, s58, 0x100
	s_addc_u32 s59, s59, 0
	s_setprio 0
	s_barrier
	s_add_u32 s62, s40, 0x20000
	ds_read_b128 v[178:181], v140 offset:16384
	ds_read_b128 v[182:185], v140 offset:17408
	ds_read_b128 v[186:189], v140 offset:18432
	ds_read_b128 v[190:193], v140 offset:19456
	ds_read_b128 v[194:197], v140 offset:20480
	ds_read_b128 v[198:201], v140 offset:21504
	ds_read_b128 v[202:205], v140 offset:22528
	ds_read_b128 v[206:209], v140 offset:23552
	s_mov_b32 m0, s35
	s_nop 0
	global_load_lds_dwordx4 v135, s[40:41]
	s_mov_b32 m0, s36
	s_addc_u32 s63, s41, 0
	global_load_lds_dwordx4 v135, s[62:63]
	s_add_u32 s62, s40, 0x40000
	s_mov_b32 m0, s37
	s_addc_u32 s63, s41, 0
	global_load_lds_dwordx4 v135, s[62:63]
	s_add_u32 s62, s40, 0x60000
	s_mov_b32 m0, s42
	s_addc_u32 s63, s41, 0
	global_load_lds_dwordx4 v135, s[62:63]
	s_mov_b32 m0, s34
	s_nop 0
	global_load_lds_dwordx4 v134, s[26:27]
	s_add_u32 s62, s26, 0x20000
	s_mov_b32 m0, s43
	s_addc_u32 s63, s27, 0
	global_load_lds_dwordx4 v134, s[62:63]
	s_waitcnt vmcnt(8) lgkmcnt(0)
	s_barrier
	s_setprio 1
	v_mfma_f32_16x16x32_bf16 v[60:63], v[144:147], v[178:181], v[60:63]
	v_mfma_f32_16x16x32_bf16 v[56:59], v[152:155], v[178:181], v[56:59]
	v_mfma_f32_16x16x32_bf16 v[52:55], v[144:147], v[186:189], v[52:55]
	v_mfma_f32_16x16x32_bf16 v[44:47], v[152:155], v[186:189], v[44:47]
	v_mfma_f32_16x16x32_bf16 v[36:39], v[144:147], v[194:197], v[36:39]
	v_mfma_f32_16x16x32_bf16 v[28:31], v[152:155], v[194:197], v[28:31]
	v_mfma_f32_16x16x32_bf16 v[20:23], v[144:147], v[202:205], v[20:23]
	v_mfma_f32_16x16x32_bf16 v[12:15], v[152:155], v[202:205], v[12:15]
	v_mfma_f32_16x16x32_bf16 v[60:63], v[148:151], v[182:185], v[60:63]
	v_mfma_f32_16x16x32_bf16 v[56:59], v[156:159], v[182:185], v[56:59]
	v_mfma_f32_16x16x32_bf16 v[52:55], v[148:151], v[190:193], v[52:55]
	v_mfma_f32_16x16x32_bf16 v[44:47], v[156:159], v[190:193], v[44:47]
	v_mfma_f32_16x16x32_bf16 v[36:39], v[148:151], v[198:201], v[36:39]
	v_mfma_f32_16x16x32_bf16 v[28:31], v[156:159], v[198:201], v[28:31]
	v_mfma_f32_16x16x32_bf16 v[20:23], v[148:151], v[206:209], v[20:23]
	v_mfma_f32_16x16x32_bf16 v[12:15], v[156:159], v[206:209], v[12:15]
	v_mfma_f32_16x16x32_bf16 v[48:51], v[160:163], v[178:181], v[48:51]
	v_mfma_f32_16x16x32_bf16 v[40:43], v[168:171], v[178:181], v[40:43]
	v_mfma_f32_16x16x32_bf16 v[32:35], v[160:163], v[186:189], v[32:35]
	v_mfma_f32_16x16x32_bf16 v[24:27], v[168:171], v[186:189], v[24:27]
	v_mfma_f32_16x16x32_bf16 v[16:19], v[160:163], v[194:197], v[16:19]
	v_mfma_f32_16x16x32_bf16 v[8:11], v[168:171], v[194:197], v[8:11]
	v_mfma_f32_16x16x32_bf16 v[4:7], v[160:163], v[202:205], v[4:7]
	v_mfma_f32_16x16x32_bf16 v[0:3], v[168:171], v[202:205], v[0:3]
	v_mfma_f32_16x16x32_bf16 v[48:51], v[164:167], v[182:185], v[48:51]
	v_mfma_f32_16x16x32_bf16 v[40:43], v[172:175], v[182:185], v[40:43]
	v_mfma_f32_16x16x32_bf16 v[32:35], v[164:167], v[190:193], v[32:35]
	v_mfma_f32_16x16x32_bf16 v[24:27], v[172:175], v[190:193], v[24:27]
	v_mfma_f32_16x16x32_bf16 v[16:19], v[164:167], v[198:201], v[16:19]
	v_mfma_f32_16x16x32_bf16 v[8:11], v[172:175], v[198:201], v[8:11]
	v_mfma_f32_16x16x32_bf16 v[4:7], v[164:167], v[206:209], v[4:7]
	v_mfma_f32_16x16x32_bf16 v[0:3], v[172:175], v[206:209], v[0:3]
	s_setprio 0
	s_barrier
; #define PG8_STAGE(bufoff, gbase, voff, p64) do { _Pragma("unroll") for (int _i = 0; _i < 2; ++_i) { \
;         const char* _gb = (const char*)(gbase) + (size_t)_i * (p64); const unsigned _la = ldsbase + (unsigned)(bufoff) + (unsigned)_i * 8192u; \
;         asm volatile("s_mov_b32 m0, %0\n\ts_nop 0\n\tglobal_load_lds_dwordx4 %1, %2" :: "s"(_la), "v"(voff), "s"(_gb) : "memory"); } } while (0)
; #define PG8_LDA(dst, b, h) do { _Pragma("unroll") for (int m = 0; m < 4; ++m) _Pragma("unroll") for (int k = 0; k < 2; ++k) dst[m][k] = *(const LAS bf16x8*)(lds + PG8_SA(b, h) + aoff + m * 2048 + k * 1024); } while (0)
; #define PG8_LDB(dst, b, h) do { _Pragma("unroll") for (int n = 0; n < 2; ++n) _Pragma("unroll") for (int k = 0; k < 2; ++k) dst[n][k] = *(const LAS bf16x8*)(lds + PG8_SB(b, h) + boff + n * 2048 + k * 1024); } while (0)
; #define PG8_MMA(ai, bj, At, Bt) do { __builtin_amdgcn_s_setprio(1); _Pragma("unroll") for (int m = 0; m < 4; ++m) _Pragma("unroll") for (int n = 0; n < 2; ++n) _Pragma("unroll") for (int k = 0; k < 2; ++k) \
;         acc[ai][bj][m][n] = __builtin_amdgcn_mfma_f32_16x16x32_bf16(Bt[n][k], At[m][k], acc[ai][bj][m][n], 0, 0, 0); __builtin_amdgcn_s_setprio(0); } while (0)
; #define PG8_WAIT_V(n) asm volatile("s_waitcnt vmcnt(" #n ")" ::: "memory")
; #define PG8_WAIT_L(n) asm volatile("s_waitcnt lgkmcnt(" #n ")" ::: "memory")
; #define PG8_BAR __builtin_amdgcn_s_barrier()
; #define PG8_SCHED __builtin_amdgcn_sched_barrier(0)
; template <class Epi, class Sched>
; __device__ __forceinline__ void gemm_phase(LAS unsigned char* lds, const Sched& S, const Epi& E) {
;     ...
;             PG8_LDB(B0, 1, 0); PG8_LDB(B1, 1, 1); PG8_SCHED; PG8_LDA(At, 1, 0); PG8_STAGE(PG8_SA(0, 1), a2 + hA2, vA2, hA2 / 2);
;             PG8_WAIT_V(8); PG8_WAIT_L(0); PG8_BAR; PG8_MMA(0, 0, At, B0); PG8_MMA(0, 1, At, B1); PG8_BAR; PG8_SCHED;
;             PG8_LDA(At, 1, 1); PG8_STAGE(PG8_SB(1, 0), b3, vB2, hB2 / 2); PG8_STAGE(PG8_SB(1, 1), b3 + hB2, vB2, hB2 / 2); PG8_STAGE(PG8_SA(1, 0), a3, vA2, hA2 / 2);
;             PG8_WAIT_V(8); PG8_WAIT_L(0); PG8_BAR; PG8_MMA(1, 0, At, B0); PG8_MMA(1, 1, At, B1); PG8_BAR; PG8_SCHED;
;         }
;         if (wr == 0) PG8_BAR;
.Lpeel_mid_36225:
	ds_read_b128 v[144:147], v141
	ds_read_b128 v[148:151], v141 offset:1024
	ds_read_b128 v[152:155], v141 offset:2048
	ds_read_b128 v[156:159], v141 offset:3072
	ds_read_b128 v[160:163], v142
	ds_read_b128 v[164:167], v142 offset:1024
	ds_read_b128 v[168:171], v142 offset:2048
	ds_read_b128 v[172:175], v142 offset:3072
	ds_read_b128 v[178:181], v140 offset:32768
	ds_read_b128 v[182:185], v140 offset:33792
	ds_read_b128 v[186:189], v140 offset:34816
	ds_read_b128 v[190:193], v140 offset:35840
	ds_read_b128 v[194:197], v140 offset:36864
	ds_read_b128 v[198:201], v140 offset:37888
	ds_read_b128 v[202:205], v140 offset:38912
	ds_read_b128 v[206:209], v140 offset:39936
	s_add_u32 s62, s26, 0x40000
	s_mov_b32 m0, s44
	s_addc_u32 s63, s27, 0
	global_load_lds_dwordx4 v134, s[62:63]
	s_add_u32 s62, s26, 0x60000
	s_mov_b32 m0, s45
	s_addc_u32 s63, s27, 0
	global_load_lds_dwordx4 v134, s[62:63]
	s_waitcnt vmcnt(8) lgkmcnt(0)
	s_barrier
	s_setprio 1
	v_mfma_f32_16x16x32_bf16 v[124:127], v[144:147], v[178:181], v[124:127]
	v_mfma_f32_16x16x32_bf16 v[120:123], v[152:155], v[178:181], v[120:123]
	v_mfma_f32_16x16x32_bf16 v[116:119], v[144:147], v[186:189], v[116:119]
	v_mfma_f32_16x16x32_bf16 v[108:111], v[152:155], v[186:189], v[108:111]
	v_mfma_f32_16x16x32_bf16 v[100:103], v[144:147], v[194:197], v[100:103]
	v_mfma_f32_16x16x32_bf16 v[92:95], v[152:155], v[194:197], v[92:95]
	v_mfma_f32_16x16x32_bf16 v[84:87], v[144:147], v[202:205], v[84:87]
	v_mfma_f32_16x16x32_bf16 v[76:79], v[152:155], v[202:205], v[76:79]
	v_mfma_f32_16x16x32_bf16 v[124:127], v[148:151], v[182:185], v[124:127]
	v_mfma_f32_16x16x32_bf16 v[120:123], v[156:159], v[182:185], v[120:123]
	v_mfma_f32_16x16x32_bf16 v[116:119], v[148:151], v[190:193], v[116:119]
	v_mfma_f32_16x16x32_bf16 v[108:111], v[156:159], v[190:193], v[108:111]
	v_mfma_f32_16x16x32_bf16 v[100:103], v[148:151], v[198:201], v[100:103]
	v_mfma_f32_16x16x32_bf16 v[92:95], v[156:159], v[198:201], v[92:95]
	v_mfma_f32_16x16x32_bf16 v[84:87], v[148:151], v[206:209], v[84:87]
	v_mfma_f32_16x16x32_bf16 v[76:79], v[156:159], v[206:209], v[76:79]
	v_mfma_f32_16x16x32_bf16 v[112:115], v[160:163], v[178:181], v[112:115]
	v_mfma_f32_16x16x32_bf16 v[104:107], v[168:171], v[178:181], v[104:107]
	v_mfma_f32_16x16x32_bf16 v[96:99], v[160:163], v[186:189], v[96:99]
	v_mfma_f32_16x16x32_bf16 v[88:91], v[168:171], v[186:189], v[88:91]
	v_mfma_f32_16x16x32_bf16 v[80:83], v[160:163], v[194:197], v[80:83]
	v_mfma_f32_16x16x32_bf16 v[72:75], v[168:171], v[194:197], v[72:75]
	v_mfma_f32_16x16x32_bf16 v[68:71], v[160:163], v[202:205], v[68:71]
	v_mfma_f32_16x16x32_bf16 v[64:67], v[168:171], v[202:205], v[64:67]
	v_mfma_f32_16x16x32_bf16 v[112:115], v[164:167], v[182:185], v[112:115]
	v_mfma_f32_16x16x32_bf16 v[104:107], v[172:175], v[182:185], v[104:107]
	v_mfma_f32_16x16x32_bf16 v[96:99], v[164:167], v[190:193], v[96:99]
	v_mfma_f32_16x16x32_bf16 v[88:91], v[172:175], v[190:193], v[88:91]
	v_mfma_f32_16x16x32_bf16 v[80:83], v[164:167], v[198:201], v[80:83]
	v_mfma_f32_16x16x32_bf16 v[72:75], v[172:175], v[198:201], v[72:75]
	v_mfma_f32_16x16x32_bf16 v[68:71], v[164:167], v[206:209], v[68:71]
	v_mfma_f32_16x16x32_bf16 v[64:67], v[172:175], v[206:209], v[64:67]
	s_setprio 0
	s_barrier
	s_add_u32 s62, s40, 0x80
	s_addc_u32 s63, s41, 0
	ds_read_b128 v[178:181], v140 offset:49152
	ds_read_b128 v[182:185], v140 offset:50176
	ds_read_b128 v[186:189], v140 offset:51200
	ds_read_b128 v[190:193], v140 offset:52224
	ds_read_b128 v[194:197], v140 offset:53248
	ds_read_b128 v[198:201], v140 offset:54272
	ds_read_b128 v[202:205], v140 offset:55296
	ds_read_b128 v[206:209], v140 offset:56320
	s_mov_b32 m0, s48
	s_nop 0
	global_load_lds_dwordx4 v135, s[62:63]
	s_add_u32 s62, s40, 0x20080
	s_mov_b32 m0, s49
	s_addc_u32 s63, s41, 0
	global_load_lds_dwordx4 v135, s[62:63]
	s_add_u32 s62, s40, 0x40080
	s_mov_b32 m0, s52
	s_addc_u32 s63, s41, 0
	global_load_lds_dwordx4 v135, s[62:63]
	s_add_u32 s40, s40, 0x60080
	s_mov_b32 m0, s53
	s_addc_u32 s41, s41, 0
	global_load_lds_dwordx4 v135, s[40:41]
	s_mov_b32 m0, s50
	s_nop 0
	global_load_lds_dwordx4 v134, s[38:39]
	s_add_u32 s26, s26, 0x20080
	s_mov_b32 m0, s51
	s_addc_u32 s27, s27, 0
	global_load_lds_dwordx4 v134, s[26:27]
	s_waitcnt vmcnt(8) lgkmcnt(0)
	s_barrier
	s_setprio 1
	v_mfma_f32_16x16x32_bf16 v[60:63], v[144:147], v[178:181], v[60:63]
	v_mfma_f32_16x16x32_bf16 v[56:59], v[152:155], v[178:181], v[56:59]
	v_mfma_f32_16x16x32_bf16 v[52:55], v[144:147], v[186:189], v[52:55]
	v_mfma_f32_16x16x32_bf16 v[44:47], v[152:155], v[186:189], v[44:47]
	v_mfma_f32_16x16x32_bf16 v[36:39], v[144:147], v[194:197], v[36:39]
	v_mfma_f32_16x16x32_bf16 v[28:31], v[152:155], v[194:197], v[28:31]
	v_mfma_f32_16x16x32_bf16 v[20:23], v[144:147], v[202:205], v[20:23]
	v_mfma_f32_16x16x32_bf16 v[12:15], v[152:155], v[202:205], v[12:15]
	v_mfma_f32_16x16x32_bf16 v[60:63], v[148:151], v[182:185], v[60:63]
	v_mfma_f32_16x16x32_bf16 v[56:59], v[156:159], v[182:185], v[56:59]
	v_mfma_f32_16x16x32_bf16 v[52:55], v[148:151], v[190:193], v[52:55]
	v_mfma_f32_16x16x32_bf16 v[44:47], v[156:159], v[190:193], v[44:47]
	v_mfma_f32_16x16x32_bf16 v[36:39], v[148:151], v[198:201], v[36:39]
	v_mfma_f32_16x16x32_bf16 v[28:31], v[156:159], v[198:201], v[28:31]
	v_mfma_f32_16x16x32_bf16 v[20:23], v[148:151], v[206:209], v[20:23]
	v_mfma_f32_16x16x32_bf16 v[12:15], v[156:159], v[206:209], v[12:15]
	v_mfma_f32_16x16x32_bf16 v[48:51], v[160:163], v[178:181], v[48:51]
	v_mfma_f32_16x16x32_bf16 v[40:43], v[168:171], v[178:181], v[40:43]
	v_mfma_f32_16x16x32_bf16 v[32:35], v[160:163], v[186:189], v[32:35]
	v_mfma_f32_16x16x32_bf16 v[24:27], v[168:171], v[186:189], v[24:27]
	v_mfma_f32_16x16x32_bf16 v[16:19], v[160:163], v[194:197], v[16:19]
	v_mfma_f32_16x16x32_bf16 v[8:11], v[168:171], v[194:197], v[8:11]
	v_mfma_f32_16x16x32_bf16 v[4:7], v[160:163], v[202:205], v[4:7]
	v_mfma_f32_16x16x32_bf16 v[0:3], v[168:171], v[202:205], v[0:3]
	v_mfma_f32_16x16x32_bf16 v[48:51], v[164:167], v[182:185], v[48:51]
	v_mfma_f32_16x16x32_bf16 v[40:43], v[172:175], v[182:185], v[40:43]
	v_mfma_f32_16x16x32_bf16 v[32:35], v[164:167], v[190:193], v[32:35]
	v_mfma_f32_16x16x32_bf16 v[24:27], v[172:175], v[190:193], v[24:27]
	v_mfma_f32_16x16x32_bf16 v[16:19], v[164:167], v[198:201], v[16:19]
	v_mfma_f32_16x16x32_bf16 v[8:11], v[172:175], v[198:201], v[8:11]
	v_mfma_f32_16x16x32_bf16 v[4:7], v[164:167], v[206:209], v[4:7]
	v_mfma_f32_16x16x32_bf16 v[0:3], v[172:175], v[206:209], v[0:3]
	s_setprio 0
	s_barrier
	s_cmp_gt_u32 s60, 13
	s_cbranch_scc0 .LBB0_1192
	s_and_b64 vcc, exec, s[14:15]
	s_cbranch_vccz .LBB0_1195
	s_barrier

; #define PG8_STAGE(bufoff, gbase, voff, p64) do { _Pragma("unroll") for (int _i = 0; _i < 2; ++_i) { \
;         const char* _gb = (const char*)(gbase) + (size_t)_i * (p64); const unsigned _la = ldsbase + (unsigned)(bufoff) + (unsigned)_i * 8192u; \
;         asm volatile("s_mov_b32 m0, %0\n\ts_nop 0\n\tglobal_load_lds_dwordx4 %1, %2" :: "s"(_la), "v"(voff), "s"(_gb) : "memory"); } } while (0)
; #define PG8_LDA(dst, b, h) do { _Pragma("unroll") for (int m = 0; m < 4; ++m) _Pragma("unroll") for (int k = 0; k < 2; ++k) dst[m][k] = *(const LAS bf16x8*)(lds + PG8_SA(b, h) + aoff + m * 2048 + k * 1024); } while (0)
; #define PG8_LDB(dst, b, h) do { _Pragma("unroll") for (int n = 0; n < 2; ++n) _Pragma("unroll") for (int k = 0; k < 2; ++k) dst[n][k] = *(const LAS bf16x8*)(lds + PG8_SB(b, h) + boff + n * 2048 + k * 1024); } while (0)
; #define PG8_WAIT_V(n) asm volatile("s_waitcnt vmcnt(" #n ")" ::: "memory")
; #define PG8_BAR __builtin_amdgcn_s_barrier()
; template <class Epi, class Sched>
; __device__ __forceinline__ void gemm_phase(LAS unsigned char* lds, const Sched& S, const Epi& E) {
;     ...
;         for (int t = 0; t < nt; t += 2) {
;             const bool last = (t == nt - 2);
;             const char* a1 = cA + (size_t)(t + 1) * kstep;
;             const char* a2 = last ? nA : cA + (size_t)(t + 2) * kstep; const char* b2 = last ? nB : cB + (size_t)(t + 2) * kstep;
;             const char* a3 = a2 + kstep; const char* b3 = b2 + kstep;
;             const unsigned vA2 = voffA, vB2 = voffB, hA2 = hA, hB2 = hB;
;             PG8_LDB(B0, 0, 0); PG8_LDB(B1, 0, 1); PG8_SCHED; PG8_LDA(At, 0, 0); PG8_STAGE(PG8_SA(1, 1), a1 + hA, voffA, hA / 2);
;             PG8_WAIT_V(8); PG8_WAIT_L(0); PG8_BAR; PG8_MMA(0, 0, At, B0); PG8_MMA(0, 1, At, B1); PG8_BAR; PG8_SCHED;
;             PG8_LDA(At, 0, 1); PG8_STAGE(PG8_SB(0, 0), b2, vB2, hB2 / 2); PG8_STAGE(PG8_SB(0, 1), b2 + hB2, vB2, hB2 / 2); PG8_STAGE(PG8_SA(0, 0), a2, vA2, hA2 / 2);
;             PG8_WAIT_V(8); PG8_WAIT_L(0); PG8_BAR; PG8_MMA(1, 0, At, B0); PG8_MMA(1, 1, At, B1); PG8_BAR; PG8_SCHED;
;     ...
; #pragma unroll
;             for (int a = 0; a < 2; ++a)
; #pragma unroll
;                 for (int b = 0; b < 2; ++b)
; #pragma unroll
;                     for (int m = 0; m < 4; ++m)
; #pragma unroll
;                         for (int n = 0; n < 2; ++n) acc[a][b][m][n] = (f32x4){0.f, 0.f, 0.f, 0.f};
.LBB0_1273:
	s_add_u32 s38, s38, 0x40080
	s_addc_u32 s39, s39, 0
	s_add_u32 s61, s40, 0x100
	s_addc_u32 s62, s41, 0
	s_mov_b32 s63, -2
	s_waitcnt vmcnt(3)
	s_waitcnt vmcnt(1)
	s_waitcnt vmcnt(0)
	ds_read_b128 v[128:131], v156
	ds_read_b128 v[132:135], v156 offset:1024
	ds_read_b128 v[140:143], v156 offset:2048
	ds_read_b128 v[144:147], v156 offset:3072
	ds_read_b128 v[148:151], v157
	ds_read_b128 v[162:165], v157 offset:1024
	ds_read_b128 v[166:169], v157 offset:2048
	ds_read_b128 v[170:173], v157 offset:3072
	s_add_u32 s30, s38, 0xfffc0080
	s_addc_u32 s40, s39, -1
	s_cmp_eq_u32 s63, 12
	s_cselect_b32 s41, s25, s40
	s_cselect_b32 s40, s24, s30
	s_cselect_b32 s44, s26, s61
	s_cselect_b32 s45, s27, s62
	s_add_u32 s42, s40, 0x80
	s_addc_u32 s43, s41, 0
	ds_read_b128 v[178:181], v158
	ds_read_b128 v[182:185], v158 offset:1024
	ds_read_b128 v[186:189], v158 offset:2048
	ds_read_b128 v[190:193], v158 offset:3072
	ds_read_b128 v[194:197], v158 offset:4096
	ds_read_b128 v[198:201], v158 offset:5120
	ds_read_b128 v[202:205], v158 offset:6144
	ds_read_b128 v[206:209], v158 offset:7168
	s_mov_b32 m0, s57
	s_nop 0
	global_load_lds_dwordx4 v152, s[38:39]
	s_add_u32 s66, s38, 0x20000
	s_mov_b32 m0, s58
	s_addc_u32 s67, s39, 0
	global_load_lds_dwordx4 v152, s[66:67]
	s_waitcnt vmcnt(8) lgkmcnt(0)
	s_barrier
	s_setprio 1
	v_mfma_f32_16x16x32_bf16 v[124:127], v[128:131], v[178:181], 0
	v_mfma_f32_16x16x32_bf16 v[116:119], v[140:143], v[178:181], 0
	v_mfma_f32_16x16x32_bf16 v[108:111], v[128:131], v[186:189], 0
	v_mfma_f32_16x16x32_bf16 v[100:103], v[140:143], v[186:189], 0
	v_mfma_f32_16x16x32_bf16 v[92:95], v[128:131], v[194:197], 0
	v_mfma_f32_16x16x32_bf16 v[84:87], v[140:143], v[194:197], 0
	v_mfma_f32_16x16x32_bf16 v[76:79], v[128:131], v[202:205], 0
	v_mfma_f32_16x16x32_bf16 v[68:71], v[140:143], v[202:205], 0
	v_mfma_f32_16x16x32_bf16 v[124:127], v[132:135], v[182:185], v[124:127]
	v_mfma_f32_16x16x32_bf16 v[116:119], v[144:147], v[182:185], v[116:119]
	v_mfma_f32_16x16x32_bf16 v[108:111], v[132:135], v[190:193], v[108:111]
	v_mfma_f32_16x16x32_bf16 v[100:103], v[144:147], v[190:193], v[100:103]
	v_mfma_f32_16x16x32_bf16 v[92:95], v[132:135], v[198:201], v[92:95]
	v_mfma_f32_16x16x32_bf16 v[84:87], v[144:147], v[198:201], v[84:87]
	v_mfma_f32_16x16x32_bf16 v[76:79], v[132:135], v[206:209], v[76:79]
	v_mfma_f32_16x16x32_bf16 v[68:71], v[144:147], v[206:209], v[68:71]
	v_mfma_f32_16x16x32_bf16 v[120:123], v[148:151], v[178:181], 0
	v_mfma_f32_16x16x32_bf16 v[112:115], v[166:169], v[178:181], 0
	v_mfma_f32_16x16x32_bf16 v[104:107], v[148:151], v[186:189], 0
	v_mfma_f32_16x16x32_bf16 v[96:99], v[166:169], v[186:189], 0
	v_mfma_f32_16x16x32_bf16 v[88:91], v[148:151], v[194:197], 0
	v_mfma_f32_16x16x32_bf16 v[80:83], v[166:169], v[194:197], 0
	v_mfma_f32_16x16x32_bf16 v[72:75], v[148:151], v[202:205], 0
	v_mfma_f32_16x16x32_bf16 v[64:67], v[166:169], v[202:205], 0
	v_mfma_f32_16x16x32_bf16 v[120:123], v[162:165], v[182:185], v[120:123]
	v_mfma_f32_16x16x32_bf16 v[112:115], v[170:173], v[182:185], v[112:115]
	v_mfma_f32_16x16x32_bf16 v[104:107], v[162:165], v[190:193], v[104:107]
	v_mfma_f32_16x16x32_bf16 v[96:99], v[170:173], v[190:193], v[96:99]
	v_mfma_f32_16x16x32_bf16 v[88:91], v[162:165], v[198:201], v[88:91]
	v_mfma_f32_16x16x32_bf16 v[80:83], v[170:173], v[198:201], v[80:83]
	v_mfma_f32_16x16x32_bf16 v[72:75], v[162:165], v[206:209], v[72:75]
	v_mfma_f32_16x16x32_bf16 v[64:67], v[170:173], v[206:209], v[64:67]
	s_add_i32 s63, s63, 2
	s_add_u32 s38, s38, 0x100
	s_addc_u32 s39, s39, 0
	s_add_u32 s61, s61, 0x100
	s_addc_u32 s62, s62, 0
	s_setprio 0
	s_barrier
	s_add_u32 s66, s44, 0x20000
	ds_read_b128 v[178:181], v158 offset:16384
	ds_read_b128 v[182:185], v158 offset:17408
	ds_read_b128 v[186:189], v158 offset:18432
	ds_read_b128 v[190:193], v158 offset:19456
	ds_read_b128 v[194:197], v158 offset:20480
	ds_read_b128 v[198:201], v158 offset:21504
	ds_read_b128 v[202:205], v158 offset:22528
	ds_read_b128 v[206:209], v158 offset:23552
	s_mov_b32 m0, s35
	s_nop 0
	global_load_lds_dwordx4 v153, s[44:45]
	s_mov_b32 m0, s36
	s_addc_u32 s67, s45, 0
	global_load_lds_dwordx4 v153, s[66:67]
	s_add_u32 s66, s44, 0x40000
	s_mov_b32 m0, s37
	s_addc_u32 s67, s45, 0
	global_load_lds_dwordx4 v153, s[66:67]
	s_add_u32 s66, s44, 0x60000
	s_mov_b32 m0, s46
	s_addc_u32 s67, s45, 0
	global_load_lds_dwordx4 v153, s[66:67]
	s_mov_b32 m0, s34
	s_nop 0
	global_load_lds_dwordx4 v152, s[40:41]
	s_add_u32 s66, s40, 0x20000
	s_mov_b32 m0, s47
	s_addc_u32 s67, s41, 0
	global_load_lds_dwordx4 v152, s[66:67]
	s_waitcnt vmcnt(8) lgkmcnt(0)
	s_barrier
	s_setprio 1
	v_mfma_f32_16x16x32_bf16 v[60:63], v[128:131], v[178:181], 0
	v_mfma_f32_16x16x32_bf16 v[52:55], v[140:143], v[178:181], 0
	v_mfma_f32_16x16x32_bf16 v[44:47], v[128:131], v[186:189], 0
	v_mfma_f32_16x16x32_bf16 v[36:39], v[140:143], v[186:189], 0
	v_mfma_f32_16x16x32_bf16 v[28:31], v[128:131], v[194:197], 0
	v_mfma_f32_16x16x32_bf16 v[20:23], v[140:143], v[194:197], 0
	v_mfma_f32_16x16x32_bf16 v[12:15], v[128:131], v[202:205], 0
	v_mfma_f32_16x16x32_bf16 v[4:7], v[140:143], v[202:205], 0
	v_mfma_f32_16x16x32_bf16 v[60:63], v[132:135], v[182:185], v[60:63]
	v_mfma_f32_16x16x32_bf16 v[52:55], v[144:147], v[182:185], v[52:55]
	v_mfma_f32_16x16x32_bf16 v[44:47], v[132:135], v[190:193], v[44:47]
	v_mfma_f32_16x16x32_bf16 v[36:39], v[144:147], v[190:193], v[36:39]
	v_mfma_f32_16x16x32_bf16 v[28:31], v[132:135], v[198:201], v[28:31]
	v_mfma_f32_16x16x32_bf16 v[20:23], v[144:147], v[198:201], v[20:23]
	v_mfma_f32_16x16x32_bf16 v[12:15], v[132:135], v[206:209], v[12:15]
	v_mfma_f32_16x16x32_bf16 v[4:7], v[144:147], v[206:209], v[4:7]
	v_mfma_f32_16x16x32_bf16 v[56:59], v[148:151], v[178:181], 0
	v_mfma_f32_16x16x32_bf16 v[48:51], v[166:169], v[178:181], 0
	v_mfma_f32_16x16x32_bf16 v[40:43], v[148:151], v[186:189], 0
	v_mfma_f32_16x16x32_bf16 v[32:35], v[166:169], v[186:189], 0
	v_mfma_f32_16x16x32_bf16 v[24:27], v[148:151], v[194:197], 0
	v_mfma_f32_16x16x32_bf16 v[16:19], v[166:169], v[194:197], 0
	v_mfma_f32_16x16x32_bf16 v[8:11], v[148:151], v[202:205], 0
	v_mfma_f32_16x16x32_bf16 v[0:3], v[166:169], v[202:205], 0
	v_mfma_f32_16x16x32_bf16 v[56:59], v[162:165], v[182:185], v[56:59]
	v_mfma_f32_16x16x32_bf16 v[48:51], v[170:173], v[182:185], v[48:51]
	v_mfma_f32_16x16x32_bf16 v[40:43], v[162:165], v[190:193], v[40:43]
	v_mfma_f32_16x16x32_bf16 v[32:35], v[170:173], v[190:193], v[32:35]
	v_mfma_f32_16x16x32_bf16 v[24:27], v[162:165], v[198:201], v[24:27]
	v_mfma_f32_16x16x32_bf16 v[16:19], v[170:173], v[198:201], v[16:19]
	v_mfma_f32_16x16x32_bf16 v[8:11], v[162:165], v[206:209], v[8:11]
	v_mfma_f32_16x16x32_bf16 v[0:3], v[170:173], v[206:209], v[0:3]
	s_setprio 0
	s_barrier
	s_branch .Lpeel_mid_37910
; #define PG8_STAGE(bufoff, gbase, voff, p64) do { _Pragma("unroll") for (int _i = 0; _i < 2; ++_i) { \
;         const char* _gb = (const char*)(gbase) + (size_t)_i * (p64); const unsigned _la = ldsbase + (unsigned)(bufoff) + (unsigned)_i * 8192u; \
;         asm volatile("s_mov_b32 m0, %0\n\ts_nop 0\n\tglobal_load_lds_dwordx4 %1, %2" :: "s"(_la), "v"(voff), "s"(_gb) : "memory"); } } while (0)
; #define PG8_LDA(dst, b, h) do { _Pragma("unroll") for (int m = 0; m < 4; ++m) _Pragma("unroll") for (int k = 0; k < 2; ++k) dst[m][k] = *(const LAS bf16x8*)(lds + PG8_SA(b, h) + aoff + m * 2048 + k * 1024); } while (0)
; #define PG8_LDB(dst, b, h) do { _Pragma("unroll") for (int n = 0; n < 2; ++n) _Pragma("unroll") for (int k = 0; k < 2; ++k) dst[n][k] = *(const LAS bf16x8*)(lds + PG8_SB(b, h) + boff + n * 2048 + k * 1024); } while (0)
; #define PG8_MMA(ai, bj, At, Bt) do { __builtin_amdgcn_s_setprio(1); _Pragma("unroll") for (int m = 0; m < 4; ++m) _Pragma("unroll") for (int n = 0; n < 2; ++n) _Pragma("unroll") for (int k = 0; k < 2; ++k) \
;         acc[ai][bj][m][n] = __builtin_amdgcn_mfma_f32_16x16x32_bf16(Bt[n][k], At[m][k], acc[ai][bj][m][n], 0, 0, 0); __builtin_amdgcn_s_setprio(0); } while (0)
; #define PG8_WAIT_V(n) asm volatile("s_waitcnt vmcnt(" #n ")" ::: "memory")
; template <class Epi, class Sched>
; __device__ __forceinline__ void gemm_phase(LAS unsigned char* lds, const Sched& S, const Epi& E) {
;     ...
;         for (int t = 0; t < nt; t += 2) {
;             const bool last = (t == nt - 2);
;             const char* a1 = cA + (size_t)(t + 1) * kstep;
;             const char* a2 = last ? nA : cA + (size_t)(t + 2) * kstep; const char* b2 = last ? nB : cB + (size_t)(t + 2) * kstep;
;             const char* a3 = a2 + kstep; const char* b3 = b2 + kstep;
;             const unsigned vA2 = voffA, vB2 = voffB, hA2 = hA, hB2 = hB;
;             PG8_LDB(B0, 0, 0); PG8_LDB(B1, 0, 1); PG8_SCHED; PG8_LDA(At, 0, 0); PG8_STAGE(PG8_SA(1, 1), a1 + hA, voffA, hA / 2);
;             PG8_WAIT_V(8); PG8_WAIT_L(0); PG8_BAR; PG8_MMA(0, 0, At, B0); PG8_MMA(0, 1, At, B1); PG8_BAR; PG8_SCHED;
;             PG8_LDA(At, 0, 1); PG8_STAGE(PG8_SB(0, 0), b2, vB2, hB2 / 2); PG8_STAGE(PG8_SB(0, 1), b2 + hB2, vB2, hB2 / 2); PG8_STAGE(PG8_SA(0, 0), a2, vA2, hA2 / 2);
;             PG8_WAIT_V(8); PG8_WAIT_L(0); PG8_BAR; PG8_MMA(1, 0, At, B0); PG8_MMA(1, 1, At, B1); PG8_BAR; PG8_SCHED;
.LBB0_1274:
	ds_read_b128 v[128:131], v156
	ds_read_b128 v[132:135], v156 offset:1024
	ds_read_b128 v[140:143], v156 offset:2048
	ds_read_b128 v[144:147], v156 offset:3072
	ds_read_b128 v[148:151], v157
	ds_read_b128 v[162:165], v157 offset:1024
	ds_read_b128 v[166:169], v157 offset:2048
	ds_read_b128 v[170:173], v157 offset:3072
	s_add_u32 s30, s38, 0xfffc0080
	s_addc_u32 s40, s39, -1
	s_cmp_eq_u32 s63, 12
	s_cselect_b32 s41, s25, s40
	s_cselect_b32 s40, s24, s30
	s_cselect_b32 s44, s26, s61
	s_cselect_b32 s45, s27, s62
	s_add_u32 s42, s40, 0x80
	s_addc_u32 s43, s41, 0
	ds_read_b128 v[178:181], v158
	ds_read_b128 v[182:185], v158 offset:1024
	ds_read_b128 v[186:189], v158 offset:2048
	ds_read_b128 v[190:193], v158 offset:3072
	ds_read_b128 v[194:197], v158 offset:4096
	ds_read_b128 v[198:201], v158 offset:5120
	ds_read_b128 v[202:205], v158 offset:6144
	ds_read_b128 v[206:209], v158 offset:7168
	s_mov_b32 m0, s57
	s_nop 0
	global_load_lds_dwordx4 v152, s[38:39]
	s_add_u32 s66, s38, 0x20000
	s_mov_b32 m0, s58
	s_addc_u32 s67, s39, 0
	global_load_lds_dwordx4 v152, s[66:67]
	s_waitcnt vmcnt(8) lgkmcnt(0)
	s_barrier
	s_setprio 1
	v_mfma_f32_16x16x32_bf16 v[124:127], v[128:131], v[178:181], v[124:127]
	v_mfma_f32_16x16x32_bf16 v[116:119], v[140:143], v[178:181], v[116:119]
	v_mfma_f32_16x16x32_bf16 v[108:111], v[128:131], v[186:189], v[108:111]
	v_mfma_f32_16x16x32_bf16 v[100:103], v[140:143], v[186:189], v[100:103]
	v_mfma_f32_16x16x32_bf16 v[92:95], v[128:131], v[194:197], v[92:95]
	v_mfma_f32_16x16x32_bf16 v[84:87], v[140:143], v[194:197], v[84:87]
	v_mfma_f32_16x16x32_bf16 v[76:79], v[128:131], v[202:205], v[76:79]
	v_mfma_f32_16x16x32_bf16 v[68:71], v[140:143], v[202:205], v[68:71]
	v_mfma_f32_16x16x32_bf16 v[124:127], v[132:135], v[182:185], v[124:127]
	v_mfma_f32_16x16x32_bf16 v[116:119], v[144:147], v[182:185], v[116:119]
	v_mfma_f32_16x16x32_bf16 v[108:111], v[132:135], v[190:193], v[108:111]
	v_mfma_f32_16x16x32_bf16 v[100:103], v[144:147], v[190:193], v[100:103]
	v_mfma_f32_16x16x32_bf16 v[92:95], v[132:135], v[198:201], v[92:95]
	v_mfma_f32_16x16x32_bf16 v[84:87], v[144:147], v[198:201], v[84:87]
	v_mfma_f32_16x16x32_bf16 v[76:79], v[132:135], v[206:209], v[76:79]
	v_mfma_f32_16x16x32_bf16 v[68:71], v[144:147], v[206:209], v[68:71]
	v_mfma_f32_16x16x32_bf16 v[120:123], v[148:151], v[178:181], v[120:123]
	v_mfma_f32_16x16x32_bf16 v[112:115], v[166:169], v[178:181], v[112:115]
	v_mfma_f32_16x16x32_bf16 v[104:107], v[148:151], v[186:189], v[104:107]
	v_mfma_f32_16x16x32_bf16 v[96:99], v[166:169], v[186:189], v[96:99]
	v_mfma_f32_16x16x32_bf16 v[88:91], v[148:151], v[194:197], v[88:91]
	v_mfma_f32_16x16x32_bf16 v[80:83], v[166:169], v[194:197], v[80:83]
	v_mfma_f32_16x16x32_bf16 v[72:75], v[148:151], v[202:205], v[72:75]
	v_mfma_f32_16x16x32_bf16 v[64:67], v[166:169], v[202:205], v[64:67]
	v_mfma_f32_16x16x32_bf16 v[120:123], v[162:165], v[182:185], v[120:123]
	v_mfma_f32_16x16x32_bf16 v[112:115], v[170:173], v[182:185], v[112:115]
	v_mfma_f32_16x16x32_bf16 v[104:107], v[162:165], v[190:193], v[104:107]
	v_mfma_f32_16x16x32_bf16 v[96:99], v[170:173], v[190:193], v[96:99]
	v_mfma_f32_16x16x32_bf16 v[88:91], v[162:165], v[198:201], v[88:91]
	v_mfma_f32_16x16x32_bf16 v[80:83], v[170:173], v[198:201], v[80:83]
	v_mfma_f32_16x16x32_bf16 v[72:75], v[162:165], v[206:209], v[72:75]
	v_mfma_f32_16x16x32_bf16 v[64:67], v[170:173], v[206:209], v[64:67]
	s_add_i32 s63, s63, 2
	s_add_u32 s38, s38, 0x100
	s_addc_u32 s39, s39, 0
	s_add_u32 s61, s61, 0x100
	s_addc_u32 s62, s62, 0
	s_setprio 0
	s_barrier
	s_add_u32 s66, s44, 0x20000
	ds_read_b128 v[178:181], v158 offset:16384
	ds_read_b128 v[182:185], v158 offset:17408
	ds_read_b128 v[186:189], v158 offset:18432
	ds_read_b128 v[190:193], v158 offset:19456
	ds_read_b128 v[194:197], v158 offset:20480
	ds_read_b128 v[198:201], v158 offset:21504
	ds_read_b128 v[202:205], v158 offset:22528
	ds_read_b128 v[206:209], v158 offset:23552
	s_mov_b32 m0, s35
	s_nop 0
	global_load_lds_dwordx4 v153, s[44:45]
	s_mov_b32 m0, s36
	s_addc_u32 s67, s45, 0
	global_load_lds_dwordx4 v153, s[66:67]
	s_add_u32 s66, s44, 0x40000
	s_mov_b32 m0, s37
	s_addc_u32 s67, s45, 0
	global_load_lds_dwordx4 v153, s[66:67]
	s_add_u32 s66, s44, 0x60000
	s_mov_b32 m0, s46
	s_addc_u32 s67, s45, 0
	global_load_lds_dwordx4 v153, s[66:67]
	s_mov_b32 m0, s34
	s_nop 0
	global_load_lds_dwordx4 v152, s[40:41]
	s_add_u32 s66, s40, 0x20000
	s_mov_b32 m0, s47
	s_addc_u32 s67, s41, 0
	global_load_lds_dwordx4 v152, s[66:67]
	s_waitcnt vmcnt(8) lgkmcnt(0)
	s_barrier
	s_setprio 1
	v_mfma_f32_16x16x32_bf16 v[60:63], v[128:131], v[178:181], v[60:63]
	v_mfma_f32_16x16x32_bf16 v[52:55], v[140:143], v[178:181], v[52:55]
	v_mfma_f32_16x16x32_bf16 v[44:47], v[128:131], v[186:189], v[44:47]
	v_mfma_f32_16x16x32_bf16 v[36:39], v[140:143], v[186:189], v[36:39]
	v_mfma_f32_16x16x32_bf16 v[28:31], v[128:131], v[194:197], v[28:31]
	v_mfma_f32_16x16x32_bf16 v[20:23], v[140:143], v[194:197], v[20:23]
	v_mfma_f32_16x16x32_bf16 v[12:15], v[128:131], v[202:205], v[12:15]
	v_mfma_f32_16x16x32_bf16 v[4:7], v[140:143], v[202:205], v[4:7]
	v_mfma_f32_16x16x32_bf16 v[60:63], v[132:135], v[182:185], v[60:63]
	v_mfma_f32_16x16x32_bf16 v[52:55], v[144:147], v[182:185], v[52:55]
	v_mfma_f32_16x16x32_bf16 v[44:47], v[132:135], v[190:193], v[44:47]
	v_mfma_f32_16x16x32_bf16 v[36:39], v[144:147], v[190:193], v[36:39]
	v_mfma_f32_16x16x32_bf16 v[28:31], v[132:135], v[198:201], v[28:31]
	v_mfma_f32_16x16x32_bf16 v[20:23], v[144:147], v[198:201], v[20:23]
	v_mfma_f32_16x16x32_bf16 v[12:15], v[132:135], v[206:209], v[12:15]
	v_mfma_f32_16x16x32_bf16 v[4:7], v[144:147], v[206:209], v[4:7]
	v_mfma_f32_16x16x32_bf16 v[56:59], v[148:151], v[178:181], v[56:59]
	v_mfma_f32_16x16x32_bf16 v[48:51], v[166:169], v[178:181], v[48:51]
	v_mfma_f32_16x16x32_bf16 v[40:43], v[148:151], v[186:189], v[40:43]
	v_mfma_f32_16x16x32_bf16 v[32:35], v[166:169], v[186:189], v[32:35]
	v_mfma_f32_16x16x32_bf16 v[24:27], v[148:151], v[194:197], v[24:27]
	v_mfma_f32_16x16x32_bf16 v[16:19], v[166:169], v[194:197], v[16:19]
	v_mfma_f32_16x16x32_bf16 v[8:11], v[148:151], v[202:205], v[8:11]
	v_mfma_f32_16x16x32_bf16 v[0:3], v[166:169], v[202:205], v[0:3]
	v_mfma_f32_16x16x32_bf16 v[56:59], v[162:165], v[182:185], v[56:59]
	v_mfma_f32_16x16x32_bf16 v[48:51], v[170:173], v[182:185], v[48:51]
	v_mfma_f32_16x16x32_bf16 v[40:43], v[162:165], v[190:193], v[40:43]
	v_mfma_f32_16x16x32_bf16 v[32:35], v[170:173], v[190:193], v[32:35]
	v_mfma_f32_16x16x32_bf16 v[24:27], v[162:165], v[198:201], v[24:27]
	v_mfma_f32_16x16x32_bf16 v[16:19], v[170:173], v[198:201], v[16:19]
	v_mfma_f32_16x16x32_bf16 v[8:11], v[162:165], v[206:209], v[8:11]
	v_mfma_f32_16x16x32_bf16 v[0:3], v[170:173], v[206:209], v[0:3]
	s_setprio 0
	s_barrier
; #define PG8_STAGE(bufoff, gbase, voff, p64) do { _Pragma("unroll") for (int _i = 0; _i < 2; ++_i) { \
;         const char* _gb = (const char*)(gbase) + (size_t)_i * (p64); const unsigned _la = ldsbase + (unsigned)(bufoff) + (unsigned)_i * 8192u; \
;         asm volatile("s_mov_b32 m0, %0\n\ts_nop 0\n\tglobal_load_lds_dwordx4 %1, %2" :: "s"(_la), "v"(voff), "s"(_gb) : "memory"); } } while (0)
; #define PG8_LDA(dst, b, h) do { _Pragma("unroll") for (int m = 0; m < 4; ++m) _Pragma("unroll") for (int k = 0; k < 2; ++k) dst[m][k] = *(const LAS bf16x8*)(lds + PG8_SA(b, h) + aoff + m * 2048 + k * 1024); } while (0)
; #define PG8_LDB(dst, b, h) do { _Pragma("unroll") for (int n = 0; n < 2; ++n) _Pragma("unroll") for (int k = 0; k < 2; ++k) dst[n][k] = *(const LAS bf16x8*)(lds + PG8_SB(b, h) + boff + n * 2048 + k * 1024); } while (0)
; #define PG8_MMA(ai, bj, At, Bt) do { __builtin_amdgcn_s_setprio(1); _Pragma("unroll") for (int m = 0; m < 4; ++m) _Pragma("unroll") for (int n = 0; n < 2; ++n) _Pragma("unroll") for (int k = 0; k < 2; ++k) \
;         acc[ai][bj][m][n] = __builtin_amdgcn_mfma_f32_16x16x32_bf16(Bt[n][k], At[m][k], acc[ai][bj][m][n], 0, 0, 0); __builtin_amdgcn_s_setprio(0); } while (0)
; #define PG8_WAIT_V(n) asm volatile("s_waitcnt vmcnt(" #n ")" ::: "memory")
; #define PG8_WAIT_L(n) asm volatile("s_waitcnt lgkmcnt(" #n ")" ::: "memory")
; #define PG8_BAR __builtin_amdgcn_s_barrier()
; #define PG8_SCHED __builtin_amdgcn_sched_barrier(0)
; template <class Epi, class Sched>
; __device__ __forceinline__ void gemm_phase(LAS unsigned char* lds, const Sched& S, const Epi& E) {
;     ...
;             PG8_LDB(B0, 1, 0); PG8_LDB(B1, 1, 1); PG8_SCHED; PG8_LDA(At, 1, 0); PG8_STAGE(PG8_SA(0, 1), a2 + hA2, vA2, hA2 / 2);
;             PG8_WAIT_V(8); PG8_WAIT_L(0); PG8_BAR; PG8_MMA(0, 0, At, B0); PG8_MMA(0, 1, At, B1); PG8_BAR; PG8_SCHED;
;             PG8_LDA(At, 1, 1); PG8_STAGE(PG8_SB(1, 0), b3, vB2, hB2 / 2); PG8_STAGE(PG8_SB(1, 1), b3 + hB2, vB2, hB2 / 2); PG8_STAGE(PG8_SA(1, 0), a3, vA2, hA2 / 2);
;             PG8_WAIT_V(8); PG8_WAIT_L(0); PG8_BAR; PG8_MMA(1, 0, At, B0); PG8_MMA(1, 1, At, B1); PG8_BAR; PG8_SCHED;
;         }
;         if (wr == 0) PG8_BAR;
.Lpeel_mid_37910:
	ds_read_b128 v[128:131], v159
	ds_read_b128 v[132:135], v159 offset:1024
	ds_read_b128 v[140:143], v159 offset:2048
	ds_read_b128 v[144:147], v159 offset:3072
	ds_read_b128 v[148:151], v160
	ds_read_b128 v[162:165], v160 offset:1024
	ds_read_b128 v[166:169], v160 offset:2048
	ds_read_b128 v[170:173], v160 offset:3072
	ds_read_b128 v[178:181], v158 offset:32768
	ds_read_b128 v[182:185], v158 offset:33792
	ds_read_b128 v[186:189], v158 offset:34816
	ds_read_b128 v[190:193], v158 offset:35840
	ds_read_b128 v[194:197], v158 offset:36864
	ds_read_b128 v[198:201], v158 offset:37888
	ds_read_b128 v[202:205], v158 offset:38912
	ds_read_b128 v[206:209], v158 offset:39936
	s_add_u32 s66, s40, 0x40000
	s_mov_b32 m0, s48
	s_addc_u32 s67, s41, 0
	global_load_lds_dwordx4 v152, s[66:67]
	s_add_u32 s66, s40, 0x60000
	s_mov_b32 m0, s49
	s_addc_u32 s67, s41, 0
	global_load_lds_dwordx4 v152, s[66:67]
	s_waitcnt vmcnt(8) lgkmcnt(0)
	s_barrier
	s_setprio 1
	v_mfma_f32_16x16x32_bf16 v[124:127], v[128:131], v[178:181], v[124:127]
	v_mfma_f32_16x16x32_bf16 v[116:119], v[140:143], v[178:181], v[116:119]
	v_mfma_f32_16x16x32_bf16 v[108:111], v[128:131], v[186:189], v[108:111]
	v_mfma_f32_16x16x32_bf16 v[100:103], v[140:143], v[186:189], v[100:103]
	v_mfma_f32_16x16x32_bf16 v[92:95], v[128:131], v[194:197], v[92:95]
	v_mfma_f32_16x16x32_bf16 v[84:87], v[140:143], v[194:197], v[84:87]
	v_mfma_f32_16x16x32_bf16 v[76:79], v[128:131], v[202:205], v[76:79]
	v_mfma_f32_16x16x32_bf16 v[68:71], v[140:143], v[202:205], v[68:71]
	v_mfma_f32_16x16x32_bf16 v[124:127], v[132:135], v[182:185], v[124:127]
	v_mfma_f32_16x16x32_bf16 v[116:119], v[144:147], v[182:185], v[116:119]
	v_mfma_f32_16x16x32_bf16 v[108:111], v[132:135], v[190:193], v[108:111]
	v_mfma_f32_16x16x32_bf16 v[100:103], v[144:147], v[190:193], v[100:103]
	v_mfma_f32_16x16x32_bf16 v[92:95], v[132:135], v[198:201], v[92:95]
	v_mfma_f32_16x16x32_bf16 v[84:87], v[144:147], v[198:201], v[84:87]
	v_mfma_f32_16x16x32_bf16 v[76:79], v[132:135], v[206:209], v[76:79]
	v_mfma_f32_16x16x32_bf16 v[68:71], v[144:147], v[206:209], v[68:71]
	v_mfma_f32_16x16x32_bf16 v[120:123], v[148:151], v[178:181], v[120:123]
	v_mfma_f32_16x16x32_bf16 v[112:115], v[166:169], v[178:181], v[112:115]
	v_mfma_f32_16x16x32_bf16 v[104:107], v[148:151], v[186:189], v[104:107]
	v_mfma_f32_16x16x32_bf16 v[96:99], v[166:169], v[186:189], v[96:99]
	v_mfma_f32_16x16x32_bf16 v[88:91], v[148:151], v[194:197], v[88:91]
	v_mfma_f32_16x16x32_bf16 v[80:83], v[166:169], v[194:197], v[80:83]
	v_mfma_f32_16x16x32_bf16 v[72:75], v[148:151], v[202:205], v[72:75]
	v_mfma_f32_16x16x32_bf16 v[64:67], v[166:169], v[202:205], v[64:67]
	v_mfma_f32_16x16x32_bf16 v[120:123], v[162:165], v[182:185], v[120:123]
	v_mfma_f32_16x16x32_bf16 v[112:115], v[170:173], v[182:185], v[112:115]
	v_mfma_f32_16x16x32_bf16 v[104:107], v[162:165], v[190:193], v[104:107]
	v_mfma_f32_16x16x32_bf16 v[96:99], v[170:173], v[190:193], v[96:99]
	v_mfma_f32_16x16x32_bf16 v[88:91], v[162:165], v[198:201], v[88:91]
	v_mfma_f32_16x16x32_bf16 v[80:83], v[170:173], v[198:201], v[80:83]
	v_mfma_f32_16x16x32_bf16 v[72:75], v[162:165], v[206:209], v[72:75]
	v_mfma_f32_16x16x32_bf16 v[64:67], v[170:173], v[206:209], v[64:67]
	s_setprio 0
	s_barrier
	s_add_u32 s66, s44, 0x80
	s_addc_u32 s67, s45, 0
	ds_read_b128 v[178:181], v158 offset:49152
	ds_read_b128 v[182:185], v158 offset:50176
	ds_read_b128 v[186:189], v158 offset:51200
	ds_read_b128 v[190:193], v158 offset:52224
	ds_read_b128 v[194:197], v158 offset:53248
	ds_read_b128 v[198:201], v158 offset:54272
	ds_read_b128 v[202:205], v158 offset:55296
	ds_read_b128 v[206:209], v158 offset:56320
	s_mov_b32 m0, s51
	s_nop 0
	global_load_lds_dwordx4 v153, s[66:67]
	s_add_u32 s66, s44, 0x20080
	s_mov_b32 m0, s52
	s_addc_u32 s67, s45, 0
	global_load_lds_dwordx4 v153, s[66:67]
	s_add_u32 s66, s44, 0x40080
	s_mov_b32 m0, s55
	s_addc_u32 s67, s45, 0
	global_load_lds_dwordx4 v153, s[66:67]
	s_add_u32 s44, s44, 0x60080
	s_mov_b32 m0, s56
	s_addc_u32 s45, s45, 0
	global_load_lds_dwordx4 v153, s[44:45]
	s_mov_b32 m0, s53
	s_nop 0
	global_load_lds_dwordx4 v152, s[42:43]
	s_add_u32 s40, s40, 0x20080
	s_mov_b32 m0, s54
	s_addc_u32 s41, s41, 0
	global_load_lds_dwordx4 v152, s[40:41]
	s_waitcnt vmcnt(8) lgkmcnt(0)
	s_barrier
	s_setprio 1
	v_mfma_f32_16x16x32_bf16 v[60:63], v[128:131], v[178:181], v[60:63]
	v_mfma_f32_16x16x32_bf16 v[52:55], v[140:143], v[178:181], v[52:55]
	v_mfma_f32_16x16x32_bf16 v[44:47], v[128:131], v[186:189], v[44:47]
	v_mfma_f32_16x16x32_bf16 v[36:39], v[140:143], v[186:189], v[36:39]
	v_mfma_f32_16x16x32_bf16 v[28:31], v[128:131], v[194:197], v[28:31]
	v_mfma_f32_16x16x32_bf16 v[20:23], v[140:143], v[194:197], v[20:23]
	v_mfma_f32_16x16x32_bf16 v[12:15], v[128:131], v[202:205], v[12:15]
	v_mfma_f32_16x16x32_bf16 v[4:7], v[140:143], v[202:205], v[4:7]
	v_mfma_f32_16x16x32_bf16 v[60:63], v[132:135], v[182:185], v[60:63]
	v_mfma_f32_16x16x32_bf16 v[52:55], v[144:147], v[182:185], v[52:55]
	v_mfma_f32_16x16x32_bf16 v[44:47], v[132:135], v[190:193], v[44:47]
	v_mfma_f32_16x16x32_bf16 v[36:39], v[144:147], v[190:193], v[36:39]
	v_mfma_f32_16x16x32_bf16 v[28:31], v[132:135], v[198:201], v[28:31]
	v_mfma_f32_16x16x32_bf16 v[20:23], v[144:147], v[198:201], v[20:23]
	v_mfma_f32_16x16x32_bf16 v[12:15], v[132:135], v[206:209], v[12:15]
	v_mfma_f32_16x16x32_bf16 v[4:7], v[144:147], v[206:209], v[4:7]
	v_mfma_f32_16x16x32_bf16 v[56:59], v[148:151], v[178:181], v[56:59]
	v_mfma_f32_16x16x32_bf16 v[48:51], v[166:169], v[178:181], v[48:51]
	v_mfma_f32_16x16x32_bf16 v[40:43], v[148:151], v[186:189], v[40:43]
	v_mfma_f32_16x16x32_bf16 v[32:35], v[166:169], v[186:189], v[32:35]
	v_mfma_f32_16x16x32_bf16 v[24:27], v[148:151], v[194:197], v[24:27]
	v_mfma_f32_16x16x32_bf16 v[16:19], v[166:169], v[194:197], v[16:19]
	v_mfma_f32_16x16x32_bf16 v[8:11], v[148:151], v[202:205], v[8:11]
	v_mfma_f32_16x16x32_bf16 v[0:3], v[166:169], v[202:205], v[0:3]
	v_mfma_f32_16x16x32_bf16 v[56:59], v[162:165], v[182:185], v[56:59]
	v_mfma_f32_16x16x32_bf16 v[48:51], v[170:173], v[182:185], v[48:51]
	v_mfma_f32_16x16x32_bf16 v[40:43], v[162:165], v[190:193], v[40:43]
	v_mfma_f32_16x16x32_bf16 v[32:35], v[170:173], v[190:193], v[32:35]
	v_mfma_f32_16x16x32_bf16 v[24:27], v[162:165], v[198:201], v[24:27]
	v_mfma_f32_16x16x32_bf16 v[16:19], v[170:173], v[198:201], v[16:19]
	v_mfma_f32_16x16x32_bf16 v[8:11], v[162:165], v[206:209], v[8:11]
	v_mfma_f32_16x16x32_bf16 v[0:3], v[170:173], v[206:209], v[0:3]
	s_setprio 0
	s_barrier
	s_cmp_gt_u32 s63, 13
	s_cbranch_scc0 .LBB0_1274
	s_and_b64 vcc, exec, s[18:19]
	s_cbranch_vccz .LBB0_1277
	s_barrier

; #define PG8_STAGE(bufoff, gbase, voff, p64) do { _Pragma("unroll") for (int _i = 0; _i < 2; ++_i) { \
;         const char* _gb = (const char*)(gbase) + (size_t)_i * (p64); const unsigned _la = ldsbase + (unsigned)(bufoff) + (unsigned)_i * 8192u; \
;         asm volatile("s_mov_b32 m0, %0\n\ts_nop 0\n\tglobal_load_lds_dwordx4 %1, %2" :: "s"(_la), "v"(voff), "s"(_gb) : "memory"); } } while (0)
; #define PG8_LDA(dst, b, h) do { _Pragma("unroll") for (int m = 0; m < 4; ++m) _Pragma("unroll") for (int k = 0; k < 2; ++k) dst[m][k] = *(const LAS bf16x8*)(lds + PG8_SA(b, h) + aoff + m * 2048 + k * 1024); } while (0)
; #define PG8_LDB(dst, b, h) do { _Pragma("unroll") for (int n = 0; n < 2; ++n) _Pragma("unroll") for (int k = 0; k < 2; ++k) dst[n][k] = *(const LAS bf16x8*)(lds + PG8_SB(b, h) + boff + n * 2048 + k * 1024); } while (0)
; #define PG8_WAIT_V(n) asm volatile("s_waitcnt vmcnt(" #n ")" ::: "memory")
; #define PG8_BAR __builtin_amdgcn_s_barrier()
; template <class Epi, class Sched>
; __device__ __forceinline__ void gemm_phase(LAS unsigned char* lds, const Sched& S, const Epi& E) {
;     ...
;         for (int t = 0; t < nt; t += 2) {
;             const bool last = (t == nt - 2);
;             const char* a1 = cA + (size_t)(t + 1) * kstep;
;             const char* a2 = last ? nA : cA + (size_t)(t + 2) * kstep; const char* b2 = last ? nB : cB + (size_t)(t + 2) * kstep;
;             const char* a3 = a2 + kstep; const char* b3 = b2 + kstep;
;             const unsigned vA2 = voffA, vB2 = voffB, hA2 = hA, hB2 = hB;
;             PG8_LDB(B0, 0, 0); PG8_LDB(B1, 0, 1); PG8_SCHED; PG8_LDA(At, 0, 0); PG8_STAGE(PG8_SA(1, 1), a1 + hA, voffA, hA / 2);
;             PG8_WAIT_V(8); PG8_WAIT_L(0); PG8_BAR; PG8_MMA(0, 0, At, B0); PG8_MMA(0, 1, At, B1); PG8_BAR; PG8_SCHED;
;             PG8_LDA(At, 0, 1); PG8_STAGE(PG8_SB(0, 0), b2, vB2, hB2 / 2); PG8_STAGE(PG8_SB(0, 1), b2 + hB2, vB2, hB2 / 2); PG8_STAGE(PG8_SA(0, 0), a2, vA2, hA2 / 2);
;             PG8_WAIT_V(8); PG8_WAIT_L(0); PG8_BAR; PG8_MMA(1, 0, At, B0); PG8_MMA(1, 1, At, B1); PG8_BAR; PG8_SCHED;
;     ...
; #pragma unroll
;             for (int a = 0; a < 2; ++a)
; #pragma unroll
;                 for (int b = 0; b < 2; ++b)
; #pragma unroll
;                     for (int m = 0; m < 4; ++m)
; #pragma unroll
;                         for (int n = 0; n < 2; ++n) acc[a][b][m][n] = (f32x4){0.f, 0.f, 0.f, 0.f};
.LBB0_1351:
	s_add_u32 s22, s22, 0x40080
	s_addc_u32 s23, s23, 0
	s_add_u32 s59, s24, 0x100
	s_addc_u32 s60, s25, 0
	s_mov_b32 s61, -2
	s_waitcnt vmcnt(3)
	s_waitcnt vmcnt(2)
	s_waitcnt vmcnt(1)
	s_waitcnt vmcnt(0)
	ds_read_b128 v[128:131], v174
	ds_read_b128 v[132:135], v174 offset:1024
	ds_read_b128 v[136:139], v174 offset:2048
	ds_read_b128 v[144:147], v174 offset:3072
	ds_read_b128 v[148:151], v175
	ds_read_b128 v[152:155], v175 offset:1024
	ds_read_b128 v[156:159], v175 offset:2048
	ds_read_b128 v[160:163], v175 offset:3072
	s_add_u32 s24, s22, 0xfffc0080
	s_addc_u32 s25, s23, -1
	s_cmp_eq_u32 s61, 12
	s_cselect_b32 s24, s18, s24
	s_cselect_b32 s25, s19, s25
	s_cselect_b32 s38, s20, s59
	s_cselect_b32 s39, s21, s60
	s_add_u32 s26, s24, 0x80
	s_addc_u32 s27, s25, 0
	ds_read_b128 v[164:167], v177
	ds_read_b128 v[180:183], v177 offset:1024
	ds_read_b128 v[184:187], v177 offset:2048
	ds_read_b128 v[188:191], v177 offset:3072
	ds_read_b128 v[192:195], v177 offset:4096
	ds_read_b128 v[196:199], v177 offset:5120
	ds_read_b128 v[200:203], v177 offset:6144
	ds_read_b128 v[204:207], v177 offset:7168
	s_mov_b32 m0, s54
	s_nop 0
	global_load_lds_dwordx4 v170, s[22:23]
	s_add_u32 s62, s22, 0x20000
	s_mov_b32 m0, s55
	s_addc_u32 s63, s23, 0
	global_load_lds_dwordx4 v170, s[62:63]
	s_waitcnt vmcnt(8) lgkmcnt(0)
	s_barrier
	s_setprio 1
	v_mfma_f32_16x16x32_bf16 v[84:87], v[128:131], v[164:167], 0
	v_mfma_f32_16x16x32_bf16 v[76:79], v[136:139], v[164:167], 0
	v_mfma_f32_16x16x32_bf16 v[124:127], v[128:131], v[184:187], 0
	v_mfma_f32_16x16x32_bf16 v[120:123], v[136:139], v[184:187], 0
	v_mfma_f32_16x16x32_bf16 v[116:119], v[128:131], v[192:195], 0
	v_mfma_f32_16x16x32_bf16 v[112:115], v[136:139], v[192:195], 0
	v_mfma_f32_16x16x32_bf16 v[108:111], v[128:131], v[200:203], 0
	v_mfma_f32_16x16x32_bf16 v[104:107], v[136:139], v[200:203], 0
	v_mfma_f32_16x16x32_bf16 v[84:87], v[132:135], v[180:183], v[84:87]
	v_mfma_f32_16x16x32_bf16 v[76:79], v[144:147], v[180:183], v[76:79]
	v_mfma_f32_16x16x32_bf16 v[124:127], v[132:135], v[188:191], v[124:127]
	v_mfma_f32_16x16x32_bf16 v[120:123], v[144:147], v[188:191], v[120:123]
	v_mfma_f32_16x16x32_bf16 v[116:119], v[132:135], v[196:199], v[116:119]
	v_mfma_f32_16x16x32_bf16 v[112:115], v[144:147], v[196:199], v[112:115]
	v_mfma_f32_16x16x32_bf16 v[108:111], v[132:135], v[204:207], v[108:111]
	v_mfma_f32_16x16x32_bf16 v[104:107], v[144:147], v[204:207], v[104:107]
	v_mfma_f32_16x16x32_bf16 v[60:63], v[148:151], v[164:167], 0
	v_mfma_f32_16x16x32_bf16 v[56:59], v[156:159], v[164:167], 0
	v_mfma_f32_16x16x32_bf16 v[52:55], v[148:151], v[184:187], 0
	v_mfma_f32_16x16x32_bf16 v[48:51], v[156:159], v[184:187], 0
	v_mfma_f32_16x16x32_bf16 v[44:47], v[148:151], v[192:195], 0
	v_mfma_f32_16x16x32_bf16 v[40:43], v[156:159], v[192:195], 0
	v_mfma_f32_16x16x32_bf16 v[36:39], v[148:151], v[200:203], 0
	v_mfma_f32_16x16x32_bf16 v[32:35], v[156:159], v[200:203], 0
	v_mfma_f32_16x16x32_bf16 v[60:63], v[152:155], v[180:183], v[60:63]
	v_mfma_f32_16x16x32_bf16 v[56:59], v[160:163], v[180:183], v[56:59]
	v_mfma_f32_16x16x32_bf16 v[52:55], v[152:155], v[188:191], v[52:55]
	v_mfma_f32_16x16x32_bf16 v[48:51], v[160:163], v[188:191], v[48:51]
	v_mfma_f32_16x16x32_bf16 v[44:47], v[152:155], v[196:199], v[44:47]
	v_mfma_f32_16x16x32_bf16 v[40:43], v[160:163], v[196:199], v[40:43]
	v_mfma_f32_16x16x32_bf16 v[36:39], v[152:155], v[204:207], v[36:39]
	v_mfma_f32_16x16x32_bf16 v[32:35], v[160:163], v[204:207], v[32:35]
	s_add_i32 s61, s61, 2
	s_add_u32 s22, s22, 0x100
	s_addc_u32 s23, s23, 0
	s_add_u32 s59, s59, 0x100
	s_addc_u32 s60, s60, 0
	s_setprio 0
	s_barrier
	s_add_u32 s62, s38, 0x20000
	ds_read_b128 v[164:167], v177 offset:16384
	ds_read_b128 v[180:183], v177 offset:17408
	ds_read_b128 v[184:187], v177 offset:18432
	ds_read_b128 v[188:191], v177 offset:19456
	ds_read_b128 v[192:195], v177 offset:20480
	ds_read_b128 v[196:199], v177 offset:21504
	ds_read_b128 v[200:203], v177 offset:22528
	ds_read_b128 v[204:207], v177 offset:23552
	s_mov_b32 m0, s35
	s_nop 0
	global_load_lds_dwordx4 v171, s[38:39]
	s_mov_b32 m0, s36
	s_addc_u32 s63, s39, 0
	global_load_lds_dwordx4 v171, s[62:63]
	s_add_u32 s62, s38, 0x40000
	s_mov_b32 m0, s37
	s_addc_u32 s63, s39, 0
	global_load_lds_dwordx4 v171, s[62:63]
	s_add_u32 s62, s38, 0x60000
	s_mov_b32 m0, s40
	s_addc_u32 s63, s39, 0
	global_load_lds_dwordx4 v171, s[62:63]
	s_mov_b32 m0, s34
	s_nop 0
	global_load_lds_dwordx4 v170, s[24:25]
	s_add_u32 s62, s24, 0x20000
	s_mov_b32 m0, s41
	s_addc_u32 s63, s25, 0
	global_load_lds_dwordx4 v170, s[62:63]
	s_waitcnt vmcnt(8) lgkmcnt(0)
	s_barrier
	s_setprio 1
	v_mfma_f32_16x16x32_bf16 v[100:103], v[128:131], v[164:167], 0
	v_mfma_f32_16x16x32_bf16 v[96:99], v[136:139], v[164:167], 0
	v_mfma_f32_16x16x32_bf16 v[92:95], v[128:131], v[184:187], 0
	v_mfma_f32_16x16x32_bf16 v[88:91], v[136:139], v[184:187], 0
	v_mfma_f32_16x16x32_bf16 v[80:83], v[128:131], v[192:195], 0
	v_mfma_f32_16x16x32_bf16 v[72:75], v[136:139], v[192:195], 0
	v_mfma_f32_16x16x32_bf16 v[68:71], v[128:131], v[200:203], 0
	v_mfma_f32_16x16x32_bf16 v[64:67], v[136:139], v[200:203], 0
	v_mfma_f32_16x16x32_bf16 v[100:103], v[132:135], v[180:183], v[100:103]
	v_mfma_f32_16x16x32_bf16 v[96:99], v[144:147], v[180:183], v[96:99]
	v_mfma_f32_16x16x32_bf16 v[92:95], v[132:135], v[188:191], v[92:95]
	v_mfma_f32_16x16x32_bf16 v[88:91], v[144:147], v[188:191], v[88:91]
	v_mfma_f32_16x16x32_bf16 v[80:83], v[132:135], v[196:199], v[80:83]
	v_mfma_f32_16x16x32_bf16 v[72:75], v[144:147], v[196:199], v[72:75]
	v_mfma_f32_16x16x32_bf16 v[68:71], v[132:135], v[204:207], v[68:71]
	v_mfma_f32_16x16x32_bf16 v[64:67], v[144:147], v[204:207], v[64:67]
	v_mfma_f32_16x16x32_bf16 v[28:31], v[148:151], v[164:167], 0
	v_mfma_f32_16x16x32_bf16 v[24:27], v[156:159], v[164:167], 0
	v_mfma_f32_16x16x32_bf16 v[20:23], v[148:151], v[184:187], 0
	v_mfma_f32_16x16x32_bf16 v[16:19], v[156:159], v[184:187], 0
	v_mfma_f32_16x16x32_bf16 v[12:15], v[148:151], v[192:195], 0
	v_mfma_f32_16x16x32_bf16 v[8:11], v[156:159], v[192:195], 0
	v_mfma_f32_16x16x32_bf16 v[4:7], v[148:151], v[200:203], 0
	v_mfma_f32_16x16x32_bf16 v[0:3], v[156:159], v[200:203], 0
	v_mfma_f32_16x16x32_bf16 v[28:31], v[152:155], v[180:183], v[28:31]
	v_mfma_f32_16x16x32_bf16 v[24:27], v[160:163], v[180:183], v[24:27]
	v_mfma_f32_16x16x32_bf16 v[20:23], v[152:155], v[188:191], v[20:23]
	v_mfma_f32_16x16x32_bf16 v[16:19], v[160:163], v[188:191], v[16:19]
	v_mfma_f32_16x16x32_bf16 v[12:15], v[152:155], v[196:199], v[12:15]
	v_mfma_f32_16x16x32_bf16 v[8:11], v[160:163], v[196:199], v[8:11]
	v_mfma_f32_16x16x32_bf16 v[4:7], v[152:155], v[204:207], v[4:7]
	v_mfma_f32_16x16x32_bf16 v[0:3], v[160:163], v[204:207], v[0:3]
	s_setprio 0
	s_barrier
	s_branch .Lpeel_mid_40254
; #define PG8_STAGE(bufoff, gbase, voff, p64) do { _Pragma("unroll") for (int _i = 0; _i < 2; ++_i) { \
;         const char* _gb = (const char*)(gbase) + (size_t)_i * (p64); const unsigned _la = ldsbase + (unsigned)(bufoff) + (unsigned)_i * 8192u; \
;         asm volatile("s_mov_b32 m0, %0\n\ts_nop 0\n\tglobal_load_lds_dwordx4 %1, %2" :: "s"(_la), "v"(voff), "s"(_gb) : "memory"); } } while (0)
; #define PG8_LDA(dst, b, h) do { _Pragma("unroll") for (int m = 0; m < 4; ++m) _Pragma("unroll") for (int k = 0; k < 2; ++k) dst[m][k] = *(const LAS bf16x8*)(lds + PG8_SA(b, h) + aoff + m * 2048 + k * 1024); } while (0)
; #define PG8_LDB(dst, b, h) do { _Pragma("unroll") for (int n = 0; n < 2; ++n) _Pragma("unroll") for (int k = 0; k < 2; ++k) dst[n][k] = *(const LAS bf16x8*)(lds + PG8_SB(b, h) + boff + n * 2048 + k * 1024); } while (0)
; #define PG8_MMA(ai, bj, At, Bt) do { __builtin_amdgcn_s_setprio(1); _Pragma("unroll") for (int m = 0; m < 4; ++m) _Pragma("unroll") for (int n = 0; n < 2; ++n) _Pragma("unroll") for (int k = 0; k < 2; ++k) \
;         acc[ai][bj][m][n] = __builtin_amdgcn_mfma_f32_16x16x32_bf16(Bt[n][k], At[m][k], acc[ai][bj][m][n], 0, 0, 0); __builtin_amdgcn_s_setprio(0); } while (0)
; #define PG8_WAIT_V(n) asm volatile("s_waitcnt vmcnt(" #n ")" ::: "memory")
; template <class Epi, class Sched>
; __device__ __forceinline__ void gemm_phase(LAS unsigned char* lds, const Sched& S, const Epi& E) {
;     ...
;         for (int t = 0; t < nt; t += 2) {
;             const bool last = (t == nt - 2);
;             const char* a1 = cA + (size_t)(t + 1) * kstep;
;             const char* a2 = last ? nA : cA + (size_t)(t + 2) * kstep; const char* b2 = last ? nB : cB + (size_t)(t + 2) * kstep;
;             const char* a3 = a2 + kstep; const char* b3 = b2 + kstep;
;             const unsigned vA2 = voffA, vB2 = voffB, hA2 = hA, hB2 = hB;
;             PG8_LDB(B0, 0, 0); PG8_LDB(B1, 0, 1); PG8_SCHED; PG8_LDA(At, 0, 0); PG8_STAGE(PG8_SA(1, 1), a1 + hA, voffA, hA / 2);
;             PG8_WAIT_V(8); PG8_WAIT_L(0); PG8_BAR; PG8_MMA(0, 0, At, B0); PG8_MMA(0, 1, At, B1); PG8_BAR; PG8_SCHED;
;             PG8_LDA(At, 0, 1); PG8_STAGE(PG8_SB(0, 0), b2, vB2, hB2 / 2); PG8_STAGE(PG8_SB(0, 1), b2 + hB2, vB2, hB2 / 2); PG8_STAGE(PG8_SA(0, 0), a2, vA2, hA2 / 2);
;             PG8_WAIT_V(8); PG8_WAIT_L(0); PG8_BAR; PG8_MMA(1, 0, At, B0); PG8_MMA(1, 1, At, B1); PG8_BAR; PG8_SCHED;
.LBB0_1352:
	ds_read_b128 v[128:131], v174
	ds_read_b128 v[132:135], v174 offset:1024
	ds_read_b128 v[136:139], v174 offset:2048
	ds_read_b128 v[144:147], v174 offset:3072
	ds_read_b128 v[148:151], v175
	ds_read_b128 v[152:155], v175 offset:1024
	ds_read_b128 v[156:159], v175 offset:2048
	ds_read_b128 v[160:163], v175 offset:3072
	s_add_u32 s24, s22, 0xfffc0080
	s_addc_u32 s25, s23, -1
	s_cmp_eq_u32 s61, 12
	s_cselect_b32 s24, s18, s24
	s_cselect_b32 s25, s19, s25
	s_cselect_b32 s38, s20, s59
	s_cselect_b32 s39, s21, s60
	s_add_u32 s26, s24, 0x80
	s_addc_u32 s27, s25, 0
	ds_read_b128 v[164:167], v177
	ds_read_b128 v[180:183], v177 offset:1024
	ds_read_b128 v[184:187], v177 offset:2048
	ds_read_b128 v[188:191], v177 offset:3072
	ds_read_b128 v[192:195], v177 offset:4096
	ds_read_b128 v[196:199], v177 offset:5120
	ds_read_b128 v[200:203], v177 offset:6144
	ds_read_b128 v[204:207], v177 offset:7168
	s_mov_b32 m0, s54
	s_nop 0
	global_load_lds_dwordx4 v170, s[22:23]
	s_add_u32 s62, s22, 0x20000
	s_mov_b32 m0, s55
	s_addc_u32 s63, s23, 0
	global_load_lds_dwordx4 v170, s[62:63]
	s_waitcnt vmcnt(8) lgkmcnt(0)
	s_barrier
	s_setprio 1
	v_mfma_f32_16x16x32_bf16 v[84:87], v[128:131], v[164:167], v[84:87]
	v_mfma_f32_16x16x32_bf16 v[76:79], v[136:139], v[164:167], v[76:79]
	v_mfma_f32_16x16x32_bf16 v[124:127], v[128:131], v[184:187], v[124:127]
	v_mfma_f32_16x16x32_bf16 v[120:123], v[136:139], v[184:187], v[120:123]
	v_mfma_f32_16x16x32_bf16 v[116:119], v[128:131], v[192:195], v[116:119]
	v_mfma_f32_16x16x32_bf16 v[112:115], v[136:139], v[192:195], v[112:115]
	v_mfma_f32_16x16x32_bf16 v[108:111], v[128:131], v[200:203], v[108:111]
	v_mfma_f32_16x16x32_bf16 v[104:107], v[136:139], v[200:203], v[104:107]
	v_mfma_f32_16x16x32_bf16 v[84:87], v[132:135], v[180:183], v[84:87]
	v_mfma_f32_16x16x32_bf16 v[76:79], v[144:147], v[180:183], v[76:79]
	v_mfma_f32_16x16x32_bf16 v[124:127], v[132:135], v[188:191], v[124:127]
	v_mfma_f32_16x16x32_bf16 v[120:123], v[144:147], v[188:191], v[120:123]
	v_mfma_f32_16x16x32_bf16 v[116:119], v[132:135], v[196:199], v[116:119]
	v_mfma_f32_16x16x32_bf16 v[112:115], v[144:147], v[196:199], v[112:115]
	v_mfma_f32_16x16x32_bf16 v[108:111], v[132:135], v[204:207], v[108:111]
	v_mfma_f32_16x16x32_bf16 v[104:107], v[144:147], v[204:207], v[104:107]
	v_mfma_f32_16x16x32_bf16 v[60:63], v[148:151], v[164:167], v[60:63]
	v_mfma_f32_16x16x32_bf16 v[56:59], v[156:159], v[164:167], v[56:59]
	v_mfma_f32_16x16x32_bf16 v[52:55], v[148:151], v[184:187], v[52:55]
	v_mfma_f32_16x16x32_bf16 v[48:51], v[156:159], v[184:187], v[48:51]
	v_mfma_f32_16x16x32_bf16 v[44:47], v[148:151], v[192:195], v[44:47]
	v_mfma_f32_16x16x32_bf16 v[40:43], v[156:159], v[192:195], v[40:43]
	v_mfma_f32_16x16x32_bf16 v[36:39], v[148:151], v[200:203], v[36:39]
	v_mfma_f32_16x16x32_bf16 v[32:35], v[156:159], v[200:203], v[32:35]
	v_mfma_f32_16x16x32_bf16 v[60:63], v[152:155], v[180:183], v[60:63]
	v_mfma_f32_16x16x32_bf16 v[56:59], v[160:163], v[180:183], v[56:59]
	v_mfma_f32_16x16x32_bf16 v[52:55], v[152:155], v[188:191], v[52:55]
	v_mfma_f32_16x16x32_bf16 v[48:51], v[160:163], v[188:191], v[48:51]
	v_mfma_f32_16x16x32_bf16 v[44:47], v[152:155], v[196:199], v[44:47]
	v_mfma_f32_16x16x32_bf16 v[40:43], v[160:163], v[196:199], v[40:43]
	v_mfma_f32_16x16x32_bf16 v[36:39], v[152:155], v[204:207], v[36:39]
	v_mfma_f32_16x16x32_bf16 v[32:35], v[160:163], v[204:207], v[32:35]
	s_add_i32 s61, s61, 2
	s_add_u32 s22, s22, 0x100
	s_addc_u32 s23, s23, 0
	s_add_u32 s59, s59, 0x100
	s_addc_u32 s60, s60, 0
	s_setprio 0
	s_barrier
	s_add_u32 s62, s38, 0x20000
	ds_read_b128 v[164:167], v177 offset:16384
	ds_read_b128 v[180:183], v177 offset:17408
	ds_read_b128 v[184:187], v177 offset:18432
	ds_read_b128 v[188:191], v177 offset:19456
	ds_read_b128 v[192:195], v177 offset:20480
	ds_read_b128 v[196:199], v177 offset:21504
	ds_read_b128 v[200:203], v177 offset:22528
	ds_read_b128 v[204:207], v177 offset:23552
	s_mov_b32 m0, s35
	s_nop 0
	global_load_lds_dwordx4 v171, s[38:39]
	s_mov_b32 m0, s36
	s_addc_u32 s63, s39, 0
	global_load_lds_dwordx4 v171, s[62:63]
	s_add_u32 s62, s38, 0x40000
	s_mov_b32 m0, s37
	s_addc_u32 s63, s39, 0
	global_load_lds_dwordx4 v171, s[62:63]
	s_add_u32 s62, s38, 0x60000
	s_mov_b32 m0, s40
	s_addc_u32 s63, s39, 0
	global_load_lds_dwordx4 v171, s[62:63]
	s_mov_b32 m0, s34
	s_nop 0
	global_load_lds_dwordx4 v170, s[24:25]
	s_add_u32 s62, s24, 0x20000
	s_mov_b32 m0, s41
	s_addc_u32 s63, s25, 0
	global_load_lds_dwordx4 v170, s[62:63]
	s_waitcnt vmcnt(8) lgkmcnt(0)
	s_barrier
	s_setprio 1
	v_mfma_f32_16x16x32_bf16 v[100:103], v[128:131], v[164:167], v[100:103]
	v_mfma_f32_16x16x32_bf16 v[96:99], v[136:139], v[164:167], v[96:99]
	v_mfma_f32_16x16x32_bf16 v[92:95], v[128:131], v[184:187], v[92:95]
	v_mfma_f32_16x16x32_bf16 v[88:91], v[136:139], v[184:187], v[88:91]
	v_mfma_f32_16x16x32_bf16 v[80:83], v[128:131], v[192:195], v[80:83]
	v_mfma_f32_16x16x32_bf16 v[72:75], v[136:139], v[192:195], v[72:75]
	v_mfma_f32_16x16x32_bf16 v[68:71], v[128:131], v[200:203], v[68:71]
	v_mfma_f32_16x16x32_bf16 v[64:67], v[136:139], v[200:203], v[64:67]
	v_mfma_f32_16x16x32_bf16 v[100:103], v[132:135], v[180:183], v[100:103]
	v_mfma_f32_16x16x32_bf16 v[96:99], v[144:147], v[180:183], v[96:99]
	v_mfma_f32_16x16x32_bf16 v[92:95], v[132:135], v[188:191], v[92:95]
	v_mfma_f32_16x16x32_bf16 v[88:91], v[144:147], v[188:191], v[88:91]
	v_mfma_f32_16x16x32_bf16 v[80:83], v[132:135], v[196:199], v[80:83]
	v_mfma_f32_16x16x32_bf16 v[72:75], v[144:147], v[196:199], v[72:75]
	v_mfma_f32_16x16x32_bf16 v[68:71], v[132:135], v[204:207], v[68:71]
	v_mfma_f32_16x16x32_bf16 v[64:67], v[144:147], v[204:207], v[64:67]
	v_mfma_f32_16x16x32_bf16 v[28:31], v[148:151], v[164:167], v[28:31]
	v_mfma_f32_16x16x32_bf16 v[24:27], v[156:159], v[164:167], v[24:27]
	v_mfma_f32_16x16x32_bf16 v[20:23], v[148:151], v[184:187], v[20:23]
	v_mfma_f32_16x16x32_bf16 v[16:19], v[156:159], v[184:187], v[16:19]
	v_mfma_f32_16x16x32_bf16 v[12:15], v[148:151], v[192:195], v[12:15]
	v_mfma_f32_16x16x32_bf16 v[8:11], v[156:159], v[192:195], v[8:11]
	v_mfma_f32_16x16x32_bf16 v[4:7], v[148:151], v[200:203], v[4:7]
	v_mfma_f32_16x16x32_bf16 v[0:3], v[156:159], v[200:203], v[0:3]
	v_mfma_f32_16x16x32_bf16 v[28:31], v[152:155], v[180:183], v[28:31]
	v_mfma_f32_16x16x32_bf16 v[24:27], v[160:163], v[180:183], v[24:27]
	v_mfma_f32_16x16x32_bf16 v[20:23], v[152:155], v[188:191], v[20:23]
	v_mfma_f32_16x16x32_bf16 v[16:19], v[160:163], v[188:191], v[16:19]
	v_mfma_f32_16x16x32_bf16 v[12:15], v[152:155], v[196:199], v[12:15]
	v_mfma_f32_16x16x32_bf16 v[8:11], v[160:163], v[196:199], v[8:11]
	v_mfma_f32_16x16x32_bf16 v[4:7], v[152:155], v[204:207], v[4:7]
	v_mfma_f32_16x16x32_bf16 v[0:3], v[160:163], v[204:207], v[0:3]
	s_setprio 0
	s_barrier
; #define PG8_STAGE(bufoff, gbase, voff, p64) do { _Pragma("unroll") for (int _i = 0; _i < 2; ++_i) { \
;         const char* _gb = (const char*)(gbase) + (size_t)_i * (p64); const unsigned _la = ldsbase + (unsigned)(bufoff) + (unsigned)_i * 8192u; \
;         asm volatile("s_mov_b32 m0, %0\n\ts_nop 0\n\tglobal_load_lds_dwordx4 %1, %2" :: "s"(_la), "v"(voff), "s"(_gb) : "memory"); } } while (0)
; #define PG8_LDA(dst, b, h) do { _Pragma("unroll") for (int m = 0; m < 4; ++m) _Pragma("unroll") for (int k = 0; k < 2; ++k) dst[m][k] = *(const LAS bf16x8*)(lds + PG8_SA(b, h) + aoff + m * 2048 + k * 1024); } while (0)
; #define PG8_LDB(dst, b, h) do { _Pragma("unroll") for (int n = 0; n < 2; ++n) _Pragma("unroll") for (int k = 0; k < 2; ++k) dst[n][k] = *(const LAS bf16x8*)(lds + PG8_SB(b, h) + boff + n * 2048 + k * 1024); } while (0)
; #define PG8_MMA(ai, bj, At, Bt) do { __builtin_amdgcn_s_setprio(1); _Pragma("unroll") for (int m = 0; m < 4; ++m) _Pragma("unroll") for (int n = 0; n < 2; ++n) _Pragma("unroll") for (int k = 0; k < 2; ++k) \
;         acc[ai][bj][m][n] = __builtin_amdgcn_mfma_f32_16x16x32_bf16(Bt[n][k], At[m][k], acc[ai][bj][m][n], 0, 0, 0); __builtin_amdgcn_s_setprio(0); } while (0)
; #define PG8_WAIT_V(n) asm volatile("s_waitcnt vmcnt(" #n ")" ::: "memory")
; #define PG8_WAIT_L(n) asm volatile("s_waitcnt lgkmcnt(" #n ")" ::: "memory")
; #define PG8_BAR __builtin_amdgcn_s_barrier()
; #define PG8_SCHED __builtin_amdgcn_sched_barrier(0)
; template <class Epi, class Sched>
; __device__ __forceinline__ void gemm_phase(LAS unsigned char* lds, const Sched& S, const Epi& E) {
;     ...
;             PG8_LDB(B0, 1, 0); PG8_LDB(B1, 1, 1); PG8_SCHED; PG8_LDA(At, 1, 0); PG8_STAGE(PG8_SA(0, 1), a2 + hA2, vA2, hA2 / 2);
;             PG8_WAIT_V(8); PG8_WAIT_L(0); PG8_BAR; PG8_MMA(0, 0, At, B0); PG8_MMA(0, 1, At, B1); PG8_BAR; PG8_SCHED;
;             PG8_LDA(At, 1, 1); PG8_STAGE(PG8_SB(1, 0), b3, vB2, hB2 / 2); PG8_STAGE(PG8_SB(1, 1), b3 + hB2, vB2, hB2 / 2); PG8_STAGE(PG8_SA(1, 0), a3, vA2, hA2 / 2);
;             PG8_WAIT_V(8); PG8_WAIT_L(0); PG8_BAR; PG8_MMA(1, 0, At, B0); PG8_MMA(1, 1, At, B1); PG8_BAR; PG8_SCHED;
;         }
;         if (wr == 0) PG8_BAR;
.Lpeel_mid_40254:
	ds_read_b128 v[128:131], v178
	ds_read_b128 v[132:135], v178 offset:1024
	ds_read_b128 v[136:139], v178 offset:2048
	ds_read_b128 v[144:147], v178 offset:3072
	ds_read_b128 v[148:151], v179
	ds_read_b128 v[152:155], v179 offset:1024
	ds_read_b128 v[156:159], v179 offset:2048
	ds_read_b128 v[160:163], v179 offset:3072
	ds_read_b128 v[164:167], v177 offset:32768
	ds_read_b128 v[180:183], v177 offset:33792
	ds_read_b128 v[184:187], v177 offset:34816
	ds_read_b128 v[188:191], v177 offset:35840
	ds_read_b128 v[192:195], v177 offset:36864
	ds_read_b128 v[196:199], v177 offset:37888
	ds_read_b128 v[200:203], v177 offset:38912
	ds_read_b128 v[204:207], v177 offset:39936
	s_add_u32 s62, s24, 0x40000
	s_mov_b32 m0, s42
	s_addc_u32 s63, s25, 0
	global_load_lds_dwordx4 v170, s[62:63]
	s_add_u32 s62, s24, 0x60000
	s_mov_b32 m0, s43
	s_addc_u32 s63, s25, 0
	global_load_lds_dwordx4 v170, s[62:63]
	s_waitcnt vmcnt(8) lgkmcnt(0)
	s_barrier
	s_setprio 1
	v_mfma_f32_16x16x32_bf16 v[84:87], v[128:131], v[164:167], v[84:87]
	v_mfma_f32_16x16x32_bf16 v[76:79], v[136:139], v[164:167], v[76:79]
	v_mfma_f32_16x16x32_bf16 v[124:127], v[128:131], v[184:187], v[124:127]
	v_mfma_f32_16x16x32_bf16 v[120:123], v[136:139], v[184:187], v[120:123]
	v_mfma_f32_16x16x32_bf16 v[116:119], v[128:131], v[192:195], v[116:119]
	v_mfma_f32_16x16x32_bf16 v[112:115], v[136:139], v[192:195], v[112:115]
	v_mfma_f32_16x16x32_bf16 v[108:111], v[128:131], v[200:203], v[108:111]
	v_mfma_f32_16x16x32_bf16 v[104:107], v[136:139], v[200:203], v[104:107]
	v_mfma_f32_16x16x32_bf16 v[84:87], v[132:135], v[180:183], v[84:87]
	v_mfma_f32_16x16x32_bf16 v[76:79], v[144:147], v[180:183], v[76:79]
	v_mfma_f32_16x16x32_bf16 v[124:127], v[132:135], v[188:191], v[124:127]
	v_mfma_f32_16x16x32_bf16 v[120:123], v[144:147], v[188:191], v[120:123]
	v_mfma_f32_16x16x32_bf16 v[116:119], v[132:135], v[196:199], v[116:119]
	v_mfma_f32_16x16x32_bf16 v[112:115], v[144:147], v[196:199], v[112:115]
	v_mfma_f32_16x16x32_bf16 v[108:111], v[132:135], v[204:207], v[108:111]
	v_mfma_f32_16x16x32_bf16 v[104:107], v[144:147], v[204:207], v[104:107]
	v_mfma_f32_16x16x32_bf16 v[60:63], v[148:151], v[164:167], v[60:63]
	v_mfma_f32_16x16x32_bf16 v[56:59], v[156:159], v[164:167], v[56:59]
	v_mfma_f32_16x16x32_bf16 v[52:55], v[148:151], v[184:187], v[52:55]
	v_mfma_f32_16x16x32_bf16 v[48:51], v[156:159], v[184:187], v[48:51]
	v_mfma_f32_16x16x32_bf16 v[44:47], v[148:151], v[192:195], v[44:47]
	v_mfma_f32_16x16x32_bf16 v[40:43], v[156:159], v[192:195], v[40:43]
	v_mfma_f32_16x16x32_bf16 v[36:39], v[148:151], v[200:203], v[36:39]
	v_mfma_f32_16x16x32_bf16 v[32:35], v[156:159], v[200:203], v[32:35]
	v_mfma_f32_16x16x32_bf16 v[60:63], v[152:155], v[180:183], v[60:63]
	v_mfma_f32_16x16x32_bf16 v[56:59], v[160:163], v[180:183], v[56:59]
	v_mfma_f32_16x16x32_bf16 v[52:55], v[152:155], v[188:191], v[52:55]
	v_mfma_f32_16x16x32_bf16 v[48:51], v[160:163], v[188:191], v[48:51]
	v_mfma_f32_16x16x32_bf16 v[44:47], v[152:155], v[196:199], v[44:47]
	v_mfma_f32_16x16x32_bf16 v[40:43], v[160:163], v[196:199], v[40:43]
	v_mfma_f32_16x16x32_bf16 v[36:39], v[152:155], v[204:207], v[36:39]
	v_mfma_f32_16x16x32_bf16 v[32:35], v[160:163], v[204:207], v[32:35]
	s_setprio 0
	s_barrier
	s_add_u32 s62, s38, 0x80
	s_addc_u32 s63, s39, 0
	ds_read_b128 v[164:167], v177 offset:49152
	ds_read_b128 v[180:183], v177 offset:50176
	ds_read_b128 v[184:187], v177 offset:51200
	ds_read_b128 v[188:191], v177 offset:52224
	ds_read_b128 v[192:195], v177 offset:53248
	ds_read_b128 v[196:199], v177 offset:54272
	ds_read_b128 v[200:203], v177 offset:55296
	ds_read_b128 v[204:207], v177 offset:56320
	s_mov_b32 m0, s48
	s_nop 0
	global_load_lds_dwordx4 v171, s[62:63]
	s_add_u32 s62, s38, 0x20080
	s_mov_b32 m0, s49
	s_addc_u32 s63, s39, 0
	global_load_lds_dwordx4 v171, s[62:63]
	s_add_u32 s62, s38, 0x40080
	s_mov_b32 m0, s52
	s_addc_u32 s63, s39, 0
	global_load_lds_dwordx4 v171, s[62:63]
	s_add_u32 s38, s38, 0x60080
	s_mov_b32 m0, s53
	s_addc_u32 s39, s39, 0
	global_load_lds_dwordx4 v171, s[38:39]
	s_mov_b32 m0, s50
	s_nop 0
	global_load_lds_dwordx4 v170, s[26:27]
	s_add_u32 s24, s24, 0x20080
	s_mov_b32 m0, s51
	s_addc_u32 s25, s25, 0
	global_load_lds_dwordx4 v170, s[24:25]
	s_waitcnt vmcnt(8) lgkmcnt(0)
	s_barrier
	s_setprio 1
	v_mfma_f32_16x16x32_bf16 v[100:103], v[128:131], v[164:167], v[100:103]
	v_mfma_f32_16x16x32_bf16 v[96:99], v[136:139], v[164:167], v[96:99]
	v_mfma_f32_16x16x32_bf16 v[92:95], v[128:131], v[184:187], v[92:95]
	v_mfma_f32_16x16x32_bf16 v[88:91], v[136:139], v[184:187], v[88:91]
	v_mfma_f32_16x16x32_bf16 v[80:83], v[128:131], v[192:195], v[80:83]
	v_mfma_f32_16x16x32_bf16 v[72:75], v[136:139], v[192:195], v[72:75]
	v_mfma_f32_16x16x32_bf16 v[68:71], v[128:131], v[200:203], v[68:71]
	v_mfma_f32_16x16x32_bf16 v[64:67], v[136:139], v[200:203], v[64:67]
	v_mfma_f32_16x16x32_bf16 v[100:103], v[132:135], v[180:183], v[100:103]
	v_mfma_f32_16x16x32_bf16 v[96:99], v[144:147], v[180:183], v[96:99]
	v_mfma_f32_16x16x32_bf16 v[92:95], v[132:135], v[188:191], v[92:95]
	v_mfma_f32_16x16x32_bf16 v[88:91], v[144:147], v[188:191], v[88:91]
	v_mfma_f32_16x16x32_bf16 v[80:83], v[132:135], v[196:199], v[80:83]
	v_mfma_f32_16x16x32_bf16 v[72:75], v[144:147], v[196:199], v[72:75]
	v_mfma_f32_16x16x32_bf16 v[68:71], v[132:135], v[204:207], v[68:71]
	v_mfma_f32_16x16x32_bf16 v[64:67], v[144:147], v[204:207], v[64:67]
	v_mfma_f32_16x16x32_bf16 v[28:31], v[148:151], v[164:167], v[28:31]
	v_mfma_f32_16x16x32_bf16 v[24:27], v[156:159], v[164:167], v[24:27]
	v_mfma_f32_16x16x32_bf16 v[20:23], v[148:151], v[184:187], v[20:23]
	v_mfma_f32_16x16x32_bf16 v[16:19], v[156:159], v[184:187], v[16:19]
	v_mfma_f32_16x16x32_bf16 v[12:15], v[148:151], v[192:195], v[12:15]
	v_mfma_f32_16x16x32_bf16 v[8:11], v[156:159], v[192:195], v[8:11]
	v_mfma_f32_16x16x32_bf16 v[4:7], v[148:151], v[200:203], v[4:7]
	v_mfma_f32_16x16x32_bf16 v[0:3], v[156:159], v[200:203], v[0:3]
	v_mfma_f32_16x16x32_bf16 v[28:31], v[152:155], v[180:183], v[28:31]
	v_mfma_f32_16x16x32_bf16 v[24:27], v[160:163], v[180:183], v[24:27]
	v_mfma_f32_16x16x32_bf16 v[20:23], v[152:155], v[188:191], v[20:23]
	v_mfma_f32_16x16x32_bf16 v[16:19], v[160:163], v[188:191], v[16:19]
	v_mfma_f32_16x16x32_bf16 v[12:15], v[152:155], v[196:199], v[12:15]
	v_mfma_f32_16x16x32_bf16 v[8:11], v[160:163], v[196:199], v[8:11]
	v_mfma_f32_16x16x32_bf16 v[4:7], v[152:155], v[204:207], v[4:7]
	v_mfma_f32_16x16x32_bf16 v[0:3], v[160:163], v[204:207], v[0:3]
	s_setprio 0
	s_barrier
	s_cmp_gt_u32 s61, 13
	s_cbranch_scc0 .LBB0_1352
	s_and_b64 vcc, exec, s[12:13]
	s_cbranch_vccz .LBB0_1355
	s_barrier

; #define PG8_STAGE(bufoff, gbase, voff, p64) do { _Pragma("unroll") for (int _i = 0; _i < 2; ++_i) { \
;         const char* _gb = (const char*)(gbase) + (size_t)_i * (p64); const unsigned _la = ldsbase + (unsigned)(bufoff) + (unsigned)_i * 8192u; \
;         asm volatile("s_mov_b32 m0, %0\n\ts_nop 0\n\tglobal_load_lds_dwordx4 %1, %2" :: "s"(_la), "v"(voff), "s"(_gb) : "memory"); } } while (0)
; #define PG8_LDA(dst, b, h) do { _Pragma("unroll") for (int m = 0; m < 4; ++m) _Pragma("unroll") for (int k = 0; k < 2; ++k) dst[m][k] = *(const LAS bf16x8*)(lds + PG8_SA(b, h) + aoff + m * 2048 + k * 1024); } while (0)
; #define PG8_LDB(dst, b, h) do { _Pragma("unroll") for (int n = 0; n < 2; ++n) _Pragma("unroll") for (int k = 0; k < 2; ++k) dst[n][k] = *(const LAS bf16x8*)(lds + PG8_SB(b, h) + boff + n * 2048 + k * 1024); } while (0)
; #define PG8_WAIT_V(n) asm volatile("s_waitcnt vmcnt(" #n ")" ::: "memory")
; #define PG8_BAR __builtin_amdgcn_s_barrier()
; template <class Epi, class Sched>
; __device__ __forceinline__ void gemm_phase(LAS unsigned char* lds, const Sched& S, const Epi& E) {
;     ...
;         for (int t = 0; t < nt; t += 2) {
;             const bool last = (t == nt - 2);
;             const char* a1 = cA + (size_t)(t + 1) * kstep;
;             const char* a2 = last ? nA : cA + (size_t)(t + 2) * kstep; const char* b2 = last ? nB : cB + (size_t)(t + 2) * kstep;
;             const char* a3 = a2 + kstep; const char* b3 = b2 + kstep;
;             const unsigned vA2 = voffA, vB2 = voffB, hA2 = hA, hB2 = hB;
;             PG8_LDB(B0, 0, 0); PG8_LDB(B1, 0, 1); PG8_SCHED; PG8_LDA(At, 0, 0); PG8_STAGE(PG8_SA(1, 1), a1 + hA, voffA, hA / 2);
;             PG8_WAIT_V(8); PG8_WAIT_L(0); PG8_BAR; PG8_MMA(0, 0, At, B0); PG8_MMA(0, 1, At, B1); PG8_BAR; PG8_SCHED;
;             PG8_LDA(At, 0, 1); PG8_STAGE(PG8_SB(0, 0), b2, vB2, hB2 / 2); PG8_STAGE(PG8_SB(0, 1), b2 + hB2, vB2, hB2 / 2); PG8_STAGE(PG8_SA(0, 0), a2, vA2, hA2 / 2);
;             PG8_WAIT_V(8); PG8_WAIT_L(0); PG8_BAR; PG8_MMA(1, 0, At, B0); PG8_MMA(1, 1, At, B1); PG8_BAR; PG8_SCHED;
;     ...
; #pragma unroll
;             for (int a = 0; a < 2; ++a)
; #pragma unroll
;                 for (int b = 0; b < 2; ++b)
; #pragma unroll
;                     for (int m = 0; m < 4; ++m)
; #pragma unroll
;                         for (int n = 0; n < 2; ++n) acc[a][b][m][n] = (f32x4){0.f, 0.f, 0.f, 0.f};
.LBB0_1484:
	s_add_u32 s24, s24, 0x40080
	s_addc_u32 s25, s25, 0
	s_add_u32 s59, s26, 0x100
	s_addc_u32 s60, s27, 0
	s_mov_b32 s61, -2
	ds_read_b128 v[144:147], v138
	ds_read_b128 v[148:151], v138 offset:1024
	ds_read_b128 v[152:155], v138 offset:2048
	ds_read_b128 v[156:159], v138 offset:3072
	ds_read_b128 v[160:163], v139
	ds_read_b128 v[164:167], v139 offset:1024
	ds_read_b128 v[168:171], v139 offset:2048
	ds_read_b128 v[172:175], v139 offset:3072
	s_add_u32 s26, s24, 0xfffc0080
	s_addc_u32 s27, s25, -1
	s_cmp_eq_u32 s61, 12
	s_cselect_b32 s26, s20, s26
	s_cselect_b32 s27, s21, s27
	s_cselect_b32 s40, s22, s59
	s_cselect_b32 s41, s23, s60
	s_add_u32 s38, s26, 0x80
	s_addc_u32 s39, s27, 0
	ds_read_b128 v[178:181], v140
	ds_read_b128 v[182:185], v140 offset:1024
	ds_read_b128 v[186:189], v140 offset:2048
	ds_read_b128 v[190:193], v140 offset:3072
	ds_read_b128 v[194:197], v140 offset:4096
	ds_read_b128 v[198:201], v140 offset:5120
	ds_read_b128 v[202:205], v140 offset:6144
	ds_read_b128 v[206:209], v140 offset:7168
	s_mov_b32 m0, s54
	s_nop 0
	global_load_lds_dwordx4 v134, s[24:25]
	s_add_u32 s62, s24, 0x20000
	s_mov_b32 m0, s55
	s_addc_u32 s63, s25, 0
	global_load_lds_dwordx4 v134, s[62:63]
	s_waitcnt vmcnt(8) lgkmcnt(0)
	s_barrier
	s_setprio 1
	v_mfma_f32_16x16x32_bf16 v[124:127], v[144:147], v[178:181], 0
	v_mfma_f32_16x16x32_bf16 v[120:123], v[152:155], v[178:181], 0
	v_mfma_f32_16x16x32_bf16 v[108:111], v[144:147], v[186:189], 0
	v_mfma_f32_16x16x32_bf16 v[104:107], v[152:155], v[186:189], 0
	v_mfma_f32_16x16x32_bf16 v[92:95], v[144:147], v[194:197], 0
	v_mfma_f32_16x16x32_bf16 v[88:91], v[152:155], v[194:197], 0
	v_mfma_f32_16x16x32_bf16 v[76:79], v[144:147], v[202:205], 0
	v_mfma_f32_16x16x32_bf16 v[72:75], v[152:155], v[202:205], 0
	v_mfma_f32_16x16x32_bf16 v[124:127], v[148:151], v[182:185], v[124:127]
	v_mfma_f32_16x16x32_bf16 v[120:123], v[156:159], v[182:185], v[120:123]
	v_mfma_f32_16x16x32_bf16 v[108:111], v[148:151], v[190:193], v[108:111]
	v_mfma_f32_16x16x32_bf16 v[104:107], v[156:159], v[190:193], v[104:107]
	v_mfma_f32_16x16x32_bf16 v[92:95], v[148:151], v[198:201], v[92:95]
	v_mfma_f32_16x16x32_bf16 v[88:91], v[156:159], v[198:201], v[88:91]
	v_mfma_f32_16x16x32_bf16 v[76:79], v[148:151], v[206:209], v[76:79]
	v_mfma_f32_16x16x32_bf16 v[72:75], v[156:159], v[206:209], v[72:75]
	v_mfma_f32_16x16x32_bf16 v[116:119], v[160:163], v[178:181], 0
	v_mfma_f32_16x16x32_bf16 v[112:115], v[168:171], v[178:181], 0
	v_mfma_f32_16x16x32_bf16 v[100:103], v[160:163], v[186:189], 0
	v_mfma_f32_16x16x32_bf16 v[96:99], v[168:171], v[186:189], 0
	v_mfma_f32_16x16x32_bf16 v[84:87], v[160:163], v[194:197], 0
	v_mfma_f32_16x16x32_bf16 v[80:83], v[168:171], v[194:197], 0
	v_mfma_f32_16x16x32_bf16 v[68:71], v[160:163], v[202:205], 0
	v_mfma_f32_16x16x32_bf16 v[64:67], v[168:171], v[202:205], 0
	v_mfma_f32_16x16x32_bf16 v[116:119], v[164:167], v[182:185], v[116:119]
	v_mfma_f32_16x16x32_bf16 v[112:115], v[172:175], v[182:185], v[112:115]
	v_mfma_f32_16x16x32_bf16 v[100:103], v[164:167], v[190:193], v[100:103]
	v_mfma_f32_16x16x32_bf16 v[96:99], v[172:175], v[190:193], v[96:99]
	v_mfma_f32_16x16x32_bf16 v[84:87], v[164:167], v[198:201], v[84:87]
	v_mfma_f32_16x16x32_bf16 v[80:83], v[172:175], v[198:201], v[80:83]
	v_mfma_f32_16x16x32_bf16 v[68:71], v[164:167], v[206:209], v[68:71]
	v_mfma_f32_16x16x32_bf16 v[64:67], v[172:175], v[206:209], v[64:67]
	s_add_i32 s61, s61, 2
	s_add_u32 s24, s24, 0x100
	s_addc_u32 s25, s25, 0
	s_add_u32 s59, s59, 0x100
	s_addc_u32 s60, s60, 0
	s_setprio 0
	s_barrier
	s_add_u32 s62, s40, 0x20000
	ds_read_b128 v[178:181], v140 offset:16384
	ds_read_b128 v[182:185], v140 offset:17408
	ds_read_b128 v[186:189], v140 offset:18432
	ds_read_b128 v[190:193], v140 offset:19456
	ds_read_b128 v[194:197], v140 offset:20480
	ds_read_b128 v[198:201], v140 offset:21504
	ds_read_b128 v[202:205], v140 offset:22528
	ds_read_b128 v[206:209], v140 offset:23552
	s_mov_b32 m0, s36
	s_nop 0
	global_load_lds_dwordx4 v135, s[40:41]
	s_mov_b32 m0, s37
	s_addc_u32 s63, s41, 0
	global_load_lds_dwordx4 v135, s[62:63]
	s_add_u32 s62, s40, 0x40000
	s_mov_b32 m0, s42
	s_addc_u32 s63, s41, 0
	global_load_lds_dwordx4 v135, s[62:63]
	s_add_u32 s62, s40, 0x60000
	s_mov_b32 m0, s43
	s_addc_u32 s63, s41, 0
	global_load_lds_dwordx4 v135, s[62:63]
	s_mov_b32 m0, s34
	s_nop 0
	global_load_lds_dwordx4 v134, s[26:27]
	s_add_u32 s62, s26, 0x20000
	s_mov_b32 m0, s44
	s_addc_u32 s63, s27, 0
	global_load_lds_dwordx4 v134, s[62:63]
	s_waitcnt vmcnt(8) lgkmcnt(0)
	s_barrier
	s_setprio 1
	v_mfma_f32_16x16x32_bf16 v[60:63], v[144:147], v[178:181], 0
	v_mfma_f32_16x16x32_bf16 v[56:59], v[152:155], v[178:181], 0
	v_mfma_f32_16x16x32_bf16 v[44:47], v[144:147], v[186:189], 0
	v_mfma_f32_16x16x32_bf16 v[40:43], v[152:155], v[186:189], 0
	v_mfma_f32_16x16x32_bf16 v[28:31], v[144:147], v[194:197], 0
	v_mfma_f32_16x16x32_bf16 v[24:27], v[152:155], v[194:197], 0
	v_mfma_f32_16x16x32_bf16 v[12:15], v[144:147], v[202:205], 0
	v_mfma_f32_16x16x32_bf16 v[8:11], v[152:155], v[202:205], 0
	v_mfma_f32_16x16x32_bf16 v[60:63], v[148:151], v[182:185], v[60:63]
	v_mfma_f32_16x16x32_bf16 v[56:59], v[156:159], v[182:185], v[56:59]
	v_mfma_f32_16x16x32_bf16 v[44:47], v[148:151], v[190:193], v[44:47]
	v_mfma_f32_16x16x32_bf16 v[40:43], v[156:159], v[190:193], v[40:43]
	v_mfma_f32_16x16x32_bf16 v[28:31], v[148:151], v[198:201], v[28:31]
	v_mfma_f32_16x16x32_bf16 v[24:27], v[156:159], v[198:201], v[24:27]
	v_mfma_f32_16x16x32_bf16 v[12:15], v[148:151], v[206:209], v[12:15]
	v_mfma_f32_16x16x32_bf16 v[8:11], v[156:159], v[206:209], v[8:11]
	v_mfma_f32_16x16x32_bf16 v[52:55], v[160:163], v[178:181], 0
	v_mfma_f32_16x16x32_bf16 v[48:51], v[168:171], v[178:181], 0
	v_mfma_f32_16x16x32_bf16 v[36:39], v[160:163], v[186:189], 0
	v_mfma_f32_16x16x32_bf16 v[32:35], v[168:171], v[186:189], 0
	v_mfma_f32_16x16x32_bf16 v[20:23], v[160:163], v[194:197], 0
	v_mfma_f32_16x16x32_bf16 v[16:19], v[168:171], v[194:197], 0
	v_mfma_f32_16x16x32_bf16 v[4:7], v[160:163], v[202:205], 0
	v_mfma_f32_16x16x32_bf16 v[0:3], v[168:171], v[202:205], 0
	v_mfma_f32_16x16x32_bf16 v[52:55], v[164:167], v[182:185], v[52:55]
	v_mfma_f32_16x16x32_bf16 v[48:51], v[172:175], v[182:185], v[48:51]
	v_mfma_f32_16x16x32_bf16 v[36:39], v[164:167], v[190:193], v[36:39]
	v_mfma_f32_16x16x32_bf16 v[32:35], v[172:175], v[190:193], v[32:35]
	v_mfma_f32_16x16x32_bf16 v[20:23], v[164:167], v[198:201], v[20:23]
	v_mfma_f32_16x16x32_bf16 v[16:19], v[172:175], v[198:201], v[16:19]
	v_mfma_f32_16x16x32_bf16 v[4:7], v[164:167], v[206:209], v[4:7]
	v_mfma_f32_16x16x32_bf16 v[0:3], v[172:175], v[206:209], v[0:3]
	s_setprio 0
	s_barrier
	s_branch .Lpeel_mid_43312
; #define PG8_STAGE(bufoff, gbase, voff, p64) do { _Pragma("unroll") for (int _i = 0; _i < 2; ++_i) { \
;         const char* _gb = (const char*)(gbase) + (size_t)_i * (p64); const unsigned _la = ldsbase + (unsigned)(bufoff) + (unsigned)_i * 8192u; \
;         asm volatile("s_mov_b32 m0, %0\n\ts_nop 0\n\tglobal_load_lds_dwordx4 %1, %2" :: "s"(_la), "v"(voff), "s"(_gb) : "memory"); } } while (0)
; #define PG8_LDA(dst, b, h) do { _Pragma("unroll") for (int m = 0; m < 4; ++m) _Pragma("unroll") for (int k = 0; k < 2; ++k) dst[m][k] = *(const LAS bf16x8*)(lds + PG8_SA(b, h) + aoff + m * 2048 + k * 1024); } while (0)
; #define PG8_LDB(dst, b, h) do { _Pragma("unroll") for (int n = 0; n < 2; ++n) _Pragma("unroll") for (int k = 0; k < 2; ++k) dst[n][k] = *(const LAS bf16x8*)(lds + PG8_SB(b, h) + boff + n * 2048 + k * 1024); } while (0)
; #define PG8_MMA(ai, bj, At, Bt) do { __builtin_amdgcn_s_setprio(1); _Pragma("unroll") for (int m = 0; m < 4; ++m) _Pragma("unroll") for (int n = 0; n < 2; ++n) _Pragma("unroll") for (int k = 0; k < 2; ++k) \
;         acc[ai][bj][m][n] = __builtin_amdgcn_mfma_f32_16x16x32_bf16(Bt[n][k], At[m][k], acc[ai][bj][m][n], 0, 0, 0); __builtin_amdgcn_s_setprio(0); } while (0)
; #define PG8_WAIT_V(n) asm volatile("s_waitcnt vmcnt(" #n ")" ::: "memory")
; template <class Epi, class Sched>
; __device__ __forceinline__ void gemm_phase(LAS unsigned char* lds, const Sched& S, const Epi& E) {
;     ...
;         for (int t = 0; t < nt; t += 2) {
;             const bool last = (t == nt - 2);
;             const char* a1 = cA + (size_t)(t + 1) * kstep;
;             const char* a2 = last ? nA : cA + (size_t)(t + 2) * kstep; const char* b2 = last ? nB : cB + (size_t)(t + 2) * kstep;
;             const char* a3 = a2 + kstep; const char* b3 = b2 + kstep;
;             const unsigned vA2 = voffA, vB2 = voffB, hA2 = hA, hB2 = hB;
;             PG8_LDB(B0, 0, 0); PG8_LDB(B1, 0, 1); PG8_SCHED; PG8_LDA(At, 0, 0); PG8_STAGE(PG8_SA(1, 1), a1 + hA, voffA, hA / 2);
;             PG8_WAIT_V(8); PG8_WAIT_L(0); PG8_BAR; PG8_MMA(0, 0, At, B0); PG8_MMA(0, 1, At, B1); PG8_BAR; PG8_SCHED;
;             PG8_LDA(At, 0, 1); PG8_STAGE(PG8_SB(0, 0), b2, vB2, hB2 / 2); PG8_STAGE(PG8_SB(0, 1), b2 + hB2, vB2, hB2 / 2); PG8_STAGE(PG8_SA(0, 0), a2, vA2, hA2 / 2);
;             PG8_WAIT_V(8); PG8_WAIT_L(0); PG8_BAR; PG8_MMA(1, 0, At, B0); PG8_MMA(1, 1, At, B1); PG8_BAR; PG8_SCHED;
.LBB0_1485:
	ds_read_b128 v[144:147], v138
	ds_read_b128 v[148:151], v138 offset:1024
	ds_read_b128 v[152:155], v138 offset:2048
	ds_read_b128 v[156:159], v138 offset:3072
	ds_read_b128 v[160:163], v139
	ds_read_b128 v[164:167], v139 offset:1024
	ds_read_b128 v[168:171], v139 offset:2048
	ds_read_b128 v[172:175], v139 offset:3072
	s_add_u32 s26, s24, 0xfffc0080
	s_addc_u32 s27, s25, -1
	s_cmp_eq_u32 s61, 12
	s_cselect_b32 s26, s20, s26
	s_cselect_b32 s27, s21, s27
	s_cselect_b32 s40, s22, s59
	s_cselect_b32 s41, s23, s60
	s_add_u32 s38, s26, 0x80
	s_addc_u32 s39, s27, 0
	ds_read_b128 v[178:181], v140
	ds_read_b128 v[182:185], v140 offset:1024
	ds_read_b128 v[186:189], v140 offset:2048
	ds_read_b128 v[190:193], v140 offset:3072
	ds_read_b128 v[194:197], v140 offset:4096
	ds_read_b128 v[198:201], v140 offset:5120
	ds_read_b128 v[202:205], v140 offset:6144
	ds_read_b128 v[206:209], v140 offset:7168
	s_mov_b32 m0, s54
	s_nop 0
	global_load_lds_dwordx4 v134, s[24:25]
	s_add_u32 s62, s24, 0x20000
	s_mov_b32 m0, s55
	s_addc_u32 s63, s25, 0
	global_load_lds_dwordx4 v134, s[62:63]
	s_waitcnt vmcnt(8) lgkmcnt(0)
	s_barrier
	s_setprio 1
	v_mfma_f32_16x16x32_bf16 v[124:127], v[144:147], v[178:181], v[124:127]
	v_mfma_f32_16x16x32_bf16 v[120:123], v[152:155], v[178:181], v[120:123]
	v_mfma_f32_16x16x32_bf16 v[108:111], v[144:147], v[186:189], v[108:111]
	v_mfma_f32_16x16x32_bf16 v[104:107], v[152:155], v[186:189], v[104:107]
	v_mfma_f32_16x16x32_bf16 v[92:95], v[144:147], v[194:197], v[92:95]
	v_mfma_f32_16x16x32_bf16 v[88:91], v[152:155], v[194:197], v[88:91]
	v_mfma_f32_16x16x32_bf16 v[76:79], v[144:147], v[202:205], v[76:79]
	v_mfma_f32_16x16x32_bf16 v[72:75], v[152:155], v[202:205], v[72:75]
	v_mfma_f32_16x16x32_bf16 v[124:127], v[148:151], v[182:185], v[124:127]
	v_mfma_f32_16x16x32_bf16 v[120:123], v[156:159], v[182:185], v[120:123]
	v_mfma_f32_16x16x32_bf16 v[108:111], v[148:151], v[190:193], v[108:111]
	v_mfma_f32_16x16x32_bf16 v[104:107], v[156:159], v[190:193], v[104:107]
	v_mfma_f32_16x16x32_bf16 v[92:95], v[148:151], v[198:201], v[92:95]
	v_mfma_f32_16x16x32_bf16 v[88:91], v[156:159], v[198:201], v[88:91]
	v_mfma_f32_16x16x32_bf16 v[76:79], v[148:151], v[206:209], v[76:79]
	v_mfma_f32_16x16x32_bf16 v[72:75], v[156:159], v[206:209], v[72:75]
	v_mfma_f32_16x16x32_bf16 v[116:119], v[160:163], v[178:181], v[116:119]
	v_mfma_f32_16x16x32_bf16 v[112:115], v[168:171], v[178:181], v[112:115]
	v_mfma_f32_16x16x32_bf16 v[100:103], v[160:163], v[186:189], v[100:103]
	v_mfma_f32_16x16x32_bf16 v[96:99], v[168:171], v[186:189], v[96:99]
	v_mfma_f32_16x16x32_bf16 v[84:87], v[160:163], v[194:197], v[84:87]
	v_mfma_f32_16x16x32_bf16 v[80:83], v[168:171], v[194:197], v[80:83]
	v_mfma_f32_16x16x32_bf16 v[68:71], v[160:163], v[202:205], v[68:71]
	v_mfma_f32_16x16x32_bf16 v[64:67], v[168:171], v[202:205], v[64:67]
	v_mfma_f32_16x16x32_bf16 v[116:119], v[164:167], v[182:185], v[116:119]
	v_mfma_f32_16x16x32_bf16 v[112:115], v[172:175], v[182:185], v[112:115]
	v_mfma_f32_16x16x32_bf16 v[100:103], v[164:167], v[190:193], v[100:103]
	v_mfma_f32_16x16x32_bf16 v[96:99], v[172:175], v[190:193], v[96:99]
	v_mfma_f32_16x16x32_bf16 v[84:87], v[164:167], v[198:201], v[84:87]
	v_mfma_f32_16x16x32_bf16 v[80:83], v[172:175], v[198:201], v[80:83]
	v_mfma_f32_16x16x32_bf16 v[68:71], v[164:167], v[206:209], v[68:71]
	v_mfma_f32_16x16x32_bf16 v[64:67], v[172:175], v[206:209], v[64:67]
	s_add_i32 s61, s61, 2
	s_add_u32 s24, s24, 0x100
	s_addc_u32 s25, s25, 0
	s_add_u32 s59, s59, 0x100
	s_addc_u32 s60, s60, 0
	s_setprio 0
	s_barrier
	s_add_u32 s62, s40, 0x20000
	ds_read_b128 v[178:181], v140 offset:16384
	ds_read_b128 v[182:185], v140 offset:17408
	ds_read_b128 v[186:189], v140 offset:18432
	ds_read_b128 v[190:193], v140 offset:19456
	ds_read_b128 v[194:197], v140 offset:20480
	ds_read_b128 v[198:201], v140 offset:21504
	ds_read_b128 v[202:205], v140 offset:22528
	ds_read_b128 v[206:209], v140 offset:23552
	s_mov_b32 m0, s36
	s_nop 0
	global_load_lds_dwordx4 v135, s[40:41]
	s_mov_b32 m0, s37
	s_addc_u32 s63, s41, 0
	global_load_lds_dwordx4 v135, s[62:63]
	s_add_u32 s62, s40, 0x40000
	s_mov_b32 m0, s42
	s_addc_u32 s63, s41, 0
	global_load_lds_dwordx4 v135, s[62:63]
	s_add_u32 s62, s40, 0x60000
	s_mov_b32 m0, s43
	s_addc_u32 s63, s41, 0
	global_load_lds_dwordx4 v135, s[62:63]
	s_mov_b32 m0, s34
	s_nop 0
	global_load_lds_dwordx4 v134, s[26:27]
	s_add_u32 s62, s26, 0x20000
	s_mov_b32 m0, s44
	s_addc_u32 s63, s27, 0
	global_load_lds_dwordx4 v134, s[62:63]
	s_waitcnt vmcnt(8) lgkmcnt(0)
	s_barrier
	s_setprio 1
	v_mfma_f32_16x16x32_bf16 v[60:63], v[144:147], v[178:181], v[60:63]
	v_mfma_f32_16x16x32_bf16 v[56:59], v[152:155], v[178:181], v[56:59]
	v_mfma_f32_16x16x32_bf16 v[44:47], v[144:147], v[186:189], v[44:47]
	v_mfma_f32_16x16x32_bf16 v[40:43], v[152:155], v[186:189], v[40:43]
	v_mfma_f32_16x16x32_bf16 v[28:31], v[144:147], v[194:197], v[28:31]
	v_mfma_f32_16x16x32_bf16 v[24:27], v[152:155], v[194:197], v[24:27]
	v_mfma_f32_16x16x32_bf16 v[12:15], v[144:147], v[202:205], v[12:15]
	v_mfma_f32_16x16x32_bf16 v[8:11], v[152:155], v[202:205], v[8:11]
	v_mfma_f32_16x16x32_bf16 v[60:63], v[148:151], v[182:185], v[60:63]
	v_mfma_f32_16x16x32_bf16 v[56:59], v[156:159], v[182:185], v[56:59]
	v_mfma_f32_16x16x32_bf16 v[44:47], v[148:151], v[190:193], v[44:47]
	v_mfma_f32_16x16x32_bf16 v[40:43], v[156:159], v[190:193], v[40:43]
	v_mfma_f32_16x16x32_bf16 v[28:31], v[148:151], v[198:201], v[28:31]
	v_mfma_f32_16x16x32_bf16 v[24:27], v[156:159], v[198:201], v[24:27]
	v_mfma_f32_16x16x32_bf16 v[12:15], v[148:151], v[206:209], v[12:15]
	v_mfma_f32_16x16x32_bf16 v[8:11], v[156:159], v[206:209], v[8:11]
	v_mfma_f32_16x16x32_bf16 v[52:55], v[160:163], v[178:181], v[52:55]
	v_mfma_f32_16x16x32_bf16 v[48:51], v[168:171], v[178:181], v[48:51]
	v_mfma_f32_16x16x32_bf16 v[36:39], v[160:163], v[186:189], v[36:39]
	v_mfma_f32_16x16x32_bf16 v[32:35], v[168:171], v[186:189], v[32:35]
	v_mfma_f32_16x16x32_bf16 v[20:23], v[160:163], v[194:197], v[20:23]
	v_mfma_f32_16x16x32_bf16 v[16:19], v[168:171], v[194:197], v[16:19]
	v_mfma_f32_16x16x32_bf16 v[4:7], v[160:163], v[202:205], v[4:7]
	v_mfma_f32_16x16x32_bf16 v[0:3], v[168:171], v[202:205], v[0:3]
	v_mfma_f32_16x16x32_bf16 v[52:55], v[164:167], v[182:185], v[52:55]
	v_mfma_f32_16x16x32_bf16 v[48:51], v[172:175], v[182:185], v[48:51]
	v_mfma_f32_16x16x32_bf16 v[36:39], v[164:167], v[190:193], v[36:39]
	v_mfma_f32_16x16x32_bf16 v[32:35], v[172:175], v[190:193], v[32:35]
	v_mfma_f32_16x16x32_bf16 v[20:23], v[164:167], v[198:201], v[20:23]
	v_mfma_f32_16x16x32_bf16 v[16:19], v[172:175], v[198:201], v[16:19]
	v_mfma_f32_16x16x32_bf16 v[4:7], v[164:167], v[206:209], v[4:7]
	v_mfma_f32_16x16x32_bf16 v[0:3], v[172:175], v[206:209], v[0:3]
	s_setprio 0
	s_barrier
; #define PG8_STAGE(bufoff, gbase, voff, p64) do { _Pragma("unroll") for (int _i = 0; _i < 2; ++_i) { \
;         const char* _gb = (const char*)(gbase) + (size_t)_i * (p64); const unsigned _la = ldsbase + (unsigned)(bufoff) + (unsigned)_i * 8192u; \
;         asm volatile("s_mov_b32 m0, %0\n\ts_nop 0\n\tglobal_load_lds_dwordx4 %1, %2" :: "s"(_la), "v"(voff), "s"(_gb) : "memory"); } } while (0)
; #define PG8_LDA(dst, b, h) do { _Pragma("unroll") for (int m = 0; m < 4; ++m) _Pragma("unroll") for (int k = 0; k < 2; ++k) dst[m][k] = *(const LAS bf16x8*)(lds + PG8_SA(b, h) + aoff + m * 2048 + k * 1024); } while (0)
; #define PG8_LDB(dst, b, h) do { _Pragma("unroll") for (int n = 0; n < 2; ++n) _Pragma("unroll") for (int k = 0; k < 2; ++k) dst[n][k] = *(const LAS bf16x8*)(lds + PG8_SB(b, h) + boff + n * 2048 + k * 1024); } while (0)
; #define PG8_MMA(ai, bj, At, Bt) do { __builtin_amdgcn_s_setprio(1); _Pragma("unroll") for (int m = 0; m < 4; ++m) _Pragma("unroll") for (int n = 0; n < 2; ++n) _Pragma("unroll") for (int k = 0; k < 2; ++k) \
;         acc[ai][bj][m][n] = __builtin_amdgcn_mfma_f32_16x16x32_bf16(Bt[n][k], At[m][k], acc[ai][bj][m][n], 0, 0, 0); __builtin_amdgcn_s_setprio(0); } while (0)
; #define PG8_WAIT_V(n) asm volatile("s_waitcnt vmcnt(" #n ")" ::: "memory")
; #define PG8_WAIT_L(n) asm volatile("s_waitcnt lgkmcnt(" #n ")" ::: "memory")
; #define PG8_BAR __builtin_amdgcn_s_barrier()
; #define PG8_SCHED __builtin_amdgcn_sched_barrier(0)
; template <class Epi, class Sched>
; __device__ __forceinline__ void gemm_phase(LAS unsigned char* lds, const Sched& S, const Epi& E) {
;     ...
;             PG8_LDB(B0, 1, 0); PG8_LDB(B1, 1, 1); PG8_SCHED; PG8_LDA(At, 1, 0); PG8_STAGE(PG8_SA(0, 1), a2 + hA2, vA2, hA2 / 2);
;             PG8_WAIT_V(8); PG8_WAIT_L(0); PG8_BAR; PG8_MMA(0, 0, At, B0); PG8_MMA(0, 1, At, B1); PG8_BAR; PG8_SCHED;
;             PG8_LDA(At, 1, 1); PG8_STAGE(PG8_SB(1, 0), b3, vB2, hB2 / 2); PG8_STAGE(PG8_SB(1, 1), b3 + hB2, vB2, hB2 / 2); PG8_STAGE(PG8_SA(1, 0), a3, vA2, hA2 / 2);
;             PG8_WAIT_V(8); PG8_WAIT_L(0); PG8_BAR; PG8_MMA(1, 0, At, B0); PG8_MMA(1, 1, At, B1); PG8_BAR; PG8_SCHED;
;         }
;         if (wr == 0) PG8_BAR;
.Lpeel_mid_43312:
	ds_read_b128 v[144:147], v141
	ds_read_b128 v[148:151], v141 offset:1024
	ds_read_b128 v[152:155], v141 offset:2048
	ds_read_b128 v[156:159], v141 offset:3072
	ds_read_b128 v[160:163], v142
	ds_read_b128 v[164:167], v142 offset:1024
	ds_read_b128 v[168:171], v142 offset:2048
	ds_read_b128 v[172:175], v142 offset:3072
	ds_read_b128 v[178:181], v140 offset:32768
	ds_read_b128 v[182:185], v140 offset:33792
	ds_read_b128 v[186:189], v140 offset:34816
	ds_read_b128 v[190:193], v140 offset:35840
	ds_read_b128 v[194:197], v140 offset:36864
	ds_read_b128 v[198:201], v140 offset:37888
	ds_read_b128 v[202:205], v140 offset:38912
	ds_read_b128 v[206:209], v140 offset:39936
	s_add_u32 s62, s26, 0x40000
	s_mov_b32 m0, s45
	s_addc_u32 s63, s27, 0
	global_load_lds_dwordx4 v134, s[62:63]
	s_add_u32 s62, s26, 0x60000
	s_mov_b32 m0, s46
	s_addc_u32 s63, s27, 0
	global_load_lds_dwordx4 v134, s[62:63]
	s_waitcnt vmcnt(8) lgkmcnt(0)
	s_barrier
	s_setprio 1
	v_mfma_f32_16x16x32_bf16 v[124:127], v[144:147], v[178:181], v[124:127]
	v_mfma_f32_16x16x32_bf16 v[120:123], v[152:155], v[178:181], v[120:123]
	v_mfma_f32_16x16x32_bf16 v[108:111], v[144:147], v[186:189], v[108:111]
	v_mfma_f32_16x16x32_bf16 v[104:107], v[152:155], v[186:189], v[104:107]
	v_mfma_f32_16x16x32_bf16 v[92:95], v[144:147], v[194:197], v[92:95]
	v_mfma_f32_16x16x32_bf16 v[88:91], v[152:155], v[194:197], v[88:91]
	v_mfma_f32_16x16x32_bf16 v[76:79], v[144:147], v[202:205], v[76:79]
	v_mfma_f32_16x16x32_bf16 v[72:75], v[152:155], v[202:205], v[72:75]
	v_mfma_f32_16x16x32_bf16 v[124:127], v[148:151], v[182:185], v[124:127]
	v_mfma_f32_16x16x32_bf16 v[120:123], v[156:159], v[182:185], v[120:123]
	v_mfma_f32_16x16x32_bf16 v[108:111], v[148:151], v[190:193], v[108:111]
	v_mfma_f32_16x16x32_bf16 v[104:107], v[156:159], v[190:193], v[104:107]
	v_mfma_f32_16x16x32_bf16 v[92:95], v[148:151], v[198:201], v[92:95]
	v_mfma_f32_16x16x32_bf16 v[88:91], v[156:159], v[198:201], v[88:91]
	v_mfma_f32_16x16x32_bf16 v[76:79], v[148:151], v[206:209], v[76:79]
	v_mfma_f32_16x16x32_bf16 v[72:75], v[156:159], v[206:209], v[72:75]
	v_mfma_f32_16x16x32_bf16 v[116:119], v[160:163], v[178:181], v[116:119]
	v_mfma_f32_16x16x32_bf16 v[112:115], v[168:171], v[178:181], v[112:115]
	v_mfma_f32_16x16x32_bf16 v[100:103], v[160:163], v[186:189], v[100:103]
	v_mfma_f32_16x16x32_bf16 v[96:99], v[168:171], v[186:189], v[96:99]
	v_mfma_f32_16x16x32_bf16 v[84:87], v[160:163], v[194:197], v[84:87]
	v_mfma_f32_16x16x32_bf16 v[80:83], v[168:171], v[194:197], v[80:83]
	v_mfma_f32_16x16x32_bf16 v[68:71], v[160:163], v[202:205], v[68:71]
	v_mfma_f32_16x16x32_bf16 v[64:67], v[168:171], v[202:205], v[64:67]
	v_mfma_f32_16x16x32_bf16 v[116:119], v[164:167], v[182:185], v[116:119]
	v_mfma_f32_16x16x32_bf16 v[112:115], v[172:175], v[182:185], v[112:115]
	v_mfma_f32_16x16x32_bf16 v[100:103], v[164:167], v[190:193], v[100:103]
	v_mfma_f32_16x16x32_bf16 v[96:99], v[172:175], v[190:193], v[96:99]
	v_mfma_f32_16x16x32_bf16 v[84:87], v[164:167], v[198:201], v[84:87]
	v_mfma_f32_16x16x32_bf16 v[80:83], v[172:175], v[198:201], v[80:83]
	v_mfma_f32_16x16x32_bf16 v[68:71], v[164:167], v[206:209], v[68:71]
	v_mfma_f32_16x16x32_bf16 v[64:67], v[172:175], v[206:209], v[64:67]
	s_setprio 0
	s_barrier
	s_add_u32 s62, s40, 0x80
	s_addc_u32 s63, s41, 0
	ds_read_b128 v[178:181], v140 offset:49152
	ds_read_b128 v[182:185], v140 offset:50176
	ds_read_b128 v[186:189], v140 offset:51200
	ds_read_b128 v[190:193], v140 offset:52224
	ds_read_b128 v[194:197], v140 offset:53248
	ds_read_b128 v[198:201], v140 offset:54272
	ds_read_b128 v[202:205], v140 offset:55296
	ds_read_b128 v[206:209], v140 offset:56320
	s_mov_b32 m0, s48
	s_nop 0
	global_load_lds_dwordx4 v135, s[62:63]
	s_add_u32 s62, s40, 0x20080
	s_mov_b32 m0, s49
	s_addc_u32 s63, s41, 0
	global_load_lds_dwordx4 v135, s[62:63]
	s_add_u32 s62, s40, 0x40080
	s_mov_b32 m0, s52
	s_addc_u32 s63, s41, 0
	global_load_lds_dwordx4 v135, s[62:63]
	s_add_u32 s40, s40, 0x60080
	s_mov_b32 m0, s53
	s_addc_u32 s41, s41, 0
	global_load_lds_dwordx4 v135, s[40:41]
	s_mov_b32 m0, s50
	s_nop 0
	global_load_lds_dwordx4 v134, s[38:39]
	s_add_u32 s26, s26, 0x20080
	s_mov_b32 m0, s51
	s_addc_u32 s27, s27, 0
	global_load_lds_dwordx4 v134, s[26:27]
	s_waitcnt vmcnt(8) lgkmcnt(0)
	s_barrier
	s_setprio 1
	v_mfma_f32_16x16x32_bf16 v[60:63], v[144:147], v[178:181], v[60:63]
	v_mfma_f32_16x16x32_bf16 v[56:59], v[152:155], v[178:181], v[56:59]
	v_mfma_f32_16x16x32_bf16 v[44:47], v[144:147], v[186:189], v[44:47]
	v_mfma_f32_16x16x32_bf16 v[40:43], v[152:155], v[186:189], v[40:43]
	v_mfma_f32_16x16x32_bf16 v[28:31], v[144:147], v[194:197], v[28:31]
	v_mfma_f32_16x16x32_bf16 v[24:27], v[152:155], v[194:197], v[24:27]
	v_mfma_f32_16x16x32_bf16 v[12:15], v[144:147], v[202:205], v[12:15]
	v_mfma_f32_16x16x32_bf16 v[8:11], v[152:155], v[202:205], v[8:11]
	v_mfma_f32_16x16x32_bf16 v[60:63], v[148:151], v[182:185], v[60:63]
	v_mfma_f32_16x16x32_bf16 v[56:59], v[156:159], v[182:185], v[56:59]
	v_mfma_f32_16x16x32_bf16 v[44:47], v[148:151], v[190:193], v[44:47]
	v_mfma_f32_16x16x32_bf16 v[40:43], v[156:159], v[190:193], v[40:43]
	v_mfma_f32_16x16x32_bf16 v[28:31], v[148:151], v[198:201], v[28:31]
	v_mfma_f32_16x16x32_bf16 v[24:27], v[156:159], v[198:201], v[24:27]
	v_mfma_f32_16x16x32_bf16 v[12:15], v[148:151], v[206:209], v[12:15]
	v_mfma_f32_16x16x32_bf16 v[8:11], v[156:159], v[206:209], v[8:11]
	v_mfma_f32_16x16x32_bf16 v[52:55], v[160:163], v[178:181], v[52:55]
	v_mfma_f32_16x16x32_bf16 v[48:51], v[168:171], v[178:181], v[48:51]
	v_mfma_f32_16x16x32_bf16 v[36:39], v[160:163], v[186:189], v[36:39]
	v_mfma_f32_16x16x32_bf16 v[32:35], v[168:171], v[186:189], v[32:35]
	v_mfma_f32_16x16x32_bf16 v[20:23], v[160:163], v[194:197], v[20:23]
	v_mfma_f32_16x16x32_bf16 v[16:19], v[168:171], v[194:197], v[16:19]
	v_mfma_f32_16x16x32_bf16 v[4:7], v[160:163], v[202:205], v[4:7]
	v_mfma_f32_16x16x32_bf16 v[0:3], v[168:171], v[202:205], v[0:3]
	v_mfma_f32_16x16x32_bf16 v[52:55], v[164:167], v[182:185], v[52:55]
	v_mfma_f32_16x16x32_bf16 v[48:51], v[172:175], v[182:185], v[48:51]
	v_mfma_f32_16x16x32_bf16 v[36:39], v[164:167], v[190:193], v[36:39]
	v_mfma_f32_16x16x32_bf16 v[32:35], v[172:175], v[190:193], v[32:35]
	v_mfma_f32_16x16x32_bf16 v[20:23], v[164:167], v[198:201], v[20:23]
	v_mfma_f32_16x16x32_bf16 v[16:19], v[172:175], v[198:201], v[16:19]
	v_mfma_f32_16x16x32_bf16 v[4:7], v[164:167], v[206:209], v[4:7]
	v_mfma_f32_16x16x32_bf16 v[0:3], v[172:175], v[206:209], v[0:3]
	s_setprio 0
	s_barrier
	s_cmp_gt_u32 s61, 13
	s_cbranch_scc0 .LBB0_1485
	s_and_b64 vcc, exec, s[14:15]
	s_cbranch_vccz .LBB0_1488
	s_barrier

; #define PG8_STAGE(bufoff, gbase, voff, p64) do { _Pragma("unroll") for (int _i = 0; _i < 2; ++_i) { \
;         const char* _gb = (const char*)(gbase) + (size_t)_i * (p64); const unsigned _la = ldsbase + (unsigned)(bufoff) + (unsigned)_i * 8192u; \
;         asm volatile("s_mov_b32 m0, %0\n\ts_nop 0\n\tglobal_load_lds_dwordx4 %1, %2" :: "s"(_la), "v"(voff), "s"(_gb) : "memory"); } } while (0)
; #define PG8_LDA(dst, b, h) do { _Pragma("unroll") for (int m = 0; m < 4; ++m) _Pragma("unroll") for (int k = 0; k < 2; ++k) dst[m][k] = *(const LAS bf16x8*)(lds + PG8_SA(b, h) + aoff + m * 2048 + k * 1024); } while (0)
; #define PG8_LDB(dst, b, h) do { _Pragma("unroll") for (int n = 0; n < 2; ++n) _Pragma("unroll") for (int k = 0; k < 2; ++k) dst[n][k] = *(const LAS bf16x8*)(lds + PG8_SB(b, h) + boff + n * 2048 + k * 1024); } while (0)
; #define PG8_WAIT_V(n) asm volatile("s_waitcnt vmcnt(" #n ")" ::: "memory")
; #define PG8_BAR __builtin_amdgcn_s_barrier()
; template <class Epi, class Sched>
; __device__ __forceinline__ void gemm_phase(LAS unsigned char* lds, const Sched& S, const Epi& E) {
;     ...
;         for (int t = 0; t < nt; t += 2) {
;             const bool last = (t == nt - 2);
;             const char* a1 = cA + (size_t)(t + 1) * kstep;
;             const char* a2 = last ? nA : cA + (size_t)(t + 2) * kstep; const char* b2 = last ? nB : cB + (size_t)(t + 2) * kstep;
;             const char* a3 = a2 + kstep; const char* b3 = b2 + kstep;
;             const unsigned vA2 = voffA, vB2 = voffB, hA2 = hA, hB2 = hB;
;             PG8_LDB(B0, 0, 0); PG8_LDB(B1, 0, 1); PG8_SCHED; PG8_LDA(At, 0, 0); PG8_STAGE(PG8_SA(1, 1), a1 + hA, voffA, hA / 2);
;             PG8_WAIT_V(8); PG8_WAIT_L(0); PG8_BAR; PG8_MMA(0, 0, At, B0); PG8_MMA(0, 1, At, B1); PG8_BAR; PG8_SCHED;
;             PG8_LDA(At, 0, 1); PG8_STAGE(PG8_SB(0, 0), b2, vB2, hB2 / 2); PG8_STAGE(PG8_SB(0, 1), b2 + hB2, vB2, hB2 / 2); PG8_STAGE(PG8_SA(0, 0), a2, vA2, hA2 / 2);
;             PG8_WAIT_V(8); PG8_WAIT_L(0); PG8_BAR; PG8_MMA(1, 0, At, B0); PG8_MMA(1, 1, At, B1); PG8_BAR; PG8_SCHED;
;     ...
; #pragma unroll
;             for (int a = 0; a < 2; ++a)
; #pragma unroll
;                 for (int b = 0; b < 2; ++b)
; #pragma unroll
;                     for (int m = 0; m < 4; ++m)
; #pragma unroll
;                         for (int n = 0; n < 2; ++n) acc[a][b][m][n] = (f32x4){0.f, 0.f, 0.f, 0.f};
.LBB0_1558:
	s_add_u32 s22, s22, 0xb0080
	s_addc_u32 s23, s23, 0
	s_add_u32 s59, s24, 0x100
	s_addc_u32 s60, s25, 0
	s_mov_b32 s61, -2
	s_waitcnt vmcnt(7)
	s_waitcnt vmcnt(6)
	s_waitcnt vmcnt(3)
	s_waitcnt vmcnt(2)
	s_waitcnt vmcnt(1)
	s_waitcnt vmcnt(0)
	ds_read_b128 v[128:131], v179
	ds_read_b128 v[132:135], v179 offset:1024
	ds_read_b128 v[136:139], v179 offset:2048
	ds_read_b128 v[140:143], v179 offset:3072
	ds_read_b128 v[150:153], v180
	ds_read_b128 v[154:157], v180 offset:1024
	ds_read_b128 v[158:161], v180 offset:2048
	ds_read_b128 v[162:165], v180 offset:3072
	s_add_u32 s24, s22, 0xfff50080
	s_addc_u32 s25, s23, -1
	s_cmp_eq_u32 s61, 40
	s_cselect_b32 s24, s18, s24
	s_cselect_b32 s25, s19, s25
	s_cselect_b32 s38, s20, s59
	s_cselect_b32 s39, s21, s60
	s_add_u32 s26, s24, 0x80
	s_addc_u32 s27, s25, 0
	ds_read_b128 v[166:169], v181
	ds_read_b128 v[170:173], v181 offset:1024
	ds_read_b128 v[184:187], v181 offset:2048
	ds_read_b128 v[188:191], v181 offset:3072
	ds_read_b128 v[192:195], v181 offset:4096
	ds_read_b128 v[196:199], v181 offset:5120
	ds_read_b128 v[200:203], v181 offset:6144
	ds_read_b128 v[204:207], v181 offset:7168
	s_mov_b32 m0, s54
	s_nop 0
	global_load_lds_dwordx4 v144, s[22:23]
	s_add_u32 s62, s22, 0x58000
	s_mov_b32 m0, s55
	s_addc_u32 s63, s23, 0
	global_load_lds_dwordx4 v144, s[62:63]
	s_waitcnt vmcnt(8) lgkmcnt(0)
	s_barrier
	s_setprio 1
	v_mfma_f32_16x16x32_bf16 v[124:127], v[128:131], v[166:169], 0
	v_mfma_f32_16x16x32_bf16 v[120:123], v[136:139], v[166:169], 0
	v_mfma_f32_16x16x32_bf16 v[116:119], v[128:131], v[184:187], 0
	v_mfma_f32_16x16x32_bf16 v[112:115], v[136:139], v[184:187], 0
	v_mfma_f32_16x16x32_bf16 v[108:111], v[128:131], v[192:195], 0
	v_mfma_f32_16x16x32_bf16 v[104:107], v[136:139], v[192:195], 0
	v_mfma_f32_16x16x32_bf16 v[100:103], v[128:131], v[200:203], 0
	v_mfma_f32_16x16x32_bf16 v[96:99], v[136:139], v[200:203], 0
	v_mfma_f32_16x16x32_bf16 v[124:127], v[132:135], v[170:173], v[124:127]
	v_mfma_f32_16x16x32_bf16 v[120:123], v[140:143], v[170:173], v[120:123]
	v_mfma_f32_16x16x32_bf16 v[116:119], v[132:135], v[188:191], v[116:119]
	v_mfma_f32_16x16x32_bf16 v[112:115], v[140:143], v[188:191], v[112:115]
	v_mfma_f32_16x16x32_bf16 v[108:111], v[132:135], v[196:199], v[108:111]
	v_mfma_f32_16x16x32_bf16 v[104:107], v[140:143], v[196:199], v[104:107]
	v_mfma_f32_16x16x32_bf16 v[100:103], v[132:135], v[204:207], v[100:103]
	v_mfma_f32_16x16x32_bf16 v[96:99], v[140:143], v[204:207], v[96:99]
	v_mfma_f32_16x16x32_bf16 v[60:63], v[150:153], v[166:169], 0
	v_mfma_f32_16x16x32_bf16 v[56:59], v[158:161], v[166:169], 0
	v_mfma_f32_16x16x32_bf16 v[52:55], v[150:153], v[184:187], 0
	v_mfma_f32_16x16x32_bf16 v[48:51], v[158:161], v[184:187], 0
	v_mfma_f32_16x16x32_bf16 v[44:47], v[150:153], v[192:195], 0
	v_mfma_f32_16x16x32_bf16 v[40:43], v[158:161], v[192:195], 0
	v_mfma_f32_16x16x32_bf16 v[36:39], v[150:153], v[200:203], 0
	v_mfma_f32_16x16x32_bf16 v[32:35], v[158:161], v[200:203], 0
	v_mfma_f32_16x16x32_bf16 v[60:63], v[154:157], v[170:173], v[60:63]
	v_mfma_f32_16x16x32_bf16 v[56:59], v[162:165], v[170:173], v[56:59]
	v_mfma_f32_16x16x32_bf16 v[52:55], v[154:157], v[188:191], v[52:55]
	v_mfma_f32_16x16x32_bf16 v[48:51], v[162:165], v[188:191], v[48:51]
	v_mfma_f32_16x16x32_bf16 v[44:47], v[154:157], v[196:199], v[44:47]
	v_mfma_f32_16x16x32_bf16 v[40:43], v[162:165], v[196:199], v[40:43]
	v_mfma_f32_16x16x32_bf16 v[36:39], v[154:157], v[204:207], v[36:39]
	v_mfma_f32_16x16x32_bf16 v[32:35], v[162:165], v[204:207], v[32:35]
	s_add_i32 s61, s61, 2
	s_add_u32 s22, s22, 0x100
	s_addc_u32 s23, s23, 0
	s_add_u32 s59, s59, 0x100
	s_addc_u32 s60, s60, 0
	s_setprio 0
	s_barrier
	s_add_u32 s62, s38, 0x58000
	ds_read_b128 v[166:169], v181 offset:16384
	ds_read_b128 v[170:173], v181 offset:17408
	ds_read_b128 v[184:187], v181 offset:18432
	ds_read_b128 v[188:191], v181 offset:19456
	ds_read_b128 v[192:195], v181 offset:20480
	ds_read_b128 v[196:199], v181 offset:21504
	ds_read_b128 v[200:203], v181 offset:22528
	ds_read_b128 v[204:207], v181 offset:23552
	s_mov_b32 m0, s35
	s_nop 0
	global_load_lds_dwordx4 v145, s[38:39]
	s_mov_b32 m0, s36
	s_addc_u32 s63, s39, 0
	global_load_lds_dwordx4 v145, s[62:63]
	s_add_u32 s62, s38, 0xb0000
	s_mov_b32 m0, s37
	s_addc_u32 s63, s39, 0
	global_load_lds_dwordx4 v145, s[62:63]
	s_add_u32 s62, s38, 0x108000
	s_mov_b32 m0, s40
	s_addc_u32 s63, s39, 0
	global_load_lds_dwordx4 v145, s[62:63]
	s_mov_b32 m0, s34
	s_nop 0
	global_load_lds_dwordx4 v144, s[24:25]
	s_add_u32 s62, s24, 0x58000
	s_mov_b32 m0, s41
	s_addc_u32 s63, s25, 0
	global_load_lds_dwordx4 v144, s[62:63]
	s_waitcnt vmcnt(8) lgkmcnt(0)
	s_barrier
	s_setprio 1
	v_mfma_f32_16x16x32_bf16 v[92:95], v[128:131], v[166:169], 0
	v_mfma_f32_16x16x32_bf16 v[88:91], v[136:139], v[166:169], 0
	v_mfma_f32_16x16x32_bf16 v[84:87], v[128:131], v[184:187], 0
	v_mfma_f32_16x16x32_bf16 v[80:83], v[136:139], v[184:187], 0
	v_mfma_f32_16x16x32_bf16 v[76:79], v[128:131], v[192:195], 0
	v_mfma_f32_16x16x32_bf16 v[72:75], v[136:139], v[192:195], 0
	v_mfma_f32_16x16x32_bf16 v[68:71], v[128:131], v[200:203], 0
	v_mfma_f32_16x16x32_bf16 v[64:67], v[136:139], v[200:203], 0
	v_mfma_f32_16x16x32_bf16 v[92:95], v[132:135], v[170:173], v[92:95]
	v_mfma_f32_16x16x32_bf16 v[88:91], v[140:143], v[170:173], v[88:91]
	v_mfma_f32_16x16x32_bf16 v[84:87], v[132:135], v[188:191], v[84:87]
	v_mfma_f32_16x16x32_bf16 v[80:83], v[140:143], v[188:191], v[80:83]
	v_mfma_f32_16x16x32_bf16 v[76:79], v[132:135], v[196:199], v[76:79]
	v_mfma_f32_16x16x32_bf16 v[72:75], v[140:143], v[196:199], v[72:75]
	v_mfma_f32_16x16x32_bf16 v[68:71], v[132:135], v[204:207], v[68:71]
	v_mfma_f32_16x16x32_bf16 v[64:67], v[140:143], v[204:207], v[64:67]
	v_mfma_f32_16x16x32_bf16 v[28:31], v[150:153], v[166:169], 0
	v_mfma_f32_16x16x32_bf16 v[24:27], v[158:161], v[166:169], 0
	v_mfma_f32_16x16x32_bf16 v[20:23], v[150:153], v[184:187], 0
	v_mfma_f32_16x16x32_bf16 v[16:19], v[158:161], v[184:187], 0
	v_mfma_f32_16x16x32_bf16 v[12:15], v[150:153], v[192:195], 0
	v_mfma_f32_16x16x32_bf16 v[8:11], v[158:161], v[192:195], 0
	v_mfma_f32_16x16x32_bf16 v[4:7], v[150:153], v[200:203], 0
	v_mfma_f32_16x16x32_bf16 v[0:3], v[158:161], v[200:203], 0
	v_mfma_f32_16x16x32_bf16 v[28:31], v[154:157], v[170:173], v[28:31]
	v_mfma_f32_16x16x32_bf16 v[24:27], v[162:165], v[170:173], v[24:27]
	v_mfma_f32_16x16x32_bf16 v[20:23], v[154:157], v[188:191], v[20:23]
	v_mfma_f32_16x16x32_bf16 v[16:19], v[162:165], v[188:191], v[16:19]
	v_mfma_f32_16x16x32_bf16 v[12:15], v[154:157], v[196:199], v[12:15]
	v_mfma_f32_16x16x32_bf16 v[8:11], v[162:165], v[196:199], v[8:11]
	v_mfma_f32_16x16x32_bf16 v[4:7], v[154:157], v[204:207], v[4:7]
	v_mfma_f32_16x16x32_bf16 v[0:3], v[162:165], v[204:207], v[0:3]
	s_setprio 0
	s_barrier
	s_branch .Lpeel_mid_45164
; #define PG8_STAGE(bufoff, gbase, voff, p64) do { _Pragma("unroll") for (int _i = 0; _i < 2; ++_i) { \
;         const char* _gb = (const char*)(gbase) + (size_t)_i * (p64); const unsigned _la = ldsbase + (unsigned)(bufoff) + (unsigned)_i * 8192u; \
;         asm volatile("s_mov_b32 m0, %0\n\ts_nop 0\n\tglobal_load_lds_dwordx4 %1, %2" :: "s"(_la), "v"(voff), "s"(_gb) : "memory"); } } while (0)
; #define PG8_LDA(dst, b, h) do { _Pragma("unroll") for (int m = 0; m < 4; ++m) _Pragma("unroll") for (int k = 0; k < 2; ++k) dst[m][k] = *(const LAS bf16x8*)(lds + PG8_SA(b, h) + aoff + m * 2048 + k * 1024); } while (0)
; #define PG8_LDB(dst, b, h) do { _Pragma("unroll") for (int n = 0; n < 2; ++n) _Pragma("unroll") for (int k = 0; k < 2; ++k) dst[n][k] = *(const LAS bf16x8*)(lds + PG8_SB(b, h) + boff + n * 2048 + k * 1024); } while (0)
; #define PG8_MMA(ai, bj, At, Bt) do { __builtin_amdgcn_s_setprio(1); _Pragma("unroll") for (int m = 0; m < 4; ++m) _Pragma("unroll") for (int n = 0; n < 2; ++n) _Pragma("unroll") for (int k = 0; k < 2; ++k) \
;         acc[ai][bj][m][n] = __builtin_amdgcn_mfma_f32_16x16x32_bf16(Bt[n][k], At[m][k], acc[ai][bj][m][n], 0, 0, 0); __builtin_amdgcn_s_setprio(0); } while (0)
; #define PG8_WAIT_V(n) asm volatile("s_waitcnt vmcnt(" #n ")" ::: "memory")
; template <class Epi, class Sched>
; __device__ __forceinline__ void gemm_phase(LAS unsigned char* lds, const Sched& S, const Epi& E) {
;     ...
;         for (int t = 0; t < nt; t += 2) {
;             const bool last = (t == nt - 2);
;             const char* a1 = cA + (size_t)(t + 1) * kstep;
;             const char* a2 = last ? nA : cA + (size_t)(t + 2) * kstep; const char* b2 = last ? nB : cB + (size_t)(t + 2) * kstep;
;             const char* a3 = a2 + kstep; const char* b3 = b2 + kstep;
;             const unsigned vA2 = voffA, vB2 = voffB, hA2 = hA, hB2 = hB;
;             PG8_LDB(B0, 0, 0); PG8_LDB(B1, 0, 1); PG8_SCHED; PG8_LDA(At, 0, 0); PG8_STAGE(PG8_SA(1, 1), a1 + hA, voffA, hA / 2);
;             PG8_WAIT_V(8); PG8_WAIT_L(0); PG8_BAR; PG8_MMA(0, 0, At, B0); PG8_MMA(0, 1, At, B1); PG8_BAR; PG8_SCHED;
;             PG8_LDA(At, 0, 1); PG8_STAGE(PG8_SB(0, 0), b2, vB2, hB2 / 2); PG8_STAGE(PG8_SB(0, 1), b2 + hB2, vB2, hB2 / 2); PG8_STAGE(PG8_SA(0, 0), a2, vA2, hA2 / 2);
;             PG8_WAIT_V(8); PG8_WAIT_L(0); PG8_BAR; PG8_MMA(1, 0, At, B0); PG8_MMA(1, 1, At, B1); PG8_BAR; PG8_SCHED;
.LBB0_1559:
	ds_read_b128 v[128:131], v179
	ds_read_b128 v[132:135], v179 offset:1024
	ds_read_b128 v[136:139], v179 offset:2048
	ds_read_b128 v[140:143], v179 offset:3072
	ds_read_b128 v[150:153], v180
	ds_read_b128 v[154:157], v180 offset:1024
	ds_read_b128 v[158:161], v180 offset:2048
	ds_read_b128 v[162:165], v180 offset:3072
	s_add_u32 s24, s22, 0xfff50080
	s_addc_u32 s25, s23, -1
	s_cmp_eq_u32 s61, 40
	s_cselect_b32 s24, s18, s24
	s_cselect_b32 s25, s19, s25
	s_cselect_b32 s38, s20, s59
	s_cselect_b32 s39, s21, s60
	s_add_u32 s26, s24, 0x80
	s_addc_u32 s27, s25, 0
	ds_read_b128 v[166:169], v181
	ds_read_b128 v[170:173], v181 offset:1024
	ds_read_b128 v[184:187], v181 offset:2048
	ds_read_b128 v[188:191], v181 offset:3072
	ds_read_b128 v[192:195], v181 offset:4096
	ds_read_b128 v[196:199], v181 offset:5120
	ds_read_b128 v[200:203], v181 offset:6144
	ds_read_b128 v[204:207], v181 offset:7168
	s_mov_b32 m0, s54
	s_nop 0
	global_load_lds_dwordx4 v144, s[22:23]
	s_add_u32 s62, s22, 0x58000
	s_mov_b32 m0, s55
	s_addc_u32 s63, s23, 0
	global_load_lds_dwordx4 v144, s[62:63]
	s_waitcnt vmcnt(8) lgkmcnt(0)
	s_barrier
	s_setprio 1
	v_mfma_f32_16x16x32_bf16 v[124:127], v[128:131], v[166:169], v[124:127]
	v_mfma_f32_16x16x32_bf16 v[120:123], v[136:139], v[166:169], v[120:123]
	v_mfma_f32_16x16x32_bf16 v[116:119], v[128:131], v[184:187], v[116:119]
	v_mfma_f32_16x16x32_bf16 v[112:115], v[136:139], v[184:187], v[112:115]
	v_mfma_f32_16x16x32_bf16 v[108:111], v[128:131], v[192:195], v[108:111]
	v_mfma_f32_16x16x32_bf16 v[104:107], v[136:139], v[192:195], v[104:107]
	v_mfma_f32_16x16x32_bf16 v[100:103], v[128:131], v[200:203], v[100:103]
	v_mfma_f32_16x16x32_bf16 v[96:99], v[136:139], v[200:203], v[96:99]
	v_mfma_f32_16x16x32_bf16 v[124:127], v[132:135], v[170:173], v[124:127]
	v_mfma_f32_16x16x32_bf16 v[120:123], v[140:143], v[170:173], v[120:123]
	v_mfma_f32_16x16x32_bf16 v[116:119], v[132:135], v[188:191], v[116:119]
	v_mfma_f32_16x16x32_bf16 v[112:115], v[140:143], v[188:191], v[112:115]
	v_mfma_f32_16x16x32_bf16 v[108:111], v[132:135], v[196:199], v[108:111]
	v_mfma_f32_16x16x32_bf16 v[104:107], v[140:143], v[196:199], v[104:107]
	v_mfma_f32_16x16x32_bf16 v[100:103], v[132:135], v[204:207], v[100:103]
	v_mfma_f32_16x16x32_bf16 v[96:99], v[140:143], v[204:207], v[96:99]
	v_mfma_f32_16x16x32_bf16 v[60:63], v[150:153], v[166:169], v[60:63]
	v_mfma_f32_16x16x32_bf16 v[56:59], v[158:161], v[166:169], v[56:59]
	v_mfma_f32_16x16x32_bf16 v[52:55], v[150:153], v[184:187], v[52:55]
	v_mfma_f32_16x16x32_bf16 v[48:51], v[158:161], v[184:187], v[48:51]
	v_mfma_f32_16x16x32_bf16 v[44:47], v[150:153], v[192:195], v[44:47]
	v_mfma_f32_16x16x32_bf16 v[40:43], v[158:161], v[192:195], v[40:43]
	v_mfma_f32_16x16x32_bf16 v[36:39], v[150:153], v[200:203], v[36:39]
	v_mfma_f32_16x16x32_bf16 v[32:35], v[158:161], v[200:203], v[32:35]
	v_mfma_f32_16x16x32_bf16 v[60:63], v[154:157], v[170:173], v[60:63]
	v_mfma_f32_16x16x32_bf16 v[56:59], v[162:165], v[170:173], v[56:59]
	v_mfma_f32_16x16x32_bf16 v[52:55], v[154:157], v[188:191], v[52:55]
	v_mfma_f32_16x16x32_bf16 v[48:51], v[162:165], v[188:191], v[48:51]
	v_mfma_f32_16x16x32_bf16 v[44:47], v[154:157], v[196:199], v[44:47]
	v_mfma_f32_16x16x32_bf16 v[40:43], v[162:165], v[196:199], v[40:43]
	v_mfma_f32_16x16x32_bf16 v[36:39], v[154:157], v[204:207], v[36:39]
	v_mfma_f32_16x16x32_bf16 v[32:35], v[162:165], v[204:207], v[32:35]
	s_add_i32 s61, s61, 2
	s_add_u32 s22, s22, 0x100
	s_addc_u32 s23, s23, 0
	s_add_u32 s59, s59, 0x100
	s_addc_u32 s60, s60, 0
	s_setprio 0
	s_barrier
	s_add_u32 s62, s38, 0x58000
	ds_read_b128 v[166:169], v181 offset:16384
	ds_read_b128 v[170:173], v181 offset:17408
	ds_read_b128 v[184:187], v181 offset:18432
	ds_read_b128 v[188:191], v181 offset:19456
	ds_read_b128 v[192:195], v181 offset:20480
	ds_read_b128 v[196:199], v181 offset:21504
	ds_read_b128 v[200:203], v181 offset:22528
	ds_read_b128 v[204:207], v181 offset:23552
	s_mov_b32 m0, s35
	s_nop 0
	global_load_lds_dwordx4 v145, s[38:39]
	s_mov_b32 m0, s36
	s_addc_u32 s63, s39, 0
	global_load_lds_dwordx4 v145, s[62:63]
	s_add_u32 s62, s38, 0xb0000
	s_mov_b32 m0, s37
	s_addc_u32 s63, s39, 0
	global_load_lds_dwordx4 v145, s[62:63]
	s_add_u32 s62, s38, 0x108000
	s_mov_b32 m0, s40
	s_addc_u32 s63, s39, 0
	global_load_lds_dwordx4 v145, s[62:63]
	s_mov_b32 m0, s34
	s_nop 0
	global_load_lds_dwordx4 v144, s[24:25]
	s_add_u32 s62, s24, 0x58000
	s_mov_b32 m0, s41
	s_addc_u32 s63, s25, 0
	global_load_lds_dwordx4 v144, s[62:63]
	s_waitcnt vmcnt(8) lgkmcnt(0)
	s_barrier
	s_setprio 1
	v_mfma_f32_16x16x32_bf16 v[92:95], v[128:131], v[166:169], v[92:95]
	v_mfma_f32_16x16x32_bf16 v[88:91], v[136:139], v[166:169], v[88:91]
	v_mfma_f32_16x16x32_bf16 v[84:87], v[128:131], v[184:187], v[84:87]
	v_mfma_f32_16x16x32_bf16 v[80:83], v[136:139], v[184:187], v[80:83]
	v_mfma_f32_16x16x32_bf16 v[76:79], v[128:131], v[192:195], v[76:79]
	v_mfma_f32_16x16x32_bf16 v[72:75], v[136:139], v[192:195], v[72:75]
	v_mfma_f32_16x16x32_bf16 v[68:71], v[128:131], v[200:203], v[68:71]
	v_mfma_f32_16x16x32_bf16 v[64:67], v[136:139], v[200:203], v[64:67]
	v_mfma_f32_16x16x32_bf16 v[92:95], v[132:135], v[170:173], v[92:95]
	v_mfma_f32_16x16x32_bf16 v[88:91], v[140:143], v[170:173], v[88:91]
	v_mfma_f32_16x16x32_bf16 v[84:87], v[132:135], v[188:191], v[84:87]
	v_mfma_f32_16x16x32_bf16 v[80:83], v[140:143], v[188:191], v[80:83]
	v_mfma_f32_16x16x32_bf16 v[76:79], v[132:135], v[196:199], v[76:79]
	v_mfma_f32_16x16x32_bf16 v[72:75], v[140:143], v[196:199], v[72:75]
	v_mfma_f32_16x16x32_bf16 v[68:71], v[132:135], v[204:207], v[68:71]
	v_mfma_f32_16x16x32_bf16 v[64:67], v[140:143], v[204:207], v[64:67]
	v_mfma_f32_16x16x32_bf16 v[28:31], v[150:153], v[166:169], v[28:31]
	v_mfma_f32_16x16x32_bf16 v[24:27], v[158:161], v[166:169], v[24:27]
	v_mfma_f32_16x16x32_bf16 v[20:23], v[150:153], v[184:187], v[20:23]
	v_mfma_f32_16x16x32_bf16 v[16:19], v[158:161], v[184:187], v[16:19]
	v_mfma_f32_16x16x32_bf16 v[12:15], v[150:153], v[192:195], v[12:15]
	v_mfma_f32_16x16x32_bf16 v[8:11], v[158:161], v[192:195], v[8:11]
	v_mfma_f32_16x16x32_bf16 v[4:7], v[150:153], v[200:203], v[4:7]
	v_mfma_f32_16x16x32_bf16 v[0:3], v[158:161], v[200:203], v[0:3]
	v_mfma_f32_16x16x32_bf16 v[28:31], v[154:157], v[170:173], v[28:31]
	v_mfma_f32_16x16x32_bf16 v[24:27], v[162:165], v[170:173], v[24:27]
	v_mfma_f32_16x16x32_bf16 v[20:23], v[154:157], v[188:191], v[20:23]
	v_mfma_f32_16x16x32_bf16 v[16:19], v[162:165], v[188:191], v[16:19]
	v_mfma_f32_16x16x32_bf16 v[12:15], v[154:157], v[196:199], v[12:15]
	v_mfma_f32_16x16x32_bf16 v[8:11], v[162:165], v[196:199], v[8:11]
	v_mfma_f32_16x16x32_bf16 v[4:7], v[154:157], v[204:207], v[4:7]
	v_mfma_f32_16x16x32_bf16 v[0:3], v[162:165], v[204:207], v[0:3]
	s_setprio 0
	s_barrier
; #define PG8_STAGE(bufoff, gbase, voff, p64) do { _Pragma("unroll") for (int _i = 0; _i < 2; ++_i) { \
;         const char* _gb = (const char*)(gbase) + (size_t)_i * (p64); const unsigned _la = ldsbase + (unsigned)(bufoff) + (unsigned)_i * 8192u; \
;         asm volatile("s_mov_b32 m0, %0\n\ts_nop 0\n\tglobal_load_lds_dwordx4 %1, %2" :: "s"(_la), "v"(voff), "s"(_gb) : "memory"); } } while (0)
; #define PG8_LDA(dst, b, h) do { _Pragma("unroll") for (int m = 0; m < 4; ++m) _Pragma("unroll") for (int k = 0; k < 2; ++k) dst[m][k] = *(const LAS bf16x8*)(lds + PG8_SA(b, h) + aoff + m * 2048 + k * 1024); } while (0)
; #define PG8_LDB(dst, b, h) do { _Pragma("unroll") for (int n = 0; n < 2; ++n) _Pragma("unroll") for (int k = 0; k < 2; ++k) dst[n][k] = *(const LAS bf16x8*)(lds + PG8_SB(b, h) + boff + n * 2048 + k * 1024); } while (0)
; #define PG8_MMA(ai, bj, At, Bt) do { __builtin_amdgcn_s_setprio(1); _Pragma("unroll") for (int m = 0; m < 4; ++m) _Pragma("unroll") for (int n = 0; n < 2; ++n) _Pragma("unroll") for (int k = 0; k < 2; ++k) \
;         acc[ai][bj][m][n] = __builtin_amdgcn_mfma_f32_16x16x32_bf16(Bt[n][k], At[m][k], acc[ai][bj][m][n], 0, 0, 0); __builtin_amdgcn_s_setprio(0); } while (0)
; #define PG8_WAIT_V(n) asm volatile("s_waitcnt vmcnt(" #n ")" ::: "memory")
; #define PG8_WAIT_L(n) asm volatile("s_waitcnt lgkmcnt(" #n ")" ::: "memory")
; #define PG8_BAR __builtin_amdgcn_s_barrier()
; #define PG8_SCHED __builtin_amdgcn_sched_barrier(0)
; template <class Epi, class Sched>
; __device__ __forceinline__ void gemm_phase(LAS unsigned char* lds, const Sched& S, const Epi& E) {
;     ...
;             PG8_LDB(B0, 1, 0); PG8_LDB(B1, 1, 1); PG8_SCHED; PG8_LDA(At, 1, 0); PG8_STAGE(PG8_SA(0, 1), a2 + hA2, vA2, hA2 / 2);
;             PG8_WAIT_V(8); PG8_WAIT_L(0); PG8_BAR; PG8_MMA(0, 0, At, B0); PG8_MMA(0, 1, At, B1); PG8_BAR; PG8_SCHED;
;             PG8_LDA(At, 1, 1); PG8_STAGE(PG8_SB(1, 0), b3, vB2, hB2 / 2); PG8_STAGE(PG8_SB(1, 1), b3 + hB2, vB2, hB2 / 2); PG8_STAGE(PG8_SA(1, 0), a3, vA2, hA2 / 2);
;             PG8_WAIT_V(8); PG8_WAIT_L(0); PG8_BAR; PG8_MMA(1, 0, At, B0); PG8_MMA(1, 1, At, B1); PG8_BAR; PG8_SCHED;
;         }
;         if (wr == 0) PG8_BAR;
.Lpeel_mid_45164:
	ds_read_b128 v[128:131], v182
	ds_read_b128 v[132:135], v182 offset:1024
	ds_read_b128 v[136:139], v182 offset:2048
	ds_read_b128 v[140:143], v182 offset:3072
	ds_read_b128 v[150:153], v183
	ds_read_b128 v[154:157], v183 offset:1024
	ds_read_b128 v[158:161], v183 offset:2048
	ds_read_b128 v[162:165], v183 offset:3072
	ds_read_b128 v[166:169], v181 offset:32768
	ds_read_b128 v[170:173], v181 offset:33792
	ds_read_b128 v[184:187], v181 offset:34816
	ds_read_b128 v[188:191], v181 offset:35840
	ds_read_b128 v[192:195], v181 offset:36864
	ds_read_b128 v[196:199], v181 offset:37888
	ds_read_b128 v[200:203], v181 offset:38912
	ds_read_b128 v[204:207], v181 offset:39936
	s_add_u32 s62, s24, 0xb0000
	s_mov_b32 m0, s42
	s_addc_u32 s63, s25, 0
	global_load_lds_dwordx4 v144, s[62:63]
	s_add_u32 s62, s24, 0x108000
	s_mov_b32 m0, s43
	s_addc_u32 s63, s25, 0
	global_load_lds_dwordx4 v144, s[62:63]
	s_waitcnt vmcnt(8) lgkmcnt(0)
	s_barrier
	s_setprio 1
	v_mfma_f32_16x16x32_bf16 v[124:127], v[128:131], v[166:169], v[124:127]
	v_mfma_f32_16x16x32_bf16 v[120:123], v[136:139], v[166:169], v[120:123]
	v_mfma_f32_16x16x32_bf16 v[116:119], v[128:131], v[184:187], v[116:119]
	v_mfma_f32_16x16x32_bf16 v[112:115], v[136:139], v[184:187], v[112:115]
	v_mfma_f32_16x16x32_bf16 v[108:111], v[128:131], v[192:195], v[108:111]
	v_mfma_f32_16x16x32_bf16 v[104:107], v[136:139], v[192:195], v[104:107]
	v_mfma_f32_16x16x32_bf16 v[100:103], v[128:131], v[200:203], v[100:103]
	v_mfma_f32_16x16x32_bf16 v[96:99], v[136:139], v[200:203], v[96:99]
	v_mfma_f32_16x16x32_bf16 v[124:127], v[132:135], v[170:173], v[124:127]
	v_mfma_f32_16x16x32_bf16 v[120:123], v[140:143], v[170:173], v[120:123]
	v_mfma_f32_16x16x32_bf16 v[116:119], v[132:135], v[188:191], v[116:119]
	v_mfma_f32_16x16x32_bf16 v[112:115], v[140:143], v[188:191], v[112:115]
	v_mfma_f32_16x16x32_bf16 v[108:111], v[132:135], v[196:199], v[108:111]
	v_mfma_f32_16x16x32_bf16 v[104:107], v[140:143], v[196:199], v[104:107]
	v_mfma_f32_16x16x32_bf16 v[100:103], v[132:135], v[204:207], v[100:103]
	v_mfma_f32_16x16x32_bf16 v[96:99], v[140:143], v[204:207], v[96:99]
	v_mfma_f32_16x16x32_bf16 v[60:63], v[150:153], v[166:169], v[60:63]
	v_mfma_f32_16x16x32_bf16 v[56:59], v[158:161], v[166:169], v[56:59]
	v_mfma_f32_16x16x32_bf16 v[52:55], v[150:153], v[184:187], v[52:55]
	v_mfma_f32_16x16x32_bf16 v[48:51], v[158:161], v[184:187], v[48:51]
	v_mfma_f32_16x16x32_bf16 v[44:47], v[150:153], v[192:195], v[44:47]
	v_mfma_f32_16x16x32_bf16 v[40:43], v[158:161], v[192:195], v[40:43]
	v_mfma_f32_16x16x32_bf16 v[36:39], v[150:153], v[200:203], v[36:39]
	v_mfma_f32_16x16x32_bf16 v[32:35], v[158:161], v[200:203], v[32:35]
	v_mfma_f32_16x16x32_bf16 v[60:63], v[154:157], v[170:173], v[60:63]
	v_mfma_f32_16x16x32_bf16 v[56:59], v[162:165], v[170:173], v[56:59]
	v_mfma_f32_16x16x32_bf16 v[52:55], v[154:157], v[188:191], v[52:55]
	v_mfma_f32_16x16x32_bf16 v[48:51], v[162:165], v[188:191], v[48:51]
	v_mfma_f32_16x16x32_bf16 v[44:47], v[154:157], v[196:199], v[44:47]
	v_mfma_f32_16x16x32_bf16 v[40:43], v[162:165], v[196:199], v[40:43]
	v_mfma_f32_16x16x32_bf16 v[36:39], v[154:157], v[204:207], v[36:39]
	v_mfma_f32_16x16x32_bf16 v[32:35], v[162:165], v[204:207], v[32:35]
	s_setprio 0
	s_barrier
	s_add_u32 s62, s38, 0x80
	s_addc_u32 s63, s39, 0
	ds_read_b128 v[166:169], v181 offset:49152
	ds_read_b128 v[170:173], v181 offset:50176
	ds_read_b128 v[184:187], v181 offset:51200
	ds_read_b128 v[188:191], v181 offset:52224
	ds_read_b128 v[192:195], v181 offset:53248
	ds_read_b128 v[196:199], v181 offset:54272
	ds_read_b128 v[200:203], v181 offset:55296
	ds_read_b128 v[204:207], v181 offset:56320
	s_mov_b32 m0, s48
	s_nop 0
	global_load_lds_dwordx4 v145, s[62:63]
	s_add_u32 s62, s38, 0x58080
	s_mov_b32 m0, s49
	s_addc_u32 s63, s39, 0
	global_load_lds_dwordx4 v145, s[62:63]
	s_add_u32 s62, s38, 0xb0080
	s_mov_b32 m0, s52
	s_addc_u32 s63, s39, 0
	global_load_lds_dwordx4 v145, s[62:63]
	s_add_u32 s38, s38, 0x108080
	s_mov_b32 m0, s53
	s_addc_u32 s39, s39, 0
	global_load_lds_dwordx4 v145, s[38:39]
	s_mov_b32 m0, s50
	s_nop 0
	global_load_lds_dwordx4 v144, s[26:27]
	s_add_u32 s24, s24, 0x58080
	s_mov_b32 m0, s51
	s_addc_u32 s25, s25, 0
	global_load_lds_dwordx4 v144, s[24:25]
	s_waitcnt vmcnt(8) lgkmcnt(0)
	s_barrier
	s_setprio 1
	v_mfma_f32_16x16x32_bf16 v[92:95], v[128:131], v[166:169], v[92:95]
	v_mfma_f32_16x16x32_bf16 v[88:91], v[136:139], v[166:169], v[88:91]
	v_mfma_f32_16x16x32_bf16 v[84:87], v[128:131], v[184:187], v[84:87]
	v_mfma_f32_16x16x32_bf16 v[80:83], v[136:139], v[184:187], v[80:83]
	v_mfma_f32_16x16x32_bf16 v[76:79], v[128:131], v[192:195], v[76:79]
	v_mfma_f32_16x16x32_bf16 v[72:75], v[136:139], v[192:195], v[72:75]
	v_mfma_f32_16x16x32_bf16 v[68:71], v[128:131], v[200:203], v[68:71]
	v_mfma_f32_16x16x32_bf16 v[64:67], v[136:139], v[200:203], v[64:67]
	v_mfma_f32_16x16x32_bf16 v[92:95], v[132:135], v[170:173], v[92:95]
	v_mfma_f32_16x16x32_bf16 v[88:91], v[140:143], v[170:173], v[88:91]
	v_mfma_f32_16x16x32_bf16 v[84:87], v[132:135], v[188:191], v[84:87]
	v_mfma_f32_16x16x32_bf16 v[80:83], v[140:143], v[188:191], v[80:83]
	v_mfma_f32_16x16x32_bf16 v[76:79], v[132:135], v[196:199], v[76:79]
	v_mfma_f32_16x16x32_bf16 v[72:75], v[140:143], v[196:199], v[72:75]
	v_mfma_f32_16x16x32_bf16 v[68:71], v[132:135], v[204:207], v[68:71]
	v_mfma_f32_16x16x32_bf16 v[64:67], v[140:143], v[204:207], v[64:67]
	v_mfma_f32_16x16x32_bf16 v[28:31], v[150:153], v[166:169], v[28:31]
	v_mfma_f32_16x16x32_bf16 v[24:27], v[158:161], v[166:169], v[24:27]
	v_mfma_f32_16x16x32_bf16 v[20:23], v[150:153], v[184:187], v[20:23]
	v_mfma_f32_16x16x32_bf16 v[16:19], v[158:161], v[184:187], v[16:19]
	v_mfma_f32_16x16x32_bf16 v[12:15], v[150:153], v[192:195], v[12:15]
	v_mfma_f32_16x16x32_bf16 v[8:11], v[158:161], v[192:195], v[8:11]
	v_mfma_f32_16x16x32_bf16 v[4:7], v[150:153], v[200:203], v[4:7]
	v_mfma_f32_16x16x32_bf16 v[0:3], v[158:161], v[200:203], v[0:3]
	v_mfma_f32_16x16x32_bf16 v[28:31], v[154:157], v[170:173], v[28:31]
	v_mfma_f32_16x16x32_bf16 v[24:27], v[162:165], v[170:173], v[24:27]
	v_mfma_f32_16x16x32_bf16 v[20:23], v[154:157], v[188:191], v[20:23]
	v_mfma_f32_16x16x32_bf16 v[16:19], v[162:165], v[188:191], v[16:19]
	v_mfma_f32_16x16x32_bf16 v[12:15], v[154:157], v[196:199], v[12:15]
	v_mfma_f32_16x16x32_bf16 v[8:11], v[162:165], v[196:199], v[8:11]
	v_mfma_f32_16x16x32_bf16 v[4:7], v[154:157], v[204:207], v[4:7]
	v_mfma_f32_16x16x32_bf16 v[0:3], v[162:165], v[204:207], v[0:3]
	s_setprio 0
	s_barrier
	s_cmp_gt_u32 s61, 41
	s_cbranch_scc0 .LBB0_1559
	s_and_b64 vcc, exec, s[12:13]
	s_cbranch_vccz .LBB0_1562
	s_barrier
